# speedup vs baseline: 1.0024x; 1.0024x over previous
; #define PG8_STAGE(bufoff, gbase, voff) do { _Pragma("unroll") for (int _i = 0; _i < 2; ++_i) \
;         __builtin_amdgcn_global_load_lds((const unsigned*)((const char*)(gbase) + (voff)[_i]), (LAS unsigned*)(lds + (bufoff) + ldsw + _i * 8192), 16, 0, 0); } while (0)
; #define PG8_LDA(dst, b, h) do { _Pragma("unroll") for (int m = 0; m < 4; ++m) _Pragma("unroll") for (int k = 0; k < 2; ++k) dst[m][k] = *(const LAS bf16x8*)(lds + PG8_SA(b, h) + aoff + m * 2048 + k * 1024); } while (0)
; #define PG8_LDB(dst, b, h) do { _Pragma("unroll") for (int n = 0; n < 2; ++n) _Pragma("unroll") for (int k = 0; k < 2; ++k) dst[n][k] = *(const LAS bf16x8*)(lds + PG8_SB(b, h) + boff + n * 2048 + k * 1024); } while (0)
; #define PG8_MMA(ai, bj, At, Bt) do { __builtin_amdgcn_s_setprio(1); _Pragma("unroll") for (int m = 0; m < 4; ++m) _Pragma("unroll") for (int n = 0; n < 2; ++n) _Pragma("unroll") for (int k = 0; k < 2; ++k) \
;         acc[ai][bj][m][n] = __builtin_amdgcn_mfma_f32_16x16x32_bf16(Bt[n][k], At[m][k], acc[ai][bj][m][n], 0, 0, 0); __builtin_amdgcn_s_setprio(0); } while (0)
; #define PG8_WAIT_L(n) asm volatile("s_waitcnt lgkmcnt(" #n ")" ::: "memory")
; #define PG8_BAR __builtin_amdgcn_s_barrier()
; #define PG8_SCHED __builtin_amdgcn_sched_barrier(0)
; template <class Epi>
; DEV void gemm_phase(LAS unsigned char* lds, const Gemm g, const StaticOrder& S, const Epi& E) {
;     ...
;             PG8_LDB(B0, 0, 0); PG8_SCHED; PG8_LDA(At, 0, 0); PG8_STAGE(PG8_SA(1, 1), a1 + hstep, voffA);
;             PG8_WAIT_L(8); PG8_BAR; PG8_WAIT_L(0); PG8_MMA(0, 0, At, B0); PG8_BAR; PG8_SCHED;
;             PG8_LDB(B1, 0, 1); PG8_STAGE(PG8_SB(0, 0), b2, voffB);
;             PG8_BAR; PG8_WAIT_L(0); PG8_MMA(0, 1, At, B1); PG8_BAR;
;             PG8_LDA(At, 0, 1); PG8_STAGE(PG8_SA(0, 0), a2, voffA);
;             PG8_BAR; PG8_WAIT_L(0); PG8_MMA(1, 0, At, B0); PG8_BAR; PG8_SCHED;
.LBB0_61:
	s_add_u32 s28, s26, 0xfff80080
	s_addc_u32 s29, s27, -1
	s_add_i32 s49, 0, 0x10000
	v_add_u32_e32 v140, s49, v178
	ds_read_b128 v[128:131], v140
	ds_read_b128 v[132:135], v140 offset:1024
	ds_read_b128 v[136:139], v140 offset:2048
	ds_read_b128 v[140:143], v140 offset:3072
	s_cmp_eq_u32 s48, 28
	s_cselect_b32 s31, s15, s29
	s_cselect_b32 s30, s19, s28
	s_cselect_b32 s29, s17, s47
	s_cselect_b32 s28, s25, s46
	v_lshl_add_u64 v[158:159], s[26:27], 0, v[150:151]
	s_add_i32 m0, s37, 0xc000
	ds_read_b128 v[154:157], v181
	ds_read_b128 v[174:177], v181 offset:1024
	ds_read_b128 v[182:185], v181 offset:2048
	ds_read_b128 v[186:189], v181 offset:3072
	ds_read_b128 v[190:193], v181 offset:4096
	ds_read_b128 v[194:197], v181 offset:5120
	ds_read_b128 v[214:217], v181 offset:6144
	ds_read_b128 v[218:221], v181 offset:7168
	global_load_lds_dwordx4 v[158:159], off
	v_lshl_add_u64 v[158:159], s[26:27], 0, v[152:153]
	s_add_i32 m0, s37, 0xe000
	s_nop 0
	global_load_lds_dwordx4 v[158:159], off
	s_waitcnt lgkmcnt(8)
	s_waitcnt vmcnt(10)
	s_barrier
	s_waitcnt lgkmcnt(0)
	s_setprio 1
	v_mfma_f32_16x16x32_bf16 v[124:127], v[128:131], v[154:157], v[124:127]
	v_mfma_f32_16x16x32_bf16 v[120:123], v[136:139], v[154:157], v[120:123]
	v_mfma_f32_16x16x32_bf16 v[108:111], v[128:131], v[182:185], v[108:111]
	v_mfma_f32_16x16x32_bf16 v[104:107], v[136:139], v[182:185], v[104:107]
	v_mfma_f32_16x16x32_bf16 v[92:95], v[128:131], v[190:193], v[92:95]
	v_mfma_f32_16x16x32_bf16 v[88:91], v[136:139], v[190:193], v[88:91]
	v_mfma_f32_16x16x32_bf16 v[76:79], v[128:131], v[214:217], v[76:79]
	v_mfma_f32_16x16x32_bf16 v[72:75], v[136:139], v[214:217], v[72:75]
	v_mfma_f32_16x16x32_bf16 v[124:127], v[132:135], v[174:177], v[124:127]
	v_mfma_f32_16x16x32_bf16 v[120:123], v[140:143], v[174:177], v[120:123]
	v_mfma_f32_16x16x32_bf16 v[108:111], v[132:135], v[186:189], v[108:111]
	v_mfma_f32_16x16x32_bf16 v[104:107], v[140:143], v[186:189], v[104:107]
	v_mfma_f32_16x16x32_bf16 v[92:95], v[132:135], v[194:197], v[92:95]
	v_mfma_f32_16x16x32_bf16 v[88:91], v[140:143], v[194:197], v[88:91]
	v_mfma_f32_16x16x32_bf16 v[76:79], v[132:135], v[218:221], v[76:79]
	v_mfma_f32_16x16x32_bf16 v[72:75], v[140:143], v[218:221], v[72:75]
	s_setprio 0
	s_barrier
	s_add_i32 s52, 0, 0x14000
	v_add_u32_e32 v158, s52, v178
	s_add_i32 s49, s49, s36
	ds_read_b128 v[222:225], v158
	ds_read_b128 v[226:229], v158 offset:1024
	ds_read_b128 v[230:233], v158 offset:2048
	ds_read_b128 v[234:237], v158 offset:3072
	v_lshl_add_u64 v[158:159], s[28:29], 0, v[160:161]
	s_mov_b32 m0, s49
	v_lshl_add_u64 v[238:239], s[28:29], 0, v[148:149]
	global_load_lds_dwordx4 v[158:159], off
	s_add_i32 m0, s49, 0x2000
	s_nop 0
	global_load_lds_dwordx4 v[238:239], off
	s_waitcnt vmcnt(10)
	s_barrier
	s_waitcnt lgkmcnt(0)
	s_setprio 1
	v_mfma_f32_16x16x32_bf16 v[116:119], v[222:225], v[154:157], v[116:119]
	v_mfma_f32_16x16x32_bf16 v[112:115], v[230:233], v[154:157], v[112:115]
	v_mfma_f32_16x16x32_bf16 v[100:103], v[222:225], v[182:185], v[100:103]
	v_mfma_f32_16x16x32_bf16 v[96:99], v[230:233], v[182:185], v[96:99]
	v_mfma_f32_16x16x32_bf16 v[84:87], v[222:225], v[190:193], v[84:87]
	v_mfma_f32_16x16x32_bf16 v[80:83], v[230:233], v[190:193], v[80:83]
	v_mfma_f32_16x16x32_bf16 v[68:71], v[222:225], v[214:217], v[68:71]
	v_mfma_f32_16x16x32_bf16 v[64:67], v[230:233], v[214:217], v[64:67]
	v_mfma_f32_16x16x32_bf16 v[116:119], v[226:229], v[174:177], v[116:119]
	v_mfma_f32_16x16x32_bf16 v[112:115], v[234:237], v[174:177], v[112:115]
	v_mfma_f32_16x16x32_bf16 v[100:103], v[226:229], v[186:189], v[100:103]
	v_mfma_f32_16x16x32_bf16 v[96:99], v[234:237], v[186:189], v[96:99]
	v_mfma_f32_16x16x32_bf16 v[84:87], v[226:229], v[194:197], v[84:87]
	v_mfma_f32_16x16x32_bf16 v[80:83], v[234:237], v[194:197], v[80:83]
	v_mfma_f32_16x16x32_bf16 v[68:71], v[226:229], v[218:221], v[68:71]
	v_mfma_f32_16x16x32_bf16 v[64:67], v[234:237], v[218:221], v[64:67]
	s_setprio 0
	s_mov_b32 m0, s37
	v_lshl_add_u64 v[240:241], s[30:31], 0, v[144:145]
	s_barrier
	ds_read_b128 v[154:157], v181 offset:16384
	ds_read_b128 v[174:177], v181 offset:17408
	ds_read_b128 v[182:185], v181 offset:18432
	ds_read_b128 v[186:189], v181 offset:19456
	ds_read_b128 v[190:193], v181 offset:20480
	ds_read_b128 v[194:197], v181 offset:21504
	ds_read_b128 v[214:217], v181 offset:22528
	ds_read_b128 v[218:221], v181 offset:23552
	global_load_lds_dwordx4 v[240:241], off
	v_lshl_add_u64 v[242:243], s[30:31], 0, v[146:147]
	s_mov_b32 m0, s38
	s_nop 0
	global_load_lds_dwordx4 v[242:243], off
	s_barrier
	s_waitcnt lgkmcnt(0)
	s_setprio 1
	v_mfma_f32_16x16x32_bf16 v[60:63], v[128:131], v[154:157], v[60:63]
	v_mfma_f32_16x16x32_bf16 v[56:59], v[136:139], v[154:157], v[56:59]
	v_mfma_f32_16x16x32_bf16 v[44:47], v[128:131], v[182:185], v[44:47]
	v_mfma_f32_16x16x32_bf16 v[40:43], v[136:139], v[182:185], v[40:43]
	v_mfma_f32_16x16x32_bf16 v[28:31], v[128:131], v[190:193], v[28:31]
	v_mfma_f32_16x16x32_bf16 v[24:27], v[136:139], v[190:193], v[24:27]
	v_mfma_f32_16x16x32_bf16 v[12:15], v[128:131], v[214:217], v[12:15]
	v_mfma_f32_16x16x32_bf16 v[8:11], v[136:139], v[214:217], v[8:11]
	v_mfma_f32_16x16x32_bf16 v[60:63], v[132:135], v[174:177], v[60:63]
	v_mfma_f32_16x16x32_bf16 v[56:59], v[140:143], v[174:177], v[56:59]
	v_mfma_f32_16x16x32_bf16 v[44:47], v[132:135], v[186:189], v[44:47]
	v_mfma_f32_16x16x32_bf16 v[40:43], v[140:143], v[186:189], v[40:43]
	v_mfma_f32_16x16x32_bf16 v[28:31], v[132:135], v[194:197], v[28:31]
	v_mfma_f32_16x16x32_bf16 v[24:27], v[140:143], v[194:197], v[24:27]
	v_mfma_f32_16x16x32_bf16 v[12:15], v[132:135], v[218:221], v[12:15]
	v_mfma_f32_16x16x32_bf16 v[8:11], v[140:143], v[218:221], v[8:11]
	s_setprio 0
	s_barrier
; #define PG8_STAGE(bufoff, gbase, voff) do { _Pragma("unroll") for (int _i = 0; _i < 2; ++_i) \
;         __builtin_amdgcn_global_load_lds((const unsigned*)((const char*)(gbase) + (voff)[_i]), (LAS unsigned*)(lds + (bufoff) + ldsw + _i * 8192), 16, 0, 0); } while (0)
; #define PG8_LDA(dst, b, h) do { _Pragma("unroll") for (int m = 0; m < 4; ++m) _Pragma("unroll") for (int k = 0; k < 2; ++k) dst[m][k] = *(const LAS bf16x8*)(lds + PG8_SA(b, h) + aoff + m * 2048 + k * 1024); } while (0)
; #define PG8_LDB(dst, b, h) do { _Pragma("unroll") for (int n = 0; n < 2; ++n) _Pragma("unroll") for (int k = 0; k < 2; ++k) dst[n][k] = *(const LAS bf16x8*)(lds + PG8_SB(b, h) + boff + n * 2048 + k * 1024); } while (0)
; #define PG8_MMA(ai, bj, At, Bt) do { __builtin_amdgcn_s_setprio(1); _Pragma("unroll") for (int m = 0; m < 4; ++m) _Pragma("unroll") for (int n = 0; n < 2; ++n) _Pragma("unroll") for (int k = 0; k < 2; ++k) \
;         acc[ai][bj][m][n] = __builtin_amdgcn_mfma_f32_16x16x32_bf16(Bt[n][k], At[m][k], acc[ai][bj][m][n], 0, 0, 0); __builtin_amdgcn_s_setprio(0); } while (0)
; #define PG8_WAIT_V(n) asm volatile("s_waitcnt vmcnt(" #n ")" ::: "memory")
; #define PG8_WAIT_L(n) asm volatile("s_waitcnt lgkmcnt(" #n ")" ::: "memory")
; #define PG8_BAR __builtin_amdgcn_s_barrier()
; #define PG8_SCHED __builtin_amdgcn_sched_barrier(0)
; template <class Epi>
; DEV void gemm_phase(LAS unsigned char* lds, const Gemm g, const StaticOrder& S, const Epi& E) {
;     ...
;             PG8_STAGE(PG8_SB(0, 1), b2 + hstep, voffB);
;             PG8_WAIT_V(6); PG8_BAR; PG8_MMA(1, 1, At, B1); PG8_BAR;
;             PG8_LDB(B0, 1, 0); PG8_SCHED; PG8_LDA(At, 1, 0); PG8_STAGE(PG8_SA(0, 1), a2 + hstep, voffA);
;             PG8_WAIT_L(8); PG8_BAR; PG8_WAIT_L(0); PG8_MMA(0, 0, At, B0); PG8_BAR; PG8_SCHED;
;             PG8_LDB(B1, 1, 1); PG8_STAGE(PG8_SB(1, 0), b3, voffB);
;             PG8_BAR; PG8_WAIT_L(0); PG8_MMA(0, 1, At, B1); PG8_BAR;
;             PG8_LDA(At, 1, 1); PG8_STAGE(PG8_SA(1, 0), a3, voffA);
	s_add_u32 s50, s28, 0x80000
	s_addc_u32 s51, s29, 0
	s_add_i32 s49, s52, s36
	v_lshl_add_u64 v[128:129], s[50:51], 0, v[160:161]
	s_mov_b32 m0, s49
	s_nop 0
	global_load_lds_dwordx4 v[128:129], off
	v_lshl_add_u64 v[128:129], s[50:51], 0, v[148:149]
	s_add_i32 m0, s49, 0x2000
	s_nop 0
	global_load_lds_dwordx4 v[128:129], off
	s_waitcnt vmcnt(10)
	s_barrier
	s_setprio 1
	v_mfma_f32_16x16x32_bf16 v[52:55], v[222:225], v[154:157], v[52:55]
	v_mfma_f32_16x16x32_bf16 v[48:51], v[230:233], v[154:157], v[48:51]
	v_mfma_f32_16x16x32_bf16 v[36:39], v[222:225], v[182:185], v[36:39]
	v_mfma_f32_16x16x32_bf16 v[32:35], v[230:233], v[182:185], v[32:35]
	v_mfma_f32_16x16x32_bf16 v[20:23], v[222:225], v[190:193], v[20:23]
	v_mfma_f32_16x16x32_bf16 v[16:19], v[230:233], v[190:193], v[16:19]
	v_mfma_f32_16x16x32_bf16 v[4:7], v[222:225], v[214:217], v[4:7]
	v_mfma_f32_16x16x32_bf16 v[0:3], v[230:233], v[214:217], v[0:3]
	v_mfma_f32_16x16x32_bf16 v[52:55], v[226:229], v[174:177], v[52:55]
	v_mfma_f32_16x16x32_bf16 v[48:51], v[234:237], v[174:177], v[48:51]
	v_mfma_f32_16x16x32_bf16 v[36:39], v[226:229], v[186:189], v[36:39]
	v_mfma_f32_16x16x32_bf16 v[32:35], v[234:237], v[186:189], v[32:35]
	v_mfma_f32_16x16x32_bf16 v[20:23], v[226:229], v[194:197], v[20:23]
	v_mfma_f32_16x16x32_bf16 v[16:19], v[234:237], v[194:197], v[16:19]
	v_mfma_f32_16x16x32_bf16 v[4:7], v[226:229], v[218:221], v[4:7]
	v_mfma_f32_16x16x32_bf16 v[0:3], v[234:237], v[218:221], v[0:3]
	s_setprio 0
	s_add_i32 s49, 0, 0x18000
	v_add_u32_e32 v140, s49, v178
	s_barrier
	ds_read_b128 v[128:131], v140
	ds_read_b128 v[132:135], v140 offset:1024
	ds_read_b128 v[136:139], v140 offset:2048
	ds_read_b128 v[140:143], v140 offset:3072
	s_add_u32 s30, s30, 0x80000
	s_addc_u32 s31, s31, 0
	s_mov_b32 m0, s39
	v_lshl_add_u64 v[222:223], s[30:31], 0, v[144:145]
	ds_read_b128 v[154:157], v181 offset:32768
	ds_read_b128 v[174:177], v181 offset:33792
	ds_read_b128 v[182:185], v181 offset:34816
	ds_read_b128 v[186:189], v181 offset:35840
	ds_read_b128 v[190:193], v181 offset:36864
	ds_read_b128 v[194:197], v181 offset:37888
	ds_read_b128 v[214:217], v181 offset:38912
	ds_read_b128 v[218:221], v181 offset:39936
	global_load_lds_dwordx4 v[222:223], off
	v_lshl_add_u64 v[222:223], s[30:31], 0, v[146:147]
	s_mov_b32 m0, s40
	s_nop 0
	global_load_lds_dwordx4 v[222:223], off
	s_waitcnt lgkmcnt(8)
	s_waitcnt vmcnt(10)
	s_barrier
	s_waitcnt lgkmcnt(0)
	s_setprio 1
	v_mfma_f32_16x16x32_bf16 v[124:127], v[128:131], v[154:157], v[124:127]
	v_mfma_f32_16x16x32_bf16 v[120:123], v[136:139], v[154:157], v[120:123]
	v_mfma_f32_16x16x32_bf16 v[108:111], v[128:131], v[182:185], v[108:111]
	v_mfma_f32_16x16x32_bf16 v[104:107], v[136:139], v[182:185], v[104:107]
	v_mfma_f32_16x16x32_bf16 v[92:95], v[128:131], v[190:193], v[92:95]
	v_mfma_f32_16x16x32_bf16 v[88:91], v[136:139], v[190:193], v[88:91]
	v_mfma_f32_16x16x32_bf16 v[76:79], v[128:131], v[214:217], v[76:79]
	v_mfma_f32_16x16x32_bf16 v[72:75], v[136:139], v[214:217], v[72:75]
	v_mfma_f32_16x16x32_bf16 v[124:127], v[132:135], v[174:177], v[124:127]
	v_mfma_f32_16x16x32_bf16 v[120:123], v[140:143], v[174:177], v[120:123]
	v_mfma_f32_16x16x32_bf16 v[108:111], v[132:135], v[186:189], v[108:111]
	v_mfma_f32_16x16x32_bf16 v[104:107], v[140:143], v[186:189], v[104:107]
	v_mfma_f32_16x16x32_bf16 v[92:95], v[132:135], v[194:197], v[92:95]
	v_mfma_f32_16x16x32_bf16 v[88:91], v[140:143], v[194:197], v[88:91]
	v_mfma_f32_16x16x32_bf16 v[76:79], v[132:135], v[218:221], v[76:79]
	v_mfma_f32_16x16x32_bf16 v[72:75], v[140:143], v[218:221], v[72:75]
	s_setprio 0
	s_barrier
	s_add_i32 s30, 0, 0x1c000
	s_add_i32 s31, s49, s36
	v_add_u32_e32 v234, s30, v178
	v_lshl_add_u64 v[158:159], v[158:159], 0, s[2:3]
	s_mov_b32 m0, s31
	ds_read_b128 v[222:225], v234
	ds_read_b128 v[226:229], v234 offset:1024
	ds_read_b128 v[230:233], v234 offset:2048
	ds_read_b128 v[234:237], v234 offset:3072
	global_load_lds_dwordx4 v[158:159], off
	v_lshl_add_u64 v[158:159], v[238:239], 0, s[2:3]
	s_add_i32 m0, s31, 0x2000
	s_nop 0
	global_load_lds_dwordx4 v[158:159], off
	s_waitcnt vmcnt(10)
	s_barrier
	s_waitcnt lgkmcnt(0)
	s_setprio 1
	v_mfma_f32_16x16x32_bf16 v[116:119], v[222:225], v[154:157], v[116:119]
	v_mfma_f32_16x16x32_bf16 v[112:115], v[230:233], v[154:157], v[112:115]
	v_mfma_f32_16x16x32_bf16 v[100:103], v[222:225], v[182:185], v[100:103]
	v_mfma_f32_16x16x32_bf16 v[96:99], v[230:233], v[182:185], v[96:99]
	v_mfma_f32_16x16x32_bf16 v[84:87], v[222:225], v[190:193], v[84:87]
	v_mfma_f32_16x16x32_bf16 v[80:83], v[230:233], v[190:193], v[80:83]
	v_mfma_f32_16x16x32_bf16 v[68:71], v[222:225], v[214:217], v[68:71]
	v_mfma_f32_16x16x32_bf16 v[64:67], v[230:233], v[214:217], v[64:67]
	v_mfma_f32_16x16x32_bf16 v[116:119], v[226:229], v[174:177], v[116:119]
	v_mfma_f32_16x16x32_bf16 v[112:115], v[234:237], v[174:177], v[112:115]
	v_mfma_f32_16x16x32_bf16 v[100:103], v[226:229], v[186:189], v[100:103]
	v_mfma_f32_16x16x32_bf16 v[96:99], v[234:237], v[186:189], v[96:99]
	v_mfma_f32_16x16x32_bf16 v[84:87], v[226:229], v[194:197], v[84:87]
	v_mfma_f32_16x16x32_bf16 v[80:83], v[234:237], v[194:197], v[80:83]
	v_mfma_f32_16x16x32_bf16 v[68:71], v[226:229], v[218:221], v[68:71]
	v_mfma_f32_16x16x32_bf16 v[64:67], v[234:237], v[218:221], v[64:67]
	s_setprio 0
	s_mov_b32 m0, s41
	v_lshl_add_u64 v[158:159], v[240:241], 0, s[2:3]
	s_barrier
	ds_read_b128 v[154:157], v181 offset:49152
	ds_read_b128 v[174:177], v181 offset:50176
	ds_read_b128 v[182:185], v181 offset:51200
	ds_read_b128 v[186:189], v181 offset:52224
	ds_read_b128 v[190:193], v181 offset:53248
	ds_read_b128 v[194:197], v181 offset:54272
	ds_read_b128 v[214:217], v181 offset:55296
	ds_read_b128 v[218:221], v181 offset:56320
	global_load_lds_dwordx4 v[158:159], off
	v_lshl_add_u64 v[158:159], v[242:243], 0, s[2:3]
	s_mov_b32 m0, s42
	s_nop 0
	global_load_lds_dwordx4 v[158:159], off
	s_barrier
; DEV bf16x8 pack8(f32x4 a, f32x4 b) { u32x4 w; w.x = cvt_pk_bf16(a[0], a[1]); w.y = cvt_pk_bf16(a[2], a[3]); w.z = cvt_pk_bf16(b[0], b[1]); w.w = cvt_pk_bf16(b[2], b[3]); return __builtin_bit_cast(bf16x8, w); }
; #define PG8_WAIT_V(n) asm volatile("s_waitcnt vmcnt(" #n ")" ::: "memory")
; #define PG8_WAIT_L(n) asm volatile("s_waitcnt lgkmcnt(" #n ")" ::: "memory")
; #define PG8_BAR __builtin_amdgcn_s_barrier()
; #define PG8_SCHED __builtin_amdgcn_sched_barrier(0)
; template <class Epi>
; DEV void gemm_phase(LAS unsigned char* lds, const Gemm g, const StaticOrder& S, const Epi& E) {
;     ...
;             PG8_BAR; PG8_WAIT_L(0); PG8_MMA(1, 0, At, B0); PG8_BAR; PG8_SCHED;
;             PG8_STAGE(PG8_SB(1, 1), b3 + hstep, voffB);
;             PG8_WAIT_V(6); PG8_BAR; PG8_MMA(1, 1, At, B1); PG8_BAR;
;     DEV void operator()(AccRef acc, const pg8::Unit& u, int wr, int wc, int fr, int fq) const {
;         const int row0 = u.pm * 256 + wr * 64 + fr, col0 = u.pn * 256 + wc * 32 + 8 * fq;
; #pragma unroll
;         for (int am = 0; am < 4; ++am) { const int ai = am >> 1, m0 = (am & 1) * 2;
;             f32x4 bv[4][2][2];
; #pragma unroll
;             for (int m = m0; m < m0 + 2; ++m)
; #pragma unroll
;                 for (int bj = 0; bj < 2; ++bj)
; #pragma unroll
;                     for (int n = 0; n < 2; ++n) bv[m][bj][n] = *(const f32x4*)(base + (size_t)(row0 + ai * 128 + m * 16) * 2048 + col0 + bj * 128 + n * 4);
; #pragma unroll
;             for (int m = m0; m < m0 + 2; ++m) { const size_t off = (size_t)(row0 + ai * 128 + m * 16) * 2048 + col0; float sq = 0.f;
; #pragma unroll
;                 for (int bj = 0; bj < 2; ++bj) { const f32x4 o0 = bv[m][bj][0] + scale * acc[ai][bj][m][0], o1 = bv[m][bj][1] + scale * acc[ai][bj][m][1];
;                     *(f32x4*)(out + off + bj * 128) = o0; *(f32x4*)(out + off + bj * 128 + 4) = o1;
;                     if (xb) { *(u32x4*)(xb + off + bj * 128) = __builtin_bit_cast(u32x4, pack8(o0, o1));
;                         sq += (o0[0] * o0[0] + o0[1] * o0[1] + o0[2] * o0[2] + o0[3] * o0[3]) + (o1[0] * o1[0] + o1[1] * o1[1] + o1[2] * o1[2] + o1[3] * o1[3]); } }
;                 if (ssout) { sq += __shfl_xor(sq, 16); sq += __shfl_xor(sq, 32);
;                     if (fq == 0) { if (red) red[(ai * 128 + wr * 64 + m * 16 + fr) * 4 + wc] = sq; else atomicAdd(ssout + (size_t)(row0 + ai * 128 + m * 16) * 8 + u.pn, sq); } } }
	s_waitcnt lgkmcnt(0)
	s_setprio 1
	v_mfma_f32_16x16x32_bf16 v[60:63], v[128:131], v[154:157], v[60:63]
	v_mfma_f32_16x16x32_bf16 v[56:59], v[136:139], v[154:157], v[56:59]
	v_mfma_f32_16x16x32_bf16 v[44:47], v[128:131], v[182:185], v[44:47]
	v_mfma_f32_16x16x32_bf16 v[40:43], v[136:139], v[182:185], v[40:43]
	v_mfma_f32_16x16x32_bf16 v[28:31], v[128:131], v[190:193], v[28:31]
	v_mfma_f32_16x16x32_bf16 v[24:27], v[136:139], v[190:193], v[24:27]
	v_mfma_f32_16x16x32_bf16 v[12:15], v[128:131], v[214:217], v[12:15]
	v_mfma_f32_16x16x32_bf16 v[8:11], v[136:139], v[214:217], v[8:11]
	v_mfma_f32_16x16x32_bf16 v[60:63], v[132:135], v[174:177], v[60:63]
	v_mfma_f32_16x16x32_bf16 v[56:59], v[140:143], v[174:177], v[56:59]
	v_mfma_f32_16x16x32_bf16 v[44:47], v[132:135], v[186:189], v[44:47]
	v_mfma_f32_16x16x32_bf16 v[40:43], v[140:143], v[186:189], v[40:43]
	v_mfma_f32_16x16x32_bf16 v[28:31], v[132:135], v[194:197], v[28:31]
	v_mfma_f32_16x16x32_bf16 v[24:27], v[140:143], v[194:197], v[24:27]
	v_mfma_f32_16x16x32_bf16 v[12:15], v[132:135], v[218:221], v[12:15]
	v_mfma_f32_16x16x32_bf16 v[8:11], v[140:143], v[218:221], v[8:11]
	s_setprio 0
	s_barrier
	s_add_u32 s28, s28, 0x80080
	s_addc_u32 s29, s29, 0
	s_add_i32 s30, s30, s36
	v_lshl_add_u64 v[128:129], s[28:29], 0, v[160:161]
	s_mov_b32 m0, s30
	s_nop 0
	global_load_lds_dwordx4 v[128:129], off
	v_lshl_add_u64 v[128:129], s[28:29], 0, v[148:149]
	s_add_i32 m0, s30, 0x2000
	s_nop 0
	global_load_lds_dwordx4 v[128:129], off
	s_waitcnt vmcnt(10)
	s_barrier
	s_setprio 1
	v_mfma_f32_16x16x32_bf16 v[52:55], v[222:225], v[154:157], v[52:55]
	v_mfma_f32_16x16x32_bf16 v[48:51], v[230:233], v[154:157], v[48:51]
	v_mfma_f32_16x16x32_bf16 v[36:39], v[222:225], v[182:185], v[36:39]
	v_mfma_f32_16x16x32_bf16 v[32:35], v[230:233], v[182:185], v[32:35]
	v_mfma_f32_16x16x32_bf16 v[20:23], v[222:225], v[190:193], v[20:23]
	v_mfma_f32_16x16x32_bf16 v[16:19], v[230:233], v[190:193], v[16:19]
	v_mfma_f32_16x16x32_bf16 v[4:7], v[222:225], v[214:217], v[4:7]
	v_mfma_f32_16x16x32_bf16 v[0:3], v[230:233], v[214:217], v[0:3]
	v_mfma_f32_16x16x32_bf16 v[52:55], v[226:229], v[174:177], v[52:55]
	v_mfma_f32_16x16x32_bf16 v[48:51], v[234:237], v[174:177], v[48:51]
	v_mfma_f32_16x16x32_bf16 v[36:39], v[226:229], v[186:189], v[36:39]
	v_mfma_f32_16x16x32_bf16 v[32:35], v[234:237], v[186:189], v[32:35]
	v_mfma_f32_16x16x32_bf16 v[20:23], v[226:229], v[194:197], v[20:23]
	v_mfma_f32_16x16x32_bf16 v[16:19], v[234:237], v[194:197], v[16:19]
	v_mfma_f32_16x16x32_bf16 v[4:7], v[226:229], v[218:221], v[4:7]
	v_mfma_f32_16x16x32_bf16 v[0:3], v[234:237], v[218:221], v[0:3]
	s_setprio 0
	s_add_i32 s48, s48, 2
	s_add_u32 s26, s26, 0x100
	s_addc_u32 s27, s27, 0
	s_add_u32 s46, s46, 0x100
	s_addc_u32 s47, s47, 0
	s_cmp_gt_u32 s48, 29
	s_barrier
	s_cbranch_scc0 .LBB0_61
	v_lshl_add_u32 v156, s24, 8, v167
	v_lshl_or_b32 v154, s14, 8, v179
	v_readlane_b32 s24, v254, 16
	v_ashrrev_i32_e32 v155, 31, v154
	v_readlane_b32 s25, v254, 17
	v_ashrrev_i32_e32 v157, 31, v156
	v_lshlrev_b64 v[128:129], 13, v[156:157]
	v_lshl_add_u64 v[158:159], v[154:155], 2, s[24:25]
	v_lshl_add_u64 v[214:215], v[158:159], 0, v[128:129]
	global_load_dwordx4 v[182:185], v[214:215], off offset:16
	global_load_dwordx4 v[186:189], v[214:215], off
	global_load_dwordx4 v[190:193], v[214:215], off offset:528
	global_load_dwordx4 v[194:197], v[214:215], off offset:512
	v_or_b32_e32 v174, 16, v156
	v_ashrrev_i32_e32 v175, 31, v174
	v_lshlrev_b64 v[128:129], 13, v[174:175]
	v_lshl_add_u64 v[176:177], v[158:159], 0, v[128:129]
	global_load_dwordx4 v[136:139], v[176:177], off offset:16
	global_load_dwordx4 v[140:143], v[176:177], off
	global_load_dwordx4 v[128:131], v[176:177], off offset:528
	global_load_dwordx4 v[132:135], v[176:177], off offset:512
	v_lshlrev_b64 v[216:217], 11, v[156:157]
	v_readlane_b32 s24, v250, 9
	v_lshl_add_u64 v[216:217], v[216:217], 0, v[154:155]
	v_readlane_b32 s25, v250, 10
	v_cmp_lt_i32_e32 vcc, v208, v206
	s_ashr_i32 s15, s14, 31
	s_waitcnt vmcnt(0)
	v_pk_add_f32 v[120:121], v[120:121], v[182:183]
	v_pk_add_f32 v[126:127], v[126:127], v[188:189]
	v_pk_add_f32 v[124:125], v[124:125], v[186:187]
	v_pk_add_f32 v[122:123], v[122:123], v[184:185]
	global_store_dwordx4 v[214:215], v[124:127], off
	global_store_dwordx4 v[214:215], v[120:123], off offset:16
	v_cvt_pk_bf16_f32 v184, v120, v121
	v_cvt_pk_bf16_f32 v182, v124, v125
	v_mul_f32_e32 v121, v121, v121
	v_cvt_pk_bf16_f32 v183, v126, v127
	v_cvt_pk_bf16_f32 v185, v122, v123
	v_lshl_add_u64 v[186:187], v[216:217], 1, s[24:25]
	v_fmac_f32_e32 v121, v120, v120
	v_pk_add_f32 v[118:119], v[118:119], v[196:197]
	v_pk_add_f32 v[116:117], v[116:117], v[194:195]
	v_pk_add_f32 v[112:113], v[112:113], v[190:191]
	global_store_dwordx4 v[186:187], v[182:185], off
	v_mul_f32_e32 v125, v125, v125
	v_fmac_f32_e32 v121, v122, v122
	v_pk_add_f32 v[114:115], v[114:115], v[192:193]
	global_store_dwordx4 v[214:215], v[116:119], off offset:512
	global_store_dwordx4 v[214:215], v[112:115], off offset:528
	v_cvt_pk_bf16_f32 v120, v116, v117
	v_cvt_pk_bf16_f32 v122, v112, v113
	v_mul_f32_e32 v117, v117, v117
	v_mul_f32_e32 v113, v113, v113
	v_fmac_f32_e32 v125, v124, v124
	v_fmac_f32_e32 v117, v116, v116
	v_fmac_f32_e32 v113, v112, v112
	v_fmac_f32_e32 v125, v126, v126
	v_fmac_f32_e32 v117, v118, v118
	v_fmac_f32_e32 v113, v114, v114
	v_fmac_f32_e32 v125, v127, v127
	v_fmac_f32_e32 v121, v123, v123
	v_fmac_f32_e32 v117, v119, v119
	v_fmac_f32_e32 v113, v115, v115
	v_add_f32_e32 v124, v125, v121
	v_add_f32_e32 v112, v117, v113
	v_cndmask_b32_e32 v113, v204, v208, vcc
	v_cvt_pk_bf16_f32 v121, v118, v119
	v_add_f32_e32 v112, v124, v112
	v_lshlrev_b32_e32 v118, 2, v113
	ds_bpermute_b32 v113, v118, v112
	v_cmp_lt_i32_e32 vcc, v207, v206
	v_cvt_pk_bf16_f32 v123, v114, v115
	global_store_dwordx4 v[186:187], v[120:123], off offset:256
	s_waitcnt lgkmcnt(0)
	v_add_f32_e32 v112, v112, v113
	v_cndmask_b32_e32 v113, v204, v207, vcc
	v_lshlrev_b32_e32 v119, 2, v113
	ds_bpermute_b32 v113, v119, v112
	s_and_saveexec_b64 s[24:25], s[6:7]
	s_cbranch_execz .LBB0_67
	s_waitcnt lgkmcnt(0)
	v_add_f32_e32 v112, v112, v113
	s_mov_b64 s[26:27], -1
	s_and_b64 vcc, exec, s[12:13]
	s_cbranch_vccz .LBB0_65
	v_readlane_b32 s26, v250, 37
	v_lshlrev_b64 v[114:115], 5, v[156:157]
	v_readlane_b32 s27, v250, 38
	s_nop 1
	v_lshl_add_u64 v[114:115], s[26:27], 0, v[114:115]
	v_lshl_add_u64 v[114:115], s[14:15], 2, v[114:115]
	global_atomic_add_f32 v[114:115], v112, off
	s_mov_b64 s[26:27], 0

; #define PG8_STAGE(bufoff, gbase, voff) do { _Pragma("unroll") for (int _i = 0; _i < 2; ++_i) \
;         __builtin_amdgcn_global_load_lds((const unsigned*)((const char*)(gbase) + (voff)[_i]), (LAS unsigned*)(lds + (bufoff) + ldsw + _i * 8192), 16, 0, 0); } while (0)
; #define PG8_LDA(dst, b, h) do { _Pragma("unroll") for (int m = 0; m < 4; ++m) _Pragma("unroll") for (int k = 0; k < 2; ++k) dst[m][k] = *(const LAS bf16x8*)(lds + PG8_SA(b, h) + aoff + m * 2048 + k * 1024); } while (0)
; #define PG8_LDB(dst, b, h) do { _Pragma("unroll") for (int n = 0; n < 2; ++n) _Pragma("unroll") for (int k = 0; k < 2; ++k) dst[n][k] = *(const LAS bf16x8*)(lds + PG8_SB(b, h) + boff + n * 2048 + k * 1024); } while (0)
; #define PG8_MMA(ai, bj, At, Bt) do { __builtin_amdgcn_s_setprio(1); _Pragma("unroll") for (int m = 0; m < 4; ++m) _Pragma("unroll") for (int n = 0; n < 2; ++n) _Pragma("unroll") for (int k = 0; k < 2; ++k) \
;         acc[ai][bj][m][n] = __builtin_amdgcn_mfma_f32_16x16x32_bf16(Bt[n][k], At[m][k], acc[ai][bj][m][n], 0, 0, 0); __builtin_amdgcn_s_setprio(0); } while (0)
; #define PG8_WAIT_L(n) asm volatile("s_waitcnt lgkmcnt(" #n ")" ::: "memory")
; #define PG8_BAR __builtin_amdgcn_s_barrier()
; #define PG8_SCHED __builtin_amdgcn_sched_barrier(0)
; template <class Epi>
; DEV void gemm_phase(LAS unsigned char* lds, const Gemm g, const StaticOrder& S, const Epi& E) {
;     ...
;             const bool last = (t == nt - 2);
;             const char* a1 = cA + (size_t)(t + 1) * kstep;
;             const char* a2 = last ? nA : cA + (size_t)(t + 2) * kstep; const char* b2 = last ? nB : cB + (size_t)(t + 2) * kstep;
;             const char* a3 = a2 + kstep; const char* b3 = b2 + kstep;
;             PG8_LDB(B0, 0, 0); PG8_SCHED; PG8_LDA(At, 0, 0); PG8_STAGE(PG8_SA(1, 1), a1 + hstep, voffA);
;             PG8_WAIT_L(8); PG8_BAR; PG8_WAIT_L(0); PG8_MMA(0, 0, At, B0); PG8_BAR; PG8_SCHED;
;             PG8_LDB(B1, 0, 1); PG8_STAGE(PG8_SB(0, 0), b2, voffB);
;             PG8_BAR; PG8_WAIT_L(0); PG8_MMA(0, 1, At, B1); PG8_BAR;
;             PG8_LDA(At, 0, 1); PG8_STAGE(PG8_SA(0, 0), a2, voffA);
;             PG8_BAR; PG8_WAIT_L(0); PG8_MMA(1, 0, At, B0); PG8_BAR; PG8_SCHED;
.LBB0_152:
	s_add_u32 s20, s18, 0xfff80080
	s_addc_u32 s21, s19, -1
	s_add_i32 s41, 0, 0x10000
	v_add_u32_e32 v140, s41, v176
	ds_read_b128 v[128:131], v140
	ds_read_b128 v[132:135], v140 offset:1024
	ds_read_b128 v[136:139], v140 offset:2048
	ds_read_b128 v[140:143], v140 offset:3072
	s_cmp_eq_u32 s40, 28
	s_cselect_b32 s23, s5, s21
	s_cselect_b32 s22, s11, s20
	s_cselect_b32 s21, s9, s39
	s_cselect_b32 s20, s37, s38
	v_lshl_add_u64 v[158:159], s[18:19], 0, v[154:155]
	s_add_i32 m0, s17, 0xc000
	ds_read_b128 v[180:183], v178
	ds_read_b128 v[184:187], v178 offset:1024
	ds_read_b128 v[188:191], v178 offset:2048
	ds_read_b128 v[192:195], v178 offset:3072
	ds_read_b128 v[214:217], v178 offset:4096
	ds_read_b128 v[218:221], v178 offset:5120
	ds_read_b128 v[222:225], v178 offset:6144
	ds_read_b128 v[226:229], v178 offset:7168
	global_load_lds_dwordx4 v[158:159], off
	v_lshl_add_u64 v[158:159], s[18:19], 0, v[156:157]
	s_add_i32 m0, s17, 0xe000
	s_nop 0
	global_load_lds_dwordx4 v[158:159], off
	s_waitcnt lgkmcnt(8)
	s_waitcnt vmcnt(10)
	s_barrier
	s_waitcnt lgkmcnt(0)
	s_setprio 1
	v_mfma_f32_16x16x32_bf16 v[124:127], v[128:131], v[180:183], v[124:127]
	v_mfma_f32_16x16x32_bf16 v[120:123], v[136:139], v[180:183], v[120:123]
	v_mfma_f32_16x16x32_bf16 v[108:111], v[128:131], v[188:191], v[108:111]
	v_mfma_f32_16x16x32_bf16 v[104:107], v[136:139], v[188:191], v[104:107]
	v_mfma_f32_16x16x32_bf16 v[92:95], v[128:131], v[214:217], v[92:95]
	v_mfma_f32_16x16x32_bf16 v[88:91], v[136:139], v[214:217], v[88:91]
	v_mfma_f32_16x16x32_bf16 v[76:79], v[128:131], v[222:225], v[76:79]
	v_mfma_f32_16x16x32_bf16 v[72:75], v[136:139], v[222:225], v[72:75]
	v_mfma_f32_16x16x32_bf16 v[124:127], v[132:135], v[184:187], v[124:127]
	v_mfma_f32_16x16x32_bf16 v[120:123], v[140:143], v[184:187], v[120:123]
	v_mfma_f32_16x16x32_bf16 v[108:111], v[132:135], v[192:195], v[108:111]
	v_mfma_f32_16x16x32_bf16 v[104:107], v[140:143], v[192:195], v[104:107]
	v_mfma_f32_16x16x32_bf16 v[92:95], v[132:135], v[218:221], v[92:95]
	v_mfma_f32_16x16x32_bf16 v[88:91], v[140:143], v[218:221], v[88:91]
	v_mfma_f32_16x16x32_bf16 v[76:79], v[132:135], v[226:229], v[76:79]
	v_mfma_f32_16x16x32_bf16 v[72:75], v[140:143], v[226:229], v[72:75]
	s_setprio 0
	s_barrier
	s_add_i32 s44, 0, 0x14000
	v_add_u32_e32 v158, s44, v176
	s_add_i32 s41, s41, s26
	ds_read_b128 v[230:233], v158
	ds_read_b128 v[234:237], v158 offset:1024
	ds_read_b128 v[238:241], v158 offset:2048
	ds_read_b128 v[242:245], v158 offset:3072
	v_lshl_add_u64 v[158:159], s[20:21], 0, v[160:161]
	s_mov_b32 m0, s41
	v_lshl_add_u64 v[174:175], s[20:21], 0, v[144:145]
	global_load_lds_dwordx4 v[158:159], off
	s_add_i32 m0, s41, 0x2000
	s_nop 0
	global_load_lds_dwordx4 v[174:175], off
	s_waitcnt vmcnt(10)
	s_barrier
	s_waitcnt lgkmcnt(0)
	s_setprio 1
	v_mfma_f32_16x16x32_bf16 v[116:119], v[230:233], v[180:183], v[116:119]
	v_mfma_f32_16x16x32_bf16 v[112:115], v[238:241], v[180:183], v[112:115]
	v_mfma_f32_16x16x32_bf16 v[100:103], v[230:233], v[188:191], v[100:103]
	v_mfma_f32_16x16x32_bf16 v[96:99], v[238:241], v[188:191], v[96:99]
	v_mfma_f32_16x16x32_bf16 v[84:87], v[230:233], v[214:217], v[84:87]
	v_mfma_f32_16x16x32_bf16 v[80:83], v[238:241], v[214:217], v[80:83]
	v_mfma_f32_16x16x32_bf16 v[68:71], v[230:233], v[222:225], v[68:71]
	v_mfma_f32_16x16x32_bf16 v[64:67], v[238:241], v[222:225], v[64:67]
	v_mfma_f32_16x16x32_bf16 v[116:119], v[234:237], v[184:187], v[116:119]
	v_mfma_f32_16x16x32_bf16 v[112:115], v[242:245], v[184:187], v[112:115]
	v_mfma_f32_16x16x32_bf16 v[100:103], v[234:237], v[192:195], v[100:103]
	v_mfma_f32_16x16x32_bf16 v[96:99], v[242:245], v[192:195], v[96:99]
	v_mfma_f32_16x16x32_bf16 v[84:87], v[234:237], v[218:221], v[84:87]
	v_mfma_f32_16x16x32_bf16 v[80:83], v[242:245], v[218:221], v[80:83]
	v_mfma_f32_16x16x32_bf16 v[68:71], v[234:237], v[226:229], v[68:71]
	v_mfma_f32_16x16x32_bf16 v[64:67], v[242:245], v[226:229], v[64:67]
	s_setprio 0
	s_mov_b32 m0, s17
	v_lshl_add_u64 v[196:197], s[22:23], 0, v[160:161]
	s_barrier
	ds_read_b128 v[180:183], v178 offset:16384
	ds_read_b128 v[184:187], v178 offset:17408
	ds_read_b128 v[188:191], v178 offset:18432
	ds_read_b128 v[192:195], v178 offset:19456
	ds_read_b128 v[214:217], v178 offset:20480
	ds_read_b128 v[218:221], v178 offset:21504
	ds_read_b128 v[222:225], v178 offset:22528
	ds_read_b128 v[226:229], v178 offset:23552
	global_load_lds_dwordx4 v[196:197], off
	v_lshl_add_u64 v[246:247], s[22:23], 0, v[144:145]
	s_mov_b32 m0, s27
	s_nop 0
	global_load_lds_dwordx4 v[246:247], off
	s_barrier
	s_waitcnt lgkmcnt(0)
	s_setprio 1
	v_mfma_f32_16x16x32_bf16 v[60:63], v[128:131], v[180:183], v[60:63]
	v_mfma_f32_16x16x32_bf16 v[56:59], v[136:139], v[180:183], v[56:59]
	v_mfma_f32_16x16x32_bf16 v[44:47], v[128:131], v[188:191], v[44:47]
	v_mfma_f32_16x16x32_bf16 v[40:43], v[136:139], v[188:191], v[40:43]
	v_mfma_f32_16x16x32_bf16 v[28:31], v[128:131], v[214:217], v[28:31]
	v_mfma_f32_16x16x32_bf16 v[24:27], v[136:139], v[214:217], v[24:27]
	v_mfma_f32_16x16x32_bf16 v[12:15], v[128:131], v[222:225], v[12:15]
	v_mfma_f32_16x16x32_bf16 v[8:11], v[136:139], v[222:225], v[8:11]
	v_mfma_f32_16x16x32_bf16 v[60:63], v[132:135], v[184:187], v[60:63]
	v_mfma_f32_16x16x32_bf16 v[56:59], v[140:143], v[184:187], v[56:59]
	v_mfma_f32_16x16x32_bf16 v[44:47], v[132:135], v[192:195], v[44:47]
	v_mfma_f32_16x16x32_bf16 v[40:43], v[140:143], v[192:195], v[40:43]
	v_mfma_f32_16x16x32_bf16 v[28:31], v[132:135], v[218:221], v[28:31]
	v_mfma_f32_16x16x32_bf16 v[24:27], v[140:143], v[218:221], v[24:27]
	v_mfma_f32_16x16x32_bf16 v[12:15], v[132:135], v[226:229], v[12:15]
	v_mfma_f32_16x16x32_bf16 v[8:11], v[140:143], v[226:229], v[8:11]
	s_setprio 0
	s_barrier
; #define PG8_STAGE(bufoff, gbase, voff) do { _Pragma("unroll") for (int _i = 0; _i < 2; ++_i) \
;         __builtin_amdgcn_global_load_lds((const unsigned*)((const char*)(gbase) + (voff)[_i]), (LAS unsigned*)(lds + (bufoff) + ldsw + _i * 8192), 16, 0, 0); } while (0)
; #define PG8_LDA(dst, b, h) do { _Pragma("unroll") for (int m = 0; m < 4; ++m) _Pragma("unroll") for (int k = 0; k < 2; ++k) dst[m][k] = *(const LAS bf16x8*)(lds + PG8_SA(b, h) + aoff + m * 2048 + k * 1024); } while (0)
; #define PG8_LDB(dst, b, h) do { _Pragma("unroll") for (int n = 0; n < 2; ++n) _Pragma("unroll") for (int k = 0; k < 2; ++k) dst[n][k] = *(const LAS bf16x8*)(lds + PG8_SB(b, h) + boff + n * 2048 + k * 1024); } while (0)
; #define PG8_MMA(ai, bj, At, Bt) do { __builtin_amdgcn_s_setprio(1); _Pragma("unroll") for (int m = 0; m < 4; ++m) _Pragma("unroll") for (int n = 0; n < 2; ++n) _Pragma("unroll") for (int k = 0; k < 2; ++k) \
;         acc[ai][bj][m][n] = __builtin_amdgcn_mfma_f32_16x16x32_bf16(Bt[n][k], At[m][k], acc[ai][bj][m][n], 0, 0, 0); __builtin_amdgcn_s_setprio(0); } while (0)
; #define PG8_WAIT_V(n) asm volatile("s_waitcnt vmcnt(" #n ")" ::: "memory")
; #define PG8_WAIT_L(n) asm volatile("s_waitcnt lgkmcnt(" #n ")" ::: "memory")
; #define PG8_BAR __builtin_amdgcn_s_barrier()
; #define PG8_SCHED __builtin_amdgcn_sched_barrier(0)
; template <class Epi>
; DEV void gemm_phase(LAS unsigned char* lds, const Gemm g, const StaticOrder& S, const Epi& E) {
;     ...
;             PG8_STAGE(PG8_SB(0, 1), b2 + hstep, voffB);
;             PG8_WAIT_V(6); PG8_BAR; PG8_MMA(1, 1, At, B1); PG8_BAR;
;             PG8_LDB(B0, 1, 0); PG8_SCHED; PG8_LDA(At, 1, 0); PG8_STAGE(PG8_SA(0, 1), a2 + hstep, voffA);
;             PG8_WAIT_L(8); PG8_BAR; PG8_WAIT_L(0); PG8_MMA(0, 0, At, B0); PG8_BAR; PG8_SCHED;
;             PG8_LDB(B1, 1, 1); PG8_STAGE(PG8_SB(1, 0), b3, voffB);
;             PG8_BAR; PG8_WAIT_L(0); PG8_MMA(0, 1, At, B1); PG8_BAR;
	s_add_u32 s42, s20, 0x80000
	s_addc_u32 s43, s21, 0
	s_add_i32 s41, s44, s26
	v_lshl_add_u64 v[128:129], s[42:43], 0, v[160:161]
	s_mov_b32 m0, s41
	s_nop 0
	global_load_lds_dwordx4 v[128:129], off
	v_lshl_add_u64 v[128:129], s[42:43], 0, v[144:145]
	s_add_i32 m0, s41, 0x2000
	s_nop 0
	global_load_lds_dwordx4 v[128:129], off
	s_waitcnt vmcnt(10)
	s_barrier
	s_setprio 1
	v_mfma_f32_16x16x32_bf16 v[52:55], v[230:233], v[180:183], v[52:55]
	v_mfma_f32_16x16x32_bf16 v[48:51], v[238:241], v[180:183], v[48:51]
	v_mfma_f32_16x16x32_bf16 v[36:39], v[230:233], v[188:191], v[36:39]
	v_mfma_f32_16x16x32_bf16 v[32:35], v[238:241], v[188:191], v[32:35]
	v_mfma_f32_16x16x32_bf16 v[20:23], v[230:233], v[214:217], v[20:23]
	v_mfma_f32_16x16x32_bf16 v[16:19], v[238:241], v[214:217], v[16:19]
	v_mfma_f32_16x16x32_bf16 v[4:7], v[230:233], v[222:225], v[4:7]
	v_mfma_f32_16x16x32_bf16 v[0:3], v[238:241], v[222:225], v[0:3]
	v_mfma_f32_16x16x32_bf16 v[52:55], v[234:237], v[184:187], v[52:55]
	v_mfma_f32_16x16x32_bf16 v[48:51], v[242:245], v[184:187], v[48:51]
	v_mfma_f32_16x16x32_bf16 v[36:39], v[234:237], v[192:195], v[36:39]
	v_mfma_f32_16x16x32_bf16 v[32:35], v[242:245], v[192:195], v[32:35]
	v_mfma_f32_16x16x32_bf16 v[20:23], v[234:237], v[218:221], v[20:23]
	v_mfma_f32_16x16x32_bf16 v[16:19], v[242:245], v[218:221], v[16:19]
	v_mfma_f32_16x16x32_bf16 v[4:7], v[234:237], v[226:229], v[4:7]
	v_mfma_f32_16x16x32_bf16 v[0:3], v[242:245], v[226:229], v[0:3]
	s_setprio 0
	s_add_i32 s41, 0, 0x18000
	v_add_u32_e32 v140, s41, v176
	s_barrier
	ds_read_b128 v[128:131], v140
	ds_read_b128 v[132:135], v140 offset:1024
	ds_read_b128 v[136:139], v140 offset:2048
	ds_read_b128 v[140:143], v140 offset:3072
	s_add_u32 s22, s22, 0x80000
	s_addc_u32 s23, s23, 0
	s_mov_b32 m0, s28
	v_lshl_add_u64 v[230:231], s[22:23], 0, v[160:161]
	ds_read_b128 v[180:183], v178 offset:32768
	ds_read_b128 v[184:187], v178 offset:33792
	ds_read_b128 v[188:191], v178 offset:34816
	ds_read_b128 v[192:195], v178 offset:35840
	ds_read_b128 v[214:217], v178 offset:36864
	ds_read_b128 v[218:221], v178 offset:37888
	ds_read_b128 v[222:225], v178 offset:38912
	ds_read_b128 v[226:229], v178 offset:39936
	global_load_lds_dwordx4 v[230:231], off
	v_lshl_add_u64 v[230:231], s[22:23], 0, v[144:145]
	s_mov_b32 m0, s29
	s_nop 0
	global_load_lds_dwordx4 v[230:231], off
	s_waitcnt lgkmcnt(8)
	s_waitcnt vmcnt(10)
	s_barrier
	s_waitcnt lgkmcnt(0)
	s_setprio 1
	v_mfma_f32_16x16x32_bf16 v[124:127], v[128:131], v[180:183], v[124:127]
	v_mfma_f32_16x16x32_bf16 v[120:123], v[136:139], v[180:183], v[120:123]
	v_mfma_f32_16x16x32_bf16 v[108:111], v[128:131], v[188:191], v[108:111]
	v_mfma_f32_16x16x32_bf16 v[104:107], v[136:139], v[188:191], v[104:107]
	v_mfma_f32_16x16x32_bf16 v[92:95], v[128:131], v[214:217], v[92:95]
	v_mfma_f32_16x16x32_bf16 v[88:91], v[136:139], v[214:217], v[88:91]
	v_mfma_f32_16x16x32_bf16 v[76:79], v[128:131], v[222:225], v[76:79]
	v_mfma_f32_16x16x32_bf16 v[72:75], v[136:139], v[222:225], v[72:75]
	v_mfma_f32_16x16x32_bf16 v[124:127], v[132:135], v[184:187], v[124:127]
	v_mfma_f32_16x16x32_bf16 v[120:123], v[140:143], v[184:187], v[120:123]
	v_mfma_f32_16x16x32_bf16 v[108:111], v[132:135], v[192:195], v[108:111]
	v_mfma_f32_16x16x32_bf16 v[104:107], v[140:143], v[192:195], v[104:107]
	v_mfma_f32_16x16x32_bf16 v[92:95], v[132:135], v[218:221], v[92:95]
	v_mfma_f32_16x16x32_bf16 v[88:91], v[140:143], v[218:221], v[88:91]
	v_mfma_f32_16x16x32_bf16 v[76:79], v[132:135], v[226:229], v[76:79]
	v_mfma_f32_16x16x32_bf16 v[72:75], v[140:143], v[226:229], v[72:75]
	s_setprio 0
	s_barrier
	s_add_i32 s22, 0, 0x1c000
	s_add_i32 s23, s41, s26
	v_add_u32_e32 v179, s22, v176
	v_lshl_add_u64 v[158:159], v[158:159], 0, s[2:3]
	s_mov_b32 m0, s23
	ds_read_b128 v[230:233], v179
	ds_read_b128 v[234:237], v179 offset:1024
	ds_read_b128 v[238:241], v179 offset:2048
	ds_read_b128 v[242:245], v179 offset:3072
	global_load_lds_dwordx4 v[158:159], off
	v_lshl_add_u64 v[158:159], v[174:175], 0, s[2:3]
	s_add_i32 m0, s23, 0x2000
	s_nop 0
	global_load_lds_dwordx4 v[158:159], off
	s_waitcnt vmcnt(10)
	s_barrier
	s_waitcnt lgkmcnt(0)
	s_setprio 1
	v_mfma_f32_16x16x32_bf16 v[116:119], v[230:233], v[180:183], v[116:119]
	v_mfma_f32_16x16x32_bf16 v[112:115], v[238:241], v[180:183], v[112:115]
	v_mfma_f32_16x16x32_bf16 v[100:103], v[230:233], v[188:191], v[100:103]
	v_mfma_f32_16x16x32_bf16 v[96:99], v[238:241], v[188:191], v[96:99]
	v_mfma_f32_16x16x32_bf16 v[84:87], v[230:233], v[214:217], v[84:87]
	v_mfma_f32_16x16x32_bf16 v[80:83], v[238:241], v[214:217], v[80:83]
	v_mfma_f32_16x16x32_bf16 v[68:71], v[230:233], v[222:225], v[68:71]
	v_mfma_f32_16x16x32_bf16 v[64:67], v[238:241], v[222:225], v[64:67]
	v_mfma_f32_16x16x32_bf16 v[116:119], v[234:237], v[184:187], v[116:119]
	v_mfma_f32_16x16x32_bf16 v[112:115], v[242:245], v[184:187], v[112:115]
	v_mfma_f32_16x16x32_bf16 v[100:103], v[234:237], v[192:195], v[100:103]
	v_mfma_f32_16x16x32_bf16 v[96:99], v[242:245], v[192:195], v[96:99]
	v_mfma_f32_16x16x32_bf16 v[84:87], v[234:237], v[218:221], v[84:87]
	v_mfma_f32_16x16x32_bf16 v[80:83], v[242:245], v[218:221], v[80:83]
	v_mfma_f32_16x16x32_bf16 v[68:71], v[234:237], v[226:229], v[68:71]
	v_mfma_f32_16x16x32_bf16 v[64:67], v[242:245], v[226:229], v[64:67]
	s_setprio 0
	s_mov_b32 m0, s30
	v_lshl_add_u64 v[158:159], v[196:197], 0, s[2:3]
	s_barrier
; #define PG8_STAGE(bufoff, gbase, voff) do { _Pragma("unroll") for (int _i = 0; _i < 2; ++_i) \
;         __builtin_amdgcn_global_load_lds((const unsigned*)((const char*)(gbase) + (voff)[_i]), (LAS unsigned*)(lds + (bufoff) + ldsw + _i * 8192), 16, 0, 0); } while (0)
; #define PG8_LDA(dst, b, h) do { _Pragma("unroll") for (int m = 0; m < 4; ++m) _Pragma("unroll") for (int k = 0; k < 2; ++k) dst[m][k] = *(const LAS bf16x8*)(lds + PG8_SA(b, h) + aoff + m * 2048 + k * 1024); } while (0)
; #define PG8_MMA(ai, bj, At, Bt) do { __builtin_amdgcn_s_setprio(1); _Pragma("unroll") for (int m = 0; m < 4; ++m) _Pragma("unroll") for (int n = 0; n < 2; ++n) _Pragma("unroll") for (int k = 0; k < 2; ++k) \
;         acc[ai][bj][m][n] = __builtin_amdgcn_mfma_f32_16x16x32_bf16(Bt[n][k], At[m][k], acc[ai][bj][m][n], 0, 0, 0); __builtin_amdgcn_s_setprio(0); } while (0)
; #define PG8_WAIT_V(n) asm volatile("s_waitcnt vmcnt(" #n ")" ::: "memory")
; #define PG8_WAIT_L(n) asm volatile("s_waitcnt lgkmcnt(" #n ")" ::: "memory")
; #define PG8_BAR __builtin_amdgcn_s_barrier()
; #define PG8_SCHED __builtin_amdgcn_sched_barrier(0)
; template <class Epi>
; DEV void gemm_phase(LAS unsigned char* lds, const Gemm g, const StaticOrder& S, const Epi& E) {
;     ...
;             PG8_LDA(At, 1, 1); PG8_STAGE(PG8_SA(1, 0), a3, voffA);
;             PG8_BAR; PG8_WAIT_L(0); PG8_MMA(1, 0, At, B0); PG8_BAR; PG8_SCHED;
;             PG8_STAGE(PG8_SB(1, 1), b3 + hstep, voffB);
;             PG8_WAIT_V(6); PG8_BAR; PG8_MMA(1, 1, At, B1); PG8_BAR;
;     DEV void operator()(AccRef acc, const pg8::Unit& u, int wr, int wc, int fr, int fq) const {
;         const int row0 = u.pm * 256 + wr * 64 + fr, col0 = u.pn * 256 + wc * 32 + 4 * fq;
;         const bool rope = (u.pn < 9) && ((wc & 1) == 0);
; #pragma unroll
;         for (int ai = 0; ai < 2; ++ai)
; #pragma unroll
;             for (int m = 0; m < 4; ++m) { const int row = row0 + ai * 128 + m * 16; u16* rowp = O + (size_t)row * 2560 + col0; const float rs = rowscale(ss, row);
;                 f32x4 cs = (f32x4){1.f, 1.f, 1.f, 1.f}, sn = (f32x4){0.f, 0.f, 0.f, 0.f};
;                 if (rope) { cs = *(const f32x4*)(cosT + row * 8 + 4 * (fq & 1)); sn = *(const f32x4*)(sinT + row * 8 + 4 * (fq & 1)); }
	ds_read_b128 v[180:183], v178 offset:49152
	ds_read_b128 v[184:187], v178 offset:50176
	ds_read_b128 v[188:191], v178 offset:51200
	ds_read_b128 v[192:195], v178 offset:52224
	ds_read_b128 v[214:217], v178 offset:53248
	ds_read_b128 v[218:221], v178 offset:54272
	ds_read_b128 v[222:225], v178 offset:55296
	ds_read_b128 v[226:229], v178 offset:56320
	global_load_lds_dwordx4 v[158:159], off
	v_lshl_add_u64 v[158:159], v[246:247], 0, s[2:3]
	s_mov_b32 m0, s31
	s_nop 0
	global_load_lds_dwordx4 v[158:159], off
	s_barrier
	s_waitcnt lgkmcnt(0)
	s_setprio 1
	v_mfma_f32_16x16x32_bf16 v[60:63], v[128:131], v[180:183], v[60:63]
	v_mfma_f32_16x16x32_bf16 v[56:59], v[136:139], v[180:183], v[56:59]
	v_mfma_f32_16x16x32_bf16 v[44:47], v[128:131], v[188:191], v[44:47]
	v_mfma_f32_16x16x32_bf16 v[40:43], v[136:139], v[188:191], v[40:43]
	v_mfma_f32_16x16x32_bf16 v[28:31], v[128:131], v[214:217], v[28:31]
	v_mfma_f32_16x16x32_bf16 v[24:27], v[136:139], v[214:217], v[24:27]
	v_mfma_f32_16x16x32_bf16 v[12:15], v[128:131], v[222:225], v[12:15]
	v_mfma_f32_16x16x32_bf16 v[8:11], v[136:139], v[222:225], v[8:11]
	v_mfma_f32_16x16x32_bf16 v[60:63], v[132:135], v[184:187], v[60:63]
	v_mfma_f32_16x16x32_bf16 v[56:59], v[140:143], v[184:187], v[56:59]
	v_mfma_f32_16x16x32_bf16 v[44:47], v[132:135], v[192:195], v[44:47]
	v_mfma_f32_16x16x32_bf16 v[40:43], v[140:143], v[192:195], v[40:43]
	v_mfma_f32_16x16x32_bf16 v[28:31], v[132:135], v[218:221], v[28:31]
	v_mfma_f32_16x16x32_bf16 v[24:27], v[140:143], v[218:221], v[24:27]
	v_mfma_f32_16x16x32_bf16 v[12:15], v[132:135], v[226:229], v[12:15]
	v_mfma_f32_16x16x32_bf16 v[8:11], v[140:143], v[226:229], v[8:11]
	s_setprio 0
	s_barrier
	s_add_u32 s20, s20, 0x80080
	s_addc_u32 s21, s21, 0
	s_add_i32 s22, s22, s26
	v_lshl_add_u64 v[128:129], s[20:21], 0, v[160:161]
	s_mov_b32 m0, s22
	s_nop 0
	global_load_lds_dwordx4 v[128:129], off
	v_lshl_add_u64 v[128:129], s[20:21], 0, v[144:145]
	s_add_i32 m0, s22, 0x2000
	s_nop 0
	global_load_lds_dwordx4 v[128:129], off
	s_waitcnt vmcnt(10)
	s_barrier
	s_setprio 1
	v_mfma_f32_16x16x32_bf16 v[52:55], v[230:233], v[180:183], v[52:55]
	v_mfma_f32_16x16x32_bf16 v[48:51], v[238:241], v[180:183], v[48:51]
	v_mfma_f32_16x16x32_bf16 v[36:39], v[230:233], v[188:191], v[36:39]
	v_mfma_f32_16x16x32_bf16 v[32:35], v[238:241], v[188:191], v[32:35]
	v_mfma_f32_16x16x32_bf16 v[20:23], v[230:233], v[214:217], v[20:23]
	v_mfma_f32_16x16x32_bf16 v[16:19], v[238:241], v[214:217], v[16:19]
	v_mfma_f32_16x16x32_bf16 v[4:7], v[230:233], v[222:225], v[4:7]
	v_mfma_f32_16x16x32_bf16 v[0:3], v[238:241], v[222:225], v[0:3]
	v_mfma_f32_16x16x32_bf16 v[52:55], v[234:237], v[184:187], v[52:55]
	v_mfma_f32_16x16x32_bf16 v[48:51], v[242:245], v[184:187], v[48:51]
	v_mfma_f32_16x16x32_bf16 v[36:39], v[234:237], v[192:195], v[36:39]
	v_mfma_f32_16x16x32_bf16 v[32:35], v[242:245], v[192:195], v[32:35]
	v_mfma_f32_16x16x32_bf16 v[20:23], v[234:237], v[218:221], v[20:23]
	v_mfma_f32_16x16x32_bf16 v[16:19], v[242:245], v[218:221], v[16:19]
	v_mfma_f32_16x16x32_bf16 v[4:7], v[234:237], v[226:229], v[4:7]
	v_mfma_f32_16x16x32_bf16 v[0:3], v[242:245], v[226:229], v[0:3]
	s_setprio 0
	s_add_i32 s40, s40, 2
	s_add_u32 s18, s18, 0x100
	s_addc_u32 s19, s19, 0
	s_add_u32 s38, s38, 0x100
	s_addc_u32 s39, s39, 0
	s_cmp_gt_u32 s40, 29
	s_barrier
	s_cbranch_scc0 .LBB0_152
	v_lshl_add_u32 v174, s4, 8, v167
	v_ashrrev_i32_e32 v175, 31, v174
	v_readlane_b32 s20, v250, 47
	v_lshlrev_b64 v[128:129], 5, v[174:175]
	v_readlane_b32 s21, v250, 48
	s_cmp_lt_i32 s16, 9
	s_cselect_b64 s[4:5], -1, 0
	v_lshl_add_u64 v[128:129], s[20:21], 0, v[128:129]
	global_load_dwordx4 v[136:139], v[128:129], off offset:16
	global_load_dwordx4 v[140:143], v[128:129], off
	s_and_b64 s[18:19], s[6:7], s[4:5]
	v_cndmask_b32_e64 v128, 0, 1, s[18:19]
	v_cmp_ne_u32_e64 s[4:5], 1, v128
	s_andn2_b64 vcc, exec, s[18:19]
	s_cbranch_vccnz .LBB0_155
	v_lshlrev_b32_e32 v128, 3, v174
	v_ashrrev_i32_e32 v129, 31, v128
	v_lshlrev_b64 v[128:129], 2, v[128:129]
	v_lshl_add_u64 v[130:131], v[152:153], 0, v[128:129]
	v_lshl_add_u64 v[132:133], v[150:151], 0, v[128:129]
	global_load_dwordx4 v[128:131], v[130:131], off
	s_nop 0
	global_load_dwordx4 v[132:135], v[132:133], off
	s_branch .LBB0_156

; #define PG8_STAGE(bufoff, gbase, voff) do { _Pragma("unroll") for (int _i = 0; _i < 2; ++_i) \
;         __builtin_amdgcn_global_load_lds((const unsigned*)((const char*)(gbase) + (voff)[_i]), (LAS unsigned*)(lds + (bufoff) + ldsw + _i * 8192), 16, 0, 0); } while (0)
; #define PG8_LDA(dst, b, h) do { _Pragma("unroll") for (int m = 0; m < 4; ++m) _Pragma("unroll") for (int k = 0; k < 2; ++k) dst[m][k] = *(const LAS bf16x8*)(lds + PG8_SA(b, h) + aoff + m * 2048 + k * 1024); } while (0)
; #define PG8_LDB(dst, b, h) do { _Pragma("unroll") for (int n = 0; n < 2; ++n) _Pragma("unroll") for (int k = 0; k < 2; ++k) dst[n][k] = *(const LAS bf16x8*)(lds + PG8_SB(b, h) + boff + n * 2048 + k * 1024); } while (0)
; #define PG8_MMA(ai, bj, At, Bt) do { __builtin_amdgcn_s_setprio(1); _Pragma("unroll") for (int m = 0; m < 4; ++m) _Pragma("unroll") for (int n = 0; n < 2; ++n) _Pragma("unroll") for (int k = 0; k < 2; ++k) \
;         acc[ai][bj][m][n] = __builtin_amdgcn_mfma_f32_16x16x32_bf16(Bt[n][k], At[m][k], acc[ai][bj][m][n], 0, 0, 0); __builtin_amdgcn_s_setprio(0); } while (0)
; #define PG8_WAIT_L(n) asm volatile("s_waitcnt lgkmcnt(" #n ")" ::: "memory")
; #define PG8_BAR __builtin_amdgcn_s_barrier()
; #define PG8_SCHED __builtin_amdgcn_sched_barrier(0)
; template <class Epi>
; DEV void gemm_phase(LAS unsigned char* lds, const Gemm g, const StaticOrder& S, const Epi& E) {
;     ...
;             const bool last = (t == nt - 2);
;             const char* a1 = cA + (size_t)(t + 1) * kstep;
;             const char* a2 = last ? nA : cA + (size_t)(t + 2) * kstep; const char* b2 = last ? nB : cB + (size_t)(t + 2) * kstep;
;             const char* a3 = a2 + kstep; const char* b3 = b2 + kstep;
;             PG8_LDB(B0, 0, 0); PG8_SCHED; PG8_LDA(At, 0, 0); PG8_STAGE(PG8_SA(1, 1), a1 + hstep, voffA);
;             PG8_WAIT_L(8); PG8_BAR; PG8_WAIT_L(0); PG8_MMA(0, 0, At, B0); PG8_BAR; PG8_SCHED;
;             PG8_LDB(B1, 0, 1); PG8_STAGE(PG8_SB(0, 0), b2, voffB);
;             PG8_BAR; PG8_WAIT_L(0); PG8_MMA(0, 1, At, B1); PG8_BAR;
;             PG8_LDA(At, 0, 1); PG8_STAGE(PG8_SA(0, 0), a2, voffA);
;             PG8_BAR; PG8_WAIT_L(0); PG8_MMA(1, 0, At, B0); PG8_BAR; PG8_SCHED;
.LBB0_260:
	s_add_u32 s34, s30, 0xfffe0080
	s_addc_u32 s35, s31, -1
	s_add_i32 s55, 0, 0x10000
	v_add_u32_e32 v140, s55, v178
	ds_read_b128 v[128:131], v140
	ds_read_b128 v[132:135], v140 offset:1024
	ds_read_b128 v[136:139], v140 offset:2048
	ds_read_b128 v[140:143], v140 offset:3072
	s_cmp_eq_u32 s54, 4
	s_cselect_b32 s37, s19, s35
	s_cselect_b32 s36, s23, s34
	s_cselect_b32 s35, s21, s53
	s_cselect_b32 s34, s29, s52
	v_lshl_add_u64 v[158:159], s[30:31], 0, v[150:151]
	s_add_i32 m0, s43, 0xc000
	ds_read_b128 v[154:157], v181
	ds_read_b128 v[174:177], v181 offset:1024
	ds_read_b128 v[182:185], v181 offset:2048
	ds_read_b128 v[186:189], v181 offset:3072
	ds_read_b128 v[190:193], v181 offset:4096
	ds_read_b128 v[194:197], v181 offset:5120
	ds_read_b128 v[214:217], v181 offset:6144
	ds_read_b128 v[218:221], v181 offset:7168
	global_load_lds_dwordx4 v[158:159], off
	v_lshl_add_u64 v[158:159], s[30:31], 0, v[152:153]
	s_add_i32 m0, s43, 0xe000
	s_nop 0
	global_load_lds_dwordx4 v[158:159], off
	s_waitcnt lgkmcnt(8)
	s_waitcnt vmcnt(10)
	s_barrier
	s_waitcnt lgkmcnt(0)
	s_setprio 1
	v_mfma_f32_16x16x32_bf16 v[124:127], v[128:131], v[154:157], v[124:127]
	v_mfma_f32_16x16x32_bf16 v[120:123], v[136:139], v[154:157], v[120:123]
	v_mfma_f32_16x16x32_bf16 v[108:111], v[128:131], v[182:185], v[108:111]
	v_mfma_f32_16x16x32_bf16 v[104:107], v[136:139], v[182:185], v[104:107]
	v_mfma_f32_16x16x32_bf16 v[92:95], v[128:131], v[190:193], v[92:95]
	v_mfma_f32_16x16x32_bf16 v[88:91], v[136:139], v[190:193], v[88:91]
	v_mfma_f32_16x16x32_bf16 v[76:79], v[128:131], v[214:217], v[76:79]
	v_mfma_f32_16x16x32_bf16 v[72:75], v[136:139], v[214:217], v[72:75]
	v_mfma_f32_16x16x32_bf16 v[124:127], v[132:135], v[174:177], v[124:127]
	v_mfma_f32_16x16x32_bf16 v[120:123], v[140:143], v[174:177], v[120:123]
	v_mfma_f32_16x16x32_bf16 v[108:111], v[132:135], v[186:189], v[108:111]
	v_mfma_f32_16x16x32_bf16 v[104:107], v[140:143], v[186:189], v[104:107]
	v_mfma_f32_16x16x32_bf16 v[92:95], v[132:135], v[194:197], v[92:95]
	v_mfma_f32_16x16x32_bf16 v[88:91], v[140:143], v[194:197], v[88:91]
	v_mfma_f32_16x16x32_bf16 v[76:79], v[132:135], v[218:221], v[76:79]
	v_mfma_f32_16x16x32_bf16 v[72:75], v[140:143], v[218:221], v[72:75]
	s_setprio 0
	s_barrier
	s_add_i32 s58, 0, 0x14000
	v_add_u32_e32 v158, s58, v178
	s_add_i32 s55, s55, s42
	ds_read_b128 v[222:225], v158
	ds_read_b128 v[226:229], v158 offset:1024
	ds_read_b128 v[230:233], v158 offset:2048
	ds_read_b128 v[234:237], v158 offset:3072
	v_lshl_add_u64 v[158:159], s[34:35], 0, v[160:161]
	s_mov_b32 m0, s55
	v_lshl_add_u64 v[238:239], s[34:35], 0, v[148:149]
	global_load_lds_dwordx4 v[158:159], off
	s_add_i32 m0, s55, 0x2000
	s_nop 0
	global_load_lds_dwordx4 v[238:239], off
	s_waitcnt vmcnt(10)
	s_barrier
	s_waitcnt lgkmcnt(0)
	s_setprio 1
	v_mfma_f32_16x16x32_bf16 v[116:119], v[222:225], v[154:157], v[116:119]
	v_mfma_f32_16x16x32_bf16 v[112:115], v[230:233], v[154:157], v[112:115]
	v_mfma_f32_16x16x32_bf16 v[100:103], v[222:225], v[182:185], v[100:103]
	v_mfma_f32_16x16x32_bf16 v[96:99], v[230:233], v[182:185], v[96:99]
	v_mfma_f32_16x16x32_bf16 v[84:87], v[222:225], v[190:193], v[84:87]
	v_mfma_f32_16x16x32_bf16 v[80:83], v[230:233], v[190:193], v[80:83]
	v_mfma_f32_16x16x32_bf16 v[68:71], v[222:225], v[214:217], v[68:71]
	v_mfma_f32_16x16x32_bf16 v[64:67], v[230:233], v[214:217], v[64:67]
	v_mfma_f32_16x16x32_bf16 v[116:119], v[226:229], v[174:177], v[116:119]
	v_mfma_f32_16x16x32_bf16 v[112:115], v[234:237], v[174:177], v[112:115]
	v_mfma_f32_16x16x32_bf16 v[100:103], v[226:229], v[186:189], v[100:103]
	v_mfma_f32_16x16x32_bf16 v[96:99], v[234:237], v[186:189], v[96:99]
	v_mfma_f32_16x16x32_bf16 v[84:87], v[226:229], v[194:197], v[84:87]
	v_mfma_f32_16x16x32_bf16 v[80:83], v[234:237], v[194:197], v[80:83]
	v_mfma_f32_16x16x32_bf16 v[68:71], v[226:229], v[218:221], v[68:71]
	v_mfma_f32_16x16x32_bf16 v[64:67], v[234:237], v[218:221], v[64:67]
	s_setprio 0
	s_mov_b32 m0, s43
	v_lshl_add_u64 v[240:241], s[36:37], 0, v[144:145]
	s_barrier
	ds_read_b128 v[154:157], v181 offset:16384
	ds_read_b128 v[174:177], v181 offset:17408
	ds_read_b128 v[182:185], v181 offset:18432
	ds_read_b128 v[186:189], v181 offset:19456
	ds_read_b128 v[190:193], v181 offset:20480
	ds_read_b128 v[194:197], v181 offset:21504
	ds_read_b128 v[214:217], v181 offset:22528
	ds_read_b128 v[218:221], v181 offset:23552
	global_load_lds_dwordx4 v[240:241], off
	v_lshl_add_u64 v[242:243], s[36:37], 0, v[146:147]
	s_mov_b32 m0, s44
	s_nop 0
	global_load_lds_dwordx4 v[242:243], off
	s_barrier
	s_waitcnt lgkmcnt(0)
	s_setprio 1
	v_mfma_f32_16x16x32_bf16 v[60:63], v[128:131], v[154:157], v[60:63]
	v_mfma_f32_16x16x32_bf16 v[56:59], v[136:139], v[154:157], v[56:59]
	v_mfma_f32_16x16x32_bf16 v[44:47], v[128:131], v[182:185], v[44:47]
	v_mfma_f32_16x16x32_bf16 v[40:43], v[136:139], v[182:185], v[40:43]
	v_mfma_f32_16x16x32_bf16 v[28:31], v[128:131], v[190:193], v[28:31]
	v_mfma_f32_16x16x32_bf16 v[24:27], v[136:139], v[190:193], v[24:27]
	v_mfma_f32_16x16x32_bf16 v[12:15], v[128:131], v[214:217], v[12:15]
	v_mfma_f32_16x16x32_bf16 v[8:11], v[136:139], v[214:217], v[8:11]
	v_mfma_f32_16x16x32_bf16 v[60:63], v[132:135], v[174:177], v[60:63]
	v_mfma_f32_16x16x32_bf16 v[56:59], v[140:143], v[174:177], v[56:59]
	v_mfma_f32_16x16x32_bf16 v[44:47], v[132:135], v[186:189], v[44:47]
	v_mfma_f32_16x16x32_bf16 v[40:43], v[140:143], v[186:189], v[40:43]
	v_mfma_f32_16x16x32_bf16 v[28:31], v[132:135], v[194:197], v[28:31]
	v_mfma_f32_16x16x32_bf16 v[24:27], v[140:143], v[194:197], v[24:27]
	v_mfma_f32_16x16x32_bf16 v[12:15], v[132:135], v[218:221], v[12:15]
	v_mfma_f32_16x16x32_bf16 v[8:11], v[140:143], v[218:221], v[8:11]
	s_setprio 0
	s_barrier
; #define PG8_STAGE(bufoff, gbase, voff) do { _Pragma("unroll") for (int _i = 0; _i < 2; ++_i) \
;         __builtin_amdgcn_global_load_lds((const unsigned*)((const char*)(gbase) + (voff)[_i]), (LAS unsigned*)(lds + (bufoff) + ldsw + _i * 8192), 16, 0, 0); } while (0)
; #define PG8_LDA(dst, b, h) do { _Pragma("unroll") for (int m = 0; m < 4; ++m) _Pragma("unroll") for (int k = 0; k < 2; ++k) dst[m][k] = *(const LAS bf16x8*)(lds + PG8_SA(b, h) + aoff + m * 2048 + k * 1024); } while (0)
; #define PG8_LDB(dst, b, h) do { _Pragma("unroll") for (int n = 0; n < 2; ++n) _Pragma("unroll") for (int k = 0; k < 2; ++k) dst[n][k] = *(const LAS bf16x8*)(lds + PG8_SB(b, h) + boff + n * 2048 + k * 1024); } while (0)
; #define PG8_MMA(ai, bj, At, Bt) do { __builtin_amdgcn_s_setprio(1); _Pragma("unroll") for (int m = 0; m < 4; ++m) _Pragma("unroll") for (int n = 0; n < 2; ++n) _Pragma("unroll") for (int k = 0; k < 2; ++k) \
;         acc[ai][bj][m][n] = __builtin_amdgcn_mfma_f32_16x16x32_bf16(Bt[n][k], At[m][k], acc[ai][bj][m][n], 0, 0, 0); __builtin_amdgcn_s_setprio(0); } while (0)
; #define PG8_WAIT_V(n) asm volatile("s_waitcnt vmcnt(" #n ")" ::: "memory")
; #define PG8_WAIT_L(n) asm volatile("s_waitcnt lgkmcnt(" #n ")" ::: "memory")
; #define PG8_BAR __builtin_amdgcn_s_barrier()
; #define PG8_SCHED __builtin_amdgcn_sched_barrier(0)
; template <class Epi>
; DEV void gemm_phase(LAS unsigned char* lds, const Gemm g, const StaticOrder& S, const Epi& E) {
;     ...
;             PG8_STAGE(PG8_SB(0, 1), b2 + hstep, voffB);
;             PG8_WAIT_V(6); PG8_BAR; PG8_MMA(1, 1, At, B1); PG8_BAR;
;             PG8_LDB(B0, 1, 0); PG8_SCHED; PG8_LDA(At, 1, 0); PG8_STAGE(PG8_SA(0, 1), a2 + hstep, voffA);
;             PG8_WAIT_L(8); PG8_BAR; PG8_WAIT_L(0); PG8_MMA(0, 0, At, B0); PG8_BAR; PG8_SCHED;
;             PG8_LDB(B1, 1, 1); PG8_STAGE(PG8_SB(1, 0), b3, voffB);
;             PG8_BAR; PG8_WAIT_L(0); PG8_MMA(0, 1, At, B1); PG8_BAR;
;             PG8_LDA(At, 1, 1); PG8_STAGE(PG8_SA(1, 0), a3, voffA);
	s_add_u32 s56, s34, 0x20000
	s_addc_u32 s57, s35, 0
	s_add_i32 s55, s58, s42
	v_lshl_add_u64 v[128:129], s[56:57], 0, v[160:161]
	s_mov_b32 m0, s55
	s_nop 0
	global_load_lds_dwordx4 v[128:129], off
	v_lshl_add_u64 v[128:129], s[56:57], 0, v[148:149]
	s_add_i32 m0, s55, 0x2000
	s_nop 0
	global_load_lds_dwordx4 v[128:129], off
	s_waitcnt vmcnt(10)
	s_barrier
	s_setprio 1
	v_mfma_f32_16x16x32_bf16 v[52:55], v[222:225], v[154:157], v[52:55]
	v_mfma_f32_16x16x32_bf16 v[48:51], v[230:233], v[154:157], v[48:51]
	v_mfma_f32_16x16x32_bf16 v[36:39], v[222:225], v[182:185], v[36:39]
	v_mfma_f32_16x16x32_bf16 v[32:35], v[230:233], v[182:185], v[32:35]
	v_mfma_f32_16x16x32_bf16 v[20:23], v[222:225], v[190:193], v[20:23]
	v_mfma_f32_16x16x32_bf16 v[16:19], v[230:233], v[190:193], v[16:19]
	v_mfma_f32_16x16x32_bf16 v[4:7], v[222:225], v[214:217], v[4:7]
	v_mfma_f32_16x16x32_bf16 v[0:3], v[230:233], v[214:217], v[0:3]
	v_mfma_f32_16x16x32_bf16 v[52:55], v[226:229], v[174:177], v[52:55]
	v_mfma_f32_16x16x32_bf16 v[48:51], v[234:237], v[174:177], v[48:51]
	v_mfma_f32_16x16x32_bf16 v[36:39], v[226:229], v[186:189], v[36:39]
	v_mfma_f32_16x16x32_bf16 v[32:35], v[234:237], v[186:189], v[32:35]
	v_mfma_f32_16x16x32_bf16 v[20:23], v[226:229], v[194:197], v[20:23]
	v_mfma_f32_16x16x32_bf16 v[16:19], v[234:237], v[194:197], v[16:19]
	v_mfma_f32_16x16x32_bf16 v[4:7], v[226:229], v[218:221], v[4:7]
	v_mfma_f32_16x16x32_bf16 v[0:3], v[234:237], v[218:221], v[0:3]
	s_setprio 0
	s_add_i32 s55, 0, 0x18000
	v_add_u32_e32 v140, s55, v178
	s_barrier
	ds_read_b128 v[128:131], v140
	ds_read_b128 v[132:135], v140 offset:1024
	ds_read_b128 v[136:139], v140 offset:2048
	ds_read_b128 v[140:143], v140 offset:3072
	s_add_u32 s36, s36, 0x20000
	s_addc_u32 s37, s37, 0
	s_mov_b32 m0, s45
	v_lshl_add_u64 v[222:223], s[36:37], 0, v[144:145]
	ds_read_b128 v[154:157], v181 offset:32768
	ds_read_b128 v[174:177], v181 offset:33792
	ds_read_b128 v[182:185], v181 offset:34816
	ds_read_b128 v[186:189], v181 offset:35840
	ds_read_b128 v[190:193], v181 offset:36864
	ds_read_b128 v[194:197], v181 offset:37888
	ds_read_b128 v[214:217], v181 offset:38912
	ds_read_b128 v[218:221], v181 offset:39936
	global_load_lds_dwordx4 v[222:223], off
	v_lshl_add_u64 v[222:223], s[36:37], 0, v[146:147]
	s_mov_b32 m0, s46
	s_nop 0
	global_load_lds_dwordx4 v[222:223], off
	s_waitcnt lgkmcnt(8)
	s_waitcnt vmcnt(10)
	s_barrier
	s_waitcnt lgkmcnt(0)
	s_setprio 1
	v_mfma_f32_16x16x32_bf16 v[124:127], v[128:131], v[154:157], v[124:127]
	v_mfma_f32_16x16x32_bf16 v[120:123], v[136:139], v[154:157], v[120:123]
	v_mfma_f32_16x16x32_bf16 v[108:111], v[128:131], v[182:185], v[108:111]
	v_mfma_f32_16x16x32_bf16 v[104:107], v[136:139], v[182:185], v[104:107]
	v_mfma_f32_16x16x32_bf16 v[92:95], v[128:131], v[190:193], v[92:95]
	v_mfma_f32_16x16x32_bf16 v[88:91], v[136:139], v[190:193], v[88:91]
	v_mfma_f32_16x16x32_bf16 v[76:79], v[128:131], v[214:217], v[76:79]
	v_mfma_f32_16x16x32_bf16 v[72:75], v[136:139], v[214:217], v[72:75]
	v_mfma_f32_16x16x32_bf16 v[124:127], v[132:135], v[174:177], v[124:127]
	v_mfma_f32_16x16x32_bf16 v[120:123], v[140:143], v[174:177], v[120:123]
	v_mfma_f32_16x16x32_bf16 v[108:111], v[132:135], v[186:189], v[108:111]
	v_mfma_f32_16x16x32_bf16 v[104:107], v[140:143], v[186:189], v[104:107]
	v_mfma_f32_16x16x32_bf16 v[92:95], v[132:135], v[194:197], v[92:95]
	v_mfma_f32_16x16x32_bf16 v[88:91], v[140:143], v[194:197], v[88:91]
	v_mfma_f32_16x16x32_bf16 v[76:79], v[132:135], v[218:221], v[76:79]
	v_mfma_f32_16x16x32_bf16 v[72:75], v[140:143], v[218:221], v[72:75]
	s_setprio 0
	s_barrier
	s_add_i32 s36, 0, 0x1c000
	s_add_i32 s37, s55, s42
	v_add_u32_e32 v234, s36, v178
	v_lshl_add_u64 v[158:159], v[158:159], 0, s[2:3]
	s_mov_b32 m0, s37
	ds_read_b128 v[222:225], v234
	ds_read_b128 v[226:229], v234 offset:1024
	ds_read_b128 v[230:233], v234 offset:2048
	ds_read_b128 v[234:237], v234 offset:3072
	global_load_lds_dwordx4 v[158:159], off
	v_lshl_add_u64 v[158:159], v[238:239], 0, s[2:3]
	s_add_i32 m0, s37, 0x2000
	s_nop 0
	global_load_lds_dwordx4 v[158:159], off
	s_waitcnt vmcnt(10)
	s_barrier
	s_waitcnt lgkmcnt(0)
	s_setprio 1
	v_mfma_f32_16x16x32_bf16 v[116:119], v[222:225], v[154:157], v[116:119]
	v_mfma_f32_16x16x32_bf16 v[112:115], v[230:233], v[154:157], v[112:115]
	v_mfma_f32_16x16x32_bf16 v[100:103], v[222:225], v[182:185], v[100:103]
	v_mfma_f32_16x16x32_bf16 v[96:99], v[230:233], v[182:185], v[96:99]
	v_mfma_f32_16x16x32_bf16 v[84:87], v[222:225], v[190:193], v[84:87]
	v_mfma_f32_16x16x32_bf16 v[80:83], v[230:233], v[190:193], v[80:83]
	v_mfma_f32_16x16x32_bf16 v[68:71], v[222:225], v[214:217], v[68:71]
	v_mfma_f32_16x16x32_bf16 v[64:67], v[230:233], v[214:217], v[64:67]
	v_mfma_f32_16x16x32_bf16 v[116:119], v[226:229], v[174:177], v[116:119]
	v_mfma_f32_16x16x32_bf16 v[112:115], v[234:237], v[174:177], v[112:115]
	v_mfma_f32_16x16x32_bf16 v[100:103], v[226:229], v[186:189], v[100:103]
	v_mfma_f32_16x16x32_bf16 v[96:99], v[234:237], v[186:189], v[96:99]
	v_mfma_f32_16x16x32_bf16 v[84:87], v[226:229], v[194:197], v[84:87]
	v_mfma_f32_16x16x32_bf16 v[80:83], v[234:237], v[194:197], v[80:83]
	v_mfma_f32_16x16x32_bf16 v[68:71], v[226:229], v[218:221], v[68:71]
	v_mfma_f32_16x16x32_bf16 v[64:67], v[234:237], v[218:221], v[64:67]
	s_setprio 0
	s_mov_b32 m0, s47
	v_lshl_add_u64 v[158:159], v[240:241], 0, s[2:3]
	s_barrier
	ds_read_b128 v[154:157], v181 offset:49152
	ds_read_b128 v[174:177], v181 offset:50176
	ds_read_b128 v[182:185], v181 offset:51200
	ds_read_b128 v[186:189], v181 offset:52224
	ds_read_b128 v[190:193], v181 offset:53248
	ds_read_b128 v[194:197], v181 offset:54272
	ds_read_b128 v[214:217], v181 offset:55296
	ds_read_b128 v[218:221], v181 offset:56320
	global_load_lds_dwordx4 v[158:159], off
	v_lshl_add_u64 v[158:159], v[242:243], 0, s[2:3]
	s_mov_b32 m0, s48
	s_nop 0
	global_load_lds_dwordx4 v[158:159], off
	s_barrier
; DEV bf16x8 pack8(f32x4 a, f32x4 b) { u32x4 w; w.x = cvt_pk_bf16(a[0], a[1]); w.y = cvt_pk_bf16(a[2], a[3]); w.z = cvt_pk_bf16(b[0], b[1]); w.w = cvt_pk_bf16(b[2], b[3]); return __builtin_bit_cast(bf16x8, w); }
; #define PG8_WAIT_V(n) asm volatile("s_waitcnt vmcnt(" #n ")" ::: "memory")
; #define PG8_WAIT_L(n) asm volatile("s_waitcnt lgkmcnt(" #n ")" ::: "memory")
; #define PG8_BAR __builtin_amdgcn_s_barrier()
; #define PG8_SCHED __builtin_amdgcn_sched_barrier(0)
; template <class Epi>
; DEV void gemm_phase(LAS unsigned char* lds, const Gemm g, const StaticOrder& S, const Epi& E) {
;     ...
;             PG8_BAR; PG8_WAIT_L(0); PG8_MMA(1, 0, At, B0); PG8_BAR; PG8_SCHED;
;             PG8_STAGE(PG8_SB(1, 1), b3 + hstep, voffB);
;             PG8_WAIT_V(6); PG8_BAR; PG8_MMA(1, 1, At, B1); PG8_BAR;
;     DEV void operator()(AccRef acc, const pg8::Unit& u, int wr, int wc, int fr, int fq) const {
;         const int row0 = u.pm * 256 + wr * 64 + fr, col0 = u.pn * 256 + wc * 32 + 8 * fq;
; #pragma unroll
;         for (int am = 0; am < 4; ++am) { const int ai = am >> 1, m0 = (am & 1) * 2;
;             f32x4 bv[4][2][2];
; #pragma unroll
;             for (int m = m0; m < m0 + 2; ++m)
; #pragma unroll
;                 for (int bj = 0; bj < 2; ++bj)
; #pragma unroll
;                     for (int n = 0; n < 2; ++n) bv[m][bj][n] = *(const f32x4*)(base + (size_t)(row0 + ai * 128 + m * 16) * 2048 + col0 + bj * 128 + n * 4);
; #pragma unroll
;             for (int m = m0; m < m0 + 2; ++m) { const size_t off = (size_t)(row0 + ai * 128 + m * 16) * 2048 + col0; float sq = 0.f;
; #pragma unroll
;                 for (int bj = 0; bj < 2; ++bj) { const f32x4 o0 = bv[m][bj][0] + scale * acc[ai][bj][m][0], o1 = bv[m][bj][1] + scale * acc[ai][bj][m][1];
;                     *(f32x4*)(out + off + bj * 128) = o0; *(f32x4*)(out + off + bj * 128 + 4) = o1;
;                     if (xb) { *(u32x4*)(xb + off + bj * 128) = __builtin_bit_cast(u32x4, pack8(o0, o1));
;                         sq += (o0[0] * o0[0] + o0[1] * o0[1] + o0[2] * o0[2] + o0[3] * o0[3]) + (o1[0] * o1[0] + o1[1] * o1[1] + o1[2] * o1[2] + o1[3] * o1[3]); } }
;                 if (ssout) { sq += __shfl_xor(sq, 16); sq += __shfl_xor(sq, 32);
;                     if (fq == 0) { if (red) red[(ai * 128 + wr * 64 + m * 16 + fr) * 4 + wc] = sq; else atomicAdd(ssout + (size_t)(row0 + ai * 128 + m * 16) * 8 + u.pn, sq); } } }
	s_waitcnt lgkmcnt(0)
	s_setprio 1
	v_mfma_f32_16x16x32_bf16 v[60:63], v[128:131], v[154:157], v[60:63]
	v_mfma_f32_16x16x32_bf16 v[56:59], v[136:139], v[154:157], v[56:59]
	v_mfma_f32_16x16x32_bf16 v[44:47], v[128:131], v[182:185], v[44:47]
	v_mfma_f32_16x16x32_bf16 v[40:43], v[136:139], v[182:185], v[40:43]
	v_mfma_f32_16x16x32_bf16 v[28:31], v[128:131], v[190:193], v[28:31]
	v_mfma_f32_16x16x32_bf16 v[24:27], v[136:139], v[190:193], v[24:27]
	v_mfma_f32_16x16x32_bf16 v[12:15], v[128:131], v[214:217], v[12:15]
	v_mfma_f32_16x16x32_bf16 v[8:11], v[136:139], v[214:217], v[8:11]
	v_mfma_f32_16x16x32_bf16 v[60:63], v[132:135], v[174:177], v[60:63]
	v_mfma_f32_16x16x32_bf16 v[56:59], v[140:143], v[174:177], v[56:59]
	v_mfma_f32_16x16x32_bf16 v[44:47], v[132:135], v[186:189], v[44:47]
	v_mfma_f32_16x16x32_bf16 v[40:43], v[140:143], v[186:189], v[40:43]
	v_mfma_f32_16x16x32_bf16 v[28:31], v[132:135], v[194:197], v[28:31]
	v_mfma_f32_16x16x32_bf16 v[24:27], v[140:143], v[194:197], v[24:27]
	v_mfma_f32_16x16x32_bf16 v[12:15], v[132:135], v[218:221], v[12:15]
	v_mfma_f32_16x16x32_bf16 v[8:11], v[140:143], v[218:221], v[8:11]
	s_setprio 0
	s_barrier
	s_add_u32 s34, s34, 0x20080
	s_addc_u32 s35, s35, 0
	s_add_i32 s36, s36, s42
	v_lshl_add_u64 v[128:129], s[34:35], 0, v[160:161]
	s_mov_b32 m0, s36
	s_nop 0
	global_load_lds_dwordx4 v[128:129], off
	v_lshl_add_u64 v[128:129], s[34:35], 0, v[148:149]
	s_add_i32 m0, s36, 0x2000
	s_nop 0
	global_load_lds_dwordx4 v[128:129], off
	s_waitcnt vmcnt(10)
	s_barrier
	s_setprio 1
	v_mfma_f32_16x16x32_bf16 v[52:55], v[222:225], v[154:157], v[52:55]
	v_mfma_f32_16x16x32_bf16 v[48:51], v[230:233], v[154:157], v[48:51]
	v_mfma_f32_16x16x32_bf16 v[36:39], v[222:225], v[182:185], v[36:39]
	v_mfma_f32_16x16x32_bf16 v[32:35], v[230:233], v[182:185], v[32:35]
	v_mfma_f32_16x16x32_bf16 v[20:23], v[222:225], v[190:193], v[20:23]
	v_mfma_f32_16x16x32_bf16 v[16:19], v[230:233], v[190:193], v[16:19]
	v_mfma_f32_16x16x32_bf16 v[4:7], v[222:225], v[214:217], v[4:7]
	v_mfma_f32_16x16x32_bf16 v[0:3], v[230:233], v[214:217], v[0:3]
	v_mfma_f32_16x16x32_bf16 v[52:55], v[226:229], v[174:177], v[52:55]
	v_mfma_f32_16x16x32_bf16 v[48:51], v[234:237], v[174:177], v[48:51]
	v_mfma_f32_16x16x32_bf16 v[36:39], v[226:229], v[186:189], v[36:39]
	v_mfma_f32_16x16x32_bf16 v[32:35], v[234:237], v[186:189], v[32:35]
	v_mfma_f32_16x16x32_bf16 v[20:23], v[226:229], v[194:197], v[20:23]
	v_mfma_f32_16x16x32_bf16 v[16:19], v[234:237], v[194:197], v[16:19]
	v_mfma_f32_16x16x32_bf16 v[4:7], v[226:229], v[218:221], v[4:7]
	v_mfma_f32_16x16x32_bf16 v[0:3], v[234:237], v[218:221], v[0:3]
	s_setprio 0
	s_add_i32 s54, s54, 2
	s_add_u32 s30, s30, 0x100
	s_addc_u32 s31, s31, 0
	s_add_u32 s52, s52, 0x100
	s_addc_u32 s53, s53, 0
	s_cmp_gt_u32 s54, 5
	s_barrier
	s_cbranch_scc0 .LBB0_260
	v_lshl_add_u32 v156, s28, 8, v167
	v_lshl_or_b32 v154, s18, 8, v179
	v_readlane_b32 s28, v254, 16
	v_ashrrev_i32_e32 v155, 31, v154
	v_readlane_b32 s29, v254, 17
	v_ashrrev_i32_e32 v157, 31, v156
	v_lshlrev_b64 v[128:129], 13, v[156:157]
	v_lshl_add_u64 v[158:159], v[154:155], 2, s[28:29]
	v_lshl_add_u64 v[214:215], v[158:159], 0, v[128:129]
	global_load_dwordx4 v[182:185], v[214:215], off offset:16
	global_load_dwordx4 v[186:189], v[214:215], off
	global_load_dwordx4 v[190:193], v[214:215], off offset:528
	global_load_dwordx4 v[194:197], v[214:215], off offset:512
	v_or_b32_e32 v174, 16, v156
	v_ashrrev_i32_e32 v175, 31, v174
	v_lshlrev_b64 v[128:129], 13, v[174:175]
	v_lshl_add_u64 v[176:177], v[158:159], 0, v[128:129]
	global_load_dwordx4 v[136:139], v[176:177], off offset:16
	global_load_dwordx4 v[140:143], v[176:177], off
	global_load_dwordx4 v[128:131], v[176:177], off offset:528
	global_load_dwordx4 v[132:135], v[176:177], off offset:512
	v_lshlrev_b64 v[216:217], 11, v[156:157]
	v_readlane_b32 s28, v250, 9
	v_lshl_add_u64 v[216:217], v[216:217], 0, v[154:155]
	v_readlane_b32 s29, v250, 10
	v_cmp_lt_i32_e32 vcc, v208, v206
	s_ashr_i32 s19, s18, 31
	s_waitcnt vmcnt(0)
	v_pk_add_f32 v[120:121], v[120:121], v[182:183]
	v_pk_add_f32 v[126:127], v[126:127], v[188:189]
	v_pk_add_f32 v[124:125], v[124:125], v[186:187]
	v_pk_add_f32 v[122:123], v[122:123], v[184:185]
	global_store_dwordx4 v[214:215], v[124:127], off
	global_store_dwordx4 v[214:215], v[120:123], off offset:16
	v_cvt_pk_bf16_f32 v184, v120, v121
	v_cvt_pk_bf16_f32 v182, v124, v125
	v_mul_f32_e32 v121, v121, v121
	v_cvt_pk_bf16_f32 v183, v126, v127
	v_cvt_pk_bf16_f32 v185, v122, v123
	v_lshl_add_u64 v[186:187], v[216:217], 1, s[28:29]
	v_fmac_f32_e32 v121, v120, v120
	v_pk_add_f32 v[118:119], v[118:119], v[196:197]
	v_pk_add_f32 v[116:117], v[116:117], v[194:195]
	v_pk_add_f32 v[112:113], v[112:113], v[190:191]
	global_store_dwordx4 v[186:187], v[182:185], off
	v_mul_f32_e32 v125, v125, v125
	v_fmac_f32_e32 v121, v122, v122
	v_pk_add_f32 v[114:115], v[114:115], v[192:193]
	global_store_dwordx4 v[214:215], v[116:119], off offset:512
	global_store_dwordx4 v[214:215], v[112:115], off offset:528
	v_cvt_pk_bf16_f32 v120, v116, v117
	v_cvt_pk_bf16_f32 v122, v112, v113
	v_mul_f32_e32 v117, v117, v117
	v_mul_f32_e32 v113, v113, v113
	v_fmac_f32_e32 v125, v124, v124
	v_fmac_f32_e32 v117, v116, v116
	v_fmac_f32_e32 v113, v112, v112
	v_fmac_f32_e32 v125, v126, v126
	v_fmac_f32_e32 v117, v118, v118
	v_fmac_f32_e32 v113, v114, v114
	v_fmac_f32_e32 v125, v127, v127
	v_fmac_f32_e32 v121, v123, v123
	v_fmac_f32_e32 v117, v119, v119
	v_fmac_f32_e32 v113, v115, v115
	v_add_f32_e32 v124, v125, v121
	v_add_f32_e32 v112, v117, v113
	v_cndmask_b32_e32 v113, v204, v208, vcc
	v_cvt_pk_bf16_f32 v121, v118, v119
	v_add_f32_e32 v112, v124, v112
	v_lshlrev_b32_e32 v118, 2, v113
	ds_bpermute_b32 v113, v118, v112
	v_cmp_lt_i32_e32 vcc, v207, v206
	v_cvt_pk_bf16_f32 v123, v114, v115
	global_store_dwordx4 v[186:187], v[120:123], off offset:256
	s_waitcnt lgkmcnt(0)
	v_add_f32_e32 v112, v112, v113
	v_cndmask_b32_e32 v113, v204, v207, vcc
	v_lshlrev_b32_e32 v119, 2, v113
	ds_bpermute_b32 v113, v119, v112
	s_and_saveexec_b64 s[28:29], s[6:7]
	s_cbranch_execz .LBB0_266
	s_waitcnt lgkmcnt(0)
	v_add_f32_e32 v112, v112, v113
	s_mov_b64 s[30:31], -1
	s_and_b64 vcc, exec, s[16:17]
	s_cbranch_vccz .LBB0_264
	v_lshlrev_b64 v[114:115], 5, v[156:157]
	v_lshl_add_u64 v[114:115], s[12:13], 0, v[114:115]
	v_lshl_add_u64 v[114:115], s[18:19], 2, v[114:115]
	global_atomic_add_f32 v[114:115], v112, off
	s_mov_b64 s[30:31], 0

; #define PG8_STAGE(bufoff, gbase, voff) do { _Pragma("unroll") for (int _i = 0; _i < 2; ++_i) \
;         __builtin_amdgcn_global_load_lds((const unsigned*)((const char*)(gbase) + (voff)[_i]), (LAS unsigned*)(lds + (bufoff) + ldsw + _i * 8192), 16, 0, 0); } while (0)
; #define PG8_LDA(dst, b, h) do { _Pragma("unroll") for (int m = 0; m < 4; ++m) _Pragma("unroll") for (int k = 0; k < 2; ++k) dst[m][k] = *(const LAS bf16x8*)(lds + PG8_SA(b, h) + aoff + m * 2048 + k * 1024); } while (0)
; #define PG8_LDB(dst, b, h) do { _Pragma("unroll") for (int n = 0; n < 2; ++n) _Pragma("unroll") for (int k = 0; k < 2; ++k) dst[n][k] = *(const LAS bf16x8*)(lds + PG8_SB(b, h) + boff + n * 2048 + k * 1024); } while (0)
; #define PG8_MMA(ai, bj, At, Bt) do { __builtin_amdgcn_s_setprio(1); _Pragma("unroll") for (int m = 0; m < 4; ++m) _Pragma("unroll") for (int n = 0; n < 2; ++n) _Pragma("unroll") for (int k = 0; k < 2; ++k) \
;         acc[ai][bj][m][n] = __builtin_amdgcn_mfma_f32_16x16x32_bf16(Bt[n][k], At[m][k], acc[ai][bj][m][n], 0, 0, 0); __builtin_amdgcn_s_setprio(0); } while (0)
; #define PG8_WAIT_L(n) asm volatile("s_waitcnt lgkmcnt(" #n ")" ::: "memory")
; #define PG8_BAR __builtin_amdgcn_s_barrier()
; #define PG8_SCHED __builtin_amdgcn_sched_barrier(0)
; template <class Epi>
; DEV void gemm_phase(LAS unsigned char* lds, const Gemm g, const StaticOrder& S, const Epi& E) {
;     ...
;             const bool last = (t == nt - 2);
;             const char* a1 = cA + (size_t)(t + 1) * kstep;
;             const char* a2 = last ? nA : cA + (size_t)(t + 2) * kstep; const char* b2 = last ? nB : cB + (size_t)(t + 2) * kstep;
;             const char* a3 = a2 + kstep; const char* b3 = b2 + kstep;
;             PG8_LDB(B0, 0, 0); PG8_SCHED; PG8_LDA(At, 0, 0); PG8_STAGE(PG8_SA(1, 1), a1 + hstep, voffA);
;             PG8_WAIT_L(8); PG8_BAR; PG8_WAIT_L(0); PG8_MMA(0, 0, At, B0); PG8_BAR; PG8_SCHED;
;             PG8_LDB(B1, 0, 1); PG8_STAGE(PG8_SB(0, 0), b2, voffB);
;             PG8_BAR; PG8_WAIT_L(0); PG8_MMA(0, 1, At, B1); PG8_BAR;
;             PG8_LDA(At, 0, 1); PG8_STAGE(PG8_SA(0, 0), a2, voffA);
;             PG8_BAR; PG8_WAIT_L(0); PG8_MMA(1, 0, At, B0); PG8_BAR; PG8_SCHED;
.LBB0_344:
	s_add_u32 s20, s18, 0xfff80080
	s_addc_u32 s21, s19, -1
	s_add_i32 s45, 0, 0x10000
	v_add_u32_e32 v146, s45, v149
	ds_read_b128 v[128:131], v146
	ds_read_b128 v[132:135], v146 offset:1024
	ds_read_b128 v[142:145], v146 offset:2048
	ds_read_b128 v[150:153], v146 offset:3072
	s_cmp_eq_u32 s44, 28
	s_cselect_b32 s23, s1, s21
	s_cselect_b32 s22, s13, s20
	s_cselect_b32 s21, s11, s43
	s_cselect_b32 s20, s41, s42
	v_lshl_add_u64 v[154:155], s[18:19], 0, v[138:139]
	s_add_i32 m0, s30, 0xc000
	ds_read_b128 v[174:177], v159
	ds_read_b128 v[178:181], v159 offset:1024
	ds_read_b128 v[182:185], v159 offset:2048
	ds_read_b128 v[186:189], v159 offset:3072
	ds_read_b128 v[190:193], v159 offset:4096
	ds_read_b128 v[194:197], v159 offset:5120
	ds_read_b128 v[214:217], v159 offset:6144
	ds_read_b128 v[218:221], v159 offset:7168
	global_load_lds_dwordx4 v[154:155], off
	v_lshl_add_u64 v[154:155], s[18:19], 0, v[140:141]
	s_add_i32 m0, s30, 0xe000
	s_nop 0
	global_load_lds_dwordx4 v[154:155], off
	s_waitcnt lgkmcnt(8)
	s_waitcnt vmcnt(10)
	s_barrier
	s_waitcnt lgkmcnt(0)
	s_setprio 1
	v_mfma_f32_16x16x32_bf16 v[124:127], v[128:131], v[174:177], v[124:127]
	v_mfma_f32_16x16x32_bf16 v[120:123], v[142:145], v[174:177], v[120:123]
	v_mfma_f32_16x16x32_bf16 v[116:119], v[128:131], v[182:185], v[116:119]
	v_mfma_f32_16x16x32_bf16 v[108:111], v[142:145], v[182:185], v[108:111]
	v_mfma_f32_16x16x32_bf16 v[100:103], v[128:131], v[190:193], v[100:103]
	v_mfma_f32_16x16x32_bf16 v[92:95], v[142:145], v[190:193], v[92:95]
	v_mfma_f32_16x16x32_bf16 v[84:87], v[128:131], v[214:217], v[84:87]
	v_mfma_f32_16x16x32_bf16 v[76:79], v[142:145], v[214:217], v[76:79]
	v_mfma_f32_16x16x32_bf16 v[124:127], v[132:135], v[178:181], v[124:127]
	v_mfma_f32_16x16x32_bf16 v[120:123], v[150:153], v[178:181], v[120:123]
	v_mfma_f32_16x16x32_bf16 v[116:119], v[132:135], v[186:189], v[116:119]
	v_mfma_f32_16x16x32_bf16 v[108:111], v[150:153], v[186:189], v[108:111]
	v_mfma_f32_16x16x32_bf16 v[100:103], v[132:135], v[194:197], v[100:103]
	v_mfma_f32_16x16x32_bf16 v[92:95], v[150:153], v[194:197], v[92:95]
	v_mfma_f32_16x16x32_bf16 v[84:87], v[132:135], v[218:221], v[84:87]
	v_mfma_f32_16x16x32_bf16 v[76:79], v[150:153], v[218:221], v[76:79]
	s_setprio 0
	s_barrier
	s_add_i32 s48, 0, 0x14000
	s_add_i32 s45, s45, s29
	v_add_u32_e32 v146, s48, v149
	v_lshl_add_u64 v[154:155], s[20:21], 0, v[160:161]
	s_mov_b32 m0, s45
	ds_read_b128 v[222:225], v146
	ds_read_b128 v[226:229], v146 offset:1024
	ds_read_b128 v[230:233], v146 offset:2048
	ds_read_b128 v[234:237], v146 offset:3072
	global_load_lds_dwordx4 v[154:155], off
	v_lshl_add_u64 v[238:239], s[20:21], 0, v[136:137]
	s_add_i32 m0, s45, 0x2000
	s_nop 0
	global_load_lds_dwordx4 v[238:239], off
	s_waitcnt vmcnt(10)
	s_barrier
	s_waitcnt lgkmcnt(0)
	s_setprio 1
	v_mfma_f32_16x16x32_bf16 v[112:115], v[222:225], v[174:177], v[112:115]
	v_mfma_f32_16x16x32_bf16 v[104:107], v[230:233], v[174:177], v[104:107]
	v_mfma_f32_16x16x32_bf16 v[96:99], v[222:225], v[182:185], v[96:99]
	v_mfma_f32_16x16x32_bf16 v[88:91], v[230:233], v[182:185], v[88:91]
	v_mfma_f32_16x16x32_bf16 v[80:83], v[222:225], v[190:193], v[80:83]
	v_mfma_f32_16x16x32_bf16 v[72:75], v[230:233], v[190:193], v[72:75]
	v_mfma_f32_16x16x32_bf16 v[68:71], v[222:225], v[214:217], v[68:71]
	v_mfma_f32_16x16x32_bf16 v[64:67], v[230:233], v[214:217], v[64:67]
	v_mfma_f32_16x16x32_bf16 v[112:115], v[226:229], v[178:181], v[112:115]
	v_mfma_f32_16x16x32_bf16 v[104:107], v[234:237], v[178:181], v[104:107]
	v_mfma_f32_16x16x32_bf16 v[96:99], v[226:229], v[186:189], v[96:99]
	v_mfma_f32_16x16x32_bf16 v[88:91], v[234:237], v[186:189], v[88:91]
	v_mfma_f32_16x16x32_bf16 v[80:83], v[226:229], v[194:197], v[80:83]
	v_mfma_f32_16x16x32_bf16 v[72:75], v[234:237], v[194:197], v[72:75]
	v_mfma_f32_16x16x32_bf16 v[68:71], v[226:229], v[218:221], v[68:71]
	v_mfma_f32_16x16x32_bf16 v[64:67], v[234:237], v[218:221], v[64:67]
	s_setprio 0
	s_mov_b32 m0, s30
	v_lshl_add_u64 v[240:241], s[22:23], 0, v[160:161]
	s_barrier
	ds_read_b128 v[174:177], v159 offset:16384
	ds_read_b128 v[178:181], v159 offset:17408
	ds_read_b128 v[182:185], v159 offset:18432
	ds_read_b128 v[186:189], v159 offset:19456
	ds_read_b128 v[190:193], v159 offset:20480
	ds_read_b128 v[194:197], v159 offset:21504
	ds_read_b128 v[214:217], v159 offset:22528
	ds_read_b128 v[218:221], v159 offset:23552
	global_load_lds_dwordx4 v[240:241], off
	v_lshl_add_u64 v[242:243], s[22:23], 0, v[136:137]
	s_mov_b32 m0, s31
	s_nop 0
	global_load_lds_dwordx4 v[242:243], off
	s_barrier
	s_waitcnt lgkmcnt(0)
	s_setprio 1
	v_mfma_f32_16x16x32_bf16 v[60:63], v[128:131], v[174:177], v[60:63]
	v_mfma_f32_16x16x32_bf16 v[56:59], v[142:145], v[174:177], v[56:59]
	v_mfma_f32_16x16x32_bf16 v[52:55], v[128:131], v[182:185], v[52:55]
	v_mfma_f32_16x16x32_bf16 v[44:47], v[142:145], v[182:185], v[44:47]
	v_mfma_f32_16x16x32_bf16 v[36:39], v[128:131], v[190:193], v[36:39]
	v_mfma_f32_16x16x32_bf16 v[28:31], v[142:145], v[190:193], v[28:31]
	v_mfma_f32_16x16x32_bf16 v[20:23], v[128:131], v[214:217], v[20:23]
	v_mfma_f32_16x16x32_bf16 v[12:15], v[142:145], v[214:217], v[12:15]
	v_mfma_f32_16x16x32_bf16 v[60:63], v[132:135], v[178:181], v[60:63]
	v_mfma_f32_16x16x32_bf16 v[56:59], v[150:153], v[178:181], v[56:59]
	v_mfma_f32_16x16x32_bf16 v[52:55], v[132:135], v[186:189], v[52:55]
	v_mfma_f32_16x16x32_bf16 v[44:47], v[150:153], v[186:189], v[44:47]
	v_mfma_f32_16x16x32_bf16 v[36:39], v[132:135], v[194:197], v[36:39]
	v_mfma_f32_16x16x32_bf16 v[28:31], v[150:153], v[194:197], v[28:31]
	v_mfma_f32_16x16x32_bf16 v[20:23], v[132:135], v[218:221], v[20:23]
	v_mfma_f32_16x16x32_bf16 v[12:15], v[150:153], v[218:221], v[12:15]
	s_setprio 0
	s_barrier
; #define PG8_STAGE(bufoff, gbase, voff) do { _Pragma("unroll") for (int _i = 0; _i < 2; ++_i) \
;         __builtin_amdgcn_global_load_lds((const unsigned*)((const char*)(gbase) + (voff)[_i]), (LAS unsigned*)(lds + (bufoff) + ldsw + _i * 8192), 16, 0, 0); } while (0)
; #define PG8_LDA(dst, b, h) do { _Pragma("unroll") for (int m = 0; m < 4; ++m) _Pragma("unroll") for (int k = 0; k < 2; ++k) dst[m][k] = *(const LAS bf16x8*)(lds + PG8_SA(b, h) + aoff + m * 2048 + k * 1024); } while (0)
; #define PG8_LDB(dst, b, h) do { _Pragma("unroll") for (int n = 0; n < 2; ++n) _Pragma("unroll") for (int k = 0; k < 2; ++k) dst[n][k] = *(const LAS bf16x8*)(lds + PG8_SB(b, h) + boff + n * 2048 + k * 1024); } while (0)
; #define PG8_MMA(ai, bj, At, Bt) do { __builtin_amdgcn_s_setprio(1); _Pragma("unroll") for (int m = 0; m < 4; ++m) _Pragma("unroll") for (int n = 0; n < 2; ++n) _Pragma("unroll") for (int k = 0; k < 2; ++k) \
;         acc[ai][bj][m][n] = __builtin_amdgcn_mfma_f32_16x16x32_bf16(Bt[n][k], At[m][k], acc[ai][bj][m][n], 0, 0, 0); __builtin_amdgcn_s_setprio(0); } while (0)
; #define PG8_WAIT_V(n) asm volatile("s_waitcnt vmcnt(" #n ")" ::: "memory")
; #define PG8_WAIT_L(n) asm volatile("s_waitcnt lgkmcnt(" #n ")" ::: "memory")
; #define PG8_BAR __builtin_amdgcn_s_barrier()
; #define PG8_SCHED __builtin_amdgcn_sched_barrier(0)
; template <class Epi>
; DEV void gemm_phase(LAS unsigned char* lds, const Gemm g, const StaticOrder& S, const Epi& E) {
;     ...
;             PG8_STAGE(PG8_SB(0, 1), b2 + hstep, voffB);
;             PG8_WAIT_V(6); PG8_BAR; PG8_MMA(1, 1, At, B1); PG8_BAR;
;             PG8_LDB(B0, 1, 0); PG8_SCHED; PG8_LDA(At, 1, 0); PG8_STAGE(PG8_SA(0, 1), a2 + hstep, voffA);
;             PG8_WAIT_L(8); PG8_BAR; PG8_WAIT_L(0); PG8_MMA(0, 0, At, B0); PG8_BAR; PG8_SCHED;
;             PG8_LDB(B1, 1, 1); PG8_STAGE(PG8_SB(1, 0), b3, voffB);
;             PG8_BAR; PG8_WAIT_L(0); PG8_MMA(0, 1, At, B1); PG8_BAR;
;             PG8_LDA(At, 1, 1); PG8_STAGE(PG8_SA(1, 0), a3, voffA);
	s_add_u32 s46, s20, 0x80000
	s_addc_u32 s47, s21, 0
	s_add_i32 s45, s48, s29
	v_lshl_add_u64 v[128:129], s[46:47], 0, v[160:161]
	s_mov_b32 m0, s45
	s_nop 0
	global_load_lds_dwordx4 v[128:129], off
	v_lshl_add_u64 v[128:129], s[46:47], 0, v[136:137]
	s_add_i32 m0, s45, 0x2000
	s_nop 0
	global_load_lds_dwordx4 v[128:129], off
	s_waitcnt vmcnt(10)
	s_barrier
	s_setprio 1
	v_mfma_f32_16x16x32_bf16 v[48:51], v[222:225], v[174:177], v[48:51]
	v_mfma_f32_16x16x32_bf16 v[40:43], v[230:233], v[174:177], v[40:43]
	v_mfma_f32_16x16x32_bf16 v[32:35], v[222:225], v[182:185], v[32:35]
	v_mfma_f32_16x16x32_bf16 v[24:27], v[230:233], v[182:185], v[24:27]
	v_mfma_f32_16x16x32_bf16 v[16:19], v[222:225], v[190:193], v[16:19]
	v_mfma_f32_16x16x32_bf16 v[8:11], v[230:233], v[190:193], v[8:11]
	v_mfma_f32_16x16x32_bf16 v[4:7], v[222:225], v[214:217], v[4:7]
	v_mfma_f32_16x16x32_bf16 v[0:3], v[230:233], v[214:217], v[0:3]
	v_mfma_f32_16x16x32_bf16 v[48:51], v[226:229], v[178:181], v[48:51]
	v_mfma_f32_16x16x32_bf16 v[40:43], v[234:237], v[178:181], v[40:43]
	v_mfma_f32_16x16x32_bf16 v[32:35], v[226:229], v[186:189], v[32:35]
	v_mfma_f32_16x16x32_bf16 v[24:27], v[234:237], v[186:189], v[24:27]
	v_mfma_f32_16x16x32_bf16 v[16:19], v[226:229], v[194:197], v[16:19]
	v_mfma_f32_16x16x32_bf16 v[8:11], v[234:237], v[194:197], v[8:11]
	v_mfma_f32_16x16x32_bf16 v[4:7], v[226:229], v[218:221], v[4:7]
	v_mfma_f32_16x16x32_bf16 v[0:3], v[234:237], v[218:221], v[0:3]
	s_setprio 0
	s_add_i32 s45, 0, 0x18000
	v_add_u32_e32 v146, s45, v149
	s_barrier
	ds_read_b128 v[128:131], v146
	ds_read_b128 v[132:135], v146 offset:1024
	ds_read_b128 v[142:145], v146 offset:2048
	ds_read_b128 v[150:153], v146 offset:3072
	s_add_u32 s22, s22, 0x80000
	s_addc_u32 s23, s23, 0
	s_mov_b32 m0, s34
	v_lshl_add_u64 v[222:223], s[22:23], 0, v[160:161]
	ds_read_b128 v[174:177], v159 offset:32768
	ds_read_b128 v[178:181], v159 offset:33792
	ds_read_b128 v[182:185], v159 offset:34816
	ds_read_b128 v[186:189], v159 offset:35840
	ds_read_b128 v[190:193], v159 offset:36864
	ds_read_b128 v[194:197], v159 offset:37888
	ds_read_b128 v[214:217], v159 offset:38912
	ds_read_b128 v[218:221], v159 offset:39936
	global_load_lds_dwordx4 v[222:223], off
	v_lshl_add_u64 v[222:223], s[22:23], 0, v[136:137]
	s_mov_b32 m0, s35
	s_nop 0
	global_load_lds_dwordx4 v[222:223], off
	s_waitcnt lgkmcnt(8)
	s_waitcnt vmcnt(10)
	s_barrier
	s_waitcnt lgkmcnt(0)
	s_setprio 1
	v_mfma_f32_16x16x32_bf16 v[124:127], v[128:131], v[174:177], v[124:127]
	v_mfma_f32_16x16x32_bf16 v[120:123], v[142:145], v[174:177], v[120:123]
	v_mfma_f32_16x16x32_bf16 v[116:119], v[128:131], v[182:185], v[116:119]
	v_mfma_f32_16x16x32_bf16 v[108:111], v[142:145], v[182:185], v[108:111]
	v_mfma_f32_16x16x32_bf16 v[100:103], v[128:131], v[190:193], v[100:103]
	v_mfma_f32_16x16x32_bf16 v[92:95], v[142:145], v[190:193], v[92:95]
	v_mfma_f32_16x16x32_bf16 v[84:87], v[128:131], v[214:217], v[84:87]
	v_mfma_f32_16x16x32_bf16 v[76:79], v[142:145], v[214:217], v[76:79]
	v_mfma_f32_16x16x32_bf16 v[124:127], v[132:135], v[178:181], v[124:127]
	v_mfma_f32_16x16x32_bf16 v[120:123], v[150:153], v[178:181], v[120:123]
	v_mfma_f32_16x16x32_bf16 v[116:119], v[132:135], v[186:189], v[116:119]
	v_mfma_f32_16x16x32_bf16 v[108:111], v[150:153], v[186:189], v[108:111]
	v_mfma_f32_16x16x32_bf16 v[100:103], v[132:135], v[194:197], v[100:103]
	v_mfma_f32_16x16x32_bf16 v[92:95], v[150:153], v[194:197], v[92:95]
	v_mfma_f32_16x16x32_bf16 v[84:87], v[132:135], v[218:221], v[84:87]
	v_mfma_f32_16x16x32_bf16 v[76:79], v[150:153], v[218:221], v[76:79]
	s_setprio 0
	s_barrier
	s_add_i32 s22, 0, 0x1c000
	s_add_i32 s23, s45, s29
	v_add_u32_e32 v146, s22, v149
	v_lshl_add_u64 v[154:155], v[154:155], 0, s[2:3]
	s_mov_b32 m0, s23
	ds_read_b128 v[222:225], v146
	ds_read_b128 v[226:229], v146 offset:1024
	ds_read_b128 v[230:233], v146 offset:2048
	ds_read_b128 v[234:237], v146 offset:3072
	global_load_lds_dwordx4 v[154:155], off
	v_lshl_add_u64 v[154:155], v[238:239], 0, s[2:3]
	s_add_i32 m0, s23, 0x2000
	s_nop 0
	global_load_lds_dwordx4 v[154:155], off
	s_waitcnt vmcnt(10)
	s_barrier
	s_waitcnt lgkmcnt(0)
	s_setprio 1
	v_mfma_f32_16x16x32_bf16 v[112:115], v[222:225], v[174:177], v[112:115]
	v_mfma_f32_16x16x32_bf16 v[104:107], v[230:233], v[174:177], v[104:107]
	v_mfma_f32_16x16x32_bf16 v[96:99], v[222:225], v[182:185], v[96:99]
	v_mfma_f32_16x16x32_bf16 v[88:91], v[230:233], v[182:185], v[88:91]
	v_mfma_f32_16x16x32_bf16 v[80:83], v[222:225], v[190:193], v[80:83]
	v_mfma_f32_16x16x32_bf16 v[72:75], v[230:233], v[190:193], v[72:75]
	v_mfma_f32_16x16x32_bf16 v[68:71], v[222:225], v[214:217], v[68:71]
	v_mfma_f32_16x16x32_bf16 v[64:67], v[230:233], v[214:217], v[64:67]
	v_mfma_f32_16x16x32_bf16 v[112:115], v[226:229], v[178:181], v[112:115]
	v_mfma_f32_16x16x32_bf16 v[104:107], v[234:237], v[178:181], v[104:107]
	v_mfma_f32_16x16x32_bf16 v[96:99], v[226:229], v[186:189], v[96:99]
	v_mfma_f32_16x16x32_bf16 v[88:91], v[234:237], v[186:189], v[88:91]
	v_mfma_f32_16x16x32_bf16 v[80:83], v[226:229], v[194:197], v[80:83]
	v_mfma_f32_16x16x32_bf16 v[72:75], v[234:237], v[194:197], v[72:75]
	v_mfma_f32_16x16x32_bf16 v[68:71], v[226:229], v[218:221], v[68:71]
	v_mfma_f32_16x16x32_bf16 v[64:67], v[234:237], v[218:221], v[64:67]
	s_setprio 0
	s_mov_b32 m0, s37
	v_lshl_add_u64 v[154:155], v[240:241], 0, s[2:3]
	s_barrier
	ds_read_b128 v[174:177], v159 offset:49152
	ds_read_b128 v[178:181], v159 offset:50176
	ds_read_b128 v[182:185], v159 offset:51200
	ds_read_b128 v[186:189], v159 offset:52224
	ds_read_b128 v[190:193], v159 offset:53248
	ds_read_b128 v[194:197], v159 offset:54272
	ds_read_b128 v[214:217], v159 offset:55296
	ds_read_b128 v[218:221], v159 offset:56320
	global_load_lds_dwordx4 v[154:155], off
	v_lshl_add_u64 v[154:155], v[242:243], 0, s[2:3]
	s_mov_b32 m0, s38
	s_nop 0
	global_load_lds_dwordx4 v[154:155], off
	s_barrier
; #define PG8_STAGE(bufoff, gbase, voff) do { _Pragma("unroll") for (int _i = 0; _i < 2; ++_i) \
;         __builtin_amdgcn_global_load_lds((const unsigned*)((const char*)(gbase) + (voff)[_i]), (LAS unsigned*)(lds + (bufoff) + ldsw + _i * 8192), 16, 0, 0); } while (0)
; #define PG8_MMA(ai, bj, At, Bt) do { __builtin_amdgcn_s_setprio(1); _Pragma("unroll") for (int m = 0; m < 4; ++m) _Pragma("unroll") for (int n = 0; n < 2; ++n) _Pragma("unroll") for (int k = 0; k < 2; ++k) \
;         acc[ai][bj][m][n] = __builtin_amdgcn_mfma_f32_16x16x32_bf16(Bt[n][k], At[m][k], acc[ai][bj][m][n], 0, 0, 0); __builtin_amdgcn_s_setprio(0); } while (0)
; #define PG8_WAIT_V(n) asm volatile("s_waitcnt vmcnt(" #n ")" ::: "memory")
; #define PG8_WAIT_L(n) asm volatile("s_waitcnt lgkmcnt(" #n ")" ::: "memory")
; #define PG8_BAR __builtin_amdgcn_s_barrier()
; #define PG8_SCHED __builtin_amdgcn_sched_barrier(0)
; template <class Epi>
; DEV void gemm_phase(LAS unsigned char* lds, const Gemm g, const StaticOrder& S, const Epi& E) {
;     ...
;             PG8_BAR; PG8_WAIT_L(0); PG8_MMA(1, 0, At, B0); PG8_BAR; PG8_SCHED;
;             PG8_STAGE(PG8_SB(1, 1), b3 + hstep, voffB);
;             PG8_WAIT_V(6); PG8_BAR; PG8_MMA(1, 1, At, B1); PG8_BAR;
; DEV float rowscale(const float* ss, int row) { const f32x4 a = *(const f32x4*)(ss + (size_t)row * 8), b = *(const f32x4*)(ss + (size_t)row * 8 + 4);
;     return rsqrtf(((a[0] + a[1]) + (a[2] + a[3]) + (b[0] + b[1]) + (b[2] + b[3])) * (1.0f / 2048.0f) + EPS); }
; template <int ACT, bool PERM>
; DEV void store_bf16_tile(AccRef acc, u16* O, int ld, int row0, int col0, const float* ss) {
;     float rsv[2][4];
; #pragma unroll
;     for (int ai = 0; ai < 2; ++ai)
; #pragma unroll
;         for (int m = 0; m < 4; ++m) rsv[ai][m] = ss ? rowscale(ss, row0 + ai * 128 + m * 16) : 1.0f;
	s_waitcnt lgkmcnt(0)
	s_setprio 1
	v_mfma_f32_16x16x32_bf16 v[60:63], v[128:131], v[174:177], v[60:63]
	v_mfma_f32_16x16x32_bf16 v[56:59], v[142:145], v[174:177], v[56:59]
	v_mfma_f32_16x16x32_bf16 v[52:55], v[128:131], v[182:185], v[52:55]
	v_mfma_f32_16x16x32_bf16 v[44:47], v[142:145], v[182:185], v[44:47]
	v_mfma_f32_16x16x32_bf16 v[36:39], v[128:131], v[190:193], v[36:39]
	v_mfma_f32_16x16x32_bf16 v[28:31], v[142:145], v[190:193], v[28:31]
	v_mfma_f32_16x16x32_bf16 v[20:23], v[128:131], v[214:217], v[20:23]
	v_mfma_f32_16x16x32_bf16 v[12:15], v[142:145], v[214:217], v[12:15]
	v_mfma_f32_16x16x32_bf16 v[60:63], v[132:135], v[178:181], v[60:63]
	v_mfma_f32_16x16x32_bf16 v[56:59], v[150:153], v[178:181], v[56:59]
	v_mfma_f32_16x16x32_bf16 v[52:55], v[132:135], v[186:189], v[52:55]
	v_mfma_f32_16x16x32_bf16 v[44:47], v[150:153], v[186:189], v[44:47]
	v_mfma_f32_16x16x32_bf16 v[36:39], v[132:135], v[194:197], v[36:39]
	v_mfma_f32_16x16x32_bf16 v[28:31], v[150:153], v[194:197], v[28:31]
	v_mfma_f32_16x16x32_bf16 v[20:23], v[132:135], v[218:221], v[20:23]
	v_mfma_f32_16x16x32_bf16 v[12:15], v[150:153], v[218:221], v[12:15]
	s_setprio 0
	s_barrier
	s_add_u32 s20, s20, 0x80080
	s_addc_u32 s21, s21, 0
	s_add_i32 s22, s22, s29
	v_lshl_add_u64 v[128:129], s[20:21], 0, v[160:161]
	s_mov_b32 m0, s22
	s_nop 0
	global_load_lds_dwordx4 v[128:129], off
	v_lshl_add_u64 v[128:129], s[20:21], 0, v[136:137]
	s_add_i32 m0, s22, 0x2000
	s_nop 0
	global_load_lds_dwordx4 v[128:129], off
	s_waitcnt vmcnt(10)
	s_barrier
	s_setprio 1
	v_mfma_f32_16x16x32_bf16 v[48:51], v[222:225], v[174:177], v[48:51]
	v_mfma_f32_16x16x32_bf16 v[40:43], v[230:233], v[174:177], v[40:43]
	v_mfma_f32_16x16x32_bf16 v[32:35], v[222:225], v[182:185], v[32:35]
	v_mfma_f32_16x16x32_bf16 v[24:27], v[230:233], v[182:185], v[24:27]
	v_mfma_f32_16x16x32_bf16 v[16:19], v[222:225], v[190:193], v[16:19]
	v_mfma_f32_16x16x32_bf16 v[8:11], v[230:233], v[190:193], v[8:11]
	v_mfma_f32_16x16x32_bf16 v[4:7], v[222:225], v[214:217], v[4:7]
	v_mfma_f32_16x16x32_bf16 v[0:3], v[230:233], v[214:217], v[0:3]
	v_mfma_f32_16x16x32_bf16 v[48:51], v[226:229], v[178:181], v[48:51]
	v_mfma_f32_16x16x32_bf16 v[40:43], v[234:237], v[178:181], v[40:43]
	v_mfma_f32_16x16x32_bf16 v[32:35], v[226:229], v[186:189], v[32:35]
	v_mfma_f32_16x16x32_bf16 v[24:27], v[234:237], v[186:189], v[24:27]
	v_mfma_f32_16x16x32_bf16 v[16:19], v[226:229], v[194:197], v[16:19]
	v_mfma_f32_16x16x32_bf16 v[8:11], v[234:237], v[194:197], v[8:11]
	v_mfma_f32_16x16x32_bf16 v[4:7], v[226:229], v[218:221], v[4:7]
	v_mfma_f32_16x16x32_bf16 v[0:3], v[234:237], v[218:221], v[0:3]
	s_setprio 0
	s_add_i32 s44, s44, 2
	s_add_u32 s18, s18, 0x100
	s_addc_u32 s19, s19, 0
	s_add_u32 s42, s42, 0x100
	s_addc_u32 s43, s43, 0
	s_cmp_gt_u32 s44, 29
	s_barrier
	s_cbranch_scc0 .LBB0_344
	v_lshl_add_u32 v142, s0, 8, v147
	v_ashrrev_i32_e32 v143, 31, v142
	v_lshlrev_b64 v[128:129], 5, v[142:143]
	v_lshl_add_u64 v[132:133], s[4:5], 0, v[128:129]
	global_load_dwordx4 v[128:131], v[132:133], off offset:16
	s_nop 0
	global_load_dwordx4 v[132:135], v[132:133], off
	s_mov_b32 s0, 0x3727c5ac
	s_mov_b32 s18, 0x3a000000
	s_mov_b32 s11, 0x800000
	s_mov_b64 s[20:21], s[16:17]
	s_waitcnt vmcnt(0)
	v_mov_b32_e32 v144, v133
	v_mov_b32_e32 v145, v134
	v_mov_b32_e32 v133, v135
	v_pk_add_f32 v[150:151], v[144:145], v[132:133]
	v_or_b32_e32 v144, 16, v142
	v_mov_b32_e32 v132, v130
	v_mov_b32_e32 v133, v128
	v_mov_b32_e32 v128, v131
	v_ashrrev_i32_e32 v145, 31, v144
	v_pk_add_f32 v[152:153], v[132:133], v[128:129]
	v_lshlrev_b64 v[128:129], 5, v[144:145]
	v_lshl_add_u64 v[132:133], s[4:5], 0, v[128:129]
	global_load_dwordx4 v[128:131], v[132:133], off offset:16
	s_nop 0
	global_load_dwordx4 v[132:135], v[132:133], off
	s_waitcnt vmcnt(0)
	v_mov_b32_e32 v154, v133
	v_mov_b32_e32 v155, v134
	v_mov_b32_e32 v133, v135
	v_pk_add_f32 v[132:133], v[154:155], v[132:133]
	v_mov_b32_e32 v134, v130
	v_mov_b32_e32 v135, v128
	v_mov_b32_e32 v128, v131
	v_pk_add_f32 v[128:129], v[134:135], v[128:129]
	v_mov_b32_e32 v130, v132
	v_mov_b32_e32 v131, v150
	v_mov_b32_e32 v150, v133
	v_pk_add_f32 v[130:131], v[130:131], v[150:151]
	v_mov_b32_e32 v132, v129
	v_mov_b32_e32 v133, v153
	v_pk_add_f32 v[130:131], v[130:131], v[132:133]
	v_mov_b32_e32 v129, v152
	v_pk_add_f32 v[128:129], v[128:129], v[130:131]
	v_mov_b64_e32 v[150:151], s[0:1]
	v_pk_fma_f32 v[128:129], v[128:129], s[18:19], v[150:151] op_sel_hi:[1,0,0]
	v_or_b32_e32 v152, 32, v142
	v_mul_f32_e32 v130, 0x4b800000, v129
	v_cmp_gt_f32_e64 s[0:1], s11, v129
	v_cmp_gt_f32_e32 vcc, s11, v128
	v_ashrrev_i32_e32 v153, 31, v152
	v_cndmask_b32_e64 v129, v129, v130, s[0:1]
	v_rsq_f32_e32 v129, v129
	s_nop 0
	v_mul_f32_e32 v130, 0x45800000, v129
	v_cndmask_b32_e64 v148, v129, v130, s[0:1]
	v_mul_f32_e32 v129, 0x4b800000, v128
	v_cndmask_b32_e32 v128, v128, v129, vcc
	v_rsq_f32_e32 v128, v128
	v_pk_mul_f32 v[106:107], v[106:107], v[148:149] op_sel_hi:[1,0]
	v_pk_mul_f32 v[104:105], v[104:105], v[148:149] op_sel_hi:[1,0]
	v_pk_mul_f32 v[114:115], v[114:115], v[148:149] op_sel_hi:[1,0]
	v_mul_f32_e32 v129, 0x45800000, v128
	v_cndmask_b32_e32 v146, v128, v129, vcc
	v_lshlrev_b64 v[128:129], 5, v[152:153]
	v_lshl_add_u64 v[132:133], s[4:5], 0, v[128:129]
	global_load_dwordx4 v[128:131], v[132:133], off offset:16
	s_nop 0
	global_load_dwordx4 v[132:135], v[132:133], off
	v_cvt_pk_bf16_f32 v104, v104, v105
	v_cvt_pk_bf16_f32 v105, v106, v107
	v_pk_mul_f32 v[90:91], v[90:91], v[146:147] op_sel_hi:[1,0]
	v_pk_mul_f32 v[88:89], v[88:89], v[146:147] op_sel_hi:[1,0]
	v_pk_mul_f32 v[112:113], v[112:113], v[148:149] op_sel_hi:[1,0]
	v_cvt_pk_bf16_f32 v88, v88, v89
	v_cvt_pk_bf16_f32 v89, v90, v91
	v_pk_mul_f32 v[98:99], v[98:99], v[146:147] op_sel_hi:[1,0]
	v_pk_mul_f32 v[96:97], v[96:97], v[146:147] op_sel_hi:[1,0]
	v_cvt_pk_bf16_f32 v112, v112, v113
	v_cvt_pk_bf16_f32 v113, v114, v115
	v_cvt_pk_bf16_f32 v96, v96, v97
	v_cvt_pk_bf16_f32 v97, v98, v99
	v_pk_mul_f32 v[126:127], v[126:127], v[148:149] op_sel_hi:[1,0]
	v_pk_mul_f32 v[124:125], v[124:125], v[148:149] op_sel_hi:[1,0]
	v_pk_mul_f32 v[122:123], v[122:123], v[148:149] op_sel_hi:[1,0]
	v_pk_mul_f32 v[120:121], v[120:121], v[148:149] op_sel_hi:[1,0]
	v_pk_mul_f32 v[106:107], v[118:119], v[146:147] op_sel_hi:[1,0]
	v_pk_mul_f32 v[110:111], v[110:111], v[146:147] op_sel_hi:[1,0]
	v_pk_mul_f32 v[108:109], v[108:109], v[146:147] op_sel_hi:[1,0]
	v_cvt_pk_bf16_f32 v124, v124, v125
	v_cvt_pk_bf16_f32 v125, v126, v127
	v_cvt_pk_bf16_f32 v120, v120, v121
	v_cvt_pk_bf16_f32 v121, v122, v123
	s_waitcnt vmcnt(0)
; DEV bf16x8 pack8(f32x4 a, f32x4 b) { u32x4 w; w.x = cvt_pk_bf16(a[0], a[1]); w.y = cvt_pk_bf16(a[2], a[3]); w.z = cvt_pk_bf16(b[0], b[1]); w.w = cvt_pk_bf16(b[2], b[3]); return __builtin_bit_cast(bf16x8, w); }
; DEV u32x2 pack4(f32x4 a) { u32x2 w; w.x = cvt_pk_bf16(a[0], a[1]); w.y = cvt_pk_bf16(a[2], a[3]); return w; }
; DEV f32x4 gelu4(f32x4 v) { f32x2 a = gelu_pk((f32x2){v[0], v[1]}), b = gelu_pk((f32x2){v[2], v[3]}); return (f32x4){a.x, a.y, b.x, b.y}; }
; DEV float rowscale(const float* ss, int row) { const f32x4 a = *(const f32x4*)(ss + (size_t)row * 8), b = *(const f32x4*)(ss + (size_t)row * 8 + 4);
;     return rsqrtf(((a[0] + a[1]) + (a[2] + a[3]) + (b[0] + b[1]) + (b[2] + b[3])) * (1.0f / 2048.0f) + EPS); }
; template <int ACT, bool PERM>
; DEV void store_bf16_tile(AccRef acc, u16* O, int ld, int row0, int col0, const float* ss) {
;     float rsv[2][4];
; #pragma unroll
;     for (int ai = 0; ai < 2; ++ai)
; #pragma unroll
;         for (int m = 0; m < 4; ++m) rsv[ai][m] = ss ? rowscale(ss, row0 + ai * 128 + m * 16) : 1.0f;
; #pragma unroll
;     for (int ai = 0; ai < 2; ++ai)
; #pragma unroll
;         for (int m = 0; m < 4; ++m) { u16* rowp = O + (size_t)(row0 + ai * 128 + m * 16) * ld + col0; const float rs = rsv[ai][m];
; #pragma unroll
;             for (int bj = 0; bj < 2; ++bj) { f32x4 v0 = acc[ai][bj][m][0] * rs, v1 = acc[ai][bj][m][1] * rs; if (ACT == 1) { v0 = gelu4(v0); v1 = gelu4(v1); }
;                 if (PERM) *(u32x4*)(rowp + bj * 128) = __builtin_bit_cast(u32x4, pack8(v0, v1));
;                 else { *(u32x2*)(rowp + bj * 128) = pack4(v0); *(u32x2*)(rowp + bj * 128 + 16) = pack4(v1); } } }
	v_mov_b32_e32 v154, v133
	v_mov_b32_e32 v155, v134
	v_mov_b32_e32 v133, v135
	v_pk_add_f32 v[174:175], v[154:155], v[132:133]
	v_or_b32_e32 v154, 48, v142
	v_mov_b32_e32 v132, v130
	v_mov_b32_e32 v133, v128
	v_mov_b32_e32 v128, v131
	v_ashrrev_i32_e32 v155, 31, v154
	v_pk_add_f32 v[176:177], v[132:133], v[128:129]
	v_lshlrev_b64 v[128:129], 5, v[154:155]
	v_lshl_add_u64 v[132:133], s[4:5], 0, v[128:129]
	global_load_dwordx4 v[128:131], v[132:133], off offset:16
	s_nop 0
	global_load_dwordx4 v[132:135], v[132:133], off
	s_waitcnt vmcnt(0)
	v_mov_b32_e32 v178, v133
	v_mov_b32_e32 v179, v134
	v_mov_b32_e32 v133, v135
	v_pk_add_f32 v[132:133], v[178:179], v[132:133]
	v_mov_b32_e32 v134, v130
	v_mov_b32_e32 v135, v128
	v_mov_b32_e32 v128, v131
	v_pk_add_f32 v[128:129], v[134:135], v[128:129]
	v_mov_b32_e32 v130, v132
	v_mov_b32_e32 v131, v174
	v_mov_b32_e32 v174, v133
	v_pk_add_f32 v[130:131], v[130:131], v[174:175]
	v_mov_b32_e32 v132, v129
	v_mov_b32_e32 v133, v177
	v_pk_add_f32 v[130:131], v[130:131], v[132:133]
	v_mov_b32_e32 v129, v176
	v_pk_add_f32 v[128:129], v[128:129], v[130:131]
	v_add_u32_e32 v174, 0x80, v142
	v_pk_fma_f32 v[128:129], v[128:129], s[18:19], v[150:151] op_sel_hi:[1,0,0]
	v_ashrrev_i32_e32 v175, 31, v174
	v_mul_f32_e32 v130, 0x4b800000, v129
	v_cmp_gt_f32_e64 s[0:1], s11, v129
	v_cmp_gt_f32_e32 vcc, s11, v128
	s_nop 0
	v_cndmask_b32_e64 v129, v129, v130, s[0:1]
	v_rsq_f32_e32 v129, v129
	s_nop 0
	v_mul_f32_e32 v130, 0x45800000, v129
	v_cndmask_b32_e64 v158, v129, v130, s[0:1]
	v_mul_f32_e32 v129, 0x4b800000, v128
	v_cndmask_b32_e32 v128, v128, v129, vcc
	v_rsq_f32_e32 v128, v128
	v_pk_mul_f32 v[74:75], v[74:75], v[158:159] op_sel_hi:[1,0]
	v_pk_mul_f32 v[72:73], v[72:73], v[158:159] op_sel_hi:[1,0]
	v_pk_mul_f32 v[82:83], v[82:83], v[158:159] op_sel_hi:[1,0]
	v_mul_f32_e32 v129, 0x45800000, v128
	v_cndmask_b32_e32 v156, v128, v129, vcc
	v_lshlrev_b64 v[128:129], 5, v[174:175]
	v_lshl_add_u64 v[132:133], s[4:5], 0, v[128:129]
	global_load_dwordx4 v[128:131], v[132:133], off offset:16
	s_nop 0
	global_load_dwordx4 v[132:135], v[132:133], off
	v_cvt_pk_bf16_f32 v72, v72, v73
	v_cvt_pk_bf16_f32 v73, v74, v75
	v_pk_mul_f32 v[66:67], v[66:67], v[156:157] op_sel_hi:[1,0]
	v_pk_mul_f32 v[64:65], v[64:65], v[156:157] op_sel_hi:[1,0]
	v_pk_mul_f32 v[80:81], v[80:81], v[158:159] op_sel_hi:[1,0]
	v_cvt_pk_bf16_f32 v64, v64, v65
	v_cvt_pk_bf16_f32 v65, v66, v67
	v_cvt_pk_bf16_f32 v80, v80, v81
	v_cvt_pk_bf16_f32 v81, v82, v83
	v_pk_mul_f32 v[90:91], v[102:103], v[158:159] op_sel_hi:[1,0]
	v_pk_mul_f32 v[94:95], v[94:95], v[158:159] op_sel_hi:[1,0]
	v_pk_mul_f32 v[92:93], v[92:93], v[158:159] op_sel_hi:[1,0]
	v_pk_mul_f32 v[74:75], v[86:87], v[156:157] op_sel_hi:[1,0]
	v_pk_mul_f32 v[78:79], v[78:79], v[156:157] op_sel_hi:[1,0]
	v_pk_mul_f32 v[76:77], v[76:77], v[156:157] op_sel_hi:[1,0]
	v_pk_mul_f32 v[70:71], v[70:71], v[156:157] op_sel_hi:[1,0]
	v_pk_mul_f32 v[68:69], v[68:69], v[156:157] op_sel_hi:[1,0]
	s_waitcnt vmcnt(0)
	v_mov_b32_e32 v176, v133
	v_mov_b32_e32 v177, v134
	v_mov_b32_e32 v133, v135
	v_pk_add_f32 v[178:179], v[176:177], v[132:133]
	v_add_u32_e32 v176, 0x90, v142
	v_mov_b32_e32 v132, v130
	v_mov_b32_e32 v133, v128
	v_mov_b32_e32 v128, v131
	v_ashrrev_i32_e32 v177, 31, v176
	v_pk_add_f32 v[180:181], v[132:133], v[128:129]
	v_lshlrev_b64 v[128:129], 5, v[176:177]
	v_lshl_add_u64 v[132:133], s[4:5], 0, v[128:129]
	global_load_dwordx4 v[128:131], v[132:133], off offset:16
	s_nop 0
	global_load_dwordx4 v[132:135], v[132:133], off
	v_cvt_pk_bf16_f32 v68, v68, v69
	v_cvt_pk_bf16_f32 v69, v70, v71
	s_waitcnt vmcnt(0)
	v_mov_b32_e32 v182, v133
	v_mov_b32_e32 v183, v134
	v_mov_b32_e32 v133, v135
	v_pk_add_f32 v[132:133], v[182:183], v[132:133]
	v_mov_b32_e32 v134, v130
	v_mov_b32_e32 v135, v128
	v_mov_b32_e32 v128, v131
	v_pk_add_f32 v[128:129], v[134:135], v[128:129]
	v_mov_b32_e32 v130, v132
	v_mov_b32_e32 v131, v178
	v_mov_b32_e32 v178, v133
	v_pk_add_f32 v[130:131], v[130:131], v[178:179]
	v_mov_b32_e32 v132, v129
	v_mov_b32_e32 v133, v181
	v_pk_add_f32 v[130:131], v[130:131], v[132:133]
	v_mov_b32_e32 v129, v180
	v_pk_add_f32 v[128:129], v[128:129], v[130:131]
	v_add_u32_e32 v182, 0xa0, v142
	v_pk_fma_f32 v[128:129], v[128:129], s[18:19], v[150:151] op_sel_hi:[1,0,0]
	v_ashrrev_i32_e32 v183, 31, v182
	v_mul_f32_e32 v130, 0x4b800000, v129
	v_cmp_gt_f32_e64 s[0:1], s11, v129
	v_cmp_gt_f32_e32 vcc, s11, v128
	s_nop 0
	v_cndmask_b32_e64 v129, v129, v130, s[0:1]
	v_rsq_f32_e32 v129, v129
	s_nop 0
	v_mul_f32_e32 v130, 0x45800000, v129
	v_cndmask_b32_e64 v180, v129, v130, s[0:1]
	v_mul_f32_e32 v129, 0x4b800000, v128
	v_cndmask_b32_e32 v128, v128, v129, vcc
	v_rsq_f32_e32 v128, v128
	v_pk_mul_f32 v[42:43], v[42:43], v[180:181] op_sel_hi:[1,0]
	v_pk_mul_f32 v[40:41], v[40:41], v[180:181] op_sel_hi:[1,0]
	v_pk_mul_f32 v[50:51], v[50:51], v[180:181] op_sel_hi:[1,0]
	v_mul_f32_e32 v129, 0x45800000, v128
	v_cndmask_b32_e32 v178, v128, v129, vcc
	v_lshlrev_b64 v[128:129], 5, v[182:183]
	v_lshl_add_u64 v[132:133], s[4:5], 0, v[128:129]
	global_load_dwordx4 v[128:131], v[132:133], off offset:16
	s_nop 0
	global_load_dwordx4 v[132:135], v[132:133], off
	v_cvt_pk_bf16_f32 v40, v40, v41
	v_cvt_pk_bf16_f32 v41, v42, v43
	v_pk_mul_f32 v[26:27], v[26:27], v[178:179] op_sel_hi:[1,0]
	v_pk_mul_f32 v[24:25], v[24:25], v[178:179] op_sel_hi:[1,0]
	v_pk_mul_f32 v[48:49], v[48:49], v[180:181] op_sel_hi:[1,0]
	v_cvt_pk_bf16_f32 v24, v24, v25
	v_cvt_pk_bf16_f32 v25, v26, v27
	v_pk_mul_f32 v[34:35], v[34:35], v[178:179] op_sel_hi:[1,0]
	v_pk_mul_f32 v[32:33], v[32:33], v[178:179] op_sel_hi:[1,0]
	v_cvt_pk_bf16_f32 v48, v48, v49
	v_cvt_pk_bf16_f32 v49, v50, v51
	v_cvt_pk_bf16_f32 v32, v32, v33
	v_cvt_pk_bf16_f32 v33, v34, v35
	v_pk_mul_f32 v[62:63], v[62:63], v[180:181] op_sel_hi:[1,0]
	v_pk_mul_f32 v[60:61], v[60:61], v[180:181] op_sel_hi:[1,0]
	v_pk_mul_f32 v[58:59], v[58:59], v[180:181] op_sel_hi:[1,0]
	v_pk_mul_f32 v[56:57], v[56:57], v[180:181] op_sel_hi:[1,0]
	v_pk_mul_f32 v[42:43], v[54:55], v[178:179] op_sel_hi:[1,0]
	v_pk_mul_f32 v[46:47], v[46:47], v[178:179] op_sel_hi:[1,0]
	v_pk_mul_f32 v[44:45], v[44:45], v[178:179] op_sel_hi:[1,0]
	v_cvt_pk_bf16_f32 v60, v60, v61
	v_cvt_pk_bf16_f32 v61, v62, v63
	v_cvt_pk_bf16_f32 v56, v56, v57
	v_cvt_pk_bf16_f32 v57, v58, v59
	s_waitcnt vmcnt(0)
; DEV bf16x8 pack8(f32x4 a, f32x4 b) { u32x4 w; w.x = cvt_pk_bf16(a[0], a[1]); w.y = cvt_pk_bf16(a[2], a[3]); w.z = cvt_pk_bf16(b[0], b[1]); w.w = cvt_pk_bf16(b[2], b[3]); return __builtin_bit_cast(bf16x8, w); }
; DEV u32x2 pack4(f32x4 a) { u32x2 w; w.x = cvt_pk_bf16(a[0], a[1]); w.y = cvt_pk_bf16(a[2], a[3]); return w; }
; DEV f32x4 gelu4(f32x4 v) { f32x2 a = gelu_pk((f32x2){v[0], v[1]}), b = gelu_pk((f32x2){v[2], v[3]}); return (f32x4){a.x, a.y, b.x, b.y}; }
; template <class Epi>
; DEV void gemm_phase(LAS unsigned char* lds, const Gemm g, const StaticOrder& S, const Epi& E) {
;     ...
;         E(acc, cur, wr, wc, fr, fq);
;         if (!has_next) break;
; template <int ACT, bool PERM>
; DEV void store_bf16_tile(AccRef acc, u16* O, int ld, int row0, int col0, const float* ss) {
;     float rsv[2][4];
; #pragma unroll
;     for (int ai = 0; ai < 2; ++ai)
; #pragma unroll
;         for (int m = 0; m < 4; ++m) rsv[ai][m] = ss ? rowscale(ss, row0 + ai * 128 + m * 16) : 1.0f;
; #pragma unroll
;     for (int ai = 0; ai < 2; ++ai)
; #pragma unroll
;         for (int m = 0; m < 4; ++m) { u16* rowp = O + (size_t)(row0 + ai * 128 + m * 16) * ld + col0; const float rs = rsv[ai][m];
; #pragma unroll
;             for (int bj = 0; bj < 2; ++bj) { f32x4 v0 = acc[ai][bj][m][0] * rs, v1 = acc[ai][bj][m][1] * rs; if (ACT == 1) { v0 = gelu4(v0); v1 = gelu4(v1); }
;                 if (PERM) *(u32x4*)(rowp + bj * 128) = __builtin_bit_cast(u32x4, pack8(v0, v1));
;                 else { *(u32x2*)(rowp + bj * 128) = pack4(v0); *(u32x2*)(rowp + bj * 128 + 16) = pack4(v1); } } }
	v_mov_b32_e32 v184, v133
	v_mov_b32_e32 v185, v134
	v_mov_b32_e32 v133, v135
	v_pk_add_f32 v[188:189], v[184:185], v[132:133]
	v_add_u32_e32 v184, 0xb0, v142
	v_mov_b32_e32 v132, v130
	v_mov_b32_e32 v133, v128
	v_mov_b32_e32 v128, v131
	v_ashrrev_i32_e32 v185, 31, v184
	v_pk_add_f32 v[186:187], v[132:133], v[128:129]
	v_lshlrev_b64 v[128:129], 5, v[184:185]
	v_lshl_add_u64 v[132:133], s[4:5], 0, v[128:129]
	global_load_dwordx4 v[128:131], v[132:133], off offset:16
	s_nop 0
	global_load_dwordx4 v[132:135], v[132:133], off
	s_waitcnt vmcnt(0)
	v_mov_b32_e32 v190, v133
	v_mov_b32_e32 v191, v134
	v_mov_b32_e32 v133, v135
	v_pk_add_f32 v[132:133], v[190:191], v[132:133]
	v_mov_b32_e32 v134, v130
	v_mov_b32_e32 v135, v128
	v_mov_b32_e32 v128, v131
	v_pk_add_f32 v[128:129], v[134:135], v[128:129]
	v_mov_b32_e32 v130, v132
	v_mov_b32_e32 v131, v188
	v_mov_b32_e32 v188, v133
	v_pk_add_f32 v[130:131], v[130:131], v[188:189]
	v_mov_b32_e32 v132, v129
	v_mov_b32_e32 v133, v187
	v_pk_add_f32 v[130:131], v[130:131], v[132:133]
	v_mov_b32_e32 v129, v186
	v_pk_add_f32 v[128:129], v[128:129], v[130:131]
	v_lshl_or_b32 v132, s40, 8, v157
	v_pk_fma_f32 v[128:129], v[128:129], s[18:19], v[150:151] op_sel_hi:[1,0,0]
	v_ashrrev_i32_e32 v133, 31, v132
	v_mul_f32_e32 v130, 0x4b800000, v129
	v_cmp_gt_f32_e64 s[0:1], s11, v129
	v_lshlrev_b64 v[134:135], 10, v[142:143]
	v_cmp_gt_f32_e32 vcc, s11, v128
	v_cndmask_b32_e64 v129, v129, v130, s[0:1]
	v_rsq_f32_e32 v129, v129
	s_mov_b32 s40, s10
	s_mov_b64 s[18:19], s[14:15]
	v_mul_f32_e32 v130, 0x45800000, v129
	v_cndmask_b32_e64 v130, v129, v130, s[0:1]
	v_readlane_b32 s0, v250, 11
	v_readlane_b32 s1, v250, 12
	v_mul_f32_e32 v129, 0x4b800000, v128
	v_cndmask_b32_e32 v128, v128, v129, vcc
	v_lshl_add_u64 v[132:133], v[132:133], 1, s[0:1]
	v_lshl_add_u64 v[134:135], v[132:133], 0, v[134:135]
	global_store_dwordx2 v[134:135], v[104:105], off offset:288
	v_lshlrev_b64 v[104:105], 10, v[144:145]
	v_lshl_add_u64 v[104:105], v[132:133], 0, v[104:105]
	global_store_dwordx2 v[104:105], v[88:89], off offset:288
	v_lshlrev_b64 v[88:89], 10, v[152:153]
	v_lshl_add_u64 v[88:89], v[132:133], 0, v[88:89]
	global_store_dwordx2 v[88:89], v[72:73], off offset:288
	v_lshlrev_b64 v[72:73], 10, v[154:155]
	v_lshl_add_u64 v[72:73], v[132:133], 0, v[72:73]
	v_rsq_f32_e32 v128, v128
	global_store_dwordx2 v[72:73], v[64:65], off offset:288
	v_lshlrev_b64 v[64:65], 10, v[174:175]
	v_lshl_add_u64 v[64:65], v[132:133], 0, v[64:65]
	global_store_dwordx2 v[64:65], v[40:41], off offset:288
	v_lshlrev_b64 v[40:41], 10, v[176:177]
	v_lshl_add_u64 v[40:41], v[132:133], 0, v[40:41]
	v_mul_f32_e32 v129, 0x45800000, v128
	global_store_dwordx2 v[40:41], v[24:25], off offset:288
	v_lshlrev_b64 v[24:25], 10, v[182:183]
	v_pk_mul_f32 v[18:19], v[18:19], v[130:131] op_sel_hi:[1,0]
	v_pk_mul_f32 v[16:17], v[16:17], v[130:131] op_sel_hi:[1,0]
	v_pk_mul_f32 v[10:11], v[10:11], v[130:131] op_sel_hi:[1,0]
	v_pk_mul_f32 v[8:9], v[8:9], v[130:131] op_sel_hi:[1,0]
	v_cndmask_b32_e32 v128, v128, v129, vcc
	v_lshl_add_u64 v[24:25], v[132:133], 0, v[24:25]
	v_cvt_pk_bf16_f32 v16, v16, v17
	v_cvt_pk_bf16_f32 v17, v18, v19
	v_cvt_pk_bf16_f32 v8, v8, v9
	v_cvt_pk_bf16_f32 v9, v10, v11
	global_store_dwordx2 v[134:135], v[112:113], off offset:256
	v_pk_mul_f32 v[112:113], v[116:117], v[146:147] op_sel_hi:[1,0]
	global_store_dwordx2 v[104:105], v[96:97], off offset:256
	v_pk_mul_f32 v[96:97], v[100:101], v[158:159] op_sel_hi:[1,0]
	global_store_dwordx2 v[88:89], v[80:81], off offset:256
	v_pk_mul_f32 v[80:81], v[84:85], v[156:157] op_sel_hi:[1,0]
	global_store_dwordx2 v[64:65], v[48:49], off offset:256
	v_pk_mul_f32 v[48:49], v[52:53], v[178:179] op_sel_hi:[1,0]
	global_store_dwordx2 v[40:41], v[32:33], off offset:256
	v_pk_mul_f32 v[26:27], v[38:39], v[130:131] op_sel_hi:[1,0]
	v_pk_mul_f32 v[32:33], v[36:37], v[130:131] op_sel_hi:[1,0]
	v_pk_mul_f32 v[30:31], v[30:31], v[130:131] op_sel_hi:[1,0]
	v_pk_mul_f32 v[28:29], v[28:29], v[130:131] op_sel_hi:[1,0]
	global_store_dwordx2 v[24:25], v[16:17], off offset:256
	global_store_dwordx2 v[24:25], v[8:9], off offset:288
	v_lshlrev_b64 v[8:9], 10, v[184:185]
	v_pk_mul_f32 v[10:11], v[22:23], v[128:129] op_sel_hi:[1,0]
	v_pk_mul_f32 v[16:17], v[20:21], v[128:129] op_sel_hi:[1,0]
	v_pk_mul_f32 v[14:15], v[14:15], v[128:129] op_sel_hi:[1,0]
	v_pk_mul_f32 v[12:13], v[12:13], v[128:129] op_sel_hi:[1,0]
	v_pk_mul_f32 v[6:7], v[6:7], v[128:129] op_sel_hi:[1,0]
	v_pk_mul_f32 v[4:5], v[4:5], v[128:129] op_sel_hi:[1,0]
	v_pk_mul_f32 v[2:3], v[2:3], v[128:129] op_sel_hi:[1,0]
	v_pk_mul_f32 v[0:1], v[0:1], v[128:129] op_sel_hi:[1,0]
	v_cvt_pk_bf16_f32 v112, v112, v113
	v_cvt_pk_bf16_f32 v113, v106, v107
	v_cvt_pk_bf16_f32 v106, v108, v109
	v_cvt_pk_bf16_f32 v107, v110, v111
	v_cvt_pk_bf16_f32 v96, v96, v97
	v_cvt_pk_bf16_f32 v97, v90, v91
	v_cvt_pk_bf16_f32 v90, v92, v93
	v_cvt_pk_bf16_f32 v91, v94, v95
	v_cvt_pk_bf16_f32 v80, v80, v81
	v_cvt_pk_bf16_f32 v81, v74, v75
	v_cvt_pk_bf16_f32 v74, v76, v77
	v_cvt_pk_bf16_f32 v75, v78, v79
	v_cvt_pk_bf16_f32 v48, v48, v49
	v_cvt_pk_bf16_f32 v49, v42, v43
	v_cvt_pk_bf16_f32 v42, v44, v45
	v_cvt_pk_bf16_f32 v43, v46, v47
	v_cvt_pk_bf16_f32 v32, v32, v33
	v_cvt_pk_bf16_f32 v33, v26, v27
	v_cvt_pk_bf16_f32 v26, v28, v29
	v_cvt_pk_bf16_f32 v27, v30, v31
	v_lshl_add_u64 v[8:9], v[132:133], 0, v[8:9]
	v_cvt_pk_bf16_f32 v16, v16, v17
	v_cvt_pk_bf16_f32 v17, v10, v11
	v_cvt_pk_bf16_f32 v10, v12, v13
	v_cvt_pk_bf16_f32 v11, v14, v15
	v_cvt_pk_bf16_f32 v4, v4, v5
	v_cvt_pk_bf16_f32 v5, v6, v7
	v_cvt_pk_bf16_f32 v0, v0, v1
	v_cvt_pk_bf16_f32 v1, v2, v3
	s_and_b64 vcc, exec, s[6:7]
	s_mov_b32 s0, s12
	global_store_dwordx2 v[134:135], v[124:125], off
	global_store_dwordx2 v[134:135], v[120:121], off offset:32
	global_store_dwordx2 v[104:105], v[112:113], off
	global_store_dwordx2 v[104:105], v[106:107], off offset:32
	global_store_dwordx2 v[88:89], v[96:97], off
	global_store_dwordx2 v[88:89], v[90:91], off offset:32
	global_store_dwordx2 v[72:73], v[80:81], off
	global_store_dwordx2 v[72:73], v[74:75], off offset:32
	global_store_dwordx2 v[72:73], v[68:69], off offset:256
	global_store_dwordx2 v[64:65], v[60:61], off
	global_store_dwordx2 v[64:65], v[56:57], off offset:32
	global_store_dwordx2 v[40:41], v[48:49], off
	global_store_dwordx2 v[40:41], v[42:43], off offset:32
	global_store_dwordx2 v[24:25], v[32:33], off
	global_store_dwordx2 v[24:25], v[26:27], off offset:32
	global_store_dwordx2 v[8:9], v[16:17], off
	global_store_dwordx2 v[8:9], v[10:11], off offset:32
	global_store_dwordx2 v[8:9], v[4:5], off offset:256
	global_store_dwordx2 v[8:9], v[0:1], off offset:288
	s_cbranch_vccz .LBB0_337
	s_waitcnt vmcnt(0)
	s_cmpk_gt_u32 s25, 0xff
	s_cbranch_scc1 .LBB0_348
	s_barrier

; #define PG8_STAGE(bufoff, gbase, voff) do { _Pragma("unroll") for (int _i = 0; _i < 2; ++_i) \
;         __builtin_amdgcn_global_load_lds((const unsigned*)((const char*)(gbase) + (voff)[_i]), (LAS unsigned*)(lds + (bufoff) + ldsw + _i * 8192), 16, 0, 0); } while (0)
; #define PG8_LDA(dst, b, h) do { _Pragma("unroll") for (int m = 0; m < 4; ++m) _Pragma("unroll") for (int k = 0; k < 2; ++k) dst[m][k] = *(const LAS bf16x8*)(lds + PG8_SA(b, h) + aoff + m * 2048 + k * 1024); } while (0)
; #define PG8_LDB(dst, b, h) do { _Pragma("unroll") for (int n = 0; n < 2; ++n) _Pragma("unroll") for (int k = 0; k < 2; ++k) dst[n][k] = *(const LAS bf16x8*)(lds + PG8_SB(b, h) + boff + n * 2048 + k * 1024); } while (0)
; #define PG8_MMA(ai, bj, At, Bt) do { __builtin_amdgcn_s_setprio(1); _Pragma("unroll") for (int m = 0; m < 4; ++m) _Pragma("unroll") for (int n = 0; n < 2; ++n) _Pragma("unroll") for (int k = 0; k < 2; ++k) \
;         acc[ai][bj][m][n] = __builtin_amdgcn_mfma_f32_16x16x32_bf16(Bt[n][k], At[m][k], acc[ai][bj][m][n], 0, 0, 0); __builtin_amdgcn_s_setprio(0); } while (0)
; #define PG8_WAIT_L(n) asm volatile("s_waitcnt lgkmcnt(" #n ")" ::: "memory")
; #define PG8_BAR __builtin_amdgcn_s_barrier()
; #define PG8_SCHED __builtin_amdgcn_sched_barrier(0)
; template <class Epi>
; DEV void gemm_phase(LAS unsigned char* lds, const Gemm g, const StaticOrder& S, const Epi& E) {
;     ...
;             const bool last = (t == nt - 2);
;             const char* a1 = cA + (size_t)(t + 1) * kstep;
;             const char* a2 = last ? nA : cA + (size_t)(t + 2) * kstep; const char* b2 = last ? nB : cB + (size_t)(t + 2) * kstep;
;             const char* a3 = a2 + kstep; const char* b3 = b2 + kstep;
;             PG8_LDB(B0, 0, 0); PG8_SCHED; PG8_LDA(At, 0, 0); PG8_STAGE(PG8_SA(1, 1), a1 + hstep, voffA);
;             PG8_WAIT_L(8); PG8_BAR; PG8_WAIT_L(0); PG8_MMA(0, 0, At, B0); PG8_BAR; PG8_SCHED;
;             PG8_LDB(B1, 0, 1); PG8_STAGE(PG8_SB(0, 0), b2, voffB);
;             PG8_BAR; PG8_WAIT_L(0); PG8_MMA(0, 1, At, B1); PG8_BAR;
;             PG8_LDA(At, 0, 1); PG8_STAGE(PG8_SA(0, 0), a2, voffA);
;             PG8_BAR; PG8_WAIT_L(0); PG8_MMA(1, 0, At, B0); PG8_BAR; PG8_SCHED;
.LBB0_362:
	s_add_u32 s26, s24, 0xfff80080
	s_addc_u32 s27, s25, -1
	s_add_i32 s56, 0, 0x10000
	v_add_u32_e32 v150, s56, v135
	ds_read_b128 v[138:141], v150
	ds_read_b128 v[142:145], v150 offset:1024
	ds_read_b128 v[146:149], v150 offset:2048
	ds_read_b128 v[150:153], v150 offset:3072
	s_cmp_eq_u32 s55, 28
	s_cselect_b32 s29, s19, s27
	s_cselect_b32 s28, s51, s26
	s_cselect_b32 s27, s17, s54
	s_cselect_b32 s26, s52, s53
	v_lshl_add_u64 v[158:159], s[24:25], 0, v[130:131]
	s_add_i32 m0, s13, 0xc000
	ds_read_b128 v[154:157], v137
	ds_read_b128 v[174:177], v137 offset:1024
	ds_read_b128 v[178:181], v137 offset:2048
	ds_read_b128 v[182:185], v137 offset:3072
	ds_read_b128 v[186:189], v137 offset:4096
	ds_read_b128 v[190:193], v137 offset:5120
	ds_read_b128 v[194:197], v137 offset:6144
	ds_read_b128 v[214:217], v137 offset:7168
	global_load_lds_dwordx4 v[158:159], off
	v_lshl_add_u64 v[158:159], s[24:25], 0, v[132:133]
	s_add_i32 m0, s13, 0xe000
	s_nop 0
	global_load_lds_dwordx4 v[158:159], off
	s_waitcnt lgkmcnt(8)
	s_waitcnt vmcnt(10)
	s_barrier
	s_waitcnt lgkmcnt(0)
	s_setprio 1
	v_mfma_f32_16x16x32_bf16 v[124:127], v[138:141], v[154:157], v[124:127]
	v_mfma_f32_16x16x32_bf16 v[120:123], v[146:149], v[154:157], v[120:123]
	v_mfma_f32_16x16x32_bf16 v[116:119], v[138:141], v[178:181], v[116:119]
	v_mfma_f32_16x16x32_bf16 v[108:111], v[146:149], v[178:181], v[108:111]
	v_mfma_f32_16x16x32_bf16 v[100:103], v[138:141], v[186:189], v[100:103]
	v_mfma_f32_16x16x32_bf16 v[92:95], v[146:149], v[186:189], v[92:95]
	v_mfma_f32_16x16x32_bf16 v[84:87], v[138:141], v[194:197], v[84:87]
	v_mfma_f32_16x16x32_bf16 v[76:79], v[146:149], v[194:197], v[76:79]
	v_mfma_f32_16x16x32_bf16 v[124:127], v[142:145], v[174:177], v[124:127]
	v_mfma_f32_16x16x32_bf16 v[120:123], v[150:153], v[174:177], v[120:123]
	v_mfma_f32_16x16x32_bf16 v[116:119], v[142:145], v[182:185], v[116:119]
	v_mfma_f32_16x16x32_bf16 v[108:111], v[150:153], v[182:185], v[108:111]
	v_mfma_f32_16x16x32_bf16 v[100:103], v[142:145], v[190:193], v[100:103]
	v_mfma_f32_16x16x32_bf16 v[92:95], v[150:153], v[190:193], v[92:95]
	v_mfma_f32_16x16x32_bf16 v[84:87], v[142:145], v[214:217], v[84:87]
	v_mfma_f32_16x16x32_bf16 v[76:79], v[150:153], v[214:217], v[76:79]
	s_setprio 0
	s_barrier
	s_add_i32 s58, 0, 0x14000
	v_add_u32_e32 v158, s58, v135
	s_add_i32 s56, s56, s41
	ds_read_b128 v[218:221], v158
	ds_read_b128 v[222:225], v158 offset:1024
	ds_read_b128 v[226:229], v158 offset:2048
	ds_read_b128 v[230:233], v158 offset:3072
	v_lshl_add_u64 v[158:159], s[26:27], 0, v[160:161]
	s_mov_b32 m0, s56
	v_lshl_add_u64 v[234:235], s[26:27], 0, v[128:129]
	global_load_lds_dwordx4 v[158:159], off
	s_add_i32 m0, s56, 0x2000
	s_nop 0
	global_load_lds_dwordx4 v[234:235], off
	s_waitcnt vmcnt(10)
	s_barrier
	s_waitcnt lgkmcnt(0)
	s_setprio 1
	v_mfma_f32_16x16x32_bf16 v[112:115], v[218:221], v[154:157], v[112:115]
	v_mfma_f32_16x16x32_bf16 v[104:107], v[226:229], v[154:157], v[104:107]
	v_mfma_f32_16x16x32_bf16 v[96:99], v[218:221], v[178:181], v[96:99]
	v_mfma_f32_16x16x32_bf16 v[88:91], v[226:229], v[178:181], v[88:91]
	v_mfma_f32_16x16x32_bf16 v[80:83], v[218:221], v[186:189], v[80:83]
	v_mfma_f32_16x16x32_bf16 v[72:75], v[226:229], v[186:189], v[72:75]
	v_mfma_f32_16x16x32_bf16 v[68:71], v[218:221], v[194:197], v[68:71]
	v_mfma_f32_16x16x32_bf16 v[64:67], v[226:229], v[194:197], v[64:67]
	v_mfma_f32_16x16x32_bf16 v[112:115], v[222:225], v[174:177], v[112:115]
	v_mfma_f32_16x16x32_bf16 v[104:107], v[230:233], v[174:177], v[104:107]
	v_mfma_f32_16x16x32_bf16 v[96:99], v[222:225], v[182:185], v[96:99]
	v_mfma_f32_16x16x32_bf16 v[88:91], v[230:233], v[182:185], v[88:91]
	v_mfma_f32_16x16x32_bf16 v[80:83], v[222:225], v[190:193], v[80:83]
	v_mfma_f32_16x16x32_bf16 v[72:75], v[230:233], v[190:193], v[72:75]
	v_mfma_f32_16x16x32_bf16 v[68:71], v[222:225], v[214:217], v[68:71]
	v_mfma_f32_16x16x32_bf16 v[64:67], v[230:233], v[214:217], v[64:67]
	s_setprio 0
	s_mov_b32 m0, s13
	v_lshl_add_u64 v[236:237], s[28:29], 0, v[160:161]
	s_barrier
	ds_read_b128 v[154:157], v137 offset:16384
	ds_read_b128 v[174:177], v137 offset:17408
	ds_read_b128 v[178:181], v137 offset:18432
	ds_read_b128 v[182:185], v137 offset:19456
	ds_read_b128 v[186:189], v137 offset:20480
	ds_read_b128 v[190:193], v137 offset:21504
	ds_read_b128 v[194:197], v137 offset:22528
	ds_read_b128 v[214:217], v137 offset:23552
	global_load_lds_dwordx4 v[236:237], off
	v_lshl_add_u64 v[238:239], s[28:29], 0, v[128:129]
	s_mov_b32 m0, s43
	s_nop 0
	global_load_lds_dwordx4 v[238:239], off
	s_barrier
	s_waitcnt lgkmcnt(0)
	s_setprio 1
	v_mfma_f32_16x16x32_bf16 v[60:63], v[138:141], v[154:157], v[60:63]
	v_mfma_f32_16x16x32_bf16 v[56:59], v[146:149], v[154:157], v[56:59]
	v_mfma_f32_16x16x32_bf16 v[52:55], v[138:141], v[178:181], v[52:55]
	v_mfma_f32_16x16x32_bf16 v[44:47], v[146:149], v[178:181], v[44:47]
	v_mfma_f32_16x16x32_bf16 v[36:39], v[138:141], v[186:189], v[36:39]
	v_mfma_f32_16x16x32_bf16 v[28:31], v[146:149], v[186:189], v[28:31]
	v_mfma_f32_16x16x32_bf16 v[20:23], v[138:141], v[194:197], v[20:23]
	v_mfma_f32_16x16x32_bf16 v[12:15], v[146:149], v[194:197], v[12:15]
	v_mfma_f32_16x16x32_bf16 v[60:63], v[142:145], v[174:177], v[60:63]
	v_mfma_f32_16x16x32_bf16 v[56:59], v[150:153], v[174:177], v[56:59]
	v_mfma_f32_16x16x32_bf16 v[52:55], v[142:145], v[182:185], v[52:55]
	v_mfma_f32_16x16x32_bf16 v[44:47], v[150:153], v[182:185], v[44:47]
	v_mfma_f32_16x16x32_bf16 v[36:39], v[142:145], v[190:193], v[36:39]
	v_mfma_f32_16x16x32_bf16 v[28:31], v[150:153], v[190:193], v[28:31]
	v_mfma_f32_16x16x32_bf16 v[20:23], v[142:145], v[214:217], v[20:23]
	v_mfma_f32_16x16x32_bf16 v[12:15], v[150:153], v[214:217], v[12:15]
	s_setprio 0
	s_barrier
; #define PG8_STAGE(bufoff, gbase, voff) do { _Pragma("unroll") for (int _i = 0; _i < 2; ++_i) \
;         __builtin_amdgcn_global_load_lds((const unsigned*)((const char*)(gbase) + (voff)[_i]), (LAS unsigned*)(lds + (bufoff) + ldsw + _i * 8192), 16, 0, 0); } while (0)
; #define PG8_LDA(dst, b, h) do { _Pragma("unroll") for (int m = 0; m < 4; ++m) _Pragma("unroll") for (int k = 0; k < 2; ++k) dst[m][k] = *(const LAS bf16x8*)(lds + PG8_SA(b, h) + aoff + m * 2048 + k * 1024); } while (0)
; #define PG8_LDB(dst, b, h) do { _Pragma("unroll") for (int n = 0; n < 2; ++n) _Pragma("unroll") for (int k = 0; k < 2; ++k) dst[n][k] = *(const LAS bf16x8*)(lds + PG8_SB(b, h) + boff + n * 2048 + k * 1024); } while (0)
; #define PG8_MMA(ai, bj, At, Bt) do { __builtin_amdgcn_s_setprio(1); _Pragma("unroll") for (int m = 0; m < 4; ++m) _Pragma("unroll") for (int n = 0; n < 2; ++n) _Pragma("unroll") for (int k = 0; k < 2; ++k) \
;         acc[ai][bj][m][n] = __builtin_amdgcn_mfma_f32_16x16x32_bf16(Bt[n][k], At[m][k], acc[ai][bj][m][n], 0, 0, 0); __builtin_amdgcn_s_setprio(0); } while (0)
; #define PG8_WAIT_V(n) asm volatile("s_waitcnt vmcnt(" #n ")" ::: "memory")
; #define PG8_WAIT_L(n) asm volatile("s_waitcnt lgkmcnt(" #n ")" ::: "memory")
; #define PG8_BAR __builtin_amdgcn_s_barrier()
; #define PG8_SCHED __builtin_amdgcn_sched_barrier(0)
; template <class Epi>
; DEV void gemm_phase(LAS unsigned char* lds, const Gemm g, const StaticOrder& S, const Epi& E) {
;     ...
;             PG8_STAGE(PG8_SB(0, 1), b2 + hstep, voffB);
;             PG8_WAIT_V(6); PG8_BAR; PG8_MMA(1, 1, At, B1); PG8_BAR;
;             PG8_LDB(B0, 1, 0); PG8_SCHED; PG8_LDA(At, 1, 0); PG8_STAGE(PG8_SA(0, 1), a2 + hstep, voffA);
;             PG8_WAIT_L(8); PG8_BAR; PG8_WAIT_L(0); PG8_MMA(0, 0, At, B0); PG8_BAR; PG8_SCHED;
;             PG8_LDB(B1, 1, 1); PG8_STAGE(PG8_SB(1, 0), b3, voffB);
;             PG8_BAR; PG8_WAIT_L(0); PG8_MMA(0, 1, At, B1); PG8_BAR;
;             PG8_LDA(At, 1, 1); PG8_STAGE(PG8_SA(1, 0), a3, voffA);
	s_add_u32 s56, s26, 0x80000
	s_addc_u32 s57, s27, 0
	s_add_i32 s58, s58, s41
	v_lshl_add_u64 v[138:139], s[56:57], 0, v[160:161]
	s_mov_b32 m0, s58
	s_nop 0
	global_load_lds_dwordx4 v[138:139], off
	v_lshl_add_u64 v[138:139], s[56:57], 0, v[128:129]
	s_add_i32 m0, s58, 0x2000
	s_nop 0
	global_load_lds_dwordx4 v[138:139], off
	s_waitcnt vmcnt(10)
	s_barrier
	s_setprio 1
	v_mfma_f32_16x16x32_bf16 v[48:51], v[218:221], v[154:157], v[48:51]
	v_mfma_f32_16x16x32_bf16 v[40:43], v[226:229], v[154:157], v[40:43]
	v_mfma_f32_16x16x32_bf16 v[32:35], v[218:221], v[178:181], v[32:35]
	v_mfma_f32_16x16x32_bf16 v[24:27], v[226:229], v[178:181], v[24:27]
	v_mfma_f32_16x16x32_bf16 v[16:19], v[218:221], v[186:189], v[16:19]
	v_mfma_f32_16x16x32_bf16 v[8:11], v[226:229], v[186:189], v[8:11]
	v_mfma_f32_16x16x32_bf16 v[4:7], v[218:221], v[194:197], v[4:7]
	v_mfma_f32_16x16x32_bf16 v[0:3], v[226:229], v[194:197], v[0:3]
	v_mfma_f32_16x16x32_bf16 v[48:51], v[222:225], v[174:177], v[48:51]
	v_mfma_f32_16x16x32_bf16 v[40:43], v[230:233], v[174:177], v[40:43]
	v_mfma_f32_16x16x32_bf16 v[32:35], v[222:225], v[182:185], v[32:35]
	v_mfma_f32_16x16x32_bf16 v[24:27], v[230:233], v[182:185], v[24:27]
	v_mfma_f32_16x16x32_bf16 v[16:19], v[222:225], v[190:193], v[16:19]
	v_mfma_f32_16x16x32_bf16 v[8:11], v[230:233], v[190:193], v[8:11]
	v_mfma_f32_16x16x32_bf16 v[4:7], v[222:225], v[214:217], v[4:7]
	v_mfma_f32_16x16x32_bf16 v[0:3], v[230:233], v[214:217], v[0:3]
	s_setprio 0
	s_add_i32 s56, 0, 0x18000
	v_add_u32_e32 v150, s56, v135
	s_barrier
	ds_read_b128 v[138:141], v150
	ds_read_b128 v[142:145], v150 offset:1024
	ds_read_b128 v[146:149], v150 offset:2048
	ds_read_b128 v[150:153], v150 offset:3072
	s_add_u32 s28, s28, 0x80000
	s_addc_u32 s29, s29, 0
	s_mov_b32 m0, s44
	v_lshl_add_u64 v[218:219], s[28:29], 0, v[160:161]
	ds_read_b128 v[154:157], v137 offset:32768
	ds_read_b128 v[174:177], v137 offset:33792
	ds_read_b128 v[178:181], v137 offset:34816
	ds_read_b128 v[182:185], v137 offset:35840
	ds_read_b128 v[186:189], v137 offset:36864
	ds_read_b128 v[190:193], v137 offset:37888
	ds_read_b128 v[194:197], v137 offset:38912
	ds_read_b128 v[214:217], v137 offset:39936
	global_load_lds_dwordx4 v[218:219], off
	v_lshl_add_u64 v[218:219], s[28:29], 0, v[128:129]
	s_mov_b32 m0, s45
	s_nop 0
	global_load_lds_dwordx4 v[218:219], off
	s_waitcnt lgkmcnt(8)
	s_waitcnt vmcnt(10)
	s_barrier
	s_waitcnt lgkmcnt(0)
	s_setprio 1
	v_mfma_f32_16x16x32_bf16 v[124:127], v[138:141], v[154:157], v[124:127]
	v_mfma_f32_16x16x32_bf16 v[120:123], v[146:149], v[154:157], v[120:123]
	v_mfma_f32_16x16x32_bf16 v[116:119], v[138:141], v[178:181], v[116:119]
	v_mfma_f32_16x16x32_bf16 v[108:111], v[146:149], v[178:181], v[108:111]
	v_mfma_f32_16x16x32_bf16 v[100:103], v[138:141], v[186:189], v[100:103]
	v_mfma_f32_16x16x32_bf16 v[92:95], v[146:149], v[186:189], v[92:95]
	v_mfma_f32_16x16x32_bf16 v[84:87], v[138:141], v[194:197], v[84:87]
	v_mfma_f32_16x16x32_bf16 v[76:79], v[146:149], v[194:197], v[76:79]
	v_mfma_f32_16x16x32_bf16 v[124:127], v[142:145], v[174:177], v[124:127]
	v_mfma_f32_16x16x32_bf16 v[120:123], v[150:153], v[174:177], v[120:123]
	v_mfma_f32_16x16x32_bf16 v[116:119], v[142:145], v[182:185], v[116:119]
	v_mfma_f32_16x16x32_bf16 v[108:111], v[150:153], v[182:185], v[108:111]
	v_mfma_f32_16x16x32_bf16 v[100:103], v[142:145], v[190:193], v[100:103]
	v_mfma_f32_16x16x32_bf16 v[92:95], v[150:153], v[190:193], v[92:95]
	v_mfma_f32_16x16x32_bf16 v[84:87], v[142:145], v[214:217], v[84:87]
	v_mfma_f32_16x16x32_bf16 v[76:79], v[150:153], v[214:217], v[76:79]
	s_setprio 0
	s_barrier
	s_add_i32 s28, 0, 0x1c000
	s_add_i32 s29, s56, s41
	v_add_u32_e32 v167, s28, v135
	v_lshl_add_u64 v[158:159], v[158:159], 0, s[2:3]
	s_mov_b32 m0, s29
	ds_read_b128 v[218:221], v167
	ds_read_b128 v[222:225], v167 offset:1024
	ds_read_b128 v[226:229], v167 offset:2048
	ds_read_b128 v[230:233], v167 offset:3072
	global_load_lds_dwordx4 v[158:159], off
	v_lshl_add_u64 v[158:159], v[234:235], 0, s[2:3]
	s_add_i32 m0, s29, 0x2000
	s_nop 0
	global_load_lds_dwordx4 v[158:159], off
	s_waitcnt vmcnt(10)
	s_barrier
	s_waitcnt lgkmcnt(0)
	s_setprio 1
	v_mfma_f32_16x16x32_bf16 v[112:115], v[218:221], v[154:157], v[112:115]
	v_mfma_f32_16x16x32_bf16 v[104:107], v[226:229], v[154:157], v[104:107]
	v_mfma_f32_16x16x32_bf16 v[96:99], v[218:221], v[178:181], v[96:99]
	v_mfma_f32_16x16x32_bf16 v[88:91], v[226:229], v[178:181], v[88:91]
	v_mfma_f32_16x16x32_bf16 v[80:83], v[218:221], v[186:189], v[80:83]
	v_mfma_f32_16x16x32_bf16 v[72:75], v[226:229], v[186:189], v[72:75]
	v_mfma_f32_16x16x32_bf16 v[68:71], v[218:221], v[194:197], v[68:71]
	v_mfma_f32_16x16x32_bf16 v[64:67], v[226:229], v[194:197], v[64:67]
	v_mfma_f32_16x16x32_bf16 v[112:115], v[222:225], v[174:177], v[112:115]
	v_mfma_f32_16x16x32_bf16 v[104:107], v[230:233], v[174:177], v[104:107]
	v_mfma_f32_16x16x32_bf16 v[96:99], v[222:225], v[182:185], v[96:99]
	v_mfma_f32_16x16x32_bf16 v[88:91], v[230:233], v[182:185], v[88:91]
	v_mfma_f32_16x16x32_bf16 v[80:83], v[222:225], v[190:193], v[80:83]
	v_mfma_f32_16x16x32_bf16 v[72:75], v[230:233], v[190:193], v[72:75]
	v_mfma_f32_16x16x32_bf16 v[68:71], v[222:225], v[214:217], v[68:71]
	v_mfma_f32_16x16x32_bf16 v[64:67], v[230:233], v[214:217], v[64:67]
	s_setprio 0
	s_mov_b32 m0, s46
	v_lshl_add_u64 v[158:159], v[236:237], 0, s[2:3]
	s_barrier
	ds_read_b128 v[154:157], v137 offset:49152
	ds_read_b128 v[174:177], v137 offset:50176
	ds_read_b128 v[178:181], v137 offset:51200
	ds_read_b128 v[182:185], v137 offset:52224
	ds_read_b128 v[186:189], v137 offset:53248
	ds_read_b128 v[190:193], v137 offset:54272
	ds_read_b128 v[194:197], v137 offset:55296
	ds_read_b128 v[214:217], v137 offset:56320
	global_load_lds_dwordx4 v[158:159], off
	v_lshl_add_u64 v[158:159], v[238:239], 0, s[2:3]
	s_mov_b32 m0, s47
	s_nop 0
	global_load_lds_dwordx4 v[158:159], off
	s_barrier
; #define PG8_STAGE(bufoff, gbase, voff) do { _Pragma("unroll") for (int _i = 0; _i < 2; ++_i) \
;         __builtin_amdgcn_global_load_lds((const unsigned*)((const char*)(gbase) + (voff)[_i]), (LAS unsigned*)(lds + (bufoff) + ldsw + _i * 8192), 16, 0, 0); } while (0)
; #define PG8_MMA(ai, bj, At, Bt) do { __builtin_amdgcn_s_setprio(1); _Pragma("unroll") for (int m = 0; m < 4; ++m) _Pragma("unroll") for (int n = 0; n < 2; ++n) _Pragma("unroll") for (int k = 0; k < 2; ++k) \
;         acc[ai][bj][m][n] = __builtin_amdgcn_mfma_f32_16x16x32_bf16(Bt[n][k], At[m][k], acc[ai][bj][m][n], 0, 0, 0); __builtin_amdgcn_s_setprio(0); } while (0)
; #define PG8_WAIT_V(n) asm volatile("s_waitcnt vmcnt(" #n ")" ::: "memory")
; #define PG8_WAIT_L(n) asm volatile("s_waitcnt lgkmcnt(" #n ")" ::: "memory")
; #define PG8_BAR __builtin_amdgcn_s_barrier()
; #define PG8_SCHED __builtin_amdgcn_sched_barrier(0)
; template <class Epi>
; DEV void gemm_phase(LAS unsigned char* lds, const Gemm g, const StaticOrder& S, const Epi& E) {
;     ...
;             PG8_BAR; PG8_WAIT_L(0); PG8_MMA(1, 0, At, B0); PG8_BAR; PG8_SCHED;
;             PG8_STAGE(PG8_SB(1, 1), b3 + hstep, voffB);
;             PG8_WAIT_V(6); PG8_BAR; PG8_MMA(1, 1, At, B1); PG8_BAR;
	s_waitcnt lgkmcnt(0)
	s_setprio 1
	v_mfma_f32_16x16x32_bf16 v[60:63], v[138:141], v[154:157], v[60:63]
	v_mfma_f32_16x16x32_bf16 v[56:59], v[146:149], v[154:157], v[56:59]
	v_mfma_f32_16x16x32_bf16 v[52:55], v[138:141], v[178:181], v[52:55]
	v_mfma_f32_16x16x32_bf16 v[44:47], v[146:149], v[178:181], v[44:47]
	v_mfma_f32_16x16x32_bf16 v[36:39], v[138:141], v[186:189], v[36:39]
	v_mfma_f32_16x16x32_bf16 v[28:31], v[146:149], v[186:189], v[28:31]
	v_mfma_f32_16x16x32_bf16 v[20:23], v[138:141], v[194:197], v[20:23]
	v_mfma_f32_16x16x32_bf16 v[12:15], v[146:149], v[194:197], v[12:15]
	v_mfma_f32_16x16x32_bf16 v[60:63], v[142:145], v[174:177], v[60:63]
	v_mfma_f32_16x16x32_bf16 v[56:59], v[150:153], v[174:177], v[56:59]
	v_mfma_f32_16x16x32_bf16 v[52:55], v[142:145], v[182:185], v[52:55]
	v_mfma_f32_16x16x32_bf16 v[44:47], v[150:153], v[182:185], v[44:47]
	v_mfma_f32_16x16x32_bf16 v[36:39], v[142:145], v[190:193], v[36:39]
	v_mfma_f32_16x16x32_bf16 v[28:31], v[150:153], v[190:193], v[28:31]
	v_mfma_f32_16x16x32_bf16 v[20:23], v[142:145], v[214:217], v[20:23]
	v_mfma_f32_16x16x32_bf16 v[12:15], v[150:153], v[214:217], v[12:15]
	s_setprio 0
	s_barrier
	s_add_u32 s26, s26, 0x80080
	s_addc_u32 s27, s27, 0
	s_add_i32 s28, s28, s41
	v_lshl_add_u64 v[138:139], s[26:27], 0, v[160:161]
	s_mov_b32 m0, s28
	s_nop 0
	global_load_lds_dwordx4 v[138:139], off
	v_lshl_add_u64 v[138:139], s[26:27], 0, v[128:129]
	s_add_i32 m0, s28, 0x2000
	s_nop 0
	global_load_lds_dwordx4 v[138:139], off
	s_waitcnt vmcnt(10)
	s_barrier
	s_setprio 1
	v_mfma_f32_16x16x32_bf16 v[48:51], v[218:221], v[154:157], v[48:51]
	v_mfma_f32_16x16x32_bf16 v[40:43], v[226:229], v[154:157], v[40:43]
	v_mfma_f32_16x16x32_bf16 v[32:35], v[218:221], v[178:181], v[32:35]
	v_mfma_f32_16x16x32_bf16 v[24:27], v[226:229], v[178:181], v[24:27]
	v_mfma_f32_16x16x32_bf16 v[16:19], v[218:221], v[186:189], v[16:19]
	v_mfma_f32_16x16x32_bf16 v[8:11], v[226:229], v[186:189], v[8:11]
	v_mfma_f32_16x16x32_bf16 v[4:7], v[218:221], v[194:197], v[4:7]
	v_mfma_f32_16x16x32_bf16 v[0:3], v[226:229], v[194:197], v[0:3]
	v_mfma_f32_16x16x32_bf16 v[48:51], v[222:225], v[174:177], v[48:51]
	v_mfma_f32_16x16x32_bf16 v[40:43], v[230:233], v[174:177], v[40:43]
	v_mfma_f32_16x16x32_bf16 v[32:35], v[222:225], v[182:185], v[32:35]
	v_mfma_f32_16x16x32_bf16 v[24:27], v[230:233], v[182:185], v[24:27]
	v_mfma_f32_16x16x32_bf16 v[16:19], v[222:225], v[190:193], v[16:19]
	v_mfma_f32_16x16x32_bf16 v[8:11], v[230:233], v[190:193], v[8:11]
	v_mfma_f32_16x16x32_bf16 v[4:7], v[222:225], v[214:217], v[4:7]
	v_mfma_f32_16x16x32_bf16 v[0:3], v[230:233], v[214:217], v[0:3]
	s_setprio 0
	s_add_i32 s55, s55, 2
	s_add_u32 s24, s24, 0x100
	s_addc_u32 s25, s25, 0
	s_add_u32 s53, s53, 0x100
	s_addc_u32 s54, s54, 0
	s_cmp_gt_u32 s55, 29
	s_barrier
	s_cbranch_scc0 .LBB0_362
; DEV bf16x8 pack8(f32x4 a, f32x4 b) { u32x4 w; w.x = cvt_pk_bf16(a[0], a[1]); w.y = cvt_pk_bf16(a[2], a[3]); w.z = cvt_pk_bf16(b[0], b[1]); w.w = cvt_pk_bf16(b[2], b[3]); return __builtin_bit_cast(bf16x8, w); }
; DEV u32x2 pack4(f32x4 a) { u32x2 w; w.x = cvt_pk_bf16(a[0], a[1]); w.y = cvt_pk_bf16(a[2], a[3]); return w; }
; DEV f32x4 gelu4(f32x4 v) { f32x2 a = gelu_pk((f32x2){v[0], v[1]}), b = gelu_pk((f32x2){v[2], v[3]}); return (f32x4){a.x, a.y, b.x, b.y}; }
; template <int ACT, bool PERM>
; DEV void store_bf16_tile(AccRef acc, u16* O, int ld, int row0, int col0, const float* ss) {
;     ...
;         for (int m = 0; m < 4; ++m) { u16* rowp = O + (size_t)(row0 + ai * 128 + m * 16) * ld + col0; const float rs = rsv[ai][m];
; #pragma unroll
;             for (int bj = 0; bj < 2; ++bj) { f32x4 v0 = acc[ai][bj][m][0] * rs, v1 = acc[ai][bj][m][1] * rs; if (ACT == 1) { v0 = gelu4(v0); v1 = gelu4(v1); }
;                 if (PERM) *(u32x4*)(rowp + bj * 128) = __builtin_bit_cast(u32x4, pack8(v0, v1));
;                 else { *(u32x2*)(rowp + bj * 128) = pack4(v0); *(u32x2*)(rowp + bj * 128 + 16) = pack4(v1); } } }
	v_lshl_add_u32 v138, s12, 8, v134
	v_lshl_or_b32 v140, s50, 8, v136
	v_ashrrev_i32_e32 v141, 31, v140
	v_ashrrev_i32_e32 v139, 31, v138
	v_lshl_add_u64 v[140:141], v[140:141], 1, s[10:11]
	v_lshlrev_b64 v[142:143], 11, v[138:139]
	v_lshl_add_u64 v[142:143], v[140:141], 0, v[142:143]
	v_cvt_pk_bf16_f32 v104, v104, v105
	v_cvt_pk_bf16_f32 v105, v106, v107
	global_store_dwordx2 v[142:143], v[104:105], off offset:288
	v_or_b32_e32 v104, 16, v138
	v_ashrrev_i32_e32 v105, 31, v104
	v_lshlrev_b64 v[104:105], 11, v[104:105]
	v_lshl_add_u64 v[104:105], v[140:141], 0, v[104:105]
	v_cvt_pk_bf16_f32 v88, v88, v89
	v_cvt_pk_bf16_f32 v89, v90, v91
	global_store_dwordx2 v[104:105], v[88:89], off offset:288
	v_or_b32_e32 v88, 32, v138
	v_ashrrev_i32_e32 v89, 31, v88
	v_lshlrev_b64 v[88:89], 11, v[88:89]
	v_lshl_add_u64 v[88:89], v[140:141], 0, v[88:89]
	v_cvt_pk_bf16_f32 v72, v72, v73
	v_cvt_pk_bf16_f32 v73, v74, v75
	global_store_dwordx2 v[88:89], v[72:73], off offset:288
	v_or_b32_e32 v72, 48, v138
	v_ashrrev_i32_e32 v73, 31, v72
	v_lshlrev_b64 v[72:73], 11, v[72:73]
	s_mov_b32 s12, 0x40000
	v_lshl_add_u64 v[72:73], v[140:141], 0, v[72:73]
	v_cvt_pk_bf16_f32 v64, v64, v65
	v_cvt_pk_bf16_f32 v65, v66, v67
	s_mov_b64 s[24:25], 0x40000
	v_cvt_pk_bf16_f32 v60, v60, v61
	v_cvt_pk_bf16_f32 v61, v62, v63
	v_add_co_u32_e32 v62, vcc, s12, v142
	global_store_dwordx2 v[72:73], v[64:65], off offset:288
	v_lshl_add_u64 v[64:65], v[142:143], 0, s[24:25]
	v_addc_co_u32_e32 v63, vcc, 0, v143, vcc
	v_cvt_pk_bf16_f32 v48, v48, v49
	v_cvt_pk_bf16_f32 v49, v50, v51
	s_mov_b32 s12, 0x48000
	global_store_dwordx2 v[64:65], v[48:49], off offset:256
	v_cvt_pk_bf16_f32 v40, v40, v41
	v_cvt_pk_bf16_f32 v41, v42, v43
	s_mov_b64 s[24:25], 0x48000
	v_add_co_u32_e32 v48, vcc, s12, v142
	global_store_dwordx2 v[64:65], v[40:41], off offset:288
	v_lshl_add_u64 v[40:41], v[142:143], 0, s[24:25]
	v_addc_co_u32_e32 v49, vcc, 0, v143, vcc
	v_cvt_pk_bf16_f32 v32, v32, v33
	v_cvt_pk_bf16_f32 v33, v34, v35
	s_mov_b32 s12, 0x50000
	global_store_dwordx2 v[40:41], v[32:33], off offset:256
	v_cvt_pk_bf16_f32 v24, v24, v25
	v_cvt_pk_bf16_f32 v25, v26, v27
	s_mov_b64 s[24:25], 0x50000
	v_add_co_u32_e32 v32, vcc, s12, v142
	global_store_dwordx2 v[40:41], v[24:25], off offset:288
	v_lshl_add_u64 v[24:25], v[142:143], 0, s[24:25]
	v_addc_co_u32_e32 v33, vcc, 0, v143, vcc
	v_cvt_pk_bf16_f32 v16, v16, v17
	v_cvt_pk_bf16_f32 v17, v18, v19
	global_store_dwordx2 v[24:25], v[16:17], off offset:256
	v_add_co_u32_e32 v16, vcc, s59, v142
	v_cvt_pk_bf16_f32 v106, v116, v117
	v_cvt_pk_bf16_f32 v107, v118, v119
	v_cvt_pk_bf16_f32 v90, v100, v101
	v_cvt_pk_bf16_f32 v91, v102, v103
	v_cvt_pk_bf16_f32 v74, v84, v85
	v_cvt_pk_bf16_f32 v75, v86, v87
	v_cvt_pk_bf16_f32 v42, v52, v53
	v_cvt_pk_bf16_f32 v43, v54, v55
	v_cvt_pk_bf16_f32 v26, v36, v37
	v_cvt_pk_bf16_f32 v27, v38, v39
	v_cvt_pk_bf16_f32 v8, v8, v9
	v_cvt_pk_bf16_f32 v9, v10, v11
	s_mov_b64 s[24:25], 0x58000
	v_cvt_pk_bf16_f32 v10, v20, v21
	v_cvt_pk_bf16_f32 v11, v22, v23
	v_addc_co_u32_e32 v17, vcc, 0, v143, vcc
	v_cvt_pk_bf16_f32 v124, v124, v125
	v_cvt_pk_bf16_f32 v125, v126, v127
	v_cvt_pk_bf16_f32 v120, v120, v121
	v_cvt_pk_bf16_f32 v121, v122, v123
	v_cvt_pk_bf16_f32 v112, v112, v113
	v_cvt_pk_bf16_f32 v113, v114, v115
	global_store_dwordx2 v[104:105], v[106:107], off
	v_cvt_pk_bf16_f32 v106, v108, v109
	v_cvt_pk_bf16_f32 v107, v110, v111
	v_cvt_pk_bf16_f32 v96, v96, v97
	v_cvt_pk_bf16_f32 v97, v98, v99
	global_store_dwordx2 v[88:89], v[90:91], off
	v_cvt_pk_bf16_f32 v90, v92, v93
	v_cvt_pk_bf16_f32 v91, v94, v95
	v_cvt_pk_bf16_f32 v80, v80, v81
	v_cvt_pk_bf16_f32 v81, v82, v83
	global_store_dwordx2 v[72:73], v[74:75], off
	v_cvt_pk_bf16_f32 v74, v76, v77
	v_cvt_pk_bf16_f32 v75, v78, v79
	v_cvt_pk_bf16_f32 v68, v68, v69
	v_cvt_pk_bf16_f32 v69, v70, v71
	v_cvt_pk_bf16_f32 v56, v56, v57
	v_cvt_pk_bf16_f32 v57, v58, v59
	global_store_dwordx2 v[48:49], v[42:43], off
	v_cvt_pk_bf16_f32 v42, v44, v45
	v_cvt_pk_bf16_f32 v43, v46, v47
	global_store_dwordx2 v[32:33], v[26:27], off
	v_cvt_pk_bf16_f32 v26, v28, v29
	v_cvt_pk_bf16_f32 v27, v30, v31
	global_store_dwordx2 v[24:25], v[8:9], off offset:288
	v_lshl_add_u64 v[8:9], v[142:143], 0, s[24:25]
	global_store_dwordx2 v[16:17], v[10:11], off
	v_cvt_pk_bf16_f32 v10, v12, v13
	v_cvt_pk_bf16_f32 v11, v14, v15
	v_cvt_pk_bf16_f32 v4, v4, v5
	v_cvt_pk_bf16_f32 v5, v6, v7
	v_cvt_pk_bf16_f32 v0, v0, v1
	v_cvt_pk_bf16_f32 v1, v2, v3
	s_and_b64 vcc, exec, s[14:15]
	s_mov_b32 s50, s16
	s_mov_b32 s12, s18
	s_mov_b64 s[26:27], s[22:23]
	s_mov_b64 s[24:25], s[20:21]
	global_store_dwordx2 v[142:143], v[124:125], off
	global_store_dwordx2 v[142:143], v[120:121], off offset:32
	global_store_dwordx2 v[142:143], v[112:113], off offset:256
	global_store_dwordx2 v[104:105], v[106:107], off offset:32
	global_store_dwordx2 v[104:105], v[96:97], off offset:256
	global_store_dwordx2 v[88:89], v[90:91], off offset:32
	global_store_dwordx2 v[88:89], v[80:81], off offset:256
	global_store_dwordx2 v[72:73], v[74:75], off offset:32
	global_store_dwordx2 v[72:73], v[68:69], off offset:256
	global_store_dwordx2 v[62:63], v[60:61], off
	global_store_dwordx2 v[64:65], v[56:57], off offset:32
	global_store_dwordx2 v[40:41], v[42:43], off offset:32
	global_store_dwordx2 v[24:25], v[26:27], off offset:32
	global_store_dwordx2 v[8:9], v[10:11], off offset:32
	global_store_dwordx2 v[8:9], v[4:5], off offset:256
	global_store_dwordx2 v[8:9], v[0:1], off offset:288
	s_cbranch_vccz .LBB0_359
	s_waitcnt vmcnt(0)
	s_cmpk_gt_u32 s36, 0xff
	s_cbranch_scc1 .LBB0_353
	s_barrier
	s_branch .LBB0_353

; #define PG8_STAGE(bufoff, gbase, voff) do { _Pragma("unroll") for (int _i = 0; _i < 2; ++_i) \
;         __builtin_amdgcn_global_load_lds((const unsigned*)((const char*)(gbase) + (voff)[_i]), (LAS unsigned*)(lds + (bufoff) + ldsw + _i * 8192), 16, 0, 0); } while (0)
; #define PG8_LDA(dst, b, h) do { _Pragma("unroll") for (int m = 0; m < 4; ++m) _Pragma("unroll") for (int k = 0; k < 2; ++k) dst[m][k] = *(const LAS bf16x8*)(lds + PG8_SA(b, h) + aoff + m * 2048 + k * 1024); } while (0)
; #define PG8_LDB(dst, b, h) do { _Pragma("unroll") for (int n = 0; n < 2; ++n) _Pragma("unroll") for (int k = 0; k < 2; ++k) dst[n][k] = *(const LAS bf16x8*)(lds + PG8_SB(b, h) + boff + n * 2048 + k * 1024); } while (0)
; #define PG8_MMA(ai, bj, At, Bt) do { __builtin_amdgcn_s_setprio(1); _Pragma("unroll") for (int m = 0; m < 4; ++m) _Pragma("unroll") for (int n = 0; n < 2; ++n) _Pragma("unroll") for (int k = 0; k < 2; ++k) \
;         acc[ai][bj][m][n] = __builtin_amdgcn_mfma_f32_16x16x32_bf16(Bt[n][k], At[m][k], acc[ai][bj][m][n], 0, 0, 0); __builtin_amdgcn_s_setprio(0); } while (0)
; #define PG8_WAIT_L(n) asm volatile("s_waitcnt lgkmcnt(" #n ")" ::: "memory")
; #define PG8_BAR __builtin_amdgcn_s_barrier()
; #define PG8_SCHED __builtin_amdgcn_sched_barrier(0)
; template <class Epi>
; DEV void gemm_phase(LAS unsigned char* lds, const Gemm g, const StaticOrder& S, const Epi& E) {
;     ...
;             const bool last = (t == nt - 2);
;             const char* a1 = cA + (size_t)(t + 1) * kstep;
;             const char* a2 = last ? nA : cA + (size_t)(t + 2) * kstep; const char* b2 = last ? nB : cB + (size_t)(t + 2) * kstep;
;             const char* a3 = a2 + kstep; const char* b3 = b2 + kstep;
;             PG8_LDB(B0, 0, 0); PG8_SCHED; PG8_LDA(At, 0, 0); PG8_STAGE(PG8_SA(1, 1), a1 + hstep, voffA);
;             PG8_WAIT_L(8); PG8_BAR; PG8_WAIT_L(0); PG8_MMA(0, 0, At, B0); PG8_BAR; PG8_SCHED;
;             PG8_LDB(B1, 0, 1); PG8_STAGE(PG8_SB(0, 0), b2, voffB);
;             PG8_BAR; PG8_WAIT_L(0); PG8_MMA(0, 1, At, B1); PG8_BAR;
;             PG8_LDA(At, 0, 1); PG8_STAGE(PG8_SA(0, 0), a2, voffA);
;             PG8_BAR; PG8_WAIT_L(0); PG8_MMA(1, 0, At, B0); PG8_BAR; PG8_SCHED;
.LBB0_404:
	s_add_u32 s28, s26, 0xfff00080
	s_addc_u32 s29, s27, -1
	s_add_i32 s49, 0, 0x10000
	v_add_u32_e32 v140, s49, v178
	ds_read_b128 v[128:131], v140
	ds_read_b128 v[132:135], v140 offset:1024
	ds_read_b128 v[136:139], v140 offset:2048
	ds_read_b128 v[140:143], v140 offset:3072
	s_cmp_eq_u32 s48, 60
	s_cselect_b32 s31, s15, s29
	s_cselect_b32 s30, s19, s28
	s_cselect_b32 s29, s17, s47
	s_cselect_b32 s28, s25, s46
	v_lshl_add_u64 v[158:159], s[26:27], 0, v[150:151]
	s_add_i32 m0, s37, 0xc000
	ds_read_b128 v[154:157], v181
	ds_read_b128 v[174:177], v181 offset:1024
	ds_read_b128 v[182:185], v181 offset:2048
	ds_read_b128 v[186:189], v181 offset:3072
	ds_read_b128 v[190:193], v181 offset:4096
	ds_read_b128 v[194:197], v181 offset:5120
	ds_read_b128 v[214:217], v181 offset:6144
	ds_read_b128 v[218:221], v181 offset:7168
	global_load_lds_dwordx4 v[158:159], off
	v_lshl_add_u64 v[158:159], s[26:27], 0, v[152:153]
	s_add_i32 m0, s37, 0xe000
	s_nop 0
	global_load_lds_dwordx4 v[158:159], off
	s_waitcnt lgkmcnt(8)
	s_waitcnt vmcnt(10)
	s_barrier
	s_waitcnt lgkmcnt(0)
	s_setprio 1
	v_mfma_f32_16x16x32_bf16 v[124:127], v[128:131], v[154:157], v[124:127]
	v_mfma_f32_16x16x32_bf16 v[120:123], v[136:139], v[154:157], v[120:123]
	v_mfma_f32_16x16x32_bf16 v[108:111], v[128:131], v[182:185], v[108:111]
	v_mfma_f32_16x16x32_bf16 v[104:107], v[136:139], v[182:185], v[104:107]
	v_mfma_f32_16x16x32_bf16 v[92:95], v[128:131], v[190:193], v[92:95]
	v_mfma_f32_16x16x32_bf16 v[88:91], v[136:139], v[190:193], v[88:91]
	v_mfma_f32_16x16x32_bf16 v[76:79], v[128:131], v[214:217], v[76:79]
	v_mfma_f32_16x16x32_bf16 v[72:75], v[136:139], v[214:217], v[72:75]
	v_mfma_f32_16x16x32_bf16 v[124:127], v[132:135], v[174:177], v[124:127]
	v_mfma_f32_16x16x32_bf16 v[120:123], v[140:143], v[174:177], v[120:123]
	v_mfma_f32_16x16x32_bf16 v[108:111], v[132:135], v[186:189], v[108:111]
	v_mfma_f32_16x16x32_bf16 v[104:107], v[140:143], v[186:189], v[104:107]
	v_mfma_f32_16x16x32_bf16 v[92:95], v[132:135], v[194:197], v[92:95]
	v_mfma_f32_16x16x32_bf16 v[88:91], v[140:143], v[194:197], v[88:91]
	v_mfma_f32_16x16x32_bf16 v[76:79], v[132:135], v[218:221], v[76:79]
	v_mfma_f32_16x16x32_bf16 v[72:75], v[140:143], v[218:221], v[72:75]
	s_setprio 0
	s_barrier
	s_add_i32 s52, 0, 0x14000
	v_add_u32_e32 v158, s52, v178
	s_add_i32 s49, s49, s36
	ds_read_b128 v[222:225], v158
	ds_read_b128 v[226:229], v158 offset:1024
	ds_read_b128 v[230:233], v158 offset:2048
	ds_read_b128 v[234:237], v158 offset:3072
	v_lshl_add_u64 v[158:159], s[28:29], 0, v[160:161]
	s_mov_b32 m0, s49
	v_lshl_add_u64 v[238:239], s[28:29], 0, v[148:149]
	global_load_lds_dwordx4 v[158:159], off
	s_add_i32 m0, s49, 0x2000
	s_nop 0
	global_load_lds_dwordx4 v[238:239], off
	s_waitcnt vmcnt(10)
	s_barrier
	s_waitcnt lgkmcnt(0)
	s_setprio 1
	v_mfma_f32_16x16x32_bf16 v[116:119], v[222:225], v[154:157], v[116:119]
	v_mfma_f32_16x16x32_bf16 v[112:115], v[230:233], v[154:157], v[112:115]
	v_mfma_f32_16x16x32_bf16 v[100:103], v[222:225], v[182:185], v[100:103]
	v_mfma_f32_16x16x32_bf16 v[96:99], v[230:233], v[182:185], v[96:99]
	v_mfma_f32_16x16x32_bf16 v[84:87], v[222:225], v[190:193], v[84:87]
	v_mfma_f32_16x16x32_bf16 v[80:83], v[230:233], v[190:193], v[80:83]
	v_mfma_f32_16x16x32_bf16 v[68:71], v[222:225], v[214:217], v[68:71]
	v_mfma_f32_16x16x32_bf16 v[64:67], v[230:233], v[214:217], v[64:67]
	v_mfma_f32_16x16x32_bf16 v[116:119], v[226:229], v[174:177], v[116:119]
	v_mfma_f32_16x16x32_bf16 v[112:115], v[234:237], v[174:177], v[112:115]
	v_mfma_f32_16x16x32_bf16 v[100:103], v[226:229], v[186:189], v[100:103]
	v_mfma_f32_16x16x32_bf16 v[96:99], v[234:237], v[186:189], v[96:99]
	v_mfma_f32_16x16x32_bf16 v[84:87], v[226:229], v[194:197], v[84:87]
	v_mfma_f32_16x16x32_bf16 v[80:83], v[234:237], v[194:197], v[80:83]
	v_mfma_f32_16x16x32_bf16 v[68:71], v[226:229], v[218:221], v[68:71]
	v_mfma_f32_16x16x32_bf16 v[64:67], v[234:237], v[218:221], v[64:67]
	s_setprio 0
	s_mov_b32 m0, s37
	v_lshl_add_u64 v[240:241], s[30:31], 0, v[144:145]
	s_barrier
	ds_read_b128 v[154:157], v181 offset:16384
	ds_read_b128 v[174:177], v181 offset:17408
	ds_read_b128 v[182:185], v181 offset:18432
	ds_read_b128 v[186:189], v181 offset:19456
	ds_read_b128 v[190:193], v181 offset:20480
	ds_read_b128 v[194:197], v181 offset:21504
	ds_read_b128 v[214:217], v181 offset:22528
	ds_read_b128 v[218:221], v181 offset:23552
	global_load_lds_dwordx4 v[240:241], off
	v_lshl_add_u64 v[242:243], s[30:31], 0, v[146:147]
	s_mov_b32 m0, s38
	s_nop 0
	global_load_lds_dwordx4 v[242:243], off
	s_barrier
	s_waitcnt lgkmcnt(0)
	s_setprio 1
	v_mfma_f32_16x16x32_bf16 v[60:63], v[128:131], v[154:157], v[60:63]
	v_mfma_f32_16x16x32_bf16 v[56:59], v[136:139], v[154:157], v[56:59]
	v_mfma_f32_16x16x32_bf16 v[44:47], v[128:131], v[182:185], v[44:47]
	v_mfma_f32_16x16x32_bf16 v[40:43], v[136:139], v[182:185], v[40:43]
	v_mfma_f32_16x16x32_bf16 v[28:31], v[128:131], v[190:193], v[28:31]
	v_mfma_f32_16x16x32_bf16 v[24:27], v[136:139], v[190:193], v[24:27]
	v_mfma_f32_16x16x32_bf16 v[12:15], v[128:131], v[214:217], v[12:15]
	v_mfma_f32_16x16x32_bf16 v[8:11], v[136:139], v[214:217], v[8:11]
	v_mfma_f32_16x16x32_bf16 v[60:63], v[132:135], v[174:177], v[60:63]
	v_mfma_f32_16x16x32_bf16 v[56:59], v[140:143], v[174:177], v[56:59]
	v_mfma_f32_16x16x32_bf16 v[44:47], v[132:135], v[186:189], v[44:47]
	v_mfma_f32_16x16x32_bf16 v[40:43], v[140:143], v[186:189], v[40:43]
	v_mfma_f32_16x16x32_bf16 v[28:31], v[132:135], v[194:197], v[28:31]
	v_mfma_f32_16x16x32_bf16 v[24:27], v[140:143], v[194:197], v[24:27]
	v_mfma_f32_16x16x32_bf16 v[12:15], v[132:135], v[218:221], v[12:15]
	v_mfma_f32_16x16x32_bf16 v[8:11], v[140:143], v[218:221], v[8:11]
	s_setprio 0
	s_barrier
; #define PG8_STAGE(bufoff, gbase, voff) do { _Pragma("unroll") for (int _i = 0; _i < 2; ++_i) \
;         __builtin_amdgcn_global_load_lds((const unsigned*)((const char*)(gbase) + (voff)[_i]), (LAS unsigned*)(lds + (bufoff) + ldsw + _i * 8192), 16, 0, 0); } while (0)
; #define PG8_LDA(dst, b, h) do { _Pragma("unroll") for (int m = 0; m < 4; ++m) _Pragma("unroll") for (int k = 0; k < 2; ++k) dst[m][k] = *(const LAS bf16x8*)(lds + PG8_SA(b, h) + aoff + m * 2048 + k * 1024); } while (0)
; #define PG8_LDB(dst, b, h) do { _Pragma("unroll") for (int n = 0; n < 2; ++n) _Pragma("unroll") for (int k = 0; k < 2; ++k) dst[n][k] = *(const LAS bf16x8*)(lds + PG8_SB(b, h) + boff + n * 2048 + k * 1024); } while (0)
; #define PG8_MMA(ai, bj, At, Bt) do { __builtin_amdgcn_s_setprio(1); _Pragma("unroll") for (int m = 0; m < 4; ++m) _Pragma("unroll") for (int n = 0; n < 2; ++n) _Pragma("unroll") for (int k = 0; k < 2; ++k) \
;         acc[ai][bj][m][n] = __builtin_amdgcn_mfma_f32_16x16x32_bf16(Bt[n][k], At[m][k], acc[ai][bj][m][n], 0, 0, 0); __builtin_amdgcn_s_setprio(0); } while (0)
; #define PG8_WAIT_V(n) asm volatile("s_waitcnt vmcnt(" #n ")" ::: "memory")
; #define PG8_WAIT_L(n) asm volatile("s_waitcnt lgkmcnt(" #n ")" ::: "memory")
; #define PG8_BAR __builtin_amdgcn_s_barrier()
; #define PG8_SCHED __builtin_amdgcn_sched_barrier(0)
; template <class Epi>
; DEV void gemm_phase(LAS unsigned char* lds, const Gemm g, const StaticOrder& S, const Epi& E) {
;     ...
;             PG8_STAGE(PG8_SB(0, 1), b2 + hstep, voffB);
;             PG8_WAIT_V(6); PG8_BAR; PG8_MMA(1, 1, At, B1); PG8_BAR;
;             PG8_LDB(B0, 1, 0); PG8_SCHED; PG8_LDA(At, 1, 0); PG8_STAGE(PG8_SA(0, 1), a2 + hstep, voffA);
;             PG8_WAIT_L(8); PG8_BAR; PG8_WAIT_L(0); PG8_MMA(0, 0, At, B0); PG8_BAR; PG8_SCHED;
;             PG8_LDB(B1, 1, 1); PG8_STAGE(PG8_SB(1, 0), b3, voffB);
;             PG8_BAR; PG8_WAIT_L(0); PG8_MMA(0, 1, At, B1); PG8_BAR;
;             PG8_LDA(At, 1, 1); PG8_STAGE(PG8_SA(1, 0), a3, voffA);
	s_add_u32 s50, s28, 0x100000
	s_addc_u32 s51, s29, 0
	s_add_i32 s49, s52, s36
	v_lshl_add_u64 v[128:129], s[50:51], 0, v[160:161]
	s_mov_b32 m0, s49
	s_nop 0
	global_load_lds_dwordx4 v[128:129], off
	v_lshl_add_u64 v[128:129], s[50:51], 0, v[148:149]
	s_add_i32 m0, s49, 0x2000
	s_nop 0
	global_load_lds_dwordx4 v[128:129], off
	s_waitcnt vmcnt(10)
	s_barrier
	s_setprio 1
	v_mfma_f32_16x16x32_bf16 v[52:55], v[222:225], v[154:157], v[52:55]
	v_mfma_f32_16x16x32_bf16 v[48:51], v[230:233], v[154:157], v[48:51]
	v_mfma_f32_16x16x32_bf16 v[36:39], v[222:225], v[182:185], v[36:39]
	v_mfma_f32_16x16x32_bf16 v[32:35], v[230:233], v[182:185], v[32:35]
	v_mfma_f32_16x16x32_bf16 v[20:23], v[222:225], v[190:193], v[20:23]
	v_mfma_f32_16x16x32_bf16 v[16:19], v[230:233], v[190:193], v[16:19]
	v_mfma_f32_16x16x32_bf16 v[4:7], v[222:225], v[214:217], v[4:7]
	v_mfma_f32_16x16x32_bf16 v[0:3], v[230:233], v[214:217], v[0:3]
	v_mfma_f32_16x16x32_bf16 v[52:55], v[226:229], v[174:177], v[52:55]
	v_mfma_f32_16x16x32_bf16 v[48:51], v[234:237], v[174:177], v[48:51]
	v_mfma_f32_16x16x32_bf16 v[36:39], v[226:229], v[186:189], v[36:39]
	v_mfma_f32_16x16x32_bf16 v[32:35], v[234:237], v[186:189], v[32:35]
	v_mfma_f32_16x16x32_bf16 v[20:23], v[226:229], v[194:197], v[20:23]
	v_mfma_f32_16x16x32_bf16 v[16:19], v[234:237], v[194:197], v[16:19]
	v_mfma_f32_16x16x32_bf16 v[4:7], v[226:229], v[218:221], v[4:7]
	v_mfma_f32_16x16x32_bf16 v[0:3], v[234:237], v[218:221], v[0:3]
	s_setprio 0
	s_add_i32 s49, 0, 0x18000
	v_add_u32_e32 v140, s49, v178
	s_barrier
	ds_read_b128 v[128:131], v140
	ds_read_b128 v[132:135], v140 offset:1024
	ds_read_b128 v[136:139], v140 offset:2048
	ds_read_b128 v[140:143], v140 offset:3072
	s_add_u32 s30, s30, 0x100000
	s_addc_u32 s31, s31, 0
	s_mov_b32 m0, s39
	v_lshl_add_u64 v[222:223], s[30:31], 0, v[144:145]
	ds_read_b128 v[154:157], v181 offset:32768
	ds_read_b128 v[174:177], v181 offset:33792
	ds_read_b128 v[182:185], v181 offset:34816
	ds_read_b128 v[186:189], v181 offset:35840
	ds_read_b128 v[190:193], v181 offset:36864
	ds_read_b128 v[194:197], v181 offset:37888
	ds_read_b128 v[214:217], v181 offset:38912
	ds_read_b128 v[218:221], v181 offset:39936
	global_load_lds_dwordx4 v[222:223], off
	v_lshl_add_u64 v[222:223], s[30:31], 0, v[146:147]
	s_mov_b32 m0, s40
	s_nop 0
	global_load_lds_dwordx4 v[222:223], off
	s_waitcnt lgkmcnt(8)
	s_waitcnt vmcnt(10)
	s_barrier
	s_waitcnt lgkmcnt(0)
	s_setprio 1
	v_mfma_f32_16x16x32_bf16 v[124:127], v[128:131], v[154:157], v[124:127]
	v_mfma_f32_16x16x32_bf16 v[120:123], v[136:139], v[154:157], v[120:123]
	v_mfma_f32_16x16x32_bf16 v[108:111], v[128:131], v[182:185], v[108:111]
	v_mfma_f32_16x16x32_bf16 v[104:107], v[136:139], v[182:185], v[104:107]
	v_mfma_f32_16x16x32_bf16 v[92:95], v[128:131], v[190:193], v[92:95]
	v_mfma_f32_16x16x32_bf16 v[88:91], v[136:139], v[190:193], v[88:91]
	v_mfma_f32_16x16x32_bf16 v[76:79], v[128:131], v[214:217], v[76:79]
	v_mfma_f32_16x16x32_bf16 v[72:75], v[136:139], v[214:217], v[72:75]
	v_mfma_f32_16x16x32_bf16 v[124:127], v[132:135], v[174:177], v[124:127]
	v_mfma_f32_16x16x32_bf16 v[120:123], v[140:143], v[174:177], v[120:123]
	v_mfma_f32_16x16x32_bf16 v[108:111], v[132:135], v[186:189], v[108:111]
	v_mfma_f32_16x16x32_bf16 v[104:107], v[140:143], v[186:189], v[104:107]
	v_mfma_f32_16x16x32_bf16 v[92:95], v[132:135], v[194:197], v[92:95]
	v_mfma_f32_16x16x32_bf16 v[88:91], v[140:143], v[194:197], v[88:91]
	v_mfma_f32_16x16x32_bf16 v[76:79], v[132:135], v[218:221], v[76:79]
	v_mfma_f32_16x16x32_bf16 v[72:75], v[140:143], v[218:221], v[72:75]
	s_setprio 0
	s_barrier
	s_add_i32 s30, 0, 0x1c000
	s_add_i32 s31, s49, s36
	v_add_u32_e32 v234, s30, v178
	v_lshl_add_u64 v[158:159], v[158:159], 0, s[2:3]
	s_mov_b32 m0, s31
	ds_read_b128 v[222:225], v234
	ds_read_b128 v[226:229], v234 offset:1024
	ds_read_b128 v[230:233], v234 offset:2048
	ds_read_b128 v[234:237], v234 offset:3072
	global_load_lds_dwordx4 v[158:159], off
	v_lshl_add_u64 v[158:159], v[238:239], 0, s[2:3]
	s_add_i32 m0, s31, 0x2000
	s_nop 0
	global_load_lds_dwordx4 v[158:159], off
	s_waitcnt vmcnt(10)
	s_barrier
	s_waitcnt lgkmcnt(0)
	s_setprio 1
	v_mfma_f32_16x16x32_bf16 v[116:119], v[222:225], v[154:157], v[116:119]
	v_mfma_f32_16x16x32_bf16 v[112:115], v[230:233], v[154:157], v[112:115]
	v_mfma_f32_16x16x32_bf16 v[100:103], v[222:225], v[182:185], v[100:103]
	v_mfma_f32_16x16x32_bf16 v[96:99], v[230:233], v[182:185], v[96:99]
	v_mfma_f32_16x16x32_bf16 v[84:87], v[222:225], v[190:193], v[84:87]
	v_mfma_f32_16x16x32_bf16 v[80:83], v[230:233], v[190:193], v[80:83]
	v_mfma_f32_16x16x32_bf16 v[68:71], v[222:225], v[214:217], v[68:71]
	v_mfma_f32_16x16x32_bf16 v[64:67], v[230:233], v[214:217], v[64:67]
	v_mfma_f32_16x16x32_bf16 v[116:119], v[226:229], v[174:177], v[116:119]
	v_mfma_f32_16x16x32_bf16 v[112:115], v[234:237], v[174:177], v[112:115]
	v_mfma_f32_16x16x32_bf16 v[100:103], v[226:229], v[186:189], v[100:103]
	v_mfma_f32_16x16x32_bf16 v[96:99], v[234:237], v[186:189], v[96:99]
	v_mfma_f32_16x16x32_bf16 v[84:87], v[226:229], v[194:197], v[84:87]
	v_mfma_f32_16x16x32_bf16 v[80:83], v[234:237], v[194:197], v[80:83]
	v_mfma_f32_16x16x32_bf16 v[68:71], v[226:229], v[218:221], v[68:71]
	v_mfma_f32_16x16x32_bf16 v[64:67], v[234:237], v[218:221], v[64:67]
	s_setprio 0
	s_mov_b32 m0, s41
	v_lshl_add_u64 v[158:159], v[240:241], 0, s[2:3]
	s_barrier
	ds_read_b128 v[154:157], v181 offset:49152
	ds_read_b128 v[174:177], v181 offset:50176
	ds_read_b128 v[182:185], v181 offset:51200
	ds_read_b128 v[186:189], v181 offset:52224
	ds_read_b128 v[190:193], v181 offset:53248
	ds_read_b128 v[194:197], v181 offset:54272
	ds_read_b128 v[214:217], v181 offset:55296
	ds_read_b128 v[218:221], v181 offset:56320
	global_load_lds_dwordx4 v[158:159], off
	v_lshl_add_u64 v[158:159], v[242:243], 0, s[2:3]
	s_mov_b32 m0, s42
	s_nop 0
	global_load_lds_dwordx4 v[158:159], off
	s_barrier
; DEV bf16x8 pack8(f32x4 a, f32x4 b) { u32x4 w; w.x = cvt_pk_bf16(a[0], a[1]); w.y = cvt_pk_bf16(a[2], a[3]); w.z = cvt_pk_bf16(b[0], b[1]); w.w = cvt_pk_bf16(b[2], b[3]); return __builtin_bit_cast(bf16x8, w); }
; #define PG8_WAIT_V(n) asm volatile("s_waitcnt vmcnt(" #n ")" ::: "memory")
; #define PG8_WAIT_L(n) asm volatile("s_waitcnt lgkmcnt(" #n ")" ::: "memory")
; #define PG8_BAR __builtin_amdgcn_s_barrier()
; #define PG8_SCHED __builtin_amdgcn_sched_barrier(0)
; template <class Epi>
; DEV void gemm_phase(LAS unsigned char* lds, const Gemm g, const StaticOrder& S, const Epi& E) {
;     ...
;             PG8_BAR; PG8_WAIT_L(0); PG8_MMA(1, 0, At, B0); PG8_BAR; PG8_SCHED;
;             PG8_STAGE(PG8_SB(1, 1), b3 + hstep, voffB);
;             PG8_WAIT_V(6); PG8_BAR; PG8_MMA(1, 1, At, B1); PG8_BAR;
;     DEV void operator()(AccRef acc, const pg8::Unit& u, int wr, int wc, int fr, int fq) const {
;         const int row0 = u.pm * 256 + wr * 64 + fr, col0 = u.pn * 256 + wc * 32 + 8 * fq;
; #pragma unroll
;         for (int am = 0; am < 4; ++am) { const int ai = am >> 1, m0 = (am & 1) * 2;
;             f32x4 bv[4][2][2];
; #pragma unroll
;             for (int m = m0; m < m0 + 2; ++m)
; #pragma unroll
;                 for (int bj = 0; bj < 2; ++bj)
; #pragma unroll
;                     for (int n = 0; n < 2; ++n) bv[m][bj][n] = *(const f32x4*)(base + (size_t)(row0 + ai * 128 + m * 16) * 2048 + col0 + bj * 128 + n * 4);
; #pragma unroll
;             for (int m = m0; m < m0 + 2; ++m) { const size_t off = (size_t)(row0 + ai * 128 + m * 16) * 2048 + col0; float sq = 0.f;
; #pragma unroll
;                 for (int bj = 0; bj < 2; ++bj) { const f32x4 o0 = bv[m][bj][0] + scale * acc[ai][bj][m][0], o1 = bv[m][bj][1] + scale * acc[ai][bj][m][1];
;                     *(f32x4*)(out + off + bj * 128) = o0; *(f32x4*)(out + off + bj * 128 + 4) = o1;
;                     if (xb) { *(u32x4*)(xb + off + bj * 128) = __builtin_bit_cast(u32x4, pack8(o0, o1));
;                         sq += (o0[0] * o0[0] + o0[1] * o0[1] + o0[2] * o0[2] + o0[3] * o0[3]) + (o1[0] * o1[0] + o1[1] * o1[1] + o1[2] * o1[2] + o1[3] * o1[3]); } }
;                 if (ssout) { sq += __shfl_xor(sq, 16); sq += __shfl_xor(sq, 32);
;                     if (fq == 0) { if (red) red[(ai * 128 + wr * 64 + m * 16 + fr) * 4 + wc] = sq; else atomicAdd(ssout + (size_t)(row0 + ai * 128 + m * 16) * 8 + u.pn, sq); } } }
	s_waitcnt lgkmcnt(0)
	s_setprio 1
	v_mfma_f32_16x16x32_bf16 v[60:63], v[128:131], v[154:157], v[60:63]
	v_mfma_f32_16x16x32_bf16 v[56:59], v[136:139], v[154:157], v[56:59]
	v_mfma_f32_16x16x32_bf16 v[44:47], v[128:131], v[182:185], v[44:47]
	v_mfma_f32_16x16x32_bf16 v[40:43], v[136:139], v[182:185], v[40:43]
	v_mfma_f32_16x16x32_bf16 v[28:31], v[128:131], v[190:193], v[28:31]
	v_mfma_f32_16x16x32_bf16 v[24:27], v[136:139], v[190:193], v[24:27]
	v_mfma_f32_16x16x32_bf16 v[12:15], v[128:131], v[214:217], v[12:15]
	v_mfma_f32_16x16x32_bf16 v[8:11], v[136:139], v[214:217], v[8:11]
	v_mfma_f32_16x16x32_bf16 v[60:63], v[132:135], v[174:177], v[60:63]
	v_mfma_f32_16x16x32_bf16 v[56:59], v[140:143], v[174:177], v[56:59]
	v_mfma_f32_16x16x32_bf16 v[44:47], v[132:135], v[186:189], v[44:47]
	v_mfma_f32_16x16x32_bf16 v[40:43], v[140:143], v[186:189], v[40:43]
	v_mfma_f32_16x16x32_bf16 v[28:31], v[132:135], v[194:197], v[28:31]
	v_mfma_f32_16x16x32_bf16 v[24:27], v[140:143], v[194:197], v[24:27]
	v_mfma_f32_16x16x32_bf16 v[12:15], v[132:135], v[218:221], v[12:15]
	v_mfma_f32_16x16x32_bf16 v[8:11], v[140:143], v[218:221], v[8:11]
	s_setprio 0
	s_barrier
	s_add_u32 s28, s28, 0x100080
	s_addc_u32 s29, s29, 0
	s_add_i32 s30, s30, s36
	v_lshl_add_u64 v[128:129], s[28:29], 0, v[160:161]
	s_mov_b32 m0, s30
	s_nop 0
	global_load_lds_dwordx4 v[128:129], off
	v_lshl_add_u64 v[128:129], s[28:29], 0, v[148:149]
	s_add_i32 m0, s30, 0x2000
	s_nop 0
	global_load_lds_dwordx4 v[128:129], off
	s_waitcnt vmcnt(10)
	s_barrier
	s_setprio 1
	v_mfma_f32_16x16x32_bf16 v[52:55], v[222:225], v[154:157], v[52:55]
	v_mfma_f32_16x16x32_bf16 v[48:51], v[230:233], v[154:157], v[48:51]
	v_mfma_f32_16x16x32_bf16 v[36:39], v[222:225], v[182:185], v[36:39]
	v_mfma_f32_16x16x32_bf16 v[32:35], v[230:233], v[182:185], v[32:35]
	v_mfma_f32_16x16x32_bf16 v[20:23], v[222:225], v[190:193], v[20:23]
	v_mfma_f32_16x16x32_bf16 v[16:19], v[230:233], v[190:193], v[16:19]
	v_mfma_f32_16x16x32_bf16 v[4:7], v[222:225], v[214:217], v[4:7]
	v_mfma_f32_16x16x32_bf16 v[0:3], v[230:233], v[214:217], v[0:3]
	v_mfma_f32_16x16x32_bf16 v[52:55], v[226:229], v[174:177], v[52:55]
	v_mfma_f32_16x16x32_bf16 v[48:51], v[234:237], v[174:177], v[48:51]
	v_mfma_f32_16x16x32_bf16 v[36:39], v[226:229], v[186:189], v[36:39]
	v_mfma_f32_16x16x32_bf16 v[32:35], v[234:237], v[186:189], v[32:35]
	v_mfma_f32_16x16x32_bf16 v[20:23], v[226:229], v[194:197], v[20:23]
	v_mfma_f32_16x16x32_bf16 v[16:19], v[234:237], v[194:197], v[16:19]
	v_mfma_f32_16x16x32_bf16 v[4:7], v[226:229], v[218:221], v[4:7]
	v_mfma_f32_16x16x32_bf16 v[0:3], v[234:237], v[218:221], v[0:3]
	s_setprio 0
	s_add_i32 s48, s48, 2
	s_add_u32 s26, s26, 0x100
	s_addc_u32 s27, s27, 0
	s_add_u32 s46, s46, 0x100
	s_addc_u32 s47, s47, 0
	s_cmp_gt_u32 s48, 61
	s_barrier
	s_cbranch_scc0 .LBB0_404
	v_lshl_add_u32 v156, s24, 8, v167
	v_lshl_or_b32 v154, s14, 8, v179
	v_readlane_b32 s24, v254, 16
	v_ashrrev_i32_e32 v155, 31, v154
	v_readlane_b32 s25, v254, 17
	v_ashrrev_i32_e32 v157, 31, v156
	v_lshlrev_b64 v[128:129], 13, v[156:157]
	v_lshl_add_u64 v[158:159], v[154:155], 2, s[24:25]
	v_lshl_add_u64 v[214:215], v[158:159], 0, v[128:129]
	global_load_dwordx4 v[182:185], v[214:215], off offset:16
	global_load_dwordx4 v[186:189], v[214:215], off
	global_load_dwordx4 v[190:193], v[214:215], off offset:528
	global_load_dwordx4 v[194:197], v[214:215], off offset:512
	v_or_b32_e32 v174, 16, v156
	v_ashrrev_i32_e32 v175, 31, v174
	v_lshlrev_b64 v[128:129], 13, v[174:175]
	v_lshl_add_u64 v[176:177], v[158:159], 0, v[128:129]
	global_load_dwordx4 v[136:139], v[176:177], off offset:16
	global_load_dwordx4 v[140:143], v[176:177], off
	global_load_dwordx4 v[128:131], v[176:177], off offset:528
	global_load_dwordx4 v[132:135], v[176:177], off offset:512
	v_lshlrev_b64 v[216:217], 11, v[156:157]
	v_readlane_b32 s24, v250, 9
	v_lshl_add_u64 v[216:217], v[216:217], 0, v[154:155]
	v_readlane_b32 s25, v250, 10
	v_cmp_lt_i32_e32 vcc, v208, v206
	s_ashr_i32 s15, s14, 31
	s_waitcnt vmcnt(0)
	v_pk_add_f32 v[120:121], v[120:121], v[182:183]
	v_pk_add_f32 v[126:127], v[126:127], v[188:189]
	v_pk_add_f32 v[124:125], v[124:125], v[186:187]
	v_pk_add_f32 v[122:123], v[122:123], v[184:185]
	global_store_dwordx4 v[214:215], v[124:127], off
	global_store_dwordx4 v[214:215], v[120:123], off offset:16
	v_cvt_pk_bf16_f32 v184, v120, v121
	v_cvt_pk_bf16_f32 v182, v124, v125
	v_mul_f32_e32 v121, v121, v121
	v_cvt_pk_bf16_f32 v183, v126, v127
	v_cvt_pk_bf16_f32 v185, v122, v123
	v_lshl_add_u64 v[186:187], v[216:217], 1, s[24:25]
	v_fmac_f32_e32 v121, v120, v120
	v_pk_add_f32 v[118:119], v[118:119], v[196:197]
	v_pk_add_f32 v[116:117], v[116:117], v[194:195]
	v_pk_add_f32 v[112:113], v[112:113], v[190:191]
	global_store_dwordx4 v[186:187], v[182:185], off
	v_mul_f32_e32 v125, v125, v125
	v_fmac_f32_e32 v121, v122, v122
	v_pk_add_f32 v[114:115], v[114:115], v[192:193]
	global_store_dwordx4 v[214:215], v[116:119], off offset:512
	global_store_dwordx4 v[214:215], v[112:115], off offset:528
	v_cvt_pk_bf16_f32 v120, v116, v117
	v_cvt_pk_bf16_f32 v122, v112, v113
	v_mul_f32_e32 v117, v117, v117
	v_mul_f32_e32 v113, v113, v113
	v_fmac_f32_e32 v125, v124, v124
	v_fmac_f32_e32 v117, v116, v116
	v_fmac_f32_e32 v113, v112, v112
	v_fmac_f32_e32 v125, v126, v126
	v_fmac_f32_e32 v117, v118, v118
	v_fmac_f32_e32 v113, v114, v114
	v_fmac_f32_e32 v125, v127, v127
	v_fmac_f32_e32 v121, v123, v123
	v_fmac_f32_e32 v117, v119, v119
	v_fmac_f32_e32 v113, v115, v115
	v_add_f32_e32 v124, v125, v121
	v_add_f32_e32 v112, v117, v113
	v_cndmask_b32_e32 v113, v204, v208, vcc
	v_cvt_pk_bf16_f32 v121, v118, v119
	v_add_f32_e32 v112, v124, v112
	v_lshlrev_b32_e32 v118, 2, v113
	ds_bpermute_b32 v113, v118, v112
	v_cmp_lt_i32_e32 vcc, v207, v206
	v_cvt_pk_bf16_f32 v123, v114, v115
	global_store_dwordx4 v[186:187], v[120:123], off offset:256
	s_waitcnt lgkmcnt(0)
	v_add_f32_e32 v112, v112, v113
	v_cndmask_b32_e32 v113, v204, v207, vcc
	v_lshlrev_b32_e32 v119, 2, v113
	ds_bpermute_b32 v113, v119, v112
	s_and_saveexec_b64 s[24:25], s[6:7]
	s_cbranch_execz .LBB0_410
	s_waitcnt lgkmcnt(0)
	v_add_f32_e32 v112, v112, v113
	s_mov_b64 s[26:27], -1
	s_and_b64 vcc, exec, s[12:13]
	s_cbranch_vccz .LBB0_408
	v_readlane_b32 s26, v250, 59
	v_lshlrev_b64 v[114:115], 5, v[156:157]
	v_readlane_b32 s27, v250, 60
	s_nop 1
	v_lshl_add_u64 v[114:115], s[26:27], 0, v[114:115]
	v_lshl_add_u64 v[114:115], s[14:15], 2, v[114:115]
	global_atomic_add_f32 v[114:115], v112, off
	s_mov_b64 s[26:27], 0

; #define PG8_STAGE(bufoff, gbase, voff) do { _Pragma("unroll") for (int _i = 0; _i < 2; ++_i) \
;         __builtin_amdgcn_global_load_lds((const unsigned*)((const char*)(gbase) + (voff)[_i]), (LAS unsigned*)(lds + (bufoff) + ldsw + _i * 8192), 16, 0, 0); } while (0)
; #define PG8_LDA(dst, b, h) do { _Pragma("unroll") for (int m = 0; m < 4; ++m) _Pragma("unroll") for (int k = 0; k < 2; ++k) dst[m][k] = *(const LAS bf16x8*)(lds + PG8_SA(b, h) + aoff + m * 2048 + k * 1024); } while (0)
; #define PG8_LDB(dst, b, h) do { _Pragma("unroll") for (int n = 0; n < 2; ++n) _Pragma("unroll") for (int k = 0; k < 2; ++k) dst[n][k] = *(const LAS bf16x8*)(lds + PG8_SB(b, h) + boff + n * 2048 + k * 1024); } while (0)
; #define PG8_MMA(ai, bj, At, Bt) do { __builtin_amdgcn_s_setprio(1); _Pragma("unroll") for (int m = 0; m < 4; ++m) _Pragma("unroll") for (int n = 0; n < 2; ++n) _Pragma("unroll") for (int k = 0; k < 2; ++k) \
;         acc[ai][bj][m][n] = __builtin_amdgcn_mfma_f32_16x16x32_bf16(Bt[n][k], At[m][k], acc[ai][bj][m][n], 0, 0, 0); __builtin_amdgcn_s_setprio(0); } while (0)
; #define PG8_WAIT_L(n) asm volatile("s_waitcnt lgkmcnt(" #n ")" ::: "memory")
; #define PG8_BAR __builtin_amdgcn_s_barrier()
; #define PG8_SCHED __builtin_amdgcn_sched_barrier(0)
; template <class Epi>
; DEV void gemm_phase(LAS unsigned char* lds, const Gemm g, const StaticOrder& S, const Epi& E) {
;     ...
;             const bool last = (t == nt - 2);
;             const char* a1 = cA + (size_t)(t + 1) * kstep;
;             const char* a2 = last ? nA : cA + (size_t)(t + 2) * kstep; const char* b2 = last ? nB : cB + (size_t)(t + 2) * kstep;
;             const char* a3 = a2 + kstep; const char* b3 = b2 + kstep;
;             PG8_LDB(B0, 0, 0); PG8_SCHED; PG8_LDA(At, 0, 0); PG8_STAGE(PG8_SA(1, 1), a1 + hstep, voffA);
;             PG8_WAIT_L(8); PG8_BAR; PG8_WAIT_L(0); PG8_MMA(0, 0, At, B0); PG8_BAR; PG8_SCHED;
;             PG8_LDB(B1, 0, 1); PG8_STAGE(PG8_SB(0, 0), b2, voffB);
;             PG8_BAR; PG8_WAIT_L(0); PG8_MMA(0, 1, At, B1); PG8_BAR;
;             PG8_LDA(At, 0, 1); PG8_STAGE(PG8_SA(0, 0), a2, voffA);
;             PG8_BAR; PG8_WAIT_L(0); PG8_MMA(1, 0, At, B0); PG8_BAR; PG8_SCHED;
.LBB0_588:
	s_add_u32 s16, s14, 0xfff80080
	s_addc_u32 s17, s15, -1
	s_add_i32 s41, 0, 0x10000
	v_add_u32_e32 v154, s41, v167
	ds_read_b128 v[128:131], v154
	ds_read_b128 v[132:135], v154 offset:1024
	ds_read_b128 v[150:153], v154 offset:2048
	ds_read_b128 v[174:177], v154 offset:3072
	s_cmp_eq_u32 s40, 28
	s_cselect_b32 s19, s1, s17
	s_cselect_b32 s18, s9, s16
	s_cselect_b32 s17, s7, s37
	s_cselect_b32 s16, s35, s36
	v_lshl_add_u64 v[154:155], s[14:15], 0, v[146:147]
	s_add_i32 m0, s24, 0xc000
	ds_read_b128 v[182:185], v219
	ds_read_b128 v[190:193], v219 offset:1024
	ds_read_b128 v[194:197], v219 offset:2048
	ds_read_b128 v[220:223], v219 offset:3072
	ds_read_b128 v[224:227], v219 offset:4096
	ds_read_b128 v[228:231], v219 offset:5120
	ds_read_b128 v[232:235], v219 offset:6144
	ds_read_b128 v[236:239], v219 offset:7168
	global_load_lds_dwordx4 v[154:155], off
	v_lshl_add_u64 v[154:155], s[14:15], 0, v[148:149]
	s_add_i32 m0, s24, 0xe000
	s_nop 0
	global_load_lds_dwordx4 v[154:155], off
	s_waitcnt lgkmcnt(8)
	s_waitcnt vmcnt(10)
	s_barrier
	s_waitcnt lgkmcnt(0)
	s_setprio 1
	v_mfma_f32_16x16x32_bf16 v[124:127], v[128:131], v[182:185], v[124:127]
	v_mfma_f32_16x16x32_bf16 v[120:123], v[150:153], v[182:185], v[120:123]
	v_mfma_f32_16x16x32_bf16 v[108:111], v[128:131], v[194:197], v[108:111]
	v_mfma_f32_16x16x32_bf16 v[104:107], v[150:153], v[194:197], v[104:107]
	v_mfma_f32_16x16x32_bf16 v[92:95], v[128:131], v[224:227], v[92:95]
	v_mfma_f32_16x16x32_bf16 v[88:91], v[150:153], v[224:227], v[88:91]
	v_mfma_f32_16x16x32_bf16 v[76:79], v[128:131], v[232:235], v[76:79]
	v_mfma_f32_16x16x32_bf16 v[72:75], v[150:153], v[232:235], v[72:75]
	v_mfma_f32_16x16x32_bf16 v[124:127], v[132:135], v[190:193], v[124:127]
	v_mfma_f32_16x16x32_bf16 v[120:123], v[174:177], v[190:193], v[120:123]
	v_mfma_f32_16x16x32_bf16 v[108:111], v[132:135], v[220:223], v[108:111]
	v_mfma_f32_16x16x32_bf16 v[104:107], v[174:177], v[220:223], v[104:107]
	v_mfma_f32_16x16x32_bf16 v[92:95], v[132:135], v[228:231], v[92:95]
	v_mfma_f32_16x16x32_bf16 v[88:91], v[174:177], v[228:231], v[88:91]
	v_mfma_f32_16x16x32_bf16 v[76:79], v[132:135], v[236:239], v[76:79]
	v_mfma_f32_16x16x32_bf16 v[72:75], v[174:177], v[236:239], v[72:75]
	s_setprio 0
	s_barrier
	s_add_i32 s44, 0, 0x14000
	v_add_u32_e32 v154, s44, v167
	s_add_i32 s41, s41, s22
	ds_read_b128 v[240:243], v154
	ds_read_b128 v[244:247], v154 offset:1024
	ds_read_b128 v[186:189], v154 offset:2048
	ds_read_b128 v[214:217], v154 offset:3072
	v_lshl_add_u64 v[154:155], s[16:17], 0, v[140:141]
	s_mov_b32 m0, s41
	v_lshl_add_u64 v[158:159], s[16:17], 0, v[136:137]
	global_load_lds_dwordx4 v[154:155], off
	s_add_i32 m0, s41, 0x2000
	s_nop 0
	global_load_lds_dwordx4 v[158:159], off
	s_waitcnt vmcnt(10)
	s_barrier
	s_waitcnt lgkmcnt(0)
	s_setprio 1
	v_mfma_f32_16x16x32_bf16 v[116:119], v[240:243], v[182:185], v[116:119]
	v_mfma_f32_16x16x32_bf16 v[112:115], v[186:189], v[182:185], v[112:115]
	v_mfma_f32_16x16x32_bf16 v[100:103], v[240:243], v[194:197], v[100:103]
	v_mfma_f32_16x16x32_bf16 v[96:99], v[186:189], v[194:197], v[96:99]
	v_mfma_f32_16x16x32_bf16 v[84:87], v[240:243], v[224:227], v[84:87]
	v_mfma_f32_16x16x32_bf16 v[80:83], v[186:189], v[224:227], v[80:83]
	v_mfma_f32_16x16x32_bf16 v[68:71], v[240:243], v[232:235], v[68:71]
	v_mfma_f32_16x16x32_bf16 v[64:67], v[186:189], v[232:235], v[64:67]
	v_mfma_f32_16x16x32_bf16 v[116:119], v[244:247], v[190:193], v[116:119]
	v_mfma_f32_16x16x32_bf16 v[112:115], v[214:217], v[190:193], v[112:115]
	v_mfma_f32_16x16x32_bf16 v[100:103], v[244:247], v[220:223], v[100:103]
	v_mfma_f32_16x16x32_bf16 v[96:99], v[214:217], v[220:223], v[96:99]
	v_mfma_f32_16x16x32_bf16 v[84:87], v[244:247], v[228:231], v[84:87]
	v_mfma_f32_16x16x32_bf16 v[80:83], v[214:217], v[228:231], v[80:83]
	v_mfma_f32_16x16x32_bf16 v[68:71], v[244:247], v[236:239], v[68:71]
	v_mfma_f32_16x16x32_bf16 v[64:67], v[214:217], v[236:239], v[64:67]
	s_setprio 0
	s_mov_b32 m0, s24
	v_lshl_add_u64 v[178:179], s[18:19], 0, v[142:143]
	s_barrier
	ds_read_b128 v[182:185], v219 offset:16384
	ds_read_b128 v[190:193], v219 offset:17408
	ds_read_b128 v[194:197], v219 offset:18432
	ds_read_b128 v[220:223], v219 offset:19456
	ds_read_b128 v[224:227], v219 offset:20480
	ds_read_b128 v[228:231], v219 offset:21504
	ds_read_b128 v[232:235], v219 offset:22528
	ds_read_b128 v[236:239], v219 offset:23552
	global_load_lds_dwordx4 v[178:179], off
	v_lshl_add_u64 v[248:249], s[18:19], 0, v[138:139]
	s_mov_b32 m0, s25
	s_nop 0
	global_load_lds_dwordx4 v[248:249], off
	s_barrier
	s_waitcnt lgkmcnt(0)
	s_setprio 1
	v_mfma_f32_16x16x32_bf16 v[60:63], v[128:131], v[182:185], v[60:63]
	v_mfma_f32_16x16x32_bf16 v[56:59], v[150:153], v[182:185], v[56:59]
	v_mfma_f32_16x16x32_bf16 v[44:47], v[128:131], v[194:197], v[44:47]
	v_mfma_f32_16x16x32_bf16 v[40:43], v[150:153], v[194:197], v[40:43]
	v_mfma_f32_16x16x32_bf16 v[28:31], v[128:131], v[224:227], v[28:31]
	v_mfma_f32_16x16x32_bf16 v[24:27], v[150:153], v[224:227], v[24:27]
	v_mfma_f32_16x16x32_bf16 v[12:15], v[128:131], v[232:235], v[12:15]
	v_mfma_f32_16x16x32_bf16 v[8:11], v[150:153], v[232:235], v[8:11]
	v_mfma_f32_16x16x32_bf16 v[60:63], v[132:135], v[190:193], v[60:63]
	v_mfma_f32_16x16x32_bf16 v[56:59], v[174:177], v[190:193], v[56:59]
	v_mfma_f32_16x16x32_bf16 v[44:47], v[132:135], v[220:223], v[44:47]
	v_mfma_f32_16x16x32_bf16 v[40:43], v[174:177], v[220:223], v[40:43]
	v_mfma_f32_16x16x32_bf16 v[28:31], v[132:135], v[228:231], v[28:31]
	v_mfma_f32_16x16x32_bf16 v[24:27], v[174:177], v[228:231], v[24:27]
	v_mfma_f32_16x16x32_bf16 v[12:15], v[132:135], v[236:239], v[12:15]
	v_mfma_f32_16x16x32_bf16 v[8:11], v[174:177], v[236:239], v[8:11]
	s_setprio 0
	s_barrier
; #define PG8_STAGE(bufoff, gbase, voff) do { _Pragma("unroll") for (int _i = 0; _i < 2; ++_i) \
;         __builtin_amdgcn_global_load_lds((const unsigned*)((const char*)(gbase) + (voff)[_i]), (LAS unsigned*)(lds + (bufoff) + ldsw + _i * 8192), 16, 0, 0); } while (0)
; #define PG8_LDA(dst, b, h) do { _Pragma("unroll") for (int m = 0; m < 4; ++m) _Pragma("unroll") for (int k = 0; k < 2; ++k) dst[m][k] = *(const LAS bf16x8*)(lds + PG8_SA(b, h) + aoff + m * 2048 + k * 1024); } while (0)
; #define PG8_LDB(dst, b, h) do { _Pragma("unroll") for (int n = 0; n < 2; ++n) _Pragma("unroll") for (int k = 0; k < 2; ++k) dst[n][k] = *(const LAS bf16x8*)(lds + PG8_SB(b, h) + boff + n * 2048 + k * 1024); } while (0)
; #define PG8_MMA(ai, bj, At, Bt) do { __builtin_amdgcn_s_setprio(1); _Pragma("unroll") for (int m = 0; m < 4; ++m) _Pragma("unroll") for (int n = 0; n < 2; ++n) _Pragma("unroll") for (int k = 0; k < 2; ++k) \
;         acc[ai][bj][m][n] = __builtin_amdgcn_mfma_f32_16x16x32_bf16(Bt[n][k], At[m][k], acc[ai][bj][m][n], 0, 0, 0); __builtin_amdgcn_s_setprio(0); } while (0)
; #define PG8_WAIT_V(n) asm volatile("s_waitcnt vmcnt(" #n ")" ::: "memory")
; #define PG8_WAIT_L(n) asm volatile("s_waitcnt lgkmcnt(" #n ")" ::: "memory")
; #define PG8_BAR __builtin_amdgcn_s_barrier()
; #define PG8_SCHED __builtin_amdgcn_sched_barrier(0)
; template <class Epi>
; DEV void gemm_phase(LAS unsigned char* lds, const Gemm g, const StaticOrder& S, const Epi& E) {
;     ...
;             PG8_STAGE(PG8_SB(0, 1), b2 + hstep, voffB);
;             PG8_WAIT_V(6); PG8_BAR; PG8_MMA(1, 1, At, B1); PG8_BAR;
;             PG8_LDB(B0, 1, 0); PG8_SCHED; PG8_LDA(At, 1, 0); PG8_STAGE(PG8_SA(0, 1), a2 + hstep, voffA);
;             PG8_WAIT_L(8); PG8_BAR; PG8_WAIT_L(0); PG8_MMA(0, 0, At, B0); PG8_BAR; PG8_SCHED;
;             PG8_LDB(B1, 1, 1); PG8_STAGE(PG8_SB(1, 0), b3, voffB);
;             PG8_BAR; PG8_WAIT_L(0); PG8_MMA(0, 1, At, B1); PG8_BAR;
;             PG8_LDA(At, 1, 1); PG8_STAGE(PG8_SA(1, 0), a3, voffA);
	s_add_u32 s42, s16, 0x80000
	s_addc_u32 s43, s17, 0
	s_add_i32 s41, s44, s22
	v_lshl_add_u64 v[128:129], s[42:43], 0, v[140:141]
	s_mov_b32 m0, s41
	s_nop 0
	global_load_lds_dwordx4 v[128:129], off
	v_lshl_add_u64 v[128:129], s[42:43], 0, v[136:137]
	s_add_i32 m0, s41, 0x2000
	s_nop 0
	global_load_lds_dwordx4 v[128:129], off
	s_waitcnt vmcnt(10)
	s_barrier
	s_setprio 1
	v_mfma_f32_16x16x32_bf16 v[52:55], v[240:243], v[182:185], v[52:55]
	v_mfma_f32_16x16x32_bf16 v[48:51], v[186:189], v[182:185], v[48:51]
	v_mfma_f32_16x16x32_bf16 v[36:39], v[240:243], v[194:197], v[36:39]
	v_mfma_f32_16x16x32_bf16 v[32:35], v[186:189], v[194:197], v[32:35]
	v_mfma_f32_16x16x32_bf16 v[20:23], v[240:243], v[224:227], v[20:23]
	v_mfma_f32_16x16x32_bf16 v[16:19], v[186:189], v[224:227], v[16:19]
	v_mfma_f32_16x16x32_bf16 v[4:7], v[240:243], v[232:235], v[4:7]
	v_mfma_f32_16x16x32_bf16 v[0:3], v[186:189], v[232:235], v[0:3]
	v_mfma_f32_16x16x32_bf16 v[52:55], v[244:247], v[190:193], v[52:55]
	v_mfma_f32_16x16x32_bf16 v[48:51], v[214:217], v[190:193], v[48:51]
	v_mfma_f32_16x16x32_bf16 v[36:39], v[244:247], v[220:223], v[36:39]
	v_mfma_f32_16x16x32_bf16 v[32:35], v[214:217], v[220:223], v[32:35]
	v_mfma_f32_16x16x32_bf16 v[20:23], v[244:247], v[228:231], v[20:23]
	v_mfma_f32_16x16x32_bf16 v[16:19], v[214:217], v[228:231], v[16:19]
	v_mfma_f32_16x16x32_bf16 v[4:7], v[244:247], v[236:239], v[4:7]
	v_mfma_f32_16x16x32_bf16 v[0:3], v[214:217], v[236:239], v[0:3]
	s_setprio 0
	s_add_i32 s41, 0, 0x18000
	v_add_u32_e32 v156, s41, v167
	s_barrier
	ds_read_b128 v[128:131], v156
	ds_read_b128 v[132:135], v156 offset:1024
	ds_read_b128 v[150:153], v156 offset:2048
	ds_read_b128 v[174:177], v156 offset:3072
	s_add_u32 s18, s18, 0x80000
	s_addc_u32 s19, s19, 0
	s_mov_b32 m0, s26
	v_lshl_add_u64 v[232:233], s[18:19], 0, v[142:143]
	ds_read_b128 v[182:185], v219 offset:32768
	ds_read_b128 v[186:189], v219 offset:33792
	ds_read_b128 v[190:193], v219 offset:34816
	ds_read_b128 v[194:197], v219 offset:35840
	ds_read_b128 v[214:217], v219 offset:36864
	ds_read_b128 v[220:223], v219 offset:37888
	ds_read_b128 v[224:227], v219 offset:38912
	ds_read_b128 v[228:231], v219 offset:39936
	global_load_lds_dwordx4 v[232:233], off
	v_lshl_add_u64 v[232:233], s[18:19], 0, v[138:139]
	s_mov_b32 m0, s27
	s_nop 0
	global_load_lds_dwordx4 v[232:233], off
	s_waitcnt lgkmcnt(8)
	s_waitcnt vmcnt(10)
	s_barrier
	s_waitcnt lgkmcnt(0)
	s_setprio 1
	v_mfma_f32_16x16x32_bf16 v[124:127], v[128:131], v[182:185], v[124:127]
	v_mfma_f32_16x16x32_bf16 v[120:123], v[150:153], v[182:185], v[120:123]
	v_mfma_f32_16x16x32_bf16 v[108:111], v[128:131], v[190:193], v[108:111]
	v_mfma_f32_16x16x32_bf16 v[104:107], v[150:153], v[190:193], v[104:107]
	v_mfma_f32_16x16x32_bf16 v[92:95], v[128:131], v[214:217], v[92:95]
	v_mfma_f32_16x16x32_bf16 v[88:91], v[150:153], v[214:217], v[88:91]
	v_mfma_f32_16x16x32_bf16 v[76:79], v[128:131], v[224:227], v[76:79]
	v_mfma_f32_16x16x32_bf16 v[72:75], v[150:153], v[224:227], v[72:75]
	v_mfma_f32_16x16x32_bf16 v[124:127], v[132:135], v[186:189], v[124:127]
	v_mfma_f32_16x16x32_bf16 v[120:123], v[174:177], v[186:189], v[120:123]
	v_mfma_f32_16x16x32_bf16 v[108:111], v[132:135], v[194:197], v[108:111]
	v_mfma_f32_16x16x32_bf16 v[104:107], v[174:177], v[194:197], v[104:107]
	v_mfma_f32_16x16x32_bf16 v[92:95], v[132:135], v[220:223], v[92:95]
	v_mfma_f32_16x16x32_bf16 v[88:91], v[174:177], v[220:223], v[88:91]
	v_mfma_f32_16x16x32_bf16 v[76:79], v[132:135], v[228:231], v[76:79]
	v_mfma_f32_16x16x32_bf16 v[72:75], v[174:177], v[228:231], v[72:75]
	s_setprio 0
	s_barrier
	s_add_i32 s18, 0, 0x1c000
	s_add_i32 s19, s41, s22
	v_add_u32_e32 v156, s18, v167
	v_lshl_add_u64 v[154:155], v[154:155], 0, s[2:3]
	s_mov_b32 m0, s19
	ds_read_b128 v[232:235], v156
	ds_read_b128 v[236:239], v156 offset:1024
	ds_read_b128 v[240:243], v156 offset:2048
	ds_read_b128 v[244:247], v156 offset:3072
	global_load_lds_dwordx4 v[154:155], off
	v_lshl_add_u64 v[154:155], v[158:159], 0, s[2:3]
	s_add_i32 m0, s19, 0x2000
	s_nop 0
	global_load_lds_dwordx4 v[154:155], off
	s_waitcnt vmcnt(10)
	s_barrier
	s_waitcnt lgkmcnt(0)
	s_setprio 1
	v_mfma_f32_16x16x32_bf16 v[116:119], v[232:235], v[182:185], v[116:119]
	v_mfma_f32_16x16x32_bf16 v[112:115], v[240:243], v[182:185], v[112:115]
	v_mfma_f32_16x16x32_bf16 v[100:103], v[232:235], v[190:193], v[100:103]
	v_mfma_f32_16x16x32_bf16 v[96:99], v[240:243], v[190:193], v[96:99]
	v_mfma_f32_16x16x32_bf16 v[84:87], v[232:235], v[214:217], v[84:87]
	v_mfma_f32_16x16x32_bf16 v[80:83], v[240:243], v[214:217], v[80:83]
	v_mfma_f32_16x16x32_bf16 v[68:71], v[232:235], v[224:227], v[68:71]
	v_mfma_f32_16x16x32_bf16 v[64:67], v[240:243], v[224:227], v[64:67]
	v_mfma_f32_16x16x32_bf16 v[116:119], v[236:239], v[186:189], v[116:119]
	v_mfma_f32_16x16x32_bf16 v[112:115], v[244:247], v[186:189], v[112:115]
	v_mfma_f32_16x16x32_bf16 v[100:103], v[236:239], v[194:197], v[100:103]
	v_mfma_f32_16x16x32_bf16 v[96:99], v[244:247], v[194:197], v[96:99]
	v_mfma_f32_16x16x32_bf16 v[84:87], v[236:239], v[220:223], v[84:87]
	v_mfma_f32_16x16x32_bf16 v[80:83], v[244:247], v[220:223], v[80:83]
	v_mfma_f32_16x16x32_bf16 v[68:71], v[236:239], v[228:231], v[68:71]
	v_mfma_f32_16x16x32_bf16 v[64:67], v[244:247], v[228:231], v[64:67]
	s_setprio 0
	s_mov_b32 m0, s28
	v_lshl_add_u64 v[154:155], v[178:179], 0, s[2:3]
	s_barrier
	ds_read_b128 v[182:185], v219 offset:49152
	ds_read_b128 v[186:189], v219 offset:50176
	ds_read_b128 v[190:193], v219 offset:51200
	ds_read_b128 v[194:197], v219 offset:52224
	ds_read_b128 v[214:217], v219 offset:53248
	ds_read_b128 v[220:223], v219 offset:54272
	ds_read_b128 v[224:227], v219 offset:55296
	ds_read_b128 v[228:231], v219 offset:56320
	global_load_lds_dwordx4 v[154:155], off
	v_lshl_add_u64 v[154:155], v[248:249], 0, s[2:3]
	s_mov_b32 m0, s29
	s_nop 0
	global_load_lds_dwordx4 v[154:155], off
	s_barrier
; #define PG8_STAGE(bufoff, gbase, voff) do { _Pragma("unroll") for (int _i = 0; _i < 2; ++_i) \
;         __builtin_amdgcn_global_load_lds((const unsigned*)((const char*)(gbase) + (voff)[_i]), (LAS unsigned*)(lds + (bufoff) + ldsw + _i * 8192), 16, 0, 0); } while (0)
; #define PG8_MMA(ai, bj, At, Bt) do { __builtin_amdgcn_s_setprio(1); _Pragma("unroll") for (int m = 0; m < 4; ++m) _Pragma("unroll") for (int n = 0; n < 2; ++n) _Pragma("unroll") for (int k = 0; k < 2; ++k) \
;         acc[ai][bj][m][n] = __builtin_amdgcn_mfma_f32_16x16x32_bf16(Bt[n][k], At[m][k], acc[ai][bj][m][n], 0, 0, 0); __builtin_amdgcn_s_setprio(0); } while (0)
; #define PG8_WAIT_V(n) asm volatile("s_waitcnt vmcnt(" #n ")" ::: "memory")
; #define PG8_WAIT_L(n) asm volatile("s_waitcnt lgkmcnt(" #n ")" ::: "memory")
; #define PG8_BAR __builtin_amdgcn_s_barrier()
; #define PG8_SCHED __builtin_amdgcn_sched_barrier(0)
;     DEV void operator()(AccRef acc, const pg8::Unit& u, int wr, int wc, int fr, int fq) const { store_bf16_tile<0, false>(acc, O, ld, u.pm * 256 + wr * 64 + fr, u.pn * 256 + wc * 32 + 4 * fq, ss); }
; template <class Epi>
; DEV void gemm_phase(LAS unsigned char* lds, const Gemm g, const StaticOrder& S, const Epi& E) {
;     ...
;             PG8_BAR; PG8_WAIT_L(0); PG8_MMA(1, 0, At, B0); PG8_BAR; PG8_SCHED;
;             PG8_STAGE(PG8_SB(1, 1), b3 + hstep, voffB);
;             PG8_WAIT_V(6); PG8_BAR; PG8_MMA(1, 1, At, B1); PG8_BAR;
;     DEV void operator()(AccRef acc, const pg8::Unit& u, int wr, int wc, int fr, int fq) const {
;         const int ct = u.pn * 256, row0 = u.pm * 256 + wr * 64 + fr, cw = wc * 32 + 8 * fq;
;         if (ct < 4096) store_bf16_tile<1, true>(acc, UV, 4096, row0, ct + cw, ss);
;         else if (ct < 6144) store_bf16_tile<0, true>(acc, Z, 2048, row0, ct - 4096 + cw, ss);
;         else if (ct < 9216) store_bf16_tile<0, true>(acc, XBC, 3072, row0, ct - 6144 + cw, ss);
;         else if (wc == 0) {
; #pragma unroll
;             for (int ai = 0; ai < 2; ++ai)
; #pragma unroll
;                 for (int m = 0; m < 4; ++m) { const float rs = rowscale(ss, row0 + ai * 128 + m * 16);
; #pragma unroll
;                     for (int n = 0; n < 2; ++n) *(f32x4*)(DTR + (size_t)(row0 + ai * 128 + m * 16) * 32 + 8 * fq + 4 * n) = acc[ai][0][m][n] * rs; }
	s_waitcnt lgkmcnt(0)
	s_setprio 1
	v_mfma_f32_16x16x32_bf16 v[60:63], v[128:131], v[182:185], v[60:63]
	v_mfma_f32_16x16x32_bf16 v[56:59], v[150:153], v[182:185], v[56:59]
	v_mfma_f32_16x16x32_bf16 v[44:47], v[128:131], v[190:193], v[44:47]
	v_mfma_f32_16x16x32_bf16 v[40:43], v[150:153], v[190:193], v[40:43]
	v_mfma_f32_16x16x32_bf16 v[28:31], v[128:131], v[214:217], v[28:31]
	v_mfma_f32_16x16x32_bf16 v[24:27], v[150:153], v[214:217], v[24:27]
	v_mfma_f32_16x16x32_bf16 v[12:15], v[128:131], v[224:227], v[12:15]
	v_mfma_f32_16x16x32_bf16 v[8:11], v[150:153], v[224:227], v[8:11]
	v_mfma_f32_16x16x32_bf16 v[60:63], v[132:135], v[186:189], v[60:63]
	v_mfma_f32_16x16x32_bf16 v[56:59], v[174:177], v[186:189], v[56:59]
	v_mfma_f32_16x16x32_bf16 v[44:47], v[132:135], v[194:197], v[44:47]
	v_mfma_f32_16x16x32_bf16 v[40:43], v[174:177], v[194:197], v[40:43]
	v_mfma_f32_16x16x32_bf16 v[28:31], v[132:135], v[220:223], v[28:31]
	v_mfma_f32_16x16x32_bf16 v[24:27], v[174:177], v[220:223], v[24:27]
	v_mfma_f32_16x16x32_bf16 v[12:15], v[132:135], v[228:231], v[12:15]
	v_mfma_f32_16x16x32_bf16 v[8:11], v[174:177], v[228:231], v[8:11]
	s_setprio 0
	s_barrier
	s_add_u32 s16, s16, 0x80080
	s_addc_u32 s17, s17, 0
	s_add_i32 s18, s18, s22
	v_lshl_add_u64 v[128:129], s[16:17], 0, v[140:141]
	s_mov_b32 m0, s18
	s_nop 0
	global_load_lds_dwordx4 v[128:129], off
	v_lshl_add_u64 v[128:129], s[16:17], 0, v[136:137]
	s_add_i32 m0, s18, 0x2000
	s_nop 0
	global_load_lds_dwordx4 v[128:129], off
	s_waitcnt vmcnt(10)
	s_barrier
	s_setprio 1
	v_mfma_f32_16x16x32_bf16 v[52:55], v[232:235], v[182:185], v[52:55]
	v_mfma_f32_16x16x32_bf16 v[48:51], v[240:243], v[182:185], v[48:51]
	v_mfma_f32_16x16x32_bf16 v[36:39], v[232:235], v[190:193], v[36:39]
	v_mfma_f32_16x16x32_bf16 v[32:35], v[240:243], v[190:193], v[32:35]
	v_mfma_f32_16x16x32_bf16 v[20:23], v[232:235], v[214:217], v[20:23]
	v_mfma_f32_16x16x32_bf16 v[16:19], v[240:243], v[214:217], v[16:19]
	v_mfma_f32_16x16x32_bf16 v[4:7], v[232:235], v[224:227], v[4:7]
	v_mfma_f32_16x16x32_bf16 v[0:3], v[240:243], v[224:227], v[0:3]
	v_mfma_f32_16x16x32_bf16 v[52:55], v[236:239], v[186:189], v[52:55]
	v_mfma_f32_16x16x32_bf16 v[48:51], v[244:247], v[186:189], v[48:51]
	v_mfma_f32_16x16x32_bf16 v[36:39], v[236:239], v[194:197], v[36:39]
	v_mfma_f32_16x16x32_bf16 v[32:35], v[244:247], v[194:197], v[32:35]
	v_mfma_f32_16x16x32_bf16 v[20:23], v[236:239], v[220:223], v[20:23]
	v_mfma_f32_16x16x32_bf16 v[16:19], v[244:247], v[220:223], v[16:19]
	v_mfma_f32_16x16x32_bf16 v[4:7], v[236:239], v[228:231], v[4:7]
	v_mfma_f32_16x16x32_bf16 v[0:3], v[244:247], v[228:231], v[0:3]
	s_setprio 0
	s_add_i32 s40, s40, 2
	s_add_u32 s14, s14, 0x100
	s_addc_u32 s15, s15, 0
	s_add_u32 s36, s36, 0x100
	s_addc_u32 s37, s37, 0
	s_cmp_gt_u32 s40, 29
	s_barrier
	s_cbranch_scc0 .LBB0_588
	s_lshl_b32 s7, s34, 8
	v_lshl_add_u32 v150, s0, 8, v157
	s_cmp_gt_i32 s34, 15
	s_mov_b64 s[0:1], -1
	s_cbranch_scc0 .LBB0_601
	s_cmp_gt_u32 s34, 23
	s_cbranch_scc0 .LBB0_598
	s_cmp_gt_u32 s34, 35
	s_cbranch_scc0 .LBB0_595
	s_andn2_b64 vcc, exec, s[4:5]
	s_cbranch_vccnz .LBB0_594
	v_ashrrev_i32_e32 v151, 31, v150
	v_readlane_b32 s0, v251, 39
	v_lshlrev_b64 v[128:129], 5, v[150:151]
	v_readlane_b32 s1, v251, 40
	s_mov_b32 s9, 0x800000
	s_nop 0
	v_lshl_add_u64 v[132:133], s[0:1], 0, v[128:129]
	global_load_dwordx4 v[128:131], v[132:133], off offset:16
	s_nop 0
	global_load_dwordx4 v[132:135], v[132:133], off
	s_waitcnt vmcnt(0)
	v_mov_b32_e32 v152, v133
	v_mov_b32_e32 v153, v134
	v_mov_b32_e32 v133, v135
	v_pk_add_f32 v[132:133], v[152:153], v[132:133]
	v_mov_b32_e32 v134, v130
	v_mov_b32_e32 v135, v128
	v_mov_b32_e32 v128, v131
	v_pk_add_f32 v[128:129], v[134:135], v[128:129]
	v_add_f32_e32 v130, v132, v133
	v_add_f32_e32 v129, v130, v129
	v_add_f32_e32 v128, v128, v129
	v_fmamk_f32 v128, v128, 0x3a000000, v199
	v_cmp_gt_f32_e32 vcc, s9, v128
	v_mul_f32_e32 v129, 0x4b800000, v128
	v_lshlrev_b64 v[134:135], 7, v[150:151]
	v_cndmask_b32_e32 v128, v128, v129, vcc
	v_rsq_f32_e32 v128, v128
	v_lshl_add_u64 v[134:135], v[144:145], 0, v[134:135]
	v_or_b32_e32 v152, 16, v150
	v_ashrrev_i32_e32 v153, 31, v152
	v_mul_f32_e32 v129, 0x45800000, v128
	v_cndmask_b32_e32 v132, v128, v129, vcc
	v_pk_mul_f32 v[130:131], v[126:127], v[132:133] op_sel_hi:[1,0]
	v_pk_mul_f32 v[128:129], v[124:125], v[132:133] op_sel_hi:[1,0]
	global_store_dwordx4 v[134:135], v[128:131], off
	s_nop 1
	v_pk_mul_f32 v[130:131], v[122:123], v[132:133] op_sel_hi:[1,0]
	v_pk_mul_f32 v[128:129], v[120:121], v[132:133] op_sel_hi:[1,0]
	global_store_dwordx4 v[134:135], v[128:131], off offset:16
	s_nop 1
	v_lshlrev_b64 v[128:129], 5, v[152:153]
	v_lshl_add_u64 v[132:133], s[0:1], 0, v[128:129]
	global_load_dwordx4 v[128:131], v[132:133], off offset:16
	s_nop 0
	global_load_dwordx4 v[132:135], v[132:133], off
	s_waitcnt vmcnt(0)
	v_mov_b32_e32 v154, v133
	v_mov_b32_e32 v155, v134
	v_mov_b32_e32 v133, v135
	v_pk_add_f32 v[132:133], v[154:155], v[132:133]
	v_mov_b32_e32 v134, v130
	v_mov_b32_e32 v135, v128
	v_mov_b32_e32 v128, v131
	v_pk_add_f32 v[128:129], v[134:135], v[128:129]
	v_add_f32_e32 v130, v132, v133
	v_add_f32_e32 v129, v130, v129
	v_add_f32_e32 v128, v128, v129
	v_fmamk_f32 v128, v128, 0x3a000000, v199
	v_cmp_gt_f32_e32 vcc, s9, v128
	v_mul_f32_e32 v129, 0x4b800000, v128
	v_lshlrev_b64 v[134:135], 7, v[152:153]
	v_cndmask_b32_e32 v128, v128, v129, vcc
	v_rsq_f32_e32 v128, v128
	v_lshl_add_u64 v[134:135], v[144:145], 0, v[134:135]
	v_or_b32_e32 v152, 32, v150
	v_ashrrev_i32_e32 v153, 31, v152
	v_mul_f32_e32 v129, 0x45800000, v128
	v_cndmask_b32_e32 v132, v128, v129, vcc
	v_pk_mul_f32 v[130:131], v[110:111], v[132:133] op_sel_hi:[1,0]
	v_pk_mul_f32 v[128:129], v[108:109], v[132:133] op_sel_hi:[1,0]
	global_store_dwordx4 v[134:135], v[128:131], off
	s_nop 1
	v_pk_mul_f32 v[130:131], v[106:107], v[132:133] op_sel_hi:[1,0]
	v_pk_mul_f32 v[128:129], v[104:105], v[132:133] op_sel_hi:[1,0]
	global_store_dwordx4 v[134:135], v[128:131], off offset:16
	s_nop 1
	v_lshlrev_b64 v[128:129], 5, v[152:153]
	v_lshl_add_u64 v[132:133], s[0:1], 0, v[128:129]
	global_load_dwordx4 v[128:131], v[132:133], off offset:16
	s_nop 0
	global_load_dwordx4 v[132:135], v[132:133], off
	s_waitcnt vmcnt(0)
; DEV float rowscale(const float* ss, int row) { const f32x4 a = *(const f32x4*)(ss + (size_t)row * 8), b = *(const f32x4*)(ss + (size_t)row * 8 + 4);
;     return rsqrtf(((a[0] + a[1]) + (a[2] + a[3]) + (b[0] + b[1]) + (b[2] + b[3])) * (1.0f / 2048.0f) + EPS); }
;     DEV void operator()(AccRef acc, const pg8::Unit& u, int wr, int wc, int fr, int fq) const {
;     ...
;                 for (int m = 0; m < 4; ++m) { const float rs = rowscale(ss, row0 + ai * 128 + m * 16);
; #pragma unroll
;                     for (int n = 0; n < 2; ++n) *(f32x4*)(DTR + (size_t)(row0 + ai * 128 + m * 16) * 32 + 8 * fq + 4 * n) = acc[ai][0][m][n] * rs; }
	v_mov_b32_e32 v154, v133
	v_mov_b32_e32 v155, v134
	v_mov_b32_e32 v133, v135
	v_pk_add_f32 v[132:133], v[154:155], v[132:133]
	v_mov_b32_e32 v134, v130
	v_mov_b32_e32 v135, v128
	v_mov_b32_e32 v128, v131
	v_pk_add_f32 v[128:129], v[134:135], v[128:129]
	v_add_f32_e32 v130, v132, v133
	v_add_f32_e32 v129, v130, v129
	v_add_f32_e32 v128, v128, v129
	v_fmamk_f32 v128, v128, 0x3a000000, v199
	v_cmp_gt_f32_e32 vcc, s9, v128
	v_mul_f32_e32 v129, 0x4b800000, v128
	v_lshlrev_b64 v[134:135], 7, v[152:153]
	v_cndmask_b32_e32 v128, v128, v129, vcc
	v_rsq_f32_e32 v128, v128
	v_lshl_add_u64 v[134:135], v[144:145], 0, v[134:135]
	v_or_b32_e32 v152, 48, v150
	v_ashrrev_i32_e32 v153, 31, v152
	v_mul_f32_e32 v129, 0x45800000, v128
	v_cndmask_b32_e32 v132, v128, v129, vcc
	v_pk_mul_f32 v[130:131], v[94:95], v[132:133] op_sel_hi:[1,0]
	v_pk_mul_f32 v[128:129], v[92:93], v[132:133] op_sel_hi:[1,0]
	global_store_dwordx4 v[134:135], v[128:131], off
	s_nop 1
	v_pk_mul_f32 v[130:131], v[90:91], v[132:133] op_sel_hi:[1,0]
	v_pk_mul_f32 v[128:129], v[88:89], v[132:133] op_sel_hi:[1,0]
	global_store_dwordx4 v[134:135], v[128:131], off offset:16
	s_nop 1
	v_lshlrev_b64 v[128:129], 5, v[152:153]
	v_lshl_add_u64 v[132:133], s[0:1], 0, v[128:129]
	global_load_dwordx4 v[128:131], v[132:133], off offset:16
	s_nop 0
	global_load_dwordx4 v[132:135], v[132:133], off
	s_waitcnt vmcnt(0)
	v_mov_b32_e32 v154, v133
	v_mov_b32_e32 v155, v134
	v_mov_b32_e32 v133, v135
	v_pk_add_f32 v[132:133], v[154:155], v[132:133]
	v_mov_b32_e32 v134, v130
	v_mov_b32_e32 v135, v128
	v_mov_b32_e32 v128, v131
	v_pk_add_f32 v[128:129], v[134:135], v[128:129]
	v_add_f32_e32 v130, v132, v133
	v_add_f32_e32 v129, v130, v129
	v_add_f32_e32 v128, v128, v129
	v_fmamk_f32 v128, v128, 0x3a000000, v199
	v_cmp_gt_f32_e32 vcc, s9, v128
	v_mul_f32_e32 v129, 0x4b800000, v128
	v_lshlrev_b64 v[134:135], 7, v[152:153]
	v_cndmask_b32_e32 v128, v128, v129, vcc
	v_rsq_f32_e32 v128, v128
	v_lshl_add_u64 v[134:135], v[144:145], 0, v[134:135]
	v_add_u32_e32 v152, 0x80, v150
	v_ashrrev_i32_e32 v153, 31, v152
	v_mul_f32_e32 v129, 0x45800000, v128
	v_cndmask_b32_e32 v132, v128, v129, vcc
	v_pk_mul_f32 v[130:131], v[78:79], v[132:133] op_sel_hi:[1,0]
	v_pk_mul_f32 v[128:129], v[76:77], v[132:133] op_sel_hi:[1,0]
	global_store_dwordx4 v[134:135], v[128:131], off
	s_nop 1
	v_pk_mul_f32 v[130:131], v[74:75], v[132:133] op_sel_hi:[1,0]
	v_pk_mul_f32 v[128:129], v[72:73], v[132:133] op_sel_hi:[1,0]
	global_store_dwordx4 v[134:135], v[128:131], off offset:16
	s_nop 1
	v_lshlrev_b64 v[128:129], 5, v[152:153]
	v_lshl_add_u64 v[132:133], s[0:1], 0, v[128:129]
	global_load_dwordx4 v[128:131], v[132:133], off offset:16
	s_nop 0
	global_load_dwordx4 v[132:135], v[132:133], off
	s_waitcnt vmcnt(0)
	v_mov_b32_e32 v154, v133
	v_mov_b32_e32 v155, v134
	v_mov_b32_e32 v133, v135
	v_pk_add_f32 v[132:133], v[154:155], v[132:133]
	v_mov_b32_e32 v134, v130
	v_mov_b32_e32 v135, v128
	v_mov_b32_e32 v128, v131
	v_pk_add_f32 v[128:129], v[134:135], v[128:129]
	v_add_f32_e32 v130, v132, v133
	v_add_f32_e32 v129, v130, v129
	v_add_f32_e32 v128, v128, v129
	v_fmamk_f32 v128, v128, 0x3a000000, v199
	v_cmp_gt_f32_e32 vcc, s9, v128
	v_mul_f32_e32 v129, 0x4b800000, v128
	v_lshlrev_b64 v[134:135], 7, v[152:153]
	v_cndmask_b32_e32 v128, v128, v129, vcc
	v_rsq_f32_e32 v128, v128
	v_lshl_add_u64 v[134:135], v[144:145], 0, v[134:135]
	v_add_u32_e32 v152, 0x90, v150
	v_ashrrev_i32_e32 v153, 31, v152
	v_mul_f32_e32 v129, 0x45800000, v128
	v_cndmask_b32_e32 v132, v128, v129, vcc
	v_pk_mul_f32 v[130:131], v[62:63], v[132:133] op_sel_hi:[1,0]
	v_pk_mul_f32 v[128:129], v[60:61], v[132:133] op_sel_hi:[1,0]
	global_store_dwordx4 v[134:135], v[128:131], off
	s_nop 1
	v_pk_mul_f32 v[130:131], v[58:59], v[132:133] op_sel_hi:[1,0]
	v_pk_mul_f32 v[128:129], v[56:57], v[132:133] op_sel_hi:[1,0]
	global_store_dwordx4 v[134:135], v[128:131], off offset:16
	s_nop 1
	v_lshlrev_b64 v[128:129], 5, v[152:153]
	v_lshl_add_u64 v[132:133], s[0:1], 0, v[128:129]
	global_load_dwordx4 v[128:131], v[132:133], off offset:16
	s_nop 0
	global_load_dwordx4 v[132:135], v[132:133], off
	s_waitcnt vmcnt(0)
; DEV float rowscale(const float* ss, int row) { const f32x4 a = *(const f32x4*)(ss + (size_t)row * 8), b = *(const f32x4*)(ss + (size_t)row * 8 + 4);
;     return rsqrtf(((a[0] + a[1]) + (a[2] + a[3]) + (b[0] + b[1]) + (b[2] + b[3])) * (1.0f / 2048.0f) + EPS); }
;     DEV void operator()(AccRef acc, const pg8::Unit& u, int wr, int wc, int fr, int fq) const {
;     ...
;                 for (int m = 0; m < 4; ++m) { const float rs = rowscale(ss, row0 + ai * 128 + m * 16);
; #pragma unroll
;                     for (int n = 0; n < 2; ++n) *(f32x4*)(DTR + (size_t)(row0 + ai * 128 + m * 16) * 32 + 8 * fq + 4 * n) = acc[ai][0][m][n] * rs; }
	v_mov_b32_e32 v154, v133
	v_mov_b32_e32 v155, v134
	v_mov_b32_e32 v133, v135
	v_pk_add_f32 v[132:133], v[154:155], v[132:133]
	v_mov_b32_e32 v134, v130
	v_mov_b32_e32 v135, v128
	v_mov_b32_e32 v128, v131
	v_pk_add_f32 v[128:129], v[134:135], v[128:129]
	v_add_f32_e32 v130, v132, v133
	v_add_f32_e32 v129, v130, v129
	v_add_f32_e32 v128, v128, v129
	v_fmamk_f32 v128, v128, 0x3a000000, v199
	v_cmp_gt_f32_e32 vcc, s9, v128
	v_mul_f32_e32 v129, 0x4b800000, v128
	v_lshlrev_b64 v[134:135], 7, v[152:153]
	v_cndmask_b32_e32 v128, v128, v129, vcc
	v_rsq_f32_e32 v128, v128
	v_lshl_add_u64 v[134:135], v[144:145], 0, v[134:135]
	v_add_u32_e32 v152, 0xa0, v150
	v_ashrrev_i32_e32 v153, 31, v152
	v_mul_f32_e32 v129, 0x45800000, v128
	v_cndmask_b32_e32 v132, v128, v129, vcc
	v_pk_mul_f32 v[130:131], v[46:47], v[132:133] op_sel_hi:[1,0]
	v_pk_mul_f32 v[128:129], v[44:45], v[132:133] op_sel_hi:[1,0]
	global_store_dwordx4 v[134:135], v[128:131], off
	s_nop 1
	v_pk_mul_f32 v[130:131], v[42:43], v[132:133] op_sel_hi:[1,0]
	v_pk_mul_f32 v[128:129], v[40:41], v[132:133] op_sel_hi:[1,0]
	global_store_dwordx4 v[134:135], v[128:131], off offset:16
	s_nop 1
	v_lshlrev_b64 v[128:129], 5, v[152:153]
	v_lshl_add_u64 v[132:133], s[0:1], 0, v[128:129]
	global_load_dwordx4 v[128:131], v[132:133], off offset:16
	s_nop 0
	global_load_dwordx4 v[132:135], v[132:133], off
	s_waitcnt vmcnt(0)
	v_mov_b32_e32 v154, v133
	v_mov_b32_e32 v155, v134
	v_mov_b32_e32 v133, v135
	v_pk_add_f32 v[132:133], v[154:155], v[132:133]
	v_mov_b32_e32 v134, v130
	v_mov_b32_e32 v135, v128
	v_mov_b32_e32 v128, v131
	v_pk_add_f32 v[128:129], v[134:135], v[128:129]
	v_add_f32_e32 v130, v132, v133
	v_add_f32_e32 v129, v130, v129
	v_add_f32_e32 v128, v128, v129
	v_fmamk_f32 v128, v128, 0x3a000000, v199
	v_cmp_gt_f32_e32 vcc, s9, v128
	v_mul_f32_e32 v129, 0x4b800000, v128
	v_lshlrev_b64 v[134:135], 7, v[152:153]
	v_cndmask_b32_e32 v128, v128, v129, vcc
	v_rsq_f32_e32 v128, v128
	v_lshl_add_u64 v[134:135], v[144:145], 0, v[134:135]
	v_add_u32_e32 v152, 0xb0, v150
	v_ashrrev_i32_e32 v153, 31, v152
	v_mul_f32_e32 v129, 0x45800000, v128
	v_cndmask_b32_e32 v132, v128, v129, vcc
	v_pk_mul_f32 v[130:131], v[30:31], v[132:133] op_sel_hi:[1,0]
	v_pk_mul_f32 v[128:129], v[28:29], v[132:133] op_sel_hi:[1,0]
	global_store_dwordx4 v[134:135], v[128:131], off
	s_nop 1
	v_pk_mul_f32 v[130:131], v[26:27], v[132:133] op_sel_hi:[1,0]
	v_pk_mul_f32 v[128:129], v[24:25], v[132:133] op_sel_hi:[1,0]
	global_store_dwordx4 v[134:135], v[128:131], off offset:16
	s_nop 1
	v_lshlrev_b64 v[128:129], 5, v[152:153]
	v_lshl_add_u64 v[132:133], s[0:1], 0, v[128:129]
	global_load_dwordx4 v[128:131], v[132:133], off offset:16
	s_nop 0
	global_load_dwordx4 v[132:135], v[132:133], off
	s_waitcnt vmcnt(0)
	v_mov_b32_e32 v154, v133
	v_mov_b32_e32 v155, v134
	v_mov_b32_e32 v133, v135
	v_pk_add_f32 v[132:133], v[154:155], v[132:133]
	v_mov_b32_e32 v134, v130
	v_mov_b32_e32 v135, v128
	v_mov_b32_e32 v128, v131
	v_pk_add_f32 v[128:129], v[134:135], v[128:129]
	v_add_f32_e32 v130, v132, v133
	v_add_f32_e32 v129, v130, v129
	v_add_f32_e32 v128, v128, v129
	v_fmamk_f32 v128, v128, 0x3a000000, v199
	v_cmp_gt_f32_e32 vcc, s9, v128
	v_mul_f32_e32 v129, 0x4b800000, v128
	v_lshlrev_b64 v[134:135], 7, v[152:153]
	v_cndmask_b32_e32 v128, v128, v129, vcc
	v_rsq_f32_e32 v128, v128
	v_lshl_add_u64 v[134:135], v[144:145], 0, v[134:135]
	v_mul_f32_e32 v129, 0x45800000, v128
	v_cndmask_b32_e32 v132, v128, v129, vcc
	v_pk_mul_f32 v[130:131], v[14:15], v[132:133] op_sel_hi:[1,0]
	v_pk_mul_f32 v[128:129], v[12:13], v[132:133] op_sel_hi:[1,0]
	global_store_dwordx4 v[134:135], v[128:131], off
	s_nop 1
	v_pk_mul_f32 v[130:131], v[10:11], v[132:133] op_sel_hi:[1,0]
	v_pk_mul_f32 v[128:129], v[8:9], v[132:133] op_sel_hi:[1,0]
	global_store_dwordx4 v[134:135], v[128:131], off offset:16

; #define PG8_STAGE(bufoff, gbase, voff) do { _Pragma("unroll") for (int _i = 0; _i < 2; ++_i) \
;         __builtin_amdgcn_global_load_lds((const unsigned*)((const char*)(gbase) + (voff)[_i]), (LAS unsigned*)(lds + (bufoff) + ldsw + _i * 8192), 16, 0, 0); } while (0)
; #define PG8_LDA(dst, b, h) do { _Pragma("unroll") for (int m = 0; m < 4; ++m) _Pragma("unroll") for (int k = 0; k < 2; ++k) dst[m][k] = *(const LAS bf16x8*)(lds + PG8_SA(b, h) + aoff + m * 2048 + k * 1024); } while (0)
; #define PG8_LDB(dst, b, h) do { _Pragma("unroll") for (int n = 0; n < 2; ++n) _Pragma("unroll") for (int k = 0; k < 2; ++k) dst[n][k] = *(const LAS bf16x8*)(lds + PG8_SB(b, h) + boff + n * 2048 + k * 1024); } while (0)
; #define PG8_MMA(ai, bj, At, Bt) do { __builtin_amdgcn_s_setprio(1); _Pragma("unroll") for (int m = 0; m < 4; ++m) _Pragma("unroll") for (int n = 0; n < 2; ++n) _Pragma("unroll") for (int k = 0; k < 2; ++k) \
;         acc[ai][bj][m][n] = __builtin_amdgcn_mfma_f32_16x16x32_bf16(Bt[n][k], At[m][k], acc[ai][bj][m][n], 0, 0, 0); __builtin_amdgcn_s_setprio(0); } while (0)
; #define PG8_WAIT_L(n) asm volatile("s_waitcnt lgkmcnt(" #n ")" ::: "memory")
; #define PG8_BAR __builtin_amdgcn_s_barrier()
; #define PG8_SCHED __builtin_amdgcn_sched_barrier(0)
; template <class Epi>
; DEV void gemm_phase(LAS unsigned char* lds, const Gemm g, const StaticOrder& S, const Epi& E) {
;     ...
;             PG8_LDB(B0, 0, 0); PG8_SCHED; PG8_LDA(At, 0, 0); PG8_STAGE(PG8_SA(1, 1), a1 + hstep, voffA);
;             PG8_WAIT_L(8); PG8_BAR; PG8_WAIT_L(0); PG8_MMA(0, 0, At, B0); PG8_BAR; PG8_SCHED;
;             PG8_LDB(B1, 0, 1); PG8_STAGE(PG8_SB(0, 0), b2, voffB);
;             PG8_BAR; PG8_WAIT_L(0); PG8_MMA(0, 1, At, B1); PG8_BAR;
;             PG8_LDA(At, 0, 1); PG8_STAGE(PG8_SA(0, 0), a2, voffA);
;             PG8_BAR; PG8_WAIT_L(0); PG8_MMA(1, 0, At, B0); PG8_BAR; PG8_SCHED;
.LBB0_657:
	s_add_u32 s6, s28, 0x100
	s_addc_u32 s7, s29, 0
	s_add_i32 s55, 0, 0x10000
	v_add_u32_e32 v140, s55, v196
	ds_read_b128 v[128:131], v140
	ds_read_b128 v[132:135], v140 offset:1024
	ds_read_b128 v[136:139], v140 offset:2048
	ds_read_b128 v[140:143], v140 offset:3072
	s_cmpk_eq_i32 s54, 0x54
	s_cselect_b32 s35, s27, s7
	s_cselect_b32 s34, s26, s6
	s_cselect_b32 s31, s9, s53
	s_cselect_b32 s30, s8, s52
	v_lshl_add_u64 v[214:215], s[28:29], 0, v[180:181]
	s_add_i32 m0, s41, 0xc000
	ds_read_b128 v[144:147], v219
	ds_read_b128 v[148:151], v219 offset:1024
	ds_read_b128 v[152:155], v219 offset:2048
	ds_read_b128 v[156:159], v219 offset:3072
	ds_read_b128 v[184:187], v219 offset:4096
	ds_read_b128 v[188:191], v219 offset:5120
	ds_read_b128 v[192:195], v219 offset:6144
	ds_read_b128 v[220:223], v219 offset:7168
	global_load_lds_dwordx4 v[214:215], off
	v_lshl_add_u64 v[214:215], s[28:29], 0, v[182:183]
	s_add_i32 m0, s41, 0xe000
	s_nop 0
	global_load_lds_dwordx4 v[214:215], off
	s_waitcnt lgkmcnt(8)
	s_waitcnt vmcnt(10)
	s_barrier
	s_waitcnt lgkmcnt(0)
	s_setprio 1
	v_mfma_f32_16x16x32_bf16 v[124:127], v[128:131], v[144:147], v[124:127]
	v_mfma_f32_16x16x32_bf16 v[120:123], v[136:139], v[144:147], v[120:123]
	v_mfma_f32_16x16x32_bf16 v[112:115], v[128:131], v[152:155], v[112:115]
	v_mfma_f32_16x16x32_bf16 v[104:107], v[136:139], v[152:155], v[104:107]
	v_mfma_f32_16x16x32_bf16 v[92:95], v[128:131], v[184:187], v[92:95]
	v_mfma_f32_16x16x32_bf16 v[88:91], v[136:139], v[184:187], v[88:91]
	v_mfma_f32_16x16x32_bf16 v[80:83], v[128:131], v[192:195], v[80:83]
	v_mfma_f32_16x16x32_bf16 v[72:75], v[136:139], v[192:195], v[72:75]
	v_mfma_f32_16x16x32_bf16 v[124:127], v[132:135], v[148:151], v[124:127]
	v_mfma_f32_16x16x32_bf16 v[120:123], v[140:143], v[148:151], v[120:123]
	v_mfma_f32_16x16x32_bf16 v[112:115], v[132:135], v[156:159], v[112:115]
	v_mfma_f32_16x16x32_bf16 v[104:107], v[140:143], v[156:159], v[104:107]
	v_mfma_f32_16x16x32_bf16 v[92:95], v[132:135], v[188:191], v[92:95]
	v_mfma_f32_16x16x32_bf16 v[88:91], v[140:143], v[188:191], v[88:91]
	v_mfma_f32_16x16x32_bf16 v[80:83], v[132:135], v[220:223], v[80:83]
	v_mfma_f32_16x16x32_bf16 v[72:75], v[140:143], v[220:223], v[72:75]
	s_setprio 0
	s_barrier
	s_add_i32 s56, 0, 0x14000
	v_add_u32_e32 v214, s56, v196
	s_add_i32 s28, s55, s40
	ds_read_b128 v[224:227], v214
	ds_read_b128 v[228:231], v214 offset:1024
	ds_read_b128 v[232:235], v214 offset:2048
	ds_read_b128 v[236:239], v214 offset:3072
	v_lshl_add_u64 v[214:215], s[30:31], 0, v[160:161]
	s_mov_b32 m0, s28
	v_lshl_add_u64 v[216:217], s[30:31], 0, v[178:179]
	global_load_lds_dwordx4 v[214:215], off
	s_add_i32 m0, s28, 0x2000
	s_nop 0
	global_load_lds_dwordx4 v[216:217], off
	s_waitcnt vmcnt(10)
	s_barrier
	s_waitcnt lgkmcnt(0)
	s_setprio 1
	v_mfma_f32_16x16x32_bf16 v[116:119], v[224:227], v[144:147], v[116:119]
	v_mfma_f32_16x16x32_bf16 v[108:111], v[232:235], v[144:147], v[108:111]
	v_mfma_f32_16x16x32_bf16 v[100:103], v[224:227], v[152:155], v[100:103]
	v_mfma_f32_16x16x32_bf16 v[96:99], v[232:235], v[152:155], v[96:99]
	v_mfma_f32_16x16x32_bf16 v[84:87], v[224:227], v[184:187], v[84:87]
	v_mfma_f32_16x16x32_bf16 v[76:79], v[232:235], v[184:187], v[76:79]
	v_mfma_f32_16x16x32_bf16 v[68:71], v[224:227], v[192:195], v[68:71]
	v_mfma_f32_16x16x32_bf16 v[64:67], v[232:235], v[192:195], v[64:67]
	v_mfma_f32_16x16x32_bf16 v[116:119], v[228:231], v[148:151], v[116:119]
	v_mfma_f32_16x16x32_bf16 v[108:111], v[236:239], v[148:151], v[108:111]
	v_mfma_f32_16x16x32_bf16 v[100:103], v[228:231], v[156:159], v[100:103]
	v_mfma_f32_16x16x32_bf16 v[96:99], v[236:239], v[156:159], v[96:99]
	v_mfma_f32_16x16x32_bf16 v[84:87], v[228:231], v[188:191], v[84:87]
	v_mfma_f32_16x16x32_bf16 v[76:79], v[236:239], v[188:191], v[76:79]
	v_mfma_f32_16x16x32_bf16 v[68:71], v[228:231], v[220:223], v[68:71]
	v_mfma_f32_16x16x32_bf16 v[64:67], v[236:239], v[220:223], v[64:67]
	s_setprio 0
	s_mov_b32 m0, s41
	v_lshl_add_u64 v[240:241], s[34:35], 0, v[174:175]
	s_barrier
	ds_read_b128 v[144:147], v219 offset:16384
	ds_read_b128 v[148:151], v219 offset:17408
	ds_read_b128 v[152:155], v219 offset:18432
	ds_read_b128 v[156:159], v219 offset:19456
	ds_read_b128 v[184:187], v219 offset:20480
	ds_read_b128 v[188:191], v219 offset:21504
	ds_read_b128 v[192:195], v219 offset:22528
	ds_read_b128 v[220:223], v219 offset:23552
	global_load_lds_dwordx4 v[240:241], off
	v_lshl_add_u64 v[242:243], s[34:35], 0, v[176:177]
	s_mov_b32 m0, s42
	s_nop 0
	global_load_lds_dwordx4 v[242:243], off
	s_barrier
	s_waitcnt lgkmcnt(0)
	s_setprio 1
	v_mfma_f32_16x16x32_bf16 v[60:63], v[128:131], v[144:147], v[60:63]
	v_mfma_f32_16x16x32_bf16 v[56:59], v[136:139], v[144:147], v[56:59]
	v_mfma_f32_16x16x32_bf16 v[48:51], v[128:131], v[152:155], v[48:51]
	v_mfma_f32_16x16x32_bf16 v[40:43], v[136:139], v[152:155], v[40:43]
	v_mfma_f32_16x16x32_bf16 v[28:31], v[128:131], v[184:187], v[28:31]
	v_mfma_f32_16x16x32_bf16 v[24:27], v[136:139], v[184:187], v[24:27]
	v_mfma_f32_16x16x32_bf16 v[16:19], v[128:131], v[192:195], v[16:19]
	v_mfma_f32_16x16x32_bf16 v[8:11], v[136:139], v[192:195], v[8:11]
	v_mfma_f32_16x16x32_bf16 v[60:63], v[132:135], v[148:151], v[60:63]
	v_mfma_f32_16x16x32_bf16 v[56:59], v[140:143], v[148:151], v[56:59]
	v_mfma_f32_16x16x32_bf16 v[48:51], v[132:135], v[156:159], v[48:51]
	v_mfma_f32_16x16x32_bf16 v[40:43], v[140:143], v[156:159], v[40:43]
	v_mfma_f32_16x16x32_bf16 v[28:31], v[132:135], v[188:191], v[28:31]
	v_mfma_f32_16x16x32_bf16 v[24:27], v[140:143], v[188:191], v[24:27]
	v_mfma_f32_16x16x32_bf16 v[16:19], v[132:135], v[220:223], v[16:19]
	v_mfma_f32_16x16x32_bf16 v[8:11], v[140:143], v[220:223], v[8:11]
	s_setprio 0
	s_barrier
; #define PG8_STAGE(bufoff, gbase, voff) do { _Pragma("unroll") for (int _i = 0; _i < 2; ++_i) \
;         __builtin_amdgcn_global_load_lds((const unsigned*)((const char*)(gbase) + (voff)[_i]), (LAS unsigned*)(lds + (bufoff) + ldsw + _i * 8192), 16, 0, 0); } while (0)
; #define PG8_LDA(dst, b, h) do { _Pragma("unroll") for (int m = 0; m < 4; ++m) _Pragma("unroll") for (int k = 0; k < 2; ++k) dst[m][k] = *(const LAS bf16x8*)(lds + PG8_SA(b, h) + aoff + m * 2048 + k * 1024); } while (0)
; #define PG8_LDB(dst, b, h) do { _Pragma("unroll") for (int n = 0; n < 2; ++n) _Pragma("unroll") for (int k = 0; k < 2; ++k) dst[n][k] = *(const LAS bf16x8*)(lds + PG8_SB(b, h) + boff + n * 2048 + k * 1024); } while (0)
; #define PG8_MMA(ai, bj, At, Bt) do { __builtin_amdgcn_s_setprio(1); _Pragma("unroll") for (int m = 0; m < 4; ++m) _Pragma("unroll") for (int n = 0; n < 2; ++n) _Pragma("unroll") for (int k = 0; k < 2; ++k) \
;         acc[ai][bj][m][n] = __builtin_amdgcn_mfma_f32_16x16x32_bf16(Bt[n][k], At[m][k], acc[ai][bj][m][n], 0, 0, 0); __builtin_amdgcn_s_setprio(0); } while (0)
; #define PG8_WAIT_V(n) asm volatile("s_waitcnt vmcnt(" #n ")" ::: "memory")
; #define PG8_WAIT_L(n) asm volatile("s_waitcnt lgkmcnt(" #n ")" ::: "memory")
; #define PG8_BAR __builtin_amdgcn_s_barrier()
; #define PG8_SCHED __builtin_amdgcn_sched_barrier(0)
; template <class Epi>
; DEV void gemm_phase(LAS unsigned char* lds, const Gemm g, const StaticOrder& S, const Epi& E) {
;     ...
;             PG8_STAGE(PG8_SB(0, 1), b2 + hstep, voffB);
;             PG8_WAIT_V(6); PG8_BAR; PG8_MMA(1, 1, At, B1); PG8_BAR;
;             PG8_LDB(B0, 1, 0); PG8_SCHED; PG8_LDA(At, 1, 0); PG8_STAGE(PG8_SA(0, 1), a2 + hstep, voffA);
;             PG8_WAIT_L(8); PG8_BAR; PG8_WAIT_L(0); PG8_MMA(0, 0, At, B0); PG8_BAR; PG8_SCHED;
;             PG8_LDB(B1, 1, 1); PG8_STAGE(PG8_SB(1, 0), b3, voffB);
;             PG8_BAR; PG8_WAIT_L(0); PG8_MMA(0, 1, At, B1); PG8_BAR;
;             PG8_LDA(At, 1, 1); PG8_STAGE(PG8_SA(1, 0), a3, voffA);
	s_add_u32 s28, s30, 0x160000
	s_addc_u32 s29, s31, 0
	s_add_i32 s55, s56, s40
	v_lshl_add_u64 v[128:129], s[28:29], 0, v[160:161]
	s_mov_b32 m0, s55
	s_nop 0
	global_load_lds_dwordx4 v[128:129], off
	v_lshl_add_u64 v[128:129], s[28:29], 0, v[178:179]
	s_add_i32 m0, s55, 0x2000
	s_nop 0
	global_load_lds_dwordx4 v[128:129], off
	s_waitcnt vmcnt(10)
	s_barrier
	s_setprio 1
	v_mfma_f32_16x16x32_bf16 v[52:55], v[224:227], v[144:147], v[52:55]
	v_mfma_f32_16x16x32_bf16 v[44:47], v[232:235], v[144:147], v[44:47]
	v_mfma_f32_16x16x32_bf16 v[36:39], v[224:227], v[152:155], v[36:39]
	v_mfma_f32_16x16x32_bf16 v[32:35], v[232:235], v[152:155], v[32:35]
	v_mfma_f32_16x16x32_bf16 v[20:23], v[224:227], v[184:187], v[20:23]
	v_mfma_f32_16x16x32_bf16 v[12:15], v[232:235], v[184:187], v[12:15]
	v_mfma_f32_16x16x32_bf16 v[4:7], v[224:227], v[192:195], v[4:7]
	v_mfma_f32_16x16x32_bf16 v[0:3], v[232:235], v[192:195], v[0:3]
	v_mfma_f32_16x16x32_bf16 v[52:55], v[228:231], v[148:151], v[52:55]
	v_mfma_f32_16x16x32_bf16 v[44:47], v[236:239], v[148:151], v[44:47]
	v_mfma_f32_16x16x32_bf16 v[36:39], v[228:231], v[156:159], v[36:39]
	v_mfma_f32_16x16x32_bf16 v[32:35], v[236:239], v[156:159], v[32:35]
	v_mfma_f32_16x16x32_bf16 v[20:23], v[228:231], v[188:191], v[20:23]
	v_mfma_f32_16x16x32_bf16 v[12:15], v[236:239], v[188:191], v[12:15]
	v_mfma_f32_16x16x32_bf16 v[4:7], v[228:231], v[220:223], v[4:7]
	v_mfma_f32_16x16x32_bf16 v[0:3], v[236:239], v[220:223], v[0:3]
	s_setprio 0
	s_add_i32 s55, 0, 0x18000
	v_add_u32_e32 v140, s55, v196
	s_barrier
	ds_read_b128 v[128:131], v140
	ds_read_b128 v[132:135], v140 offset:1024
	ds_read_b128 v[136:139], v140 offset:2048
	ds_read_b128 v[140:143], v140 offset:3072
	s_add_u32 s28, s34, 0x160000
	s_addc_u32 s29, s35, 0
	s_mov_b32 m0, s43
	v_lshl_add_u64 v[224:225], s[28:29], 0, v[174:175]
	ds_read_b128 v[144:147], v219 offset:32768
	ds_read_b128 v[148:151], v219 offset:33792
	ds_read_b128 v[152:155], v219 offset:34816
	ds_read_b128 v[156:159], v219 offset:35840
	ds_read_b128 v[184:187], v219 offset:36864
	ds_read_b128 v[188:191], v219 offset:37888
	ds_read_b128 v[192:195], v219 offset:38912
	ds_read_b128 v[220:223], v219 offset:39936
	global_load_lds_dwordx4 v[224:225], off
	v_lshl_add_u64 v[224:225], s[28:29], 0, v[176:177]
	s_mov_b32 m0, s44
	s_nop 0
	global_load_lds_dwordx4 v[224:225], off
	s_waitcnt lgkmcnt(8)
	s_waitcnt vmcnt(10)
	s_barrier
	s_waitcnt lgkmcnt(0)
	s_setprio 1
	v_mfma_f32_16x16x32_bf16 v[124:127], v[128:131], v[144:147], v[124:127]
	v_mfma_f32_16x16x32_bf16 v[120:123], v[136:139], v[144:147], v[120:123]
	v_mfma_f32_16x16x32_bf16 v[112:115], v[128:131], v[152:155], v[112:115]
	v_mfma_f32_16x16x32_bf16 v[104:107], v[136:139], v[152:155], v[104:107]
	v_mfma_f32_16x16x32_bf16 v[92:95], v[128:131], v[184:187], v[92:95]
	v_mfma_f32_16x16x32_bf16 v[88:91], v[136:139], v[184:187], v[88:91]
	v_mfma_f32_16x16x32_bf16 v[80:83], v[128:131], v[192:195], v[80:83]
	v_mfma_f32_16x16x32_bf16 v[72:75], v[136:139], v[192:195], v[72:75]
	v_mfma_f32_16x16x32_bf16 v[124:127], v[132:135], v[148:151], v[124:127]
	v_mfma_f32_16x16x32_bf16 v[120:123], v[140:143], v[148:151], v[120:123]
	v_mfma_f32_16x16x32_bf16 v[112:115], v[132:135], v[156:159], v[112:115]
	v_mfma_f32_16x16x32_bf16 v[104:107], v[140:143], v[156:159], v[104:107]
	v_mfma_f32_16x16x32_bf16 v[92:95], v[132:135], v[188:191], v[92:95]
	v_mfma_f32_16x16x32_bf16 v[88:91], v[140:143], v[188:191], v[88:91]
	v_mfma_f32_16x16x32_bf16 v[80:83], v[132:135], v[220:223], v[80:83]
	v_mfma_f32_16x16x32_bf16 v[72:75], v[140:143], v[220:223], v[72:75]
	s_setprio 0
	s_barrier
	s_add_i32 s34, 0, 0x1c000
	s_add_i32 s28, s55, s40
	v_add_u32_e32 v236, s34, v196
	v_lshl_add_u64 v[214:215], v[214:215], 0, s[2:3]
	s_mov_b32 m0, s28
	ds_read_b128 v[224:227], v236
	ds_read_b128 v[228:231], v236 offset:1024
	ds_read_b128 v[232:235], v236 offset:2048
	ds_read_b128 v[236:239], v236 offset:3072
	global_load_lds_dwordx4 v[214:215], off
	v_lshl_add_u64 v[214:215], v[216:217], 0, s[2:3]
	s_add_i32 m0, s28, 0x2000
	s_nop 0
	global_load_lds_dwordx4 v[214:215], off
	s_waitcnt vmcnt(10)
	s_barrier
	s_waitcnt lgkmcnt(0)
	s_setprio 1
	v_mfma_f32_16x16x32_bf16 v[116:119], v[224:227], v[144:147], v[116:119]
	v_mfma_f32_16x16x32_bf16 v[108:111], v[232:235], v[144:147], v[108:111]
	v_mfma_f32_16x16x32_bf16 v[100:103], v[224:227], v[152:155], v[100:103]
	v_mfma_f32_16x16x32_bf16 v[96:99], v[232:235], v[152:155], v[96:99]
	v_mfma_f32_16x16x32_bf16 v[84:87], v[224:227], v[184:187], v[84:87]
	v_mfma_f32_16x16x32_bf16 v[76:79], v[232:235], v[184:187], v[76:79]
	v_mfma_f32_16x16x32_bf16 v[68:71], v[224:227], v[192:195], v[68:71]
	v_mfma_f32_16x16x32_bf16 v[64:67], v[232:235], v[192:195], v[64:67]
	v_mfma_f32_16x16x32_bf16 v[116:119], v[228:231], v[148:151], v[116:119]
	v_mfma_f32_16x16x32_bf16 v[108:111], v[236:239], v[148:151], v[108:111]
	v_mfma_f32_16x16x32_bf16 v[100:103], v[228:231], v[156:159], v[100:103]
	v_mfma_f32_16x16x32_bf16 v[96:99], v[236:239], v[156:159], v[96:99]
	v_mfma_f32_16x16x32_bf16 v[84:87], v[228:231], v[188:191], v[84:87]
	v_mfma_f32_16x16x32_bf16 v[76:79], v[236:239], v[188:191], v[76:79]
	v_mfma_f32_16x16x32_bf16 v[68:71], v[228:231], v[220:223], v[68:71]
	v_mfma_f32_16x16x32_bf16 v[64:67], v[236:239], v[220:223], v[64:67]
	s_setprio 0
	s_mov_b32 m0, s45
	v_lshl_add_u64 v[214:215], v[240:241], 0, s[2:3]
	s_barrier
	ds_read_b128 v[144:147], v219 offset:49152
	ds_read_b128 v[148:151], v219 offset:50176
	ds_read_b128 v[152:155], v219 offset:51200
	ds_read_b128 v[156:159], v219 offset:52224
	ds_read_b128 v[184:187], v219 offset:53248
	ds_read_b128 v[188:191], v219 offset:54272
	ds_read_b128 v[192:195], v219 offset:55296
	ds_read_b128 v[220:223], v219 offset:56320
	global_load_lds_dwordx4 v[214:215], off
	v_lshl_add_u64 v[214:215], v[242:243], 0, s[2:3]
	s_mov_b32 m0, s46
	s_nop 0
	global_load_lds_dwordx4 v[214:215], off
	s_barrier
; DEV bf16x8 pack8(f32x4 a, f32x4 b) { u32x4 w; w.x = cvt_pk_bf16(a[0], a[1]); w.y = cvt_pk_bf16(a[2], a[3]); w.z = cvt_pk_bf16(b[0], b[1]); w.w = cvt_pk_bf16(b[2], b[3]); return __builtin_bit_cast(bf16x8, w); }
; #define PG8_STAGE(bufoff, gbase, voff) do { _Pragma("unroll") for (int _i = 0; _i < 2; ++_i) \
;         __builtin_amdgcn_global_load_lds((const unsigned*)((const char*)(gbase) + (voff)[_i]), (LAS unsigned*)(lds + (bufoff) + ldsw + _i * 8192), 16, 0, 0); } while (0)
; #define PG8_WAIT_V(n) asm volatile("s_waitcnt vmcnt(" #n ")" ::: "memory")
; #define PG8_WAIT_L(n) asm volatile("s_waitcnt lgkmcnt(" #n ")" ::: "memory")
; #define PG8_BAR __builtin_amdgcn_s_barrier()
; #define PG8_SCHED __builtin_amdgcn_sched_barrier(0)
; template <class Epi>
; DEV void gemm_phase(LAS unsigned char* lds, const Gemm g, const StaticOrder& S, const Epi& E) {
;     ...
;             PG8_BAR; PG8_WAIT_L(0); PG8_MMA(1, 0, At, B0); PG8_BAR; PG8_SCHED;
;             PG8_STAGE(PG8_SB(1, 1), b3 + hstep, voffB);
;             PG8_WAIT_V(6); PG8_BAR; PG8_MMA(1, 1, At, B1); PG8_BAR;
;     DEV void operator()(AccRef acc, const pg8::Unit& u, int wr, int wc, int fr, int fq) const {
;     ...
;                     for (int n = 0; n < 2; ++n) bv[m][bj][n] = *(const f32x4*)(base + (size_t)(row0 + ai * 128 + m * 16) * 2048 + col0 + bj * 128 + n * 4);
; #pragma unroll
;             for (int m = m0; m < m0 + 2; ++m) { const size_t off = (size_t)(row0 + ai * 128 + m * 16) * 2048 + col0; float sq = 0.f;
; #pragma unroll
;                 for (int bj = 0; bj < 2; ++bj) { const f32x4 o0 = bv[m][bj][0] + scale * acc[ai][bj][m][0], o1 = bv[m][bj][1] + scale * acc[ai][bj][m][1];
;                     *(f32x4*)(out + off + bj * 128) = o0; *(f32x4*)(out + off + bj * 128 + 4) = o1;
;                     if (xb) { *(u32x4*)(xb + off + bj * 128) = __builtin_bit_cast(u32x4, pack8(o0, o1));
;                         sq += (o0[0] * o0[0] + o0[1] * o0[1] + o0[2] * o0[2] + o0[3] * o0[3]) + (o1[0] * o1[0] + o1[1] * o1[1] + o1[2] * o1[2] + o1[3] * o1[3]); } }
;                 if (ssout) { sq += __shfl_xor(sq, 16); sq += __shfl_xor(sq, 32);
;                     if (fq == 0) { if (red) red[(ai * 128 + wr * 64 + m * 16 + fr) * 4 + wc] = sq; else atomicAdd(ssout + (size_t)(row0 + ai * 128 + m * 16) * 8 + u.pn, sq); } } }
	s_waitcnt lgkmcnt(0)
	s_setprio 1
	v_mfma_f32_16x16x32_bf16 v[60:63], v[128:131], v[144:147], v[60:63]
	v_mfma_f32_16x16x32_bf16 v[56:59], v[136:139], v[144:147], v[56:59]
	v_mfma_f32_16x16x32_bf16 v[48:51], v[128:131], v[152:155], v[48:51]
	v_mfma_f32_16x16x32_bf16 v[40:43], v[136:139], v[152:155], v[40:43]
	v_mfma_f32_16x16x32_bf16 v[28:31], v[128:131], v[184:187], v[28:31]
	v_mfma_f32_16x16x32_bf16 v[24:27], v[136:139], v[184:187], v[24:27]
	v_mfma_f32_16x16x32_bf16 v[16:19], v[128:131], v[192:195], v[16:19]
	v_mfma_f32_16x16x32_bf16 v[8:11], v[136:139], v[192:195], v[8:11]
	v_mfma_f32_16x16x32_bf16 v[60:63], v[132:135], v[148:151], v[60:63]
	v_mfma_f32_16x16x32_bf16 v[56:59], v[140:143], v[148:151], v[56:59]
	v_mfma_f32_16x16x32_bf16 v[48:51], v[132:135], v[156:159], v[48:51]
	v_mfma_f32_16x16x32_bf16 v[40:43], v[140:143], v[156:159], v[40:43]
	v_mfma_f32_16x16x32_bf16 v[28:31], v[132:135], v[188:191], v[28:31]
	v_mfma_f32_16x16x32_bf16 v[24:27], v[140:143], v[188:191], v[24:27]
	v_mfma_f32_16x16x32_bf16 v[16:19], v[132:135], v[220:223], v[16:19]
	v_mfma_f32_16x16x32_bf16 v[8:11], v[140:143], v[220:223], v[8:11]
	s_setprio 0
	s_barrier
	s_add_u32 s28, s30, 0x160080
	s_addc_u32 s29, s31, 0
	s_add_i32 s30, s34, s40
	v_lshl_add_u64 v[128:129], s[28:29], 0, v[160:161]
	s_mov_b32 m0, s30
	s_nop 0
	global_load_lds_dwordx4 v[128:129], off
	v_lshl_add_u64 v[128:129], s[28:29], 0, v[178:179]
	s_add_i32 m0, s30, 0x2000
	s_nop 0
	global_load_lds_dwordx4 v[128:129], off
	s_waitcnt vmcnt(10)
	s_barrier
	s_setprio 1
	v_mfma_f32_16x16x32_bf16 v[52:55], v[224:227], v[144:147], v[52:55]
	v_mfma_f32_16x16x32_bf16 v[44:47], v[232:235], v[144:147], v[44:47]
	v_mfma_f32_16x16x32_bf16 v[36:39], v[224:227], v[152:155], v[36:39]
	v_mfma_f32_16x16x32_bf16 v[32:35], v[232:235], v[152:155], v[32:35]
	v_mfma_f32_16x16x32_bf16 v[20:23], v[224:227], v[184:187], v[20:23]
	v_mfma_f32_16x16x32_bf16 v[12:15], v[232:235], v[184:187], v[12:15]
	v_mfma_f32_16x16x32_bf16 v[4:7], v[224:227], v[192:195], v[4:7]
	v_mfma_f32_16x16x32_bf16 v[0:3], v[232:235], v[192:195], v[0:3]
	v_mfma_f32_16x16x32_bf16 v[52:55], v[228:231], v[148:151], v[52:55]
	v_mfma_f32_16x16x32_bf16 v[44:47], v[236:239], v[148:151], v[44:47]
	v_mfma_f32_16x16x32_bf16 v[36:39], v[228:231], v[156:159], v[36:39]
	v_mfma_f32_16x16x32_bf16 v[32:35], v[236:239], v[156:159], v[32:35]
	v_mfma_f32_16x16x32_bf16 v[20:23], v[228:231], v[188:191], v[20:23]
	v_mfma_f32_16x16x32_bf16 v[12:15], v[236:239], v[188:191], v[12:15]
	v_mfma_f32_16x16x32_bf16 v[4:7], v[228:231], v[220:223], v[4:7]
	v_mfma_f32_16x16x32_bf16 v[0:3], v[236:239], v[220:223], v[0:3]
	s_setprio 0
	s_add_i32 s54, s54, 2
	s_add_u32 s52, s52, 0x100
	s_addc_u32 s53, s53, 0
	s_cmpk_gt_u32 s54, 0x55
	s_mov_b64 s[28:29], s[6:7]
	s_barrier
	s_cbranch_scc0 .LBB0_657
	v_lshl_add_u32 v186, s23, 8, v167
	v_lshl_or_b32 v184, s22, 8, v197
	v_ashrrev_i32_e32 v185, 31, v184
	v_ashrrev_i32_e32 v187, 31, v186
	v_lshl_add_u64 v[188:189], v[184:185], 2, s[24:25]
	v_lshlrev_b64 v[128:129], 13, v[186:187]
	v_or_b32_e32 v190, 16, v186
	v_lshl_add_u64 v[128:129], v[188:189], 0, v[128:129]
	v_ashrrev_i32_e32 v191, 31, v190
	global_load_dwordx4 v[152:155], v[128:129], off offset:16
	global_load_dwordx4 v[156:159], v[128:129], off
	global_load_dwordx4 v[144:147], v[128:129], off offset:528
	global_load_dwordx4 v[148:151], v[128:129], off offset:512
	v_lshlrev_b64 v[128:129], 13, v[190:191]
	v_lshl_add_u64 v[132:133], v[188:189], 0, v[128:129]
	global_load_dwordx4 v[136:139], v[132:133], off offset:16
	global_load_dwordx4 v[140:143], v[132:133], off
	global_load_dwordx4 v[128:131], v[132:133], off offset:528
	s_nop 0
	global_load_dwordx4 v[132:135], v[132:133], off offset:512
	v_lshlrev_b64 v[192:193], 11, v[186:187]
	v_lshl_add_u64 v[194:195], v[192:193], 0, v[184:185]
	s_ashr_i32 s23, s22, 31
	v_lshl_add_u64 v[192:193], v[194:195], 2, s[68:69]
	s_mov_b64 s[28:29], -1
	s_andn2_b64 vcc, exec, s[18:19]
	s_waitcnt vmcnt(0)
	v_pk_fma_f32 v[152:153], v[120:121], 0.5, v[152:153] op_sel_hi:[1,0,1]
	v_cndmask_b32_e64 v120, 0, 1, s[18:19]
	v_pk_fma_f32 v[158:159], v[126:127], 0.5, v[158:159] op_sel_hi:[1,0,1]
	v_pk_fma_f32 v[156:157], v[124:125], 0.5, v[156:157] op_sel_hi:[1,0,1]
	v_pk_fma_f32 v[154:155], v[122:123], 0.5, v[154:155] op_sel_hi:[1,0,1]
	v_cmp_ne_u32_e64 s[6:7], 1, v120
	v_pk_fma_f32 v[120:121], v[116:117], 0.5, v[148:149] op_sel_hi:[1,0,1]
	v_pk_fma_f32 v[124:125], v[108:109], 0.5, v[144:145] op_sel_hi:[1,0,1]
	global_store_dwordx4 v[192:193], v[156:159], off
	global_store_dwordx4 v[192:193], v[152:155], off offset:16
	s_cbranch_vccnz .LBB0_665
	v_mul_f32_e32 v108, v157, v157
	v_mul_f32_e32 v109, v153, v153
	v_fmac_f32_e32 v108, v156, v156
	v_fmac_f32_e32 v109, v152, v152
	v_fmac_f32_e32 v108, v158, v158
	v_fmac_f32_e32 v109, v154, v154
	v_fmac_f32_e32 v108, v159, v159
	v_fmac_f32_e32 v109, v155, v155
	v_add_f32_e32 v108, v108, v109
	v_mul_f32_e32 v109, v121, v121
	v_mul_f32_e32 v144, v125, v125
	v_pk_fma_f32 v[122:123], v[118:119], 0.5, v[150:151] op_sel_hi:[1,0,1]
	v_pk_fma_f32 v[126:127], v[110:111], 0.5, v[146:147] op_sel_hi:[1,0,1]
	v_fmac_f32_e32 v109, v120, v120
	v_fmac_f32_e32 v144, v124, v124
	v_fmac_f32_e32 v109, v122, v122
	v_fmac_f32_e32 v144, v126, v126
	v_fmac_f32_e32 v109, v123, v123
	v_fmac_f32_e32 v144, v127, v127
	v_add_f32_e32 v109, v109, v144
	v_cmp_lt_i32_e32 vcc, v208, v206
	v_add_f32_e32 v108, v108, v109
	v_readlane_b32 s28, v250, 9
	v_cndmask_b32_e32 v109, v204, v208, vcc
	v_lshlrev_b32_e32 v109, 2, v109
	ds_bpermute_b32 v109, v109, v108
	v_cmp_lt_i32_e32 vcc, v207, v206
	v_readlane_b32 s29, v250, 10
	v_cvt_pk_bf16_f32 v220, v156, v157
	v_cvt_pk_bf16_f32 v221, v158, v159
	s_waitcnt lgkmcnt(0)
	v_add_f32_e32 v108, v108, v109
	v_cndmask_b32_e32 v109, v204, v207, vcc
	v_lshlrev_b32_e32 v109, 2, v109
	ds_bpermute_b32 v109, v109, v108
	v_cvt_pk_bf16_f32 v222, v152, v153
	v_cvt_pk_bf16_f32 v223, v154, v155
	v_lshl_add_u64 v[116:117], v[194:195], 1, s[28:29]
	v_cvt_pk_bf16_f32 v152, v120, v121
	v_cvt_pk_bf16_f32 v153, v122, v123
	v_cvt_pk_bf16_f32 v154, v124, v125
	v_cvt_pk_bf16_f32 v155, v126, v127
	global_store_dwordx4 v[116:117], v[220:223], off
	global_store_dwordx4 v[192:193], v[120:123], off offset:512
	global_store_dwordx4 v[192:193], v[124:127], off offset:528
	global_store_dwordx4 v[116:117], v[152:155], off offset:256
	s_and_saveexec_b64 s[28:29], s[10:11]
	s_cbranch_execz .LBB0_664
	s_waitcnt lgkmcnt(0)
	v_add_f32_e32 v108, v108, v109
	s_andn2_b64 vcc, exec, s[20:21]
	s_mov_b64 s[30:31], -1
	s_cbranch_vccnz .LBB0_662
	s_mov_b64 s[30:31], 0
	ds_write_b32 v218, v108

; #define PG8_STAGE(bufoff, gbase, voff) do { _Pragma("unroll") for (int _i = 0; _i < 2; ++_i) \
;         __builtin_amdgcn_global_load_lds((const unsigned*)((const char*)(gbase) + (voff)[_i]), (LAS unsigned*)(lds + (bufoff) + ldsw + _i * 8192), 16, 0, 0); } while (0)
; #define PG8_LDA(dst, b, h) do { _Pragma("unroll") for (int m = 0; m < 4; ++m) _Pragma("unroll") for (int k = 0; k < 2; ++k) dst[m][k] = *(const LAS bf16x8*)(lds + PG8_SA(b, h) + aoff + m * 2048 + k * 1024); } while (0)
; #define PG8_LDB(dst, b, h) do { _Pragma("unroll") for (int n = 0; n < 2; ++n) _Pragma("unroll") for (int k = 0; k < 2; ++k) dst[n][k] = *(const LAS bf16x8*)(lds + PG8_SB(b, h) + boff + n * 2048 + k * 1024); } while (0)
; #define PG8_MMA(ai, bj, At, Bt) do { __builtin_amdgcn_s_setprio(1); _Pragma("unroll") for (int m = 0; m < 4; ++m) _Pragma("unroll") for (int n = 0; n < 2; ++n) _Pragma("unroll") for (int k = 0; k < 2; ++k) \
;         acc[ai][bj][m][n] = __builtin_amdgcn_mfma_f32_16x16x32_bf16(Bt[n][k], At[m][k], acc[ai][bj][m][n], 0, 0, 0); __builtin_amdgcn_s_setprio(0); } while (0)
; #define PG8_WAIT_L(n) asm volatile("s_waitcnt lgkmcnt(" #n ")" ::: "memory")
; #define PG8_BAR __builtin_amdgcn_s_barrier()
; #define PG8_SCHED __builtin_amdgcn_sched_barrier(0)
; template <class Epi>
; DEV void gemm_phase(LAS unsigned char* lds, const Gemm g, const StaticOrder& S, const Epi& E) {
;     ...
;             PG8_LDB(B0, 0, 0); PG8_SCHED; PG8_LDA(At, 0, 0); PG8_STAGE(PG8_SA(1, 1), a1 + hstep, voffA);
;             PG8_WAIT_L(8); PG8_BAR; PG8_WAIT_L(0); PG8_MMA(0, 0, At, B0); PG8_BAR; PG8_SCHED;
;             PG8_LDB(B1, 0, 1); PG8_STAGE(PG8_SB(0, 0), b2, voffB);
;             PG8_BAR; PG8_WAIT_L(0); PG8_MMA(0, 1, At, B1); PG8_BAR;
;             PG8_LDA(At, 0, 1); PG8_STAGE(PG8_SA(0, 0), a2, voffA);
;             PG8_BAR; PG8_WAIT_L(0); PG8_MMA(1, 0, At, B0); PG8_BAR; PG8_SCHED;
.LBB0_755:
	s_add_u32 s22, s20, 0xfff80080
	s_addc_u32 s23, s21, -1
	s_add_i32 s47, 0, 0x10000
	v_add_u32_e32 v146, s47, v155
	ds_read_b128 v[128:131], v146
	ds_read_b128 v[132:135], v146 offset:1024
	ds_read_b128 v[150:153], v146 offset:2048
	ds_read_b128 v[174:177], v146 offset:3072
	s_cmp_eq_u32 s46, 28
	s_cselect_b32 s25, s5, s23
	s_cselect_b32 s24, s15, s22
	s_cselect_b32 s23, s11, s45
	s_cselect_b32 s22, s43, s44
	v_lshl_add_u64 v[146:147], s[20:21], 0, v[142:143]
	s_add_i32 m0, s34, 0xc000
	ds_read_b128 v[178:181], v167
	ds_read_b128 v[182:185], v167 offset:1024
	ds_read_b128 v[186:189], v167 offset:2048
	ds_read_b128 v[190:193], v167 offset:3072
	ds_read_b128 v[194:197], v167 offset:4096
	ds_read_b128 v[218:221], v167 offset:5120
	ds_read_b128 v[222:225], v167 offset:6144
	ds_read_b128 v[226:229], v167 offset:7168
	global_load_lds_dwordx4 v[146:147], off
	v_lshl_add_u64 v[146:147], s[20:21], 0, v[144:145]
	s_add_i32 m0, s34, 0xe000
	s_nop 0
	global_load_lds_dwordx4 v[146:147], off
	s_waitcnt lgkmcnt(8)
	s_waitcnt vmcnt(10)
	s_barrier
	s_waitcnt lgkmcnt(0)
	s_setprio 1
	v_mfma_f32_16x16x32_bf16 v[124:127], v[128:131], v[178:181], v[124:127]
	v_mfma_f32_16x16x32_bf16 v[116:119], v[150:153], v[178:181], v[116:119]
	v_mfma_f32_16x16x32_bf16 v[108:111], v[128:131], v[186:189], v[108:111]
	v_mfma_f32_16x16x32_bf16 v[100:103], v[150:153], v[186:189], v[100:103]
	v_mfma_f32_16x16x32_bf16 v[92:95], v[128:131], v[194:197], v[92:95]
	v_mfma_f32_16x16x32_bf16 v[84:87], v[150:153], v[194:197], v[84:87]
	v_mfma_f32_16x16x32_bf16 v[76:79], v[128:131], v[222:225], v[76:79]
	v_mfma_f32_16x16x32_bf16 v[68:71], v[150:153], v[222:225], v[68:71]
	v_mfma_f32_16x16x32_bf16 v[124:127], v[132:135], v[182:185], v[124:127]
	v_mfma_f32_16x16x32_bf16 v[116:119], v[174:177], v[182:185], v[116:119]
	v_mfma_f32_16x16x32_bf16 v[108:111], v[132:135], v[190:193], v[108:111]
	v_mfma_f32_16x16x32_bf16 v[100:103], v[174:177], v[190:193], v[100:103]
	v_mfma_f32_16x16x32_bf16 v[92:95], v[132:135], v[218:221], v[92:95]
	v_mfma_f32_16x16x32_bf16 v[84:87], v[174:177], v[218:221], v[84:87]
	v_mfma_f32_16x16x32_bf16 v[76:79], v[132:135], v[226:229], v[76:79]
	v_mfma_f32_16x16x32_bf16 v[68:71], v[174:177], v[226:229], v[68:71]
	s_setprio 0
	s_barrier
	s_add_i32 s50, 0, 0x14000
	v_add_u32_e32 v146, s50, v155
	s_add_i32 s47, s47, s30
	ds_read_b128 v[230:233], v146
	ds_read_b128 v[234:237], v146 offset:1024
	ds_read_b128 v[238:241], v146 offset:2048
	ds_read_b128 v[242:245], v146 offset:3072
	v_lshl_add_u64 v[146:147], s[22:23], 0, v[160:161]
	s_mov_b32 m0, s47
	v_lshl_add_u64 v[158:159], s[22:23], 0, v[136:137]
	global_load_lds_dwordx4 v[146:147], off
	s_add_i32 m0, s47, 0x2000
	s_nop 0
	global_load_lds_dwordx4 v[158:159], off
	s_waitcnt vmcnt(10)
	s_barrier
	s_waitcnt lgkmcnt(0)
	s_setprio 1
	v_mfma_f32_16x16x32_bf16 v[120:123], v[230:233], v[178:181], v[120:123]
	v_mfma_f32_16x16x32_bf16 v[112:115], v[238:241], v[178:181], v[112:115]
	v_mfma_f32_16x16x32_bf16 v[104:107], v[230:233], v[186:189], v[104:107]
	v_mfma_f32_16x16x32_bf16 v[96:99], v[238:241], v[186:189], v[96:99]
	v_mfma_f32_16x16x32_bf16 v[88:91], v[230:233], v[194:197], v[88:91]
	v_mfma_f32_16x16x32_bf16 v[80:83], v[238:241], v[194:197], v[80:83]
	v_mfma_f32_16x16x32_bf16 v[72:75], v[230:233], v[222:225], v[72:75]
	v_mfma_f32_16x16x32_bf16 v[64:67], v[238:241], v[222:225], v[64:67]
	v_mfma_f32_16x16x32_bf16 v[120:123], v[234:237], v[182:185], v[120:123]
	v_mfma_f32_16x16x32_bf16 v[112:115], v[242:245], v[182:185], v[112:115]
	v_mfma_f32_16x16x32_bf16 v[104:107], v[234:237], v[190:193], v[104:107]
	v_mfma_f32_16x16x32_bf16 v[96:99], v[242:245], v[190:193], v[96:99]
	v_mfma_f32_16x16x32_bf16 v[88:91], v[234:237], v[218:221], v[88:91]
	v_mfma_f32_16x16x32_bf16 v[80:83], v[242:245], v[218:221], v[80:83]
	v_mfma_f32_16x16x32_bf16 v[72:75], v[234:237], v[226:229], v[72:75]
	v_mfma_f32_16x16x32_bf16 v[64:67], v[242:245], v[226:229], v[64:67]
	s_setprio 0
	s_mov_b32 m0, s34
	v_lshl_add_u64 v[214:215], s[24:25], 0, v[140:141]
	s_barrier
	ds_read_b128 v[178:181], v167 offset:16384
	ds_read_b128 v[182:185], v167 offset:17408
	ds_read_b128 v[186:189], v167 offset:18432
	ds_read_b128 v[190:193], v167 offset:19456
	ds_read_b128 v[194:197], v167 offset:20480
	ds_read_b128 v[218:221], v167 offset:21504
	ds_read_b128 v[222:225], v167 offset:22528
	ds_read_b128 v[226:229], v167 offset:23552
	global_load_lds_dwordx4 v[214:215], off
	v_lshl_add_u64 v[216:217], s[24:25], 0, v[138:139]
	s_mov_b32 m0, s35
	s_nop 0
	global_load_lds_dwordx4 v[216:217], off
	s_barrier
	s_waitcnt lgkmcnt(0)
	s_setprio 1
	v_mfma_f32_16x16x32_bf16 v[60:63], v[128:131], v[178:181], v[60:63]
	v_mfma_f32_16x16x32_bf16 v[52:55], v[150:153], v[178:181], v[52:55]
	v_mfma_f32_16x16x32_bf16 v[44:47], v[128:131], v[186:189], v[44:47]
	v_mfma_f32_16x16x32_bf16 v[36:39], v[150:153], v[186:189], v[36:39]
	v_mfma_f32_16x16x32_bf16 v[28:31], v[128:131], v[194:197], v[28:31]
	v_mfma_f32_16x16x32_bf16 v[20:23], v[150:153], v[194:197], v[20:23]
	v_mfma_f32_16x16x32_bf16 v[12:15], v[128:131], v[222:225], v[12:15]
	v_mfma_f32_16x16x32_bf16 v[4:7], v[150:153], v[222:225], v[4:7]
	v_mfma_f32_16x16x32_bf16 v[60:63], v[132:135], v[182:185], v[60:63]
	v_mfma_f32_16x16x32_bf16 v[52:55], v[174:177], v[182:185], v[52:55]
	v_mfma_f32_16x16x32_bf16 v[44:47], v[132:135], v[190:193], v[44:47]
	v_mfma_f32_16x16x32_bf16 v[36:39], v[174:177], v[190:193], v[36:39]
	v_mfma_f32_16x16x32_bf16 v[28:31], v[132:135], v[218:221], v[28:31]
	v_mfma_f32_16x16x32_bf16 v[20:23], v[174:177], v[218:221], v[20:23]
	v_mfma_f32_16x16x32_bf16 v[12:15], v[132:135], v[226:229], v[12:15]
	v_mfma_f32_16x16x32_bf16 v[4:7], v[174:177], v[226:229], v[4:7]
	s_setprio 0
	s_barrier
; #define PG8_STAGE(bufoff, gbase, voff) do { _Pragma("unroll") for (int _i = 0; _i < 2; ++_i) \
;         __builtin_amdgcn_global_load_lds((const unsigned*)((const char*)(gbase) + (voff)[_i]), (LAS unsigned*)(lds + (bufoff) + ldsw + _i * 8192), 16, 0, 0); } while (0)
; #define PG8_LDA(dst, b, h) do { _Pragma("unroll") for (int m = 0; m < 4; ++m) _Pragma("unroll") for (int k = 0; k < 2; ++k) dst[m][k] = *(const LAS bf16x8*)(lds + PG8_SA(b, h) + aoff + m * 2048 + k * 1024); } while (0)
; #define PG8_LDB(dst, b, h) do { _Pragma("unroll") for (int n = 0; n < 2; ++n) _Pragma("unroll") for (int k = 0; k < 2; ++k) dst[n][k] = *(const LAS bf16x8*)(lds + PG8_SB(b, h) + boff + n * 2048 + k * 1024); } while (0)
; #define PG8_MMA(ai, bj, At, Bt) do { __builtin_amdgcn_s_setprio(1); _Pragma("unroll") for (int m = 0; m < 4; ++m) _Pragma("unroll") for (int n = 0; n < 2; ++n) _Pragma("unroll") for (int k = 0; k < 2; ++k) \
;         acc[ai][bj][m][n] = __builtin_amdgcn_mfma_f32_16x16x32_bf16(Bt[n][k], At[m][k], acc[ai][bj][m][n], 0, 0, 0); __builtin_amdgcn_s_setprio(0); } while (0)
; #define PG8_WAIT_V(n) asm volatile("s_waitcnt vmcnt(" #n ")" ::: "memory")
; #define PG8_WAIT_L(n) asm volatile("s_waitcnt lgkmcnt(" #n ")" ::: "memory")
; #define PG8_BAR __builtin_amdgcn_s_barrier()
; #define PG8_SCHED __builtin_amdgcn_sched_barrier(0)
; template <class Epi>
; DEV void gemm_phase(LAS unsigned char* lds, const Gemm g, const StaticOrder& S, const Epi& E) {
;     ...
;             PG8_STAGE(PG8_SB(0, 1), b2 + hstep, voffB);
;             PG8_WAIT_V(6); PG8_BAR; PG8_MMA(1, 1, At, B1); PG8_BAR;
;             PG8_LDB(B0, 1, 0); PG8_SCHED; PG8_LDA(At, 1, 0); PG8_STAGE(PG8_SA(0, 1), a2 + hstep, voffA);
;             PG8_WAIT_L(8); PG8_BAR; PG8_WAIT_L(0); PG8_MMA(0, 0, At, B0); PG8_BAR; PG8_SCHED;
;             PG8_LDB(B1, 1, 1); PG8_STAGE(PG8_SB(1, 0), b3, voffB);
;             PG8_BAR; PG8_WAIT_L(0); PG8_MMA(0, 1, At, B1); PG8_BAR;
;             PG8_LDA(At, 1, 1); PG8_STAGE(PG8_SA(1, 0), a3, voffA);
	s_add_u32 s48, s22, 0x80000
	s_addc_u32 s49, s23, 0
	s_add_i32 s47, s50, s30
	v_lshl_add_u64 v[128:129], s[48:49], 0, v[160:161]
	s_mov_b32 m0, s47
	s_nop 0
	global_load_lds_dwordx4 v[128:129], off
	v_lshl_add_u64 v[128:129], s[48:49], 0, v[136:137]
	s_add_i32 m0, s47, 0x2000
	s_nop 0
	global_load_lds_dwordx4 v[128:129], off
	s_waitcnt vmcnt(10)
	s_barrier
	s_setprio 1
	v_mfma_f32_16x16x32_bf16 v[56:59], v[230:233], v[178:181], v[56:59]
	v_mfma_f32_16x16x32_bf16 v[48:51], v[238:241], v[178:181], v[48:51]
	v_mfma_f32_16x16x32_bf16 v[40:43], v[230:233], v[186:189], v[40:43]
	v_mfma_f32_16x16x32_bf16 v[32:35], v[238:241], v[186:189], v[32:35]
	v_mfma_f32_16x16x32_bf16 v[24:27], v[230:233], v[194:197], v[24:27]
	v_mfma_f32_16x16x32_bf16 v[16:19], v[238:241], v[194:197], v[16:19]
	v_mfma_f32_16x16x32_bf16 v[8:11], v[230:233], v[222:225], v[8:11]
	v_mfma_f32_16x16x32_bf16 v[0:3], v[238:241], v[222:225], v[0:3]
	v_mfma_f32_16x16x32_bf16 v[56:59], v[234:237], v[182:185], v[56:59]
	v_mfma_f32_16x16x32_bf16 v[48:51], v[242:245], v[182:185], v[48:51]
	v_mfma_f32_16x16x32_bf16 v[40:43], v[234:237], v[190:193], v[40:43]
	v_mfma_f32_16x16x32_bf16 v[32:35], v[242:245], v[190:193], v[32:35]
	v_mfma_f32_16x16x32_bf16 v[24:27], v[234:237], v[218:221], v[24:27]
	v_mfma_f32_16x16x32_bf16 v[16:19], v[242:245], v[218:221], v[16:19]
	v_mfma_f32_16x16x32_bf16 v[8:11], v[234:237], v[226:229], v[8:11]
	v_mfma_f32_16x16x32_bf16 v[0:3], v[242:245], v[226:229], v[0:3]
	s_setprio 0
	s_add_i32 s47, 0, 0x18000
	v_add_u32_e32 v148, s47, v155
	s_barrier
	ds_read_b128 v[128:131], v148
	ds_read_b128 v[132:135], v148 offset:1024
	ds_read_b128 v[150:153], v148 offset:2048
	ds_read_b128 v[174:177], v148 offset:3072
	s_add_u32 s24, s24, 0x80000
	s_addc_u32 s25, s25, 0
	s_mov_b32 m0, s36
	v_lshl_add_u64 v[230:231], s[24:25], 0, v[140:141]
	ds_read_b128 v[178:181], v167 offset:32768
	ds_read_b128 v[182:185], v167 offset:33792
	ds_read_b128 v[186:189], v167 offset:34816
	ds_read_b128 v[190:193], v167 offset:35840
	ds_read_b128 v[194:197], v167 offset:36864
	ds_read_b128 v[218:221], v167 offset:37888
	ds_read_b128 v[222:225], v167 offset:38912
	ds_read_b128 v[226:229], v167 offset:39936
	global_load_lds_dwordx4 v[230:231], off
	v_lshl_add_u64 v[230:231], s[24:25], 0, v[138:139]
	s_mov_b32 m0, s37
	s_nop 0
	global_load_lds_dwordx4 v[230:231], off
	s_waitcnt lgkmcnt(8)
	s_waitcnt vmcnt(10)
	s_barrier
	s_waitcnt lgkmcnt(0)
	s_setprio 1
	v_mfma_f32_16x16x32_bf16 v[124:127], v[128:131], v[178:181], v[124:127]
	v_mfma_f32_16x16x32_bf16 v[116:119], v[150:153], v[178:181], v[116:119]
	v_mfma_f32_16x16x32_bf16 v[108:111], v[128:131], v[186:189], v[108:111]
	v_mfma_f32_16x16x32_bf16 v[100:103], v[150:153], v[186:189], v[100:103]
	v_mfma_f32_16x16x32_bf16 v[92:95], v[128:131], v[194:197], v[92:95]
	v_mfma_f32_16x16x32_bf16 v[84:87], v[150:153], v[194:197], v[84:87]
	v_mfma_f32_16x16x32_bf16 v[76:79], v[128:131], v[222:225], v[76:79]
	v_mfma_f32_16x16x32_bf16 v[68:71], v[150:153], v[222:225], v[68:71]
	v_mfma_f32_16x16x32_bf16 v[124:127], v[132:135], v[182:185], v[124:127]
	v_mfma_f32_16x16x32_bf16 v[116:119], v[174:177], v[182:185], v[116:119]
	v_mfma_f32_16x16x32_bf16 v[108:111], v[132:135], v[190:193], v[108:111]
	v_mfma_f32_16x16x32_bf16 v[100:103], v[174:177], v[190:193], v[100:103]
	v_mfma_f32_16x16x32_bf16 v[92:95], v[132:135], v[218:221], v[92:95]
	v_mfma_f32_16x16x32_bf16 v[84:87], v[174:177], v[218:221], v[84:87]
	v_mfma_f32_16x16x32_bf16 v[76:79], v[132:135], v[226:229], v[76:79]
	v_mfma_f32_16x16x32_bf16 v[68:71], v[174:177], v[226:229], v[68:71]
	s_setprio 0
	s_barrier
	s_add_i32 s24, 0, 0x1c000
	s_add_i32 s25, s47, s30
	v_add_u32_e32 v148, s24, v155
	v_lshl_add_u64 v[146:147], v[146:147], 0, s[2:3]
	s_mov_b32 m0, s25
	ds_read_b128 v[230:233], v148
	ds_read_b128 v[234:237], v148 offset:1024
	ds_read_b128 v[238:241], v148 offset:2048
	ds_read_b128 v[242:245], v148 offset:3072
	global_load_lds_dwordx4 v[146:147], off
	v_lshl_add_u64 v[146:147], v[158:159], 0, s[2:3]
	s_add_i32 m0, s25, 0x2000
	s_nop 0
	global_load_lds_dwordx4 v[146:147], off
	s_waitcnt vmcnt(10)
	s_barrier
	s_waitcnt lgkmcnt(0)
	s_setprio 1
	v_mfma_f32_16x16x32_bf16 v[120:123], v[230:233], v[178:181], v[120:123]
	v_mfma_f32_16x16x32_bf16 v[112:115], v[238:241], v[178:181], v[112:115]
	v_mfma_f32_16x16x32_bf16 v[104:107], v[230:233], v[186:189], v[104:107]
	v_mfma_f32_16x16x32_bf16 v[96:99], v[238:241], v[186:189], v[96:99]
	v_mfma_f32_16x16x32_bf16 v[88:91], v[230:233], v[194:197], v[88:91]
	v_mfma_f32_16x16x32_bf16 v[80:83], v[238:241], v[194:197], v[80:83]
	v_mfma_f32_16x16x32_bf16 v[72:75], v[230:233], v[222:225], v[72:75]
	v_mfma_f32_16x16x32_bf16 v[64:67], v[238:241], v[222:225], v[64:67]
	v_mfma_f32_16x16x32_bf16 v[120:123], v[234:237], v[182:185], v[120:123]
	v_mfma_f32_16x16x32_bf16 v[112:115], v[242:245], v[182:185], v[112:115]
	v_mfma_f32_16x16x32_bf16 v[104:107], v[234:237], v[190:193], v[104:107]
	v_mfma_f32_16x16x32_bf16 v[96:99], v[242:245], v[190:193], v[96:99]
	v_mfma_f32_16x16x32_bf16 v[88:91], v[234:237], v[218:221], v[88:91]
	v_mfma_f32_16x16x32_bf16 v[80:83], v[242:245], v[218:221], v[80:83]
	v_mfma_f32_16x16x32_bf16 v[72:75], v[234:237], v[226:229], v[72:75]
	v_mfma_f32_16x16x32_bf16 v[64:67], v[242:245], v[226:229], v[64:67]
	s_setprio 0
	s_mov_b32 m0, s38
	v_lshl_add_u64 v[146:147], v[214:215], 0, s[2:3]
	s_barrier
	ds_read_b128 v[178:181], v167 offset:49152
	ds_read_b128 v[182:185], v167 offset:50176
	ds_read_b128 v[186:189], v167 offset:51200
	ds_read_b128 v[190:193], v167 offset:52224
	ds_read_b128 v[194:197], v167 offset:53248
	ds_read_b128 v[218:221], v167 offset:54272
	ds_read_b128 v[222:225], v167 offset:55296
	ds_read_b128 v[226:229], v167 offset:56320
	global_load_lds_dwordx4 v[146:147], off
	v_lshl_add_u64 v[146:147], v[216:217], 0, s[2:3]
	s_mov_b32 m0, s39
	s_nop 0
	global_load_lds_dwordx4 v[146:147], off
	s_barrier
; #define PG8_STAGE(bufoff, gbase, voff) do { _Pragma("unroll") for (int _i = 0; _i < 2; ++_i) \
;         __builtin_amdgcn_global_load_lds((const unsigned*)((const char*)(gbase) + (voff)[_i]), (LAS unsigned*)(lds + (bufoff) + ldsw + _i * 8192), 16, 0, 0); } while (0)
; #define PG8_MMA(ai, bj, At, Bt) do { __builtin_amdgcn_s_setprio(1); _Pragma("unroll") for (int m = 0; m < 4; ++m) _Pragma("unroll") for (int n = 0; n < 2; ++n) _Pragma("unroll") for (int k = 0; k < 2; ++k) \
;         acc[ai][bj][m][n] = __builtin_amdgcn_mfma_f32_16x16x32_bf16(Bt[n][k], At[m][k], acc[ai][bj][m][n], 0, 0, 0); __builtin_amdgcn_s_setprio(0); } while (0)
; #define PG8_WAIT_V(n) asm volatile("s_waitcnt vmcnt(" #n ")" ::: "memory")
; #define PG8_WAIT_L(n) asm volatile("s_waitcnt lgkmcnt(" #n ")" ::: "memory")
; #define PG8_BAR __builtin_amdgcn_s_barrier()
; #define PG8_SCHED __builtin_amdgcn_sched_barrier(0)
; template <class Epi>
; DEV void gemm_phase(LAS unsigned char* lds, const Gemm g, const StaticOrder& S, const Epi& E) {
;     ...
;             PG8_BAR; PG8_WAIT_L(0); PG8_MMA(1, 0, At, B0); PG8_BAR; PG8_SCHED;
;             PG8_STAGE(PG8_SB(1, 1), b3 + hstep, voffB);
;             PG8_WAIT_V(6); PG8_BAR; PG8_MMA(1, 1, At, B1); PG8_BAR;
;     DEV void operator()(AccRef acc, const pg8::Unit& u, int wr, int wc, int fr, int fq) const {
;         const int row0 = u.pm * 256 + wr * 64 + fr, col0 = u.pn * 128 + wc * 32 + 8 * fq;
;         float rsv[2][4];
; #pragma unroll
;         for (int ai = 0; ai < 2; ++ai)
; #pragma unroll
;             for (int m = 0; m < 4; ++m) rsv[ai][m] = rowscale(ss, row0 + ai * 128 + m * 16);
	s_waitcnt lgkmcnt(0)
	s_setprio 1
	v_mfma_f32_16x16x32_bf16 v[60:63], v[128:131], v[178:181], v[60:63]
	v_mfma_f32_16x16x32_bf16 v[52:55], v[150:153], v[178:181], v[52:55]
	v_mfma_f32_16x16x32_bf16 v[44:47], v[128:131], v[186:189], v[44:47]
	v_mfma_f32_16x16x32_bf16 v[36:39], v[150:153], v[186:189], v[36:39]
	v_mfma_f32_16x16x32_bf16 v[28:31], v[128:131], v[194:197], v[28:31]
	v_mfma_f32_16x16x32_bf16 v[20:23], v[150:153], v[194:197], v[20:23]
	v_mfma_f32_16x16x32_bf16 v[12:15], v[128:131], v[222:225], v[12:15]
	v_mfma_f32_16x16x32_bf16 v[4:7], v[150:153], v[222:225], v[4:7]
	v_mfma_f32_16x16x32_bf16 v[60:63], v[132:135], v[182:185], v[60:63]
	v_mfma_f32_16x16x32_bf16 v[52:55], v[174:177], v[182:185], v[52:55]
	v_mfma_f32_16x16x32_bf16 v[44:47], v[132:135], v[190:193], v[44:47]
	v_mfma_f32_16x16x32_bf16 v[36:39], v[174:177], v[190:193], v[36:39]
	v_mfma_f32_16x16x32_bf16 v[28:31], v[132:135], v[218:221], v[28:31]
	v_mfma_f32_16x16x32_bf16 v[20:23], v[174:177], v[218:221], v[20:23]
	v_mfma_f32_16x16x32_bf16 v[12:15], v[132:135], v[226:229], v[12:15]
	v_mfma_f32_16x16x32_bf16 v[4:7], v[174:177], v[226:229], v[4:7]
	s_setprio 0
	s_barrier
	s_add_u32 s22, s22, 0x80080
	s_addc_u32 s23, s23, 0
	s_add_i32 s24, s24, s30
	v_lshl_add_u64 v[128:129], s[22:23], 0, v[160:161]
	s_mov_b32 m0, s24
	s_nop 0
	global_load_lds_dwordx4 v[128:129], off
	v_lshl_add_u64 v[128:129], s[22:23], 0, v[136:137]
	s_add_i32 m0, s24, 0x2000
	s_nop 0
	global_load_lds_dwordx4 v[128:129], off
	s_waitcnt vmcnt(10)
	s_barrier
	s_setprio 1
	v_mfma_f32_16x16x32_bf16 v[56:59], v[230:233], v[178:181], v[56:59]
	v_mfma_f32_16x16x32_bf16 v[48:51], v[238:241], v[178:181], v[48:51]
	v_mfma_f32_16x16x32_bf16 v[40:43], v[230:233], v[186:189], v[40:43]
	v_mfma_f32_16x16x32_bf16 v[32:35], v[238:241], v[186:189], v[32:35]
	v_mfma_f32_16x16x32_bf16 v[24:27], v[230:233], v[194:197], v[24:27]
	v_mfma_f32_16x16x32_bf16 v[16:19], v[238:241], v[194:197], v[16:19]
	v_mfma_f32_16x16x32_bf16 v[8:11], v[230:233], v[222:225], v[8:11]
	v_mfma_f32_16x16x32_bf16 v[0:3], v[238:241], v[222:225], v[0:3]
	v_mfma_f32_16x16x32_bf16 v[56:59], v[234:237], v[182:185], v[56:59]
	v_mfma_f32_16x16x32_bf16 v[48:51], v[242:245], v[182:185], v[48:51]
	v_mfma_f32_16x16x32_bf16 v[40:43], v[234:237], v[190:193], v[40:43]
	v_mfma_f32_16x16x32_bf16 v[32:35], v[242:245], v[190:193], v[32:35]
	v_mfma_f32_16x16x32_bf16 v[24:27], v[234:237], v[218:221], v[24:27]
	v_mfma_f32_16x16x32_bf16 v[16:19], v[242:245], v[218:221], v[16:19]
	v_mfma_f32_16x16x32_bf16 v[8:11], v[234:237], v[226:229], v[8:11]
	v_mfma_f32_16x16x32_bf16 v[0:3], v[242:245], v[226:229], v[0:3]
	s_setprio 0
	s_add_i32 s46, s46, 2
	s_add_u32 s20, s20, 0x100
	s_addc_u32 s21, s21, 0
	s_add_u32 s44, s44, 0x100
	s_addc_u32 s45, s45, 0
	s_cmp_gt_u32 s46, 29
	s_barrier
	s_cbranch_scc0 .LBB0_755
	v_lshl_add_u32 v186, s4, 8, v149
	v_ashrrev_i32_e32 v187, 31, v186
	v_lshlrev_b64 v[146:147], 5, v[186:187]
	v_lshl_add_u64 v[146:147], s[8:9], 0, v[146:147]
	v_add_co_u32_e32 v158, vcc, 0x1000, v146
	global_load_dwordx4 v[218:221], v[146:147], off
	global_load_dwordx4 v[222:225], v[146:147], off offset:16
	v_addc_co_u32_e32 v159, vcc, 0, v147, vcc
	global_load_dwordx4 v[174:177], v[146:147], off offset:512
	global_load_dwordx4 v[230:233], v[146:147], off offset:528
	global_load_dwordx4 v[234:237], v[146:147], off offset:1024
	global_load_dwordx4 v[238:241], v[146:147], off offset:1040
	global_load_dwordx4 v[242:245], v[146:147], off offset:1536
	global_load_dwordx4 v[246:249], v[146:147], off offset:1552
	global_load_dwordx4 v[190:193], v[158:159], off
	global_load_dwordx4 v[194:197], v[158:159], off offset:16
	global_load_dwordx4 v[214:217], v[158:159], off offset:512
	global_load_dwordx4 v[132:135], v[158:159], off offset:528
	global_load_dwordx4 v[150:153], v[158:159], off offset:1024
	global_load_dwordx4 v[128:131], v[158:159], off offset:1040
	global_load_dwordx4 v[226:229], v[158:159], off offset:1536
	global_load_dwordx4 v[180:183], v[158:159], off offset:1552
	s_mov_b32 s12, 0x3a000000
	s_mov_b64 s[22:23], s[18:19]
	s_mov_b64 s[20:21], s[16:17]
	s_movk_i32 s11, 0x2c00
	v_readlane_b32 s4, v250, 11
	v_readlane_b32 s5, v250, 12
	s_waitcnt vmcnt(14)
	v_add_f32_e32 v218, v218, v219
	v_add_f32_e32 v220, v220, v221
	v_add_f32_e32 v222, v222, v223
	v_add_f32_e32 v224, v224, v225
	v_add_f32_e32 v218, v218, v220
	v_add_f32_e32 v218, v218, v222
	v_add_f32_e32 v218, v218, v224
	v_fmamk_f32 v218, v218, 0x3a000000, v199
	v_rsq_f32_e32 v184, v218
	s_waitcnt vmcnt(12)
	v_add_f32_e32 v174, v174, v175
	v_add_f32_e32 v176, v176, v177
	v_add_f32_e32 v230, v230, v231
	v_add_f32_e32 v232, v232, v233
	v_add_f32_e32 v174, v174, v176
	v_add_f32_e32 v174, v174, v230
	v_add_f32_e32 v174, v174, v232
	v_fmamk_f32 v174, v174, 0x3a000000, v199
	v_rsq_f32_e32 v176, v174
	v_pk_mul_f32 v[124:125], v[124:125], v[184:185] op_sel_hi:[1,0]
	v_pk_mul_f32 v[120:121], v[120:121], v[184:185] op_sel_hi:[1,0]
	v_pk_mul_f32 v[122:123], v[122:123], v[184:185] op_sel_hi:[1,0]
	v_pk_mul_f32 v[116:117], v[116:117], v[184:185] op_sel_hi:[1,0]
	v_pk_mul_f32 v[112:113], v[112:113], v[184:185] op_sel_hi:[1,0]
	v_pk_mul_f32 v[114:115], v[114:115], v[184:185] op_sel_hi:[1,0]
	s_waitcnt vmcnt(10)
	v_add_f32_e32 v234, v234, v235
	v_add_f32_e32 v236, v236, v237
	v_add_f32_e32 v238, v238, v239
	v_add_f32_e32 v240, v240, v241
	v_add_f32_e32 v234, v234, v236
	v_add_f32_e32 v234, v234, v238
	v_add_f32_e32 v234, v234, v240
	v_fmamk_f32 v234, v234, 0x3a000000, v199
	v_rsq_f32_e32 v178, v234
	v_pk_mul_f32 v[108:109], v[108:109], v[176:177] op_sel_hi:[1,0]
	v_pk_mul_f32 v[104:105], v[104:105], v[176:177] op_sel_hi:[1,0]
	v_pk_mul_f32 v[106:107], v[106:107], v[176:177] op_sel_hi:[1,0]
	v_pk_mul_f32 v[100:101], v[100:101], v[176:177] op_sel_hi:[1,0]
	v_pk_mul_f32 v[96:97], v[96:97], v[176:177] op_sel_hi:[1,0]
	v_pk_mul_f32 v[98:99], v[98:99], v[176:177] op_sel_hi:[1,0]
	s_waitcnt vmcnt(8)
; DEV float siluf(float x) { return x * __builtin_amdgcn_rcpf(1.0f + __builtin_amdgcn_exp2f(x * -1.4426950408889634f)); }
;     DEV void operator()(AccRef acc, const pg8::Unit& u, int wr, int wc, int fr, int fq) const {
;     ...
;             for (int m = 0; m < 4; ++m) rsv[ai][m] = rowscale(ss, row0 + ai * 128 + m * 16);
; #pragma unroll
;         for (int ai = 0; ai < 2; ++ai)
; #pragma unroll
;             for (int m = 0; m < 4; ++m) { u16* rowp = O + (size_t)(row0 + ai * 128 + m * 16) * 5632 + col0; const float rs = rsv[ai][m]; f32x4 r[2];
; #pragma unroll
;                 for (int n = 0; n < 2; ++n) { const f32x4 g = acc[ai][0][m][n] * rs, uu = acc[ai][1][m][n] * rs;
; #pragma unroll
;                     for (int e = 0; e < 4; ++e) r[n][e] = siluf(g[e]) * uu[e]; }
	v_add_f32_e32 v242, v242, v243
	v_add_f32_e32 v244, v244, v245
	v_add_f32_e32 v246, v246, v247
	v_add_f32_e32 v248, v248, v249
	v_add_f32_e32 v242, v242, v244
	v_add_f32_e32 v242, v242, v246
	v_add_f32_e32 v242, v242, v248
	v_fmamk_f32 v242, v242, 0x3a000000, v199
	v_rsq_f32_e32 v154, v242
	v_pk_mul_f32 v[92:93], v[92:93], v[178:179] op_sel_hi:[1,0]
	v_pk_mul_f32 v[88:89], v[88:89], v[178:179] op_sel_hi:[1,0]
	v_pk_mul_f32 v[90:91], v[90:91], v[178:179] op_sel_hi:[1,0]
	v_pk_mul_f32 v[84:85], v[84:85], v[178:179] op_sel_hi:[1,0]
	v_pk_mul_f32 v[80:81], v[80:81], v[178:179] op_sel_hi:[1,0]
	v_pk_mul_f32 v[82:83], v[82:83], v[178:179] op_sel_hi:[1,0]
	s_waitcnt vmcnt(6)
	v_add_f32_e32 v190, v190, v191
	v_add_f32_e32 v192, v192, v193
	v_add_f32_e32 v194, v194, v195
	v_add_f32_e32 v196, v196, v197
	v_add_f32_e32 v190, v190, v192
	v_add_f32_e32 v190, v190, v194
	v_add_f32_e32 v190, v190, v196
	v_fmamk_f32 v190, v190, 0x3a000000, v199
	v_rsq_f32_e32 v156, v190
	v_pk_mul_f32 v[76:77], v[76:77], v[154:155] op_sel_hi:[1,0]
	v_pk_mul_f32 v[72:73], v[72:73], v[154:155] op_sel_hi:[1,0]
	v_pk_mul_f32 v[74:75], v[74:75], v[154:155] op_sel_hi:[1,0]
	v_pk_mul_f32 v[68:69], v[68:69], v[154:155] op_sel_hi:[1,0]
	v_pk_mul_f32 v[64:65], v[64:65], v[154:155] op_sel_hi:[1,0]
	v_pk_mul_f32 v[66:67], v[66:67], v[154:155] op_sel_hi:[1,0]
	s_waitcnt vmcnt(4)
	v_add_f32_e32 v214, v214, v215
	v_add_f32_e32 v216, v216, v217
	v_add_f32_e32 v132, v132, v133
	v_add_f32_e32 v134, v134, v135
	v_add_f32_e32 v214, v214, v216
	v_add_f32_e32 v214, v214, v132
	v_add_f32_e32 v214, v214, v134
	v_fmamk_f32 v214, v214, 0x3a000000, v199
	v_rsq_f32_e32 v148, v214
	v_pk_mul_f32 v[60:61], v[60:61], v[156:157] op_sel_hi:[1,0]
	v_pk_mul_f32 v[56:57], v[56:57], v[156:157] op_sel_hi:[1,0]
	v_pk_mul_f32 v[58:59], v[58:59], v[156:157] op_sel_hi:[1,0]
	v_pk_mul_f32 v[52:53], v[52:53], v[156:157] op_sel_hi:[1,0]
	v_pk_mul_f32 v[48:49], v[48:49], v[156:157] op_sel_hi:[1,0]
	v_pk_mul_f32 v[50:51], v[50:51], v[156:157] op_sel_hi:[1,0]
	s_waitcnt vmcnt(2)
	v_add_f32_e32 v150, v150, v151
	v_add_f32_e32 v152, v152, v153
	v_add_f32_e32 v128, v128, v129
	v_add_f32_e32 v130, v130, v131
	v_add_f32_e32 v150, v150, v152
	v_add_f32_e32 v150, v150, v128
	v_add_f32_e32 v150, v150, v130
	v_fmamk_f32 v150, v150, 0x3a000000, v199
	v_rsq_f32_e32 v130, v150
	v_pk_mul_f32 v[44:45], v[44:45], v[148:149] op_sel_hi:[1,0]
	v_pk_mul_f32 v[40:41], v[40:41], v[148:149] op_sel_hi:[1,0]
	v_pk_mul_f32 v[42:43], v[42:43], v[148:149] op_sel_hi:[1,0]
	v_pk_mul_f32 v[36:37], v[36:37], v[148:149] op_sel_hi:[1,0]
	v_pk_mul_f32 v[32:33], v[32:33], v[148:149] op_sel_hi:[1,0]
	v_pk_mul_f32 v[34:35], v[34:35], v[148:149] op_sel_hi:[1,0]
	s_waitcnt vmcnt(0)
	v_add_f32_e32 v226, v226, v227
	v_add_f32_e32 v228, v228, v229
	v_add_f32_e32 v180, v180, v181
	v_add_f32_e32 v182, v182, v183
	v_add_f32_e32 v226, v226, v228
	v_add_f32_e32 v226, v226, v180
	v_add_f32_e32 v226, v226, v182
	v_fmamk_f32 v226, v226, 0x3a000000, v199
	v_rsq_f32_e32 v128, v226
	v_pk_mul_f32 v[28:29], v[28:29], v[130:131] op_sel_hi:[1,0]
	v_or_b32_e32 v182, 16, v186
	v_ashrrev_i32_e32 v183, 31, v182
	v_or_b32_e32 v180, 32, v186
	v_ashrrev_i32_e32 v181, 31, v180
	v_or_b32_e32 v174, 48, v186
	v_ashrrev_i32_e32 v175, 31, v174
	v_add_u32_e32 v158, 0x80, v186
	v_ashrrev_i32_e32 v159, 31, v158
	v_add_u32_e32 v152, 0x90, v186
	v_ashrrev_i32_e32 v153, 31, v152
	v_add_u32_e32 v150, 0xa0, v186
	v_ashrrev_i32_e32 v151, 31, v150
	v_add_u32_e32 v146, 0xb0, v186
	v_ashrrev_i32_e32 v147, 31, v146
	v_lshl_or_b32 v134, s42, 7, v157
	v_ashrrev_i32_e32 v135, 31, v134
	s_mov_b32 s42, s10
	v_mul_f32_e32 v129, 0xbfb8aa3b, v124
	v_exp_f32_e32 v129, v129
	v_mov_b64_e32 v[132:133], s[4:5]
	v_mad_i64_i32 v[186:187], s[4:5], v186, s11, v[132:133]
	v_add_f32_e32 v129, 1.0, v129
	v_rcp_f32_e32 v188, v129
	v_mul_f32_e32 v129, 0xbfb8aa3b, v125
	v_exp_f32_e32 v129, v129
	v_pk_mul_f32 v[24:25], v[24:25], v[130:131] op_sel_hi:[1,0]
	v_pk_mul_f32 v[26:27], v[26:27], v[130:131] op_sel_hi:[1,0]
	v_pk_mul_f32 v[20:21], v[20:21], v[130:131] op_sel_hi:[1,0]
	v_add_f32_e32 v129, 1.0, v129
	v_rcp_f32_e32 v189, v129
	v_pk_mul_f32 v[16:17], v[16:17], v[130:131] op_sel_hi:[1,0]
	v_pk_mul_f32 v[18:19], v[18:19], v[130:131] op_sel_hi:[1,0]
	v_pk_mul_f32 v[12:13], v[12:13], v[128:129] op_sel_hi:[1,0]
	v_pk_mul_f32 v[124:125], v[124:125], v[188:189]
	v_pk_mul_f32 v[8:9], v[8:9], v[128:129] op_sel_hi:[1,0]
	v_pk_mul_f32 v[120:121], v[120:121], v[124:125]
	v_pk_mul_f32 v[124:125], v[126:127], v[184:185] op_sel_hi:[1,0]
	v_pk_mul_f32 v[10:11], v[10:11], v[128:129] op_sel_hi:[1,0]
	v_mul_f32_e32 v126, 0xbfb8aa3b, v124
	v_mul_f32_e32 v127, 0xbfb8aa3b, v125
	v_exp_f32_e32 v126, v126
	v_exp_f32_e32 v127, v127
	v_pk_mul_f32 v[4:5], v[4:5], v[128:129] op_sel_hi:[1,0]
	v_pk_mul_f32 v[0:1], v[0:1], v[128:129] op_sel_hi:[1,0]
	v_add_f32_e32 v126, 1.0, v126
	v_add_f32_e32 v127, 1.0, v127
	v_rcp_f32_e32 v126, v126
	v_rcp_f32_e32 v127, v127
	v_pk_mul_f32 v[2:3], v[2:3], v[128:129] op_sel_hi:[1,0]
	s_and_b64 vcc, exec, s[0:1]
	v_pk_mul_f32 v[124:125], v[124:125], v[126:127]
	s_nop 0
	v_pk_mul_f32 v[122:123], v[122:123], v[124:125]
	v_mul_f32_e32 v124, 0xbfb8aa3b, v116
	v_mul_f32_e32 v125, 0xbfb8aa3b, v117
	v_exp_f32_e32 v124, v124
	v_exp_f32_e32 v125, v125
	v_add_f32_e32 v124, 1.0, v124
	v_add_f32_e32 v125, 1.0, v125
	v_rcp_f32_e32 v124, v124
	v_rcp_f32_e32 v125, v125
	s_nop 0
	v_pk_mul_f32 v[116:117], v[116:117], v[124:125]
	s_nop 0
	v_pk_mul_f32 v[116:117], v[112:113], v[116:117]
	v_pk_mul_f32 v[112:113], v[118:119], v[184:185] op_sel_hi:[1,0]
	v_cvt_pk_bf16_f32 v116, v116, v117
	v_mul_f32_e32 v118, 0xbfb8aa3b, v112
; DEV float siluf(float x) { return x * __builtin_amdgcn_rcpf(1.0f + __builtin_amdgcn_exp2f(x * -1.4426950408889634f)); }
; DEV bf16x8 pack8(f32x4 a, f32x4 b) { u32x4 w; w.x = cvt_pk_bf16(a[0], a[1]); w.y = cvt_pk_bf16(a[2], a[3]); w.z = cvt_pk_bf16(b[0], b[1]); w.w = cvt_pk_bf16(b[2], b[3]); return __builtin_bit_cast(bf16x8, w); }
;     DEV void operator()(AccRef acc, const pg8::Unit& u, int wr, int wc, int fr, int fq) const {
;     ...
;             for (int m = 0; m < 4; ++m) { u16* rowp = O + (size_t)(row0 + ai * 128 + m * 16) * 5632 + col0; const float rs = rsv[ai][m]; f32x4 r[2];
; #pragma unroll
;                 for (int n = 0; n < 2; ++n) { const f32x4 g = acc[ai][0][m][n] * rs, uu = acc[ai][1][m][n] * rs;
; #pragma unroll
;                     for (int e = 0; e < 4; ++e) r[n][e] = siluf(g[e]) * uu[e]; }
;                 *(u32x4*)rowp = __builtin_bit_cast(u32x4, pack8(r[0], r[1])); }
	v_mul_f32_e32 v119, 0xbfb8aa3b, v113
	v_exp_f32_e32 v118, v118
	v_exp_f32_e32 v119, v119
	v_add_f32_e32 v118, 1.0, v118
	v_add_f32_e32 v119, 1.0, v119
	v_rcp_f32_e32 v118, v118
	v_rcp_f32_e32 v119, v119
	s_nop 0
	v_pk_mul_f32 v[112:113], v[112:113], v[118:119]
	s_nop 0
	v_pk_mul_f32 v[118:119], v[114:115], v[112:113]
	v_lshlrev_b64 v[112:113], 1, v[134:135]
	v_lshl_add_u64 v[124:125], v[186:187], 0, v[112:113]
	v_cvt_pk_bf16_f32 v114, v120, v121
	v_cvt_pk_bf16_f32 v115, v122, v123
	v_cvt_pk_bf16_f32 v117, v118, v119
	global_store_dwordx4 v[124:125], v[114:117], off
	s_nop 1
	v_mul_f32_e32 v116, 0xbfb8aa3b, v108
	v_mul_f32_e32 v117, 0xbfb8aa3b, v109
	v_exp_f32_e32 v116, v116
	v_exp_f32_e32 v117, v117
	v_mad_i64_i32 v[114:115], s[4:5], v182, s11, v[132:133]
	v_add_f32_e32 v116, 1.0, v116
	v_add_f32_e32 v117, 1.0, v117
	v_rcp_f32_e32 v116, v116
	v_rcp_f32_e32 v117, v117
	s_nop 0
	v_pk_mul_f32 v[108:109], v[108:109], v[116:117]
	s_nop 0
	v_pk_mul_f32 v[104:105], v[104:105], v[108:109]
	v_pk_mul_f32 v[108:109], v[110:111], v[176:177] op_sel_hi:[1,0]
	s_nop 0
	v_mul_f32_e32 v110, 0xbfb8aa3b, v108
	v_mul_f32_e32 v111, 0xbfb8aa3b, v109
	v_exp_f32_e32 v110, v110
	v_exp_f32_e32 v111, v111
	v_add_f32_e32 v110, 1.0, v110
	v_add_f32_e32 v111, 1.0, v111
	v_rcp_f32_e32 v110, v110
	v_rcp_f32_e32 v111, v111
	s_nop 0
	v_pk_mul_f32 v[108:109], v[108:109], v[110:111]
	s_nop 0
	v_pk_mul_f32 v[106:107], v[106:107], v[108:109]
	v_mul_f32_e32 v108, 0xbfb8aa3b, v100
	v_mul_f32_e32 v109, 0xbfb8aa3b, v101
	v_exp_f32_e32 v108, v108
	v_exp_f32_e32 v109, v109
	v_add_f32_e32 v108, 1.0, v108
	v_add_f32_e32 v109, 1.0, v109
	v_rcp_f32_e32 v108, v108
	v_rcp_f32_e32 v109, v109
	s_nop 0
	v_pk_mul_f32 v[100:101], v[100:101], v[108:109]
	s_nop 0
	v_pk_mul_f32 v[100:101], v[96:97], v[100:101]
	v_pk_mul_f32 v[96:97], v[102:103], v[176:177] op_sel_hi:[1,0]
	v_lshl_add_u64 v[108:109], v[114:115], 0, v[112:113]
	v_mul_f32_e32 v102, 0xbfb8aa3b, v96
	v_mul_f32_e32 v103, 0xbfb8aa3b, v97
	v_exp_f32_e32 v102, v102
	v_exp_f32_e32 v103, v103
	v_add_f32_e32 v102, 1.0, v102
	v_add_f32_e32 v103, 1.0, v103
	v_rcp_f32_e32 v102, v102
	v_rcp_f32_e32 v103, v103
	s_nop 0
	v_pk_mul_f32 v[96:97], v[96:97], v[102:103]
	s_nop 0
	v_pk_mul_f32 v[102:103], v[98:99], v[96:97]
	v_cvt_pk_bf16_f32 v96, v104, v105
	v_cvt_pk_bf16_f32 v97, v106, v107
	v_cvt_pk_bf16_f32 v98, v100, v101
	v_cvt_pk_bf16_f32 v99, v102, v103
	global_store_dwordx4 v[108:109], v[96:99], off
	s_nop 1
	v_mul_f32_e32 v98, 0xbfb8aa3b, v92
	v_mul_f32_e32 v99, 0xbfb8aa3b, v93
	v_exp_f32_e32 v98, v98
	v_exp_f32_e32 v99, v99
	v_mad_i64_i32 v[96:97], s[4:5], v180, s11, v[132:133]
	v_add_f32_e32 v98, 1.0, v98
	v_add_f32_e32 v99, 1.0, v99
	v_rcp_f32_e32 v98, v98
	v_rcp_f32_e32 v99, v99
	s_nop 0
	v_pk_mul_f32 v[92:93], v[92:93], v[98:99]
	s_nop 0
	v_pk_mul_f32 v[88:89], v[88:89], v[92:93]
	v_pk_mul_f32 v[92:93], v[94:95], v[178:179] op_sel_hi:[1,0]
	s_nop 0
	v_mul_f32_e32 v94, 0xbfb8aa3b, v92
	v_mul_f32_e32 v95, 0xbfb8aa3b, v93
	v_exp_f32_e32 v94, v94
	v_exp_f32_e32 v95, v95
	v_add_f32_e32 v94, 1.0, v94
	v_add_f32_e32 v95, 1.0, v95
	v_rcp_f32_e32 v94, v94
	v_rcp_f32_e32 v95, v95
	s_nop 0
	v_pk_mul_f32 v[92:93], v[92:93], v[94:95]
	s_nop 0
	v_pk_mul_f32 v[90:91], v[90:91], v[92:93]
	v_mul_f32_e32 v92, 0xbfb8aa3b, v84
	v_mul_f32_e32 v93, 0xbfb8aa3b, v85
	v_exp_f32_e32 v92, v92
	v_exp_f32_e32 v93, v93
	v_add_f32_e32 v92, 1.0, v92
	v_add_f32_e32 v93, 1.0, v93
	v_rcp_f32_e32 v92, v92
	v_rcp_f32_e32 v93, v93
	s_nop 0
	v_pk_mul_f32 v[84:85], v[84:85], v[92:93]
	s_nop 0
	v_pk_mul_f32 v[84:85], v[80:81], v[84:85]
	v_pk_mul_f32 v[80:81], v[86:87], v[178:179] op_sel_hi:[1,0]
	v_lshl_add_u64 v[92:93], v[96:97], 0, v[112:113]
	v_mul_f32_e32 v86, 0xbfb8aa3b, v80
	v_mul_f32_e32 v87, 0xbfb8aa3b, v81
	v_exp_f32_e32 v86, v86
	v_exp_f32_e32 v87, v87
	v_add_f32_e32 v86, 1.0, v86
	v_add_f32_e32 v87, 1.0, v87
	v_rcp_f32_e32 v86, v86
	v_rcp_f32_e32 v87, v87
	s_nop 0
	v_pk_mul_f32 v[80:81], v[80:81], v[86:87]
	s_nop 0
	v_pk_mul_f32 v[86:87], v[82:83], v[80:81]
	v_cvt_pk_bf16_f32 v80, v88, v89
	v_cvt_pk_bf16_f32 v81, v90, v91
	v_cvt_pk_bf16_f32 v82, v84, v85
	v_cvt_pk_bf16_f32 v83, v86, v87
	global_store_dwordx4 v[92:93], v[80:83], off
	s_nop 1
	v_mul_f32_e32 v82, 0xbfb8aa3b, v76
	v_mul_f32_e32 v83, 0xbfb8aa3b, v77
	v_exp_f32_e32 v82, v82
	v_exp_f32_e32 v83, v83
	v_mad_i64_i32 v[80:81], s[4:5], v174, s11, v[132:133]
	v_add_f32_e32 v82, 1.0, v82
	v_add_f32_e32 v83, 1.0, v83
	v_rcp_f32_e32 v82, v82
	v_rcp_f32_e32 v83, v83
	s_nop 0
	v_pk_mul_f32 v[76:77], v[76:77], v[82:83]
	s_nop 0
	v_pk_mul_f32 v[72:73], v[72:73], v[76:77]
	v_pk_mul_f32 v[76:77], v[78:79], v[154:155] op_sel_hi:[1,0]
	s_nop 0
	v_mul_f32_e32 v78, 0xbfb8aa3b, v76
	v_mul_f32_e32 v79, 0xbfb8aa3b, v77
	v_exp_f32_e32 v78, v78
	v_exp_f32_e32 v79, v79
	v_add_f32_e32 v78, 1.0, v78
	v_add_f32_e32 v79, 1.0, v79
	v_rcp_f32_e32 v78, v78
	v_rcp_f32_e32 v79, v79
	s_nop 0
	v_pk_mul_f32 v[76:77], v[76:77], v[78:79]
	s_nop 0
	v_pk_mul_f32 v[74:75], v[74:75], v[76:77]
	v_mul_f32_e32 v76, 0xbfb8aa3b, v68
	v_mul_f32_e32 v77, 0xbfb8aa3b, v69
	v_exp_f32_e32 v76, v76
	v_exp_f32_e32 v77, v77
	v_add_f32_e32 v76, 1.0, v76
	v_add_f32_e32 v77, 1.0, v77
	v_rcp_f32_e32 v76, v76
	v_rcp_f32_e32 v77, v77
	s_nop 0
	v_pk_mul_f32 v[68:69], v[68:69], v[76:77]
	s_nop 0
	v_pk_mul_f32 v[68:69], v[64:65], v[68:69]
	v_pk_mul_f32 v[64:65], v[70:71], v[154:155] op_sel_hi:[1,0]
	v_lshl_add_u64 v[76:77], v[80:81], 0, v[112:113]
	v_mul_f32_e32 v70, 0xbfb8aa3b, v64
	v_mul_f32_e32 v71, 0xbfb8aa3b, v65
	v_exp_f32_e32 v70, v70
	v_exp_f32_e32 v71, v71
	v_add_f32_e32 v70, 1.0, v70
	v_add_f32_e32 v71, 1.0, v71
	v_rcp_f32_e32 v70, v70
	v_rcp_f32_e32 v71, v71
; DEV float siluf(float x) { return x * __builtin_amdgcn_rcpf(1.0f + __builtin_amdgcn_exp2f(x * -1.4426950408889634f)); }
; DEV bf16x8 pack8(f32x4 a, f32x4 b) { u32x4 w; w.x = cvt_pk_bf16(a[0], a[1]); w.y = cvt_pk_bf16(a[2], a[3]); w.z = cvt_pk_bf16(b[0], b[1]); w.w = cvt_pk_bf16(b[2], b[3]); return __builtin_bit_cast(bf16x8, w); }
;     DEV void operator()(AccRef acc, const pg8::Unit& u, int wr, int wc, int fr, int fq) const {
;     ...
;             for (int m = 0; m < 4; ++m) { u16* rowp = O + (size_t)(row0 + ai * 128 + m * 16) * 5632 + col0; const float rs = rsv[ai][m]; f32x4 r[2];
; #pragma unroll
;                 for (int n = 0; n < 2; ++n) { const f32x4 g = acc[ai][0][m][n] * rs, uu = acc[ai][1][m][n] * rs;
; #pragma unroll
;                     for (int e = 0; e < 4; ++e) r[n][e] = siluf(g[e]) * uu[e]; }
;                 *(u32x4*)rowp = __builtin_bit_cast(u32x4, pack8(r[0], r[1])); }
	s_nop 0
	v_pk_mul_f32 v[64:65], v[64:65], v[70:71]
	s_nop 0
	v_pk_mul_f32 v[70:71], v[66:67], v[64:65]
	v_cvt_pk_bf16_f32 v64, v72, v73
	v_cvt_pk_bf16_f32 v65, v74, v75
	v_cvt_pk_bf16_f32 v66, v68, v69
	v_cvt_pk_bf16_f32 v67, v70, v71
	global_store_dwordx4 v[76:77], v[64:67], off
	s_nop 1
	v_mul_f32_e32 v66, 0xbfb8aa3b, v60
	v_mul_f32_e32 v67, 0xbfb8aa3b, v61
	v_exp_f32_e32 v66, v66
	v_exp_f32_e32 v67, v67
	v_mad_i64_i32 v[64:65], s[4:5], v158, s11, v[132:133]
	v_add_f32_e32 v66, 1.0, v66
	v_add_f32_e32 v67, 1.0, v67
	v_rcp_f32_e32 v66, v66
	v_rcp_f32_e32 v67, v67
	s_nop 0
	v_pk_mul_f32 v[60:61], v[60:61], v[66:67]
	s_nop 0
	v_pk_mul_f32 v[56:57], v[56:57], v[60:61]
	v_pk_mul_f32 v[60:61], v[62:63], v[156:157] op_sel_hi:[1,0]
	s_nop 0
	v_mul_f32_e32 v62, 0xbfb8aa3b, v60
	v_mul_f32_e32 v63, 0xbfb8aa3b, v61
	v_exp_f32_e32 v62, v62
	v_exp_f32_e32 v63, v63
	v_add_f32_e32 v62, 1.0, v62
	v_add_f32_e32 v63, 1.0, v63
	v_rcp_f32_e32 v62, v62
	v_rcp_f32_e32 v63, v63
	s_nop 0
	v_pk_mul_f32 v[60:61], v[60:61], v[62:63]
	s_nop 0
	v_pk_mul_f32 v[58:59], v[58:59], v[60:61]
	v_mul_f32_e32 v60, 0xbfb8aa3b, v52
	v_mul_f32_e32 v61, 0xbfb8aa3b, v53
	v_exp_f32_e32 v60, v60
	v_exp_f32_e32 v61, v61
	v_add_f32_e32 v60, 1.0, v60
	v_add_f32_e32 v61, 1.0, v61
	v_rcp_f32_e32 v60, v60
	v_rcp_f32_e32 v61, v61
	s_nop 0
	v_pk_mul_f32 v[52:53], v[52:53], v[60:61]
	s_nop 0
	v_pk_mul_f32 v[52:53], v[48:49], v[52:53]
	v_pk_mul_f32 v[48:49], v[54:55], v[156:157] op_sel_hi:[1,0]
	v_lshl_add_u64 v[60:61], v[64:65], 0, v[112:113]
	v_mul_f32_e32 v54, 0xbfb8aa3b, v48
	v_mul_f32_e32 v55, 0xbfb8aa3b, v49
	v_exp_f32_e32 v54, v54
	v_exp_f32_e32 v55, v55
	v_add_f32_e32 v54, 1.0, v54
	v_add_f32_e32 v55, 1.0, v55
	v_rcp_f32_e32 v54, v54
	v_rcp_f32_e32 v55, v55
	s_nop 0
	v_pk_mul_f32 v[48:49], v[48:49], v[54:55]
	s_nop 0
	v_pk_mul_f32 v[54:55], v[50:51], v[48:49]
	v_cvt_pk_bf16_f32 v48, v56, v57
	v_cvt_pk_bf16_f32 v49, v58, v59
	v_cvt_pk_bf16_f32 v50, v52, v53
	v_cvt_pk_bf16_f32 v51, v54, v55
	global_store_dwordx4 v[60:61], v[48:51], off
	s_nop 1
	v_mul_f32_e32 v50, 0xbfb8aa3b, v44
	v_mul_f32_e32 v51, 0xbfb8aa3b, v45
	v_exp_f32_e32 v50, v50
	v_exp_f32_e32 v51, v51
	v_mad_i64_i32 v[48:49], s[4:5], v152, s11, v[132:133]
	v_add_f32_e32 v50, 1.0, v50
	v_add_f32_e32 v51, 1.0, v51
	v_rcp_f32_e32 v50, v50
	v_rcp_f32_e32 v51, v51
	s_nop 0
	v_pk_mul_f32 v[44:45], v[44:45], v[50:51]
	s_nop 0
	v_pk_mul_f32 v[40:41], v[40:41], v[44:45]
	v_pk_mul_f32 v[44:45], v[46:47], v[148:149] op_sel_hi:[1,0]
	s_nop 0
	v_mul_f32_e32 v46, 0xbfb8aa3b, v44
	v_mul_f32_e32 v47, 0xbfb8aa3b, v45
	v_exp_f32_e32 v46, v46
	v_exp_f32_e32 v47, v47
	v_add_f32_e32 v46, 1.0, v46
	v_add_f32_e32 v47, 1.0, v47
	v_rcp_f32_e32 v46, v46
	v_rcp_f32_e32 v47, v47
	s_nop 0
	v_pk_mul_f32 v[44:45], v[44:45], v[46:47]
	s_nop 0
	v_pk_mul_f32 v[42:43], v[42:43], v[44:45]
	v_mul_f32_e32 v44, 0xbfb8aa3b, v36
	v_mul_f32_e32 v45, 0xbfb8aa3b, v37
	v_exp_f32_e32 v44, v44
	v_exp_f32_e32 v45, v45
	v_add_f32_e32 v44, 1.0, v44
	v_add_f32_e32 v45, 1.0, v45
	v_rcp_f32_e32 v44, v44
	v_rcp_f32_e32 v45, v45
	s_nop 0
	v_pk_mul_f32 v[36:37], v[36:37], v[44:45]
	s_nop 0
	v_pk_mul_f32 v[36:37], v[32:33], v[36:37]
	v_pk_mul_f32 v[32:33], v[38:39], v[148:149] op_sel_hi:[1,0]
	v_lshl_add_u64 v[44:45], v[48:49], 0, v[112:113]
	v_mul_f32_e32 v38, 0xbfb8aa3b, v32
	v_mul_f32_e32 v39, 0xbfb8aa3b, v33
	v_exp_f32_e32 v38, v38
	v_exp_f32_e32 v39, v39
	v_add_f32_e32 v38, 1.0, v38
	v_add_f32_e32 v39, 1.0, v39
	v_rcp_f32_e32 v38, v38
	v_rcp_f32_e32 v39, v39
	s_nop 0
	v_pk_mul_f32 v[32:33], v[32:33], v[38:39]
	s_nop 0
	v_pk_mul_f32 v[38:39], v[34:35], v[32:33]
	v_cvt_pk_bf16_f32 v32, v40, v41
	v_cvt_pk_bf16_f32 v33, v42, v43
; DEV float siluf(float x) { return x * __builtin_amdgcn_rcpf(1.0f + __builtin_amdgcn_exp2f(x * -1.4426950408889634f)); }
; DEV bf16x8 pack8(f32x4 a, f32x4 b) { u32x4 w; w.x = cvt_pk_bf16(a[0], a[1]); w.y = cvt_pk_bf16(a[2], a[3]); w.z = cvt_pk_bf16(b[0], b[1]); w.w = cvt_pk_bf16(b[2], b[3]); return __builtin_bit_cast(bf16x8, w); }
; #define PG8_WAIT_V(n) asm volatile("s_waitcnt vmcnt(" #n ")" ::: "memory")
; #define PG8_BAR __builtin_amdgcn_s_barrier()
; template <class Epi>
; DEV void gemm_phase(LAS unsigned char* lds, const Gemm g, const StaticOrder& S, const Epi& E) {
;     ...
;     PG8_WAIT_V(0);
;     if (wr == 0) PG8_BAR;
;     PG8_BAR;
;     DEV void operator()(AccRef acc, const pg8::Unit& u, int wr, int wc, int fr, int fq) const {
;     ...
;             for (int m = 0; m < 4; ++m) { u16* rowp = O + (size_t)(row0 + ai * 128 + m * 16) * 5632 + col0; const float rs = rsv[ai][m]; f32x4 r[2];
; #pragma unroll
;                 for (int n = 0; n < 2; ++n) { const f32x4 g = acc[ai][0][m][n] * rs, uu = acc[ai][1][m][n] * rs;
; #pragma unroll
;                     for (int e = 0; e < 4; ++e) r[n][e] = siluf(g[e]) * uu[e]; }
;                 *(u32x4*)rowp = __builtin_bit_cast(u32x4, pack8(r[0], r[1])); }
	v_cvt_pk_bf16_f32 v34, v36, v37
	v_cvt_pk_bf16_f32 v35, v38, v39
	global_store_dwordx4 v[44:45], v[32:35], off
	s_nop 1
	v_mul_f32_e32 v34, 0xbfb8aa3b, v28
	v_mul_f32_e32 v35, 0xbfb8aa3b, v29
	v_exp_f32_e32 v34, v34
	v_exp_f32_e32 v35, v35
	v_mad_i64_i32 v[32:33], s[4:5], v150, s11, v[132:133]
	v_add_f32_e32 v34, 1.0, v34
	v_add_f32_e32 v35, 1.0, v35
	v_rcp_f32_e32 v34, v34
	v_rcp_f32_e32 v35, v35
	s_nop 0
	v_pk_mul_f32 v[28:29], v[28:29], v[34:35]
	s_nop 0
	v_pk_mul_f32 v[24:25], v[24:25], v[28:29]
	v_pk_mul_f32 v[28:29], v[30:31], v[130:131] op_sel_hi:[1,0]
	s_nop 0
	v_mul_f32_e32 v30, 0xbfb8aa3b, v28
	v_mul_f32_e32 v31, 0xbfb8aa3b, v29
	v_exp_f32_e32 v30, v30
	v_exp_f32_e32 v31, v31
	v_add_f32_e32 v30, 1.0, v30
	v_add_f32_e32 v31, 1.0, v31
	v_rcp_f32_e32 v30, v30
	v_rcp_f32_e32 v31, v31
	s_nop 0
	v_pk_mul_f32 v[28:29], v[28:29], v[30:31]
	s_nop 0
	v_pk_mul_f32 v[26:27], v[26:27], v[28:29]
	v_mul_f32_e32 v28, 0xbfb8aa3b, v20
	v_mul_f32_e32 v29, 0xbfb8aa3b, v21
	v_exp_f32_e32 v28, v28
	v_exp_f32_e32 v29, v29
	v_add_f32_e32 v28, 1.0, v28
	v_add_f32_e32 v29, 1.0, v29
	v_rcp_f32_e32 v28, v28
	v_rcp_f32_e32 v29, v29
	s_nop 0
	v_pk_mul_f32 v[20:21], v[20:21], v[28:29]
	s_nop 0
	v_pk_mul_f32 v[20:21], v[16:17], v[20:21]
	v_pk_mul_f32 v[16:17], v[22:23], v[130:131] op_sel_hi:[1,0]
	v_lshl_add_u64 v[28:29], v[32:33], 0, v[112:113]
	v_mul_f32_e32 v22, 0xbfb8aa3b, v16
	v_mul_f32_e32 v23, 0xbfb8aa3b, v17
	v_exp_f32_e32 v22, v22
	v_exp_f32_e32 v23, v23
	v_add_f32_e32 v22, 1.0, v22
	v_add_f32_e32 v23, 1.0, v23
	v_rcp_f32_e32 v22, v22
	v_rcp_f32_e32 v23, v23
	s_nop 0
	v_pk_mul_f32 v[16:17], v[16:17], v[22:23]
	s_nop 0
	v_pk_mul_f32 v[22:23], v[18:19], v[16:17]
	v_cvt_pk_bf16_f32 v16, v24, v25
	v_cvt_pk_bf16_f32 v17, v26, v27
	v_cvt_pk_bf16_f32 v18, v20, v21
	v_cvt_pk_bf16_f32 v19, v22, v23
	global_store_dwordx4 v[28:29], v[16:19], off
	s_nop 1
	v_mul_f32_e32 v18, 0xbfb8aa3b, v12
	v_mul_f32_e32 v19, 0xbfb8aa3b, v13
	v_exp_f32_e32 v18, v18
	v_exp_f32_e32 v19, v19
	v_mad_i64_i32 v[16:17], s[4:5], v146, s11, v[132:133]
	v_add_f32_e32 v18, 1.0, v18
	v_add_f32_e32 v19, 1.0, v19
	v_rcp_f32_e32 v18, v18
	v_rcp_f32_e32 v19, v19
	s_mov_b32 s4, s14
	v_pk_mul_f32 v[12:13], v[12:13], v[18:19]
	s_nop 0
	v_pk_mul_f32 v[8:9], v[8:9], v[12:13]
	v_pk_mul_f32 v[12:13], v[14:15], v[128:129] op_sel_hi:[1,0]
	s_nop 0
	v_mul_f32_e32 v14, 0xbfb8aa3b, v12
	v_mul_f32_e32 v15, 0xbfb8aa3b, v13
	v_exp_f32_e32 v14, v14
	v_exp_f32_e32 v15, v15
	v_add_f32_e32 v14, 1.0, v14
	v_add_f32_e32 v15, 1.0, v15
	v_rcp_f32_e32 v14, v14
	v_rcp_f32_e32 v15, v15
	s_nop 0
	v_pk_mul_f32 v[12:13], v[12:13], v[14:15]
	s_nop 0
	v_pk_mul_f32 v[10:11], v[10:11], v[12:13]
	v_mul_f32_e32 v12, 0xbfb8aa3b, v4
	v_mul_f32_e32 v13, 0xbfb8aa3b, v5
	v_exp_f32_e32 v12, v12
	v_exp_f32_e32 v13, v13
	v_add_f32_e32 v12, 1.0, v12
	v_add_f32_e32 v13, 1.0, v13
	v_rcp_f32_e32 v12, v12
	v_rcp_f32_e32 v13, v13
	s_nop 0
	v_pk_mul_f32 v[4:5], v[4:5], v[12:13]
	s_nop 0
	v_pk_mul_f32 v[4:5], v[0:1], v[4:5]
	v_pk_mul_f32 v[0:1], v[6:7], v[128:129] op_sel_hi:[1,0]
	v_lshl_add_u64 v[12:13], v[16:17], 0, v[112:113]
	v_mul_f32_e32 v6, 0xbfb8aa3b, v0
	v_mul_f32_e32 v7, 0xbfb8aa3b, v1
	v_exp_f32_e32 v6, v6
	v_exp_f32_e32 v7, v7
	v_add_f32_e32 v6, 1.0, v6
	v_add_f32_e32 v7, 1.0, v7
	v_rcp_f32_e32 v6, v6
	v_rcp_f32_e32 v7, v7
	s_nop 0
	v_pk_mul_f32 v[0:1], v[0:1], v[6:7]
	s_nop 0
	v_pk_mul_f32 v[6:7], v[2:3], v[0:1]
	v_cvt_pk_bf16_f32 v0, v8, v9
	v_cvt_pk_bf16_f32 v1, v10, v11
	v_cvt_pk_bf16_f32 v2, v4, v5
	v_cvt_pk_bf16_f32 v3, v6, v7
	global_store_dwordx4 v[12:13], v[0:3], off
	s_cbranch_vccz .LBB0_752
	s_waitcnt vmcnt(0)
	s_cmpk_gt_u32 s27, 0xff
	s_cbranch_scc1 .LBB0_759
	s_barrier
